# GEMM loops: removed the back-to-back setprio 0/1 dip between the two MFMA clusters of each phase (on top of saddr DMA + attention double buffer)
# speedup vs baseline: 1.0037x; 1.0008x over previous
; #define PG8_STAGE(bufoff, gbase, voff) do { _Pragma("unroll") for (int _i = 0; _i < 2; ++_i) \
;         __builtin_amdgcn_global_load_lds((const unsigned*)((const char*)(gbase) + (voff)[_i]), (LAS unsigned*)(lds + (bufoff) + ldsw + _i * 8192), 16, 0, 0); } while (0)
; #define PG8_LDA(dst, b, h) do { _Pragma("unroll") for (int m = 0; m < 4; ++m) _Pragma("unroll") for (int k = 0; k < 2; ++k) dst[m][k] = *(const LAS bf16x8*)(lds + PG8_SA(b, h) + aoff + m * 2048 + k * 1024); } while (0)
; #define PG8_LDB(dst, b, h) do { _Pragma("unroll") for (int n = 0; n < 2; ++n) _Pragma("unroll") for (int k = 0; k < 2; ++k) dst[n][k] = *(const LAS bf16x8*)(lds + PG8_SB(b, h) + boff + n * 2048 + k * 1024); } while (0)
; #define PG8_MMA(ai, bj, At, Bt) do { __builtin_amdgcn_s_setprio(1); _Pragma("unroll") for (int m = 0; m < 4; ++m) _Pragma("unroll") for (int n = 0; n < 2; ++n) _Pragma("unroll") for (int k = 0; k < 2; ++k) \
;         acc[ai][bj][m][n] = __builtin_amdgcn_mfma_f32_16x16x32_bf16(Bt[n][k], At[m][k], acc[ai][bj][m][n], 0, 0, 0); __builtin_amdgcn_s_setprio(0); } while (0)
; #define PG8_WAIT_V(n) asm volatile("s_waitcnt vmcnt(" #n ")" ::: "memory")
; #define PG8_WAIT_L(n) asm volatile("s_waitcnt lgkmcnt(" #n ")" ::: "memory")
; #define PG8_BAR __builtin_amdgcn_s_barrier()
; #define PG8_SCHED __builtin_amdgcn_sched_barrier(0)
; template <class Epi, bool ALIGN_EPI, int K, int LDA, int LDB>
; __device__ __forceinline__ void gemm_phase(LAS unsigned char* lds, const int wid, const Gemm g, const StaticOrder& S, const Epi& E) {
;     ...
;             PG8_LDB(B0, 0, 0); PG8_LDB(B1, 0, 1); PG8_SCHED; PG8_LDA(At, 0, 0); PG8_STAGE(PG8_SA(1, 1), a1 + hA, voffA);
;             PG8_WAIT_V(8); PG8_WAIT_L(0); PG8_BAR; PG8_MMA(0, 0, At, B0); PG8_MMA(0, 1, At, B1); PG8_BAR; PG8_SCHED;
;             PG8_LDA(At, 0, 1); PG8_STAGE(PG8_SB(0, 0), b2, voffB); PG8_STAGE(PG8_SB(0, 1), b2 + hB, voffB); PG8_STAGE(PG8_SA(0, 0), a2, voffA);
;             PG8_WAIT_V(8); PG8_WAIT_L(0); PG8_BAR; PG8_MMA(1, 0, At, B0); PG8_MMA(1, 1, At, B1); PG8_BAR; PG8_SCHED;
.LBB0_232:
	ds_read_b128 v[148:151], v145
	ds_read_b128 v[152:155], v145 offset:1024
	ds_read_b128 v[156:159], v145 offset:2048
	ds_read_b128 v[160:163], v145 offset:3072
	ds_read_b128 v[164:167], v146
	ds_read_b128 v[168:171], v146 offset:1024
	ds_read_b128 v[172:175], v146 offset:2048
	ds_read_b128 v[176:179], v146 offset:3072
	s_add_u32 s24, s22, 0xfffc0080
	s_addc_u32 s25, s23, -1
	s_cmp_eq_u32 s55, 12
	s_cselect_b32 s27, s17, s25
	s_cselect_b32 s26, s48, s24
	s_cselect_b32 s25, s15, s54
	s_cselect_b32 s24, s49, s51
	s_add_i32 m0, s13, 0xc000
	ds_read_b128 v[180:183], v147
	ds_read_b128 v[184:187], v147 offset:1024
	ds_read_b128 v[188:191], v147 offset:2048
	ds_read_b128 v[192:195], v147 offset:3072
	ds_read_b128 v[196:199], v147 offset:4096
	ds_read_b128 v[200:203], v147 offset:5120
	ds_read_b128 v[204:207], v147 offset:6144
	ds_read_b128 v[208:211], v147 offset:7168
	global_load_lds_dwordx4 v136, s[22:23]
	s_add_i32 m0, s13, 0xe000
	s_nop 0
	global_load_lds_dwordx4 v138, s[22:23]
	s_waitcnt vmcnt(8)
	s_waitcnt lgkmcnt(0)
	s_barrier
	s_setprio 1
	s_waitcnt lgkmcnt(0)
	v_mfma_f32_16x16x32_bf16 v[124:127], v[148:151], v[180:183], v[124:127]
	v_mfma_f32_16x16x32_bf16 v[120:123], v[156:159], v[180:183], v[120:123]
	v_mfma_f32_16x16x32_bf16 v[116:119], v[148:151], v[188:191], v[116:119]
	v_mfma_f32_16x16x32_bf16 v[112:115], v[156:159], v[188:191], v[112:115]
	v_mfma_f32_16x16x32_bf16 v[100:103], v[148:151], v[196:199], v[100:103]
	v_mfma_f32_16x16x32_bf16 v[96:99], v[156:159], v[196:199], v[96:99]
	v_mfma_f32_16x16x32_bf16 v[84:87], v[148:151], v[204:207], v[84:87]
	v_mfma_f32_16x16x32_bf16 v[80:83], v[156:159], v[204:207], v[80:83]
	v_mfma_f32_16x16x32_bf16 v[124:127], v[152:155], v[184:187], v[124:127]
	v_mfma_f32_16x16x32_bf16 v[120:123], v[160:163], v[184:187], v[120:123]
	v_mfma_f32_16x16x32_bf16 v[116:119], v[152:155], v[192:195], v[116:119]
	v_mfma_f32_16x16x32_bf16 v[112:115], v[160:163], v[192:195], v[112:115]
	v_mfma_f32_16x16x32_bf16 v[100:103], v[152:155], v[200:203], v[100:103]
	v_mfma_f32_16x16x32_bf16 v[96:99], v[160:163], v[200:203], v[96:99]
	v_mfma_f32_16x16x32_bf16 v[84:87], v[152:155], v[208:211], v[84:87]
	v_mfma_f32_16x16x32_bf16 v[80:83], v[160:163], v[208:211], v[80:83]
	v_mfma_f32_16x16x32_bf16 v[108:111], v[164:167], v[180:183], v[108:111]
	v_mfma_f32_16x16x32_bf16 v[104:107], v[172:175], v[180:183], v[104:107]
	v_mfma_f32_16x16x32_bf16 v[92:95], v[164:167], v[188:191], v[92:95]
	v_mfma_f32_16x16x32_bf16 v[88:91], v[172:175], v[188:191], v[88:91]
	v_mfma_f32_16x16x32_bf16 v[76:79], v[164:167], v[196:199], v[76:79]
	v_mfma_f32_16x16x32_bf16 v[72:75], v[172:175], v[196:199], v[72:75]
	v_mfma_f32_16x16x32_bf16 v[68:71], v[164:167], v[204:207], v[68:71]
	v_mfma_f32_16x16x32_bf16 v[64:67], v[172:175], v[204:207], v[64:67]
	v_mfma_f32_16x16x32_bf16 v[108:111], v[168:171], v[184:187], v[108:111]
	v_mfma_f32_16x16x32_bf16 v[104:107], v[176:179], v[184:187], v[104:107]
	v_mfma_f32_16x16x32_bf16 v[92:95], v[168:171], v[192:195], v[92:95]
	v_mfma_f32_16x16x32_bf16 v[88:91], v[176:179], v[192:195], v[88:91]
	v_mfma_f32_16x16x32_bf16 v[76:79], v[168:171], v[200:203], v[76:79]
	v_mfma_f32_16x16x32_bf16 v[72:75], v[176:179], v[200:203], v[72:75]
	v_mfma_f32_16x16x32_bf16 v[68:71], v[168:171], v[208:211], v[68:71]
	v_mfma_f32_16x16x32_bf16 v[64:67], v[176:179], v[208:211], v[64:67]
	s_setprio 0
	s_barrier
	s_add_u32 s98, s24, s10
	s_addc_u32 s99, s25, s11
	s_add_u32 s100, s26, s10
	s_addc_u32 s101, s27, s11
	s_add_i32 s56, s40, s3
	s_mov_b32 m0, s56
	ds_read_b128 v[180:183], v147 offset:16384
	ds_read_b128 v[184:187], v147 offset:17408
	ds_read_b128 v[188:191], v147 offset:18432
	ds_read_b128 v[192:195], v147 offset:19456
	ds_read_b128 v[196:199], v147 offset:20480
	ds_read_b128 v[200:203], v147 offset:21504
	ds_read_b128 v[204:207], v147 offset:22528
	ds_read_b128 v[208:211], v147 offset:23552
	global_load_lds_dwordx4 v132, s[24:25]
	s_add_i32 m0, s56, 0x2000
	s_add_u32 s56, s24, 0x40000
	s_addc_u32 s57, s25, 0
	s_add_i32 s58, s41, s3
	global_load_lds_dwordx4 v128, s[24:25]
	s_mov_b32 m0, s58
	s_nop 0
	global_load_lds_dwordx4 v132, s[56:57]
	s_add_i32 m0, s58, 0x2000
	s_nop 0
	global_load_lds_dwordx4 v128, s[56:57]
	s_mov_b32 m0, s13
	s_nop 0
	global_load_lds_dwordx4 v134, s[26:27]
	s_mov_b32 m0, s30
	s_nop 0
	global_load_lds_dwordx4 v130, s[26:27]
	s_waitcnt vmcnt(8)
	s_waitcnt lgkmcnt(0)
	s_barrier
	s_setprio 1
	s_waitcnt lgkmcnt(0)
	v_mfma_f32_16x16x32_bf16 v[60:63], v[148:151], v[180:183], v[60:63]
	v_mfma_f32_16x16x32_bf16 v[56:59], v[156:159], v[180:183], v[56:59]
	v_mfma_f32_16x16x32_bf16 v[52:55], v[148:151], v[188:191], v[52:55]
	v_mfma_f32_16x16x32_bf16 v[48:51], v[156:159], v[188:191], v[48:51]
	v_mfma_f32_16x16x32_bf16 v[36:39], v[148:151], v[196:199], v[36:39]
	v_mfma_f32_16x16x32_bf16 v[32:35], v[156:159], v[196:199], v[32:35]
	v_mfma_f32_16x16x32_bf16 v[20:23], v[148:151], v[204:207], v[20:23]
	v_mfma_f32_16x16x32_bf16 v[16:19], v[156:159], v[204:207], v[16:19]
	v_mfma_f32_16x16x32_bf16 v[60:63], v[152:155], v[184:187], v[60:63]
	v_mfma_f32_16x16x32_bf16 v[56:59], v[160:163], v[184:187], v[56:59]
	v_mfma_f32_16x16x32_bf16 v[52:55], v[152:155], v[192:195], v[52:55]
	v_mfma_f32_16x16x32_bf16 v[48:51], v[160:163], v[192:195], v[48:51]
	v_mfma_f32_16x16x32_bf16 v[36:39], v[152:155], v[200:203], v[36:39]
	v_mfma_f32_16x16x32_bf16 v[32:35], v[160:163], v[200:203], v[32:35]
	v_mfma_f32_16x16x32_bf16 v[20:23], v[152:155], v[208:211], v[20:23]
	v_mfma_f32_16x16x32_bf16 v[16:19], v[160:163], v[208:211], v[16:19]
	v_mfma_f32_16x16x32_bf16 v[44:47], v[164:167], v[180:183], v[44:47]
	v_mfma_f32_16x16x32_bf16 v[40:43], v[172:175], v[180:183], v[40:43]
	v_mfma_f32_16x16x32_bf16 v[28:31], v[164:167], v[188:191], v[28:31]
	v_mfma_f32_16x16x32_bf16 v[24:27], v[172:175], v[188:191], v[24:27]
	v_mfma_f32_16x16x32_bf16 v[12:15], v[164:167], v[196:199], v[12:15]
	v_mfma_f32_16x16x32_bf16 v[8:11], v[172:175], v[196:199], v[8:11]
	v_mfma_f32_16x16x32_bf16 v[4:7], v[164:167], v[204:207], v[4:7]
	v_mfma_f32_16x16x32_bf16 v[0:3], v[172:175], v[204:207], v[0:3]
	v_mfma_f32_16x16x32_bf16 v[44:47], v[168:171], v[184:187], v[44:47]
	v_mfma_f32_16x16x32_bf16 v[40:43], v[176:179], v[184:187], v[40:43]
	v_mfma_f32_16x16x32_bf16 v[28:31], v[168:171], v[192:195], v[28:31]
	v_mfma_f32_16x16x32_bf16 v[24:27], v[176:179], v[192:195], v[24:27]
	v_mfma_f32_16x16x32_bf16 v[12:15], v[168:171], v[200:203], v[12:15]
	v_mfma_f32_16x16x32_bf16 v[8:11], v[176:179], v[200:203], v[8:11]
	v_mfma_f32_16x16x32_bf16 v[4:7], v[168:171], v[208:211], v[4:7]
	v_mfma_f32_16x16x32_bf16 v[0:3], v[176:179], v[208:211], v[0:3]
	s_setprio 0
	s_barrier
; #define PG8_STAGE(bufoff, gbase, voff) do { _Pragma("unroll") for (int _i = 0; _i < 2; ++_i) \
;         __builtin_amdgcn_global_load_lds((const unsigned*)((const char*)(gbase) + (voff)[_i]), (LAS unsigned*)(lds + (bufoff) + ldsw + _i * 8192), 16, 0, 0); } while (0)
; #define PG8_LDA(dst, b, h) do { _Pragma("unroll") for (int m = 0; m < 4; ++m) _Pragma("unroll") for (int k = 0; k < 2; ++k) dst[m][k] = *(const LAS bf16x8*)(lds + PG8_SA(b, h) + aoff + m * 2048 + k * 1024); } while (0)
; #define PG8_LDB(dst, b, h) do { _Pragma("unroll") for (int n = 0; n < 2; ++n) _Pragma("unroll") for (int k = 0; k < 2; ++k) dst[n][k] = *(const LAS bf16x8*)(lds + PG8_SB(b, h) + boff + n * 2048 + k * 1024); } while (0)
; #define PG8_MMA(ai, bj, At, Bt) do { __builtin_amdgcn_s_setprio(1); _Pragma("unroll") for (int m = 0; m < 4; ++m) _Pragma("unroll") for (int n = 0; n < 2; ++n) _Pragma("unroll") for (int k = 0; k < 2; ++k) \
;         acc[ai][bj][m][n] = __builtin_amdgcn_mfma_f32_16x16x32_bf16(Bt[n][k], At[m][k], acc[ai][bj][m][n], 0, 0, 0); __builtin_amdgcn_s_setprio(0); } while (0)
; #define PG8_WAIT_V(n) asm volatile("s_waitcnt vmcnt(" #n ")" ::: "memory")
; #define PG8_WAIT_L(n) asm volatile("s_waitcnt lgkmcnt(" #n ")" ::: "memory")
; #define PG8_BAR __builtin_amdgcn_s_barrier()
; #define PG8_SCHED __builtin_amdgcn_sched_barrier(0)
; template <class Epi, bool ALIGN_EPI, int K, int LDA, int LDB>
; __device__ __forceinline__ void gemm_phase(LAS unsigned char* lds, const int wid, const Gemm g, const StaticOrder& S, const Epi& E) {
;     ...
;             PG8_LDB(B0, 1, 0); PG8_LDB(B1, 1, 1); PG8_SCHED; PG8_LDA(At, 1, 0); PG8_STAGE(PG8_SA(0, 1), a2 + hA, voffA);
;             PG8_WAIT_V(8); PG8_WAIT_L(0); PG8_BAR; PG8_MMA(0, 0, At, B0); PG8_MMA(0, 1, At, B1); PG8_BAR; PG8_SCHED;
;             PG8_LDA(At, 1, 1); PG8_STAGE(PG8_SB(1, 0), b3, voffB); PG8_STAGE(PG8_SB(1, 1), b3 + hB, voffB); PG8_STAGE(PG8_SA(1, 0), a3, voffA);
;             PG8_WAIT_V(8); PG8_WAIT_L(0); PG8_BAR; PG8_MMA(1, 0, At, B0); PG8_MMA(1, 1, At, B1); PG8_BAR; PG8_SCHED;
;         }
;         if constexpr (ALIGN_EPI) { if (wr == 0) PG8_BAR; }
	s_add_i32 s56, 0, 0x18000
	s_add_i32 s57, 0, 0x1c000
	v_add_u32_e32 v160, s56, v144
	v_add_u32_e32 v176, s57, v144
	ds_read_b128 v[148:151], v160
	ds_read_b128 v[152:155], v160 offset:1024
	ds_read_b128 v[156:159], v160 offset:2048
	ds_read_b128 v[160:163], v160 offset:3072
	ds_read_b128 v[164:167], v176
	ds_read_b128 v[168:171], v176 offset:1024
	ds_read_b128 v[172:175], v176 offset:2048
	ds_read_b128 v[176:179], v176 offset:3072
	s_add_u32 s26, s26, 0x40000
	s_addc_u32 s27, s27, 0
	s_mov_b32 m0, s31
	ds_read_b128 v[180:183], v147 offset:32768
	ds_read_b128 v[184:187], v147 offset:33792
	ds_read_b128 v[188:191], v147 offset:34816
	ds_read_b128 v[192:195], v147 offset:35840
	ds_read_b128 v[196:199], v147 offset:36864
	ds_read_b128 v[200:203], v147 offset:37888
	ds_read_b128 v[204:207], v147 offset:38912
	ds_read_b128 v[208:211], v147 offset:39936
	global_load_lds_dwordx4 v134, s[26:27]
	s_mov_b32 m0, s33
	s_nop 0
	global_load_lds_dwordx4 v130, s[26:27]
	s_waitcnt vmcnt(8)
	s_waitcnt lgkmcnt(0)
	s_barrier
	s_setprio 1
	s_waitcnt lgkmcnt(0)
	v_mfma_f32_16x16x32_bf16 v[124:127], v[148:151], v[180:183], v[124:127]
	v_mfma_f32_16x16x32_bf16 v[120:123], v[156:159], v[180:183], v[120:123]
	v_mfma_f32_16x16x32_bf16 v[116:119], v[148:151], v[188:191], v[116:119]
	v_mfma_f32_16x16x32_bf16 v[112:115], v[156:159], v[188:191], v[112:115]
	v_mfma_f32_16x16x32_bf16 v[100:103], v[148:151], v[196:199], v[100:103]
	v_mfma_f32_16x16x32_bf16 v[96:99], v[156:159], v[196:199], v[96:99]
	v_mfma_f32_16x16x32_bf16 v[84:87], v[148:151], v[204:207], v[84:87]
	v_mfma_f32_16x16x32_bf16 v[80:83], v[156:159], v[204:207], v[80:83]
	v_mfma_f32_16x16x32_bf16 v[124:127], v[152:155], v[184:187], v[124:127]
	v_mfma_f32_16x16x32_bf16 v[120:123], v[160:163], v[184:187], v[120:123]
	v_mfma_f32_16x16x32_bf16 v[116:119], v[152:155], v[192:195], v[116:119]
	v_mfma_f32_16x16x32_bf16 v[112:115], v[160:163], v[192:195], v[112:115]
	v_mfma_f32_16x16x32_bf16 v[100:103], v[152:155], v[200:203], v[100:103]
	v_mfma_f32_16x16x32_bf16 v[96:99], v[160:163], v[200:203], v[96:99]
	v_mfma_f32_16x16x32_bf16 v[84:87], v[152:155], v[208:211], v[84:87]
	v_mfma_f32_16x16x32_bf16 v[80:83], v[160:163], v[208:211], v[80:83]
	v_mfma_f32_16x16x32_bf16 v[108:111], v[164:167], v[180:183], v[108:111]
	v_mfma_f32_16x16x32_bf16 v[104:107], v[172:175], v[180:183], v[104:107]
	v_mfma_f32_16x16x32_bf16 v[92:95], v[164:167], v[188:191], v[92:95]
	v_mfma_f32_16x16x32_bf16 v[88:91], v[172:175], v[188:191], v[88:91]
	v_mfma_f32_16x16x32_bf16 v[76:79], v[164:167], v[196:199], v[76:79]
	v_mfma_f32_16x16x32_bf16 v[72:75], v[172:175], v[196:199], v[72:75]
	v_mfma_f32_16x16x32_bf16 v[68:71], v[164:167], v[204:207], v[68:71]
	v_mfma_f32_16x16x32_bf16 v[64:67], v[172:175], v[204:207], v[64:67]
	v_mfma_f32_16x16x32_bf16 v[108:111], v[168:171], v[184:187], v[108:111]
	v_mfma_f32_16x16x32_bf16 v[104:107], v[176:179], v[184:187], v[104:107]
	v_mfma_f32_16x16x32_bf16 v[92:95], v[168:171], v[192:195], v[92:95]
	v_mfma_f32_16x16x32_bf16 v[88:91], v[176:179], v[192:195], v[88:91]
	v_mfma_f32_16x16x32_bf16 v[76:79], v[168:171], v[200:203], v[76:79]
	v_mfma_f32_16x16x32_bf16 v[72:75], v[176:179], v[200:203], v[72:75]
	v_mfma_f32_16x16x32_bf16 v[68:71], v[168:171], v[208:211], v[68:71]
	v_mfma_f32_16x16x32_bf16 v[64:67], v[176:179], v[208:211], v[64:67]
	s_setprio 0
	s_barrier
	s_add_i32 s26, s56, s3
	s_mov_b32 m0, s26
	ds_read_b128 v[180:183], v147 offset:49152
	ds_read_b128 v[184:187], v147 offset:50176
	ds_read_b128 v[188:191], v147 offset:51200
	ds_read_b128 v[192:195], v147 offset:52224
	ds_read_b128 v[196:199], v147 offset:53248
	ds_read_b128 v[200:203], v147 offset:54272
	ds_read_b128 v[204:207], v147 offset:55296
	ds_read_b128 v[208:211], v147 offset:56320
	global_load_lds_dwordx4 v132, s[98:99]
	s_add_i32 m0, s26, 0x2000
	s_add_u32 s24, s24, 0x40080
	s_addc_u32 s25, s25, 0
	s_add_i32 s26, s57, s3
	global_load_lds_dwordx4 v128, s[98:99]
	s_mov_b32 m0, s26
	s_nop 0
	global_load_lds_dwordx4 v132, s[24:25]
	s_add_i32 m0, s26, 0x2000
	s_nop 0
	global_load_lds_dwordx4 v128, s[24:25]
	s_mov_b32 m0, s38
	s_nop 0
	global_load_lds_dwordx4 v134, s[100:101]
	s_mov_b32 m0, s39
	s_nop 0
	global_load_lds_dwordx4 v130, s[100:101]
	s_waitcnt vmcnt(8)
	s_waitcnt lgkmcnt(0)
	s_barrier
	s_setprio 1
	s_waitcnt lgkmcnt(0)
	v_mfma_f32_16x16x32_bf16 v[60:63], v[148:151], v[180:183], v[60:63]
	v_mfma_f32_16x16x32_bf16 v[56:59], v[156:159], v[180:183], v[56:59]
	v_mfma_f32_16x16x32_bf16 v[52:55], v[148:151], v[188:191], v[52:55]
	v_mfma_f32_16x16x32_bf16 v[48:51], v[156:159], v[188:191], v[48:51]
	v_mfma_f32_16x16x32_bf16 v[36:39], v[148:151], v[196:199], v[36:39]
	v_mfma_f32_16x16x32_bf16 v[32:35], v[156:159], v[196:199], v[32:35]
	v_mfma_f32_16x16x32_bf16 v[20:23], v[148:151], v[204:207], v[20:23]
	v_mfma_f32_16x16x32_bf16 v[16:19], v[156:159], v[204:207], v[16:19]
	v_mfma_f32_16x16x32_bf16 v[60:63], v[152:155], v[184:187], v[60:63]
	v_mfma_f32_16x16x32_bf16 v[56:59], v[160:163], v[184:187], v[56:59]
	v_mfma_f32_16x16x32_bf16 v[52:55], v[152:155], v[192:195], v[52:55]
	v_mfma_f32_16x16x32_bf16 v[48:51], v[160:163], v[192:195], v[48:51]
	v_mfma_f32_16x16x32_bf16 v[36:39], v[152:155], v[200:203], v[36:39]
	v_mfma_f32_16x16x32_bf16 v[32:35], v[160:163], v[200:203], v[32:35]
	v_mfma_f32_16x16x32_bf16 v[20:23], v[152:155], v[208:211], v[20:23]
	v_mfma_f32_16x16x32_bf16 v[16:19], v[160:163], v[208:211], v[16:19]
	v_mfma_f32_16x16x32_bf16 v[44:47], v[164:167], v[180:183], v[44:47]
	v_mfma_f32_16x16x32_bf16 v[40:43], v[172:175], v[180:183], v[40:43]
	v_mfma_f32_16x16x32_bf16 v[28:31], v[164:167], v[188:191], v[28:31]
	v_mfma_f32_16x16x32_bf16 v[24:27], v[172:175], v[188:191], v[24:27]
	v_mfma_f32_16x16x32_bf16 v[12:15], v[164:167], v[196:199], v[12:15]
	v_mfma_f32_16x16x32_bf16 v[8:11], v[172:175], v[196:199], v[8:11]
	v_mfma_f32_16x16x32_bf16 v[4:7], v[164:167], v[204:207], v[4:7]
	v_mfma_f32_16x16x32_bf16 v[0:3], v[172:175], v[204:207], v[0:3]
	v_mfma_f32_16x16x32_bf16 v[44:47], v[168:171], v[184:187], v[44:47]
	v_mfma_f32_16x16x32_bf16 v[40:43], v[176:179], v[184:187], v[40:43]
	v_mfma_f32_16x16x32_bf16 v[28:31], v[168:171], v[192:195], v[28:31]
	v_mfma_f32_16x16x32_bf16 v[24:27], v[176:179], v[192:195], v[24:27]
	v_mfma_f32_16x16x32_bf16 v[12:15], v[168:171], v[200:203], v[12:15]
	v_mfma_f32_16x16x32_bf16 v[8:11], v[176:179], v[200:203], v[8:11]
	v_mfma_f32_16x16x32_bf16 v[4:7], v[168:171], v[208:211], v[4:7]
	v_mfma_f32_16x16x32_bf16 v[0:3], v[176:179], v[208:211], v[0:3]
	s_setprio 0
	s_barrier
	s_add_i32 s55, s55, 2
	s_add_u32 s22, s22, 0x100
	s_addc_u32 s23, s23, 0
	s_add_u32 s51, s51, 0x100
	s_addc_u32 s54, s54, 0
	s_cmp_gt_u32 s55, 13
	s_cbranch_scc0 .LBB0_232
	s_and_b64 vcc, exec, s[8:9]
	s_cbranch_vccz .LBB0_235
	s_barrier

; #define PG8_STAGE(bufoff, gbase, voff) do { _Pragma("unroll") for (int _i = 0; _i < 2; ++_i) \
;         __builtin_amdgcn_global_load_lds((const unsigned*)((const char*)(gbase) + (voff)[_i]), (LAS unsigned*)(lds + (bufoff) + ldsw + _i * 8192), 16, 0, 0); } while (0)
; #define PG8_LDA(dst, b, h) do { _Pragma("unroll") for (int m = 0; m < 4; ++m) _Pragma("unroll") for (int k = 0; k < 2; ++k) dst[m][k] = *(const LAS bf16x8*)(lds + PG8_SA(b, h) + aoff + m * 2048 + k * 1024); } while (0)
; #define PG8_LDB(dst, b, h) do { _Pragma("unroll") for (int n = 0; n < 2; ++n) _Pragma("unroll") for (int k = 0; k < 2; ++k) dst[n][k] = *(const LAS bf16x8*)(lds + PG8_SB(b, h) + boff + n * 2048 + k * 1024); } while (0)
; #define PG8_MMA(ai, bj, At, Bt) do { __builtin_amdgcn_s_setprio(1); _Pragma("unroll") for (int m = 0; m < 4; ++m) _Pragma("unroll") for (int n = 0; n < 2; ++n) _Pragma("unroll") for (int k = 0; k < 2; ++k) \
;         acc[ai][bj][m][n] = __builtin_amdgcn_mfma_f32_16x16x32_bf16(Bt[n][k], At[m][k], acc[ai][bj][m][n], 0, 0, 0); __builtin_amdgcn_s_setprio(0); } while (0)
; #define PG8_WAIT_V(n) asm volatile("s_waitcnt vmcnt(" #n ")" ::: "memory")
; #define PG8_WAIT_L(n) asm volatile("s_waitcnt lgkmcnt(" #n ")" ::: "memory")
; #define PG8_BAR __builtin_amdgcn_s_barrier()
; #define PG8_SCHED __builtin_amdgcn_sched_barrier(0)
; template <class Epi, bool ALIGN_EPI, int K, int LDA, int LDB>
; __device__ __forceinline__ void gemm_phase(LAS unsigned char* lds, const int wid, const Gemm g, const StaticOrder& S, const Epi& E) {
;     ...
;             PG8_LDB(B0, 0, 0); PG8_LDB(B1, 0, 1); PG8_SCHED; PG8_LDA(At, 0, 0); PG8_STAGE(PG8_SA(1, 1), a1 + hA, voffA);
;             PG8_WAIT_V(8); PG8_WAIT_L(0); PG8_BAR; PG8_MMA(0, 0, At, B0); PG8_MMA(0, 1, At, B1); PG8_BAR; PG8_SCHED;
;             PG8_LDA(At, 0, 1); PG8_STAGE(PG8_SB(0, 0), b2, voffB); PG8_STAGE(PG8_SB(0, 1), b2 + hB, voffB); PG8_STAGE(PG8_SA(0, 0), a2, voffA);
;             PG8_WAIT_V(8); PG8_WAIT_L(0); PG8_BAR; PG8_MMA(1, 0, At, B0); PG8_MMA(1, 1, At, B1); PG8_BAR; PG8_SCHED;
.LBB0_665:
	ds_read_b128 v[8:11], v158
	ds_read_b128 v[12:15], v158 offset:1024
	ds_read_b128 v[16:19], v158 offset:2048
	ds_read_b128 v[20:23], v158 offset:3072
	ds_read_b128 v[24:27], v159
	ds_read_b128 v[28:31], v159 offset:1024
	ds_read_b128 v[32:35], v159 offset:2048
	ds_read_b128 v[36:39], v159 offset:3072
	s_add_u32 s6, s36, 0xa0080
	s_addc_u32 s7, s37, 0
	s_add_i32 s71, s42, 0xc000
	v_lshl_add_u64 v[64:65], s[6:7], 0, v[142:143]
	s_mov_b32 m0, s71
	ds_read_b128 v[0:3], v157
	ds_read_b128 v[4:7], v157 offset:1024
	ds_read_b128 v[40:43], v157 offset:2048
	ds_read_b128 v[44:47], v157 offset:3072
	ds_read_b128 v[48:51], v157 offset:4096
	ds_read_b128 v[52:55], v157 offset:5120
	ds_read_b128 v[56:59], v157 offset:6144
	ds_read_b128 v[60:63], v157 offset:7168
	global_load_lds_dwordx4 v[64:65], off
	v_lshl_add_u64 v[64:65], s[6:7], 0, v[138:139]
	s_add_i32 s6, s42, 0xe000
	s_mov_b32 m0, s6
	s_nop 0
	global_load_lds_dwordx4 v[64:65], off
	s_waitcnt vmcnt(8)
	s_waitcnt lgkmcnt(0)
	s_barrier
	s_setprio 1
	s_waitcnt lgkmcnt(0)
	v_mfma_f32_16x16x32_bf16 v[64:67], v[8:11], v[0:3], 0
	v_mfma_f32_16x16x32_bf16 v[68:71], v[16:19], v[0:3], 0
	v_mfma_f32_16x16x32_bf16 v[72:75], v[8:11], v[40:43], 0
	v_mfma_f32_16x16x32_bf16 v[76:79], v[16:19], v[40:43], 0
	v_mfma_f32_16x16x32_bf16 v[80:83], v[8:11], v[48:51], 0
	v_mfma_f32_16x16x32_bf16 v[84:87], v[16:19], v[48:51], 0
	s_waitcnt vmcnt(0)
	v_mfma_f32_16x16x32_bf16 v[88:91], v[8:11], v[56:59], 0
	v_mfma_f32_16x16x32_bf16 v[92:95], v[16:19], v[56:59], 0
	v_mfma_f32_16x16x32_bf16 v[64:67], v[12:15], v[4:7], v[64:67]
	v_mfma_f32_16x16x32_bf16 v[68:71], v[20:23], v[4:7], v[68:71]
	v_mfma_f32_16x16x32_bf16 v[72:75], v[12:15], v[44:47], v[72:75]
	v_mfma_f32_16x16x32_bf16 v[76:79], v[20:23], v[44:47], v[76:79]
	v_mfma_f32_16x16x32_bf16 v[80:83], v[12:15], v[52:55], v[80:83]
	v_mfma_f32_16x16x32_bf16 v[84:87], v[20:23], v[52:55], v[84:87]
	v_mfma_f32_16x16x32_bf16 v[88:91], v[12:15], v[60:63], v[88:91]
	v_mfma_f32_16x16x32_bf16 v[92:95], v[20:23], v[60:63], v[92:95]
	v_mfma_f32_16x16x32_bf16 v[96:99], v[24:27], v[0:3], 0
	v_mfma_f32_16x16x32_bf16 v[0:3], v[32:35], v[0:3], 0
	v_mfma_f32_16x16x32_bf16 v[100:103], v[36:39], v[4:7], v[0:3]
	v_mfma_f32_16x16x32_bf16 v[0:3], v[24:27], v[40:43], 0
	v_mfma_f32_16x16x32_bf16 v[104:107], v[28:31], v[44:47], v[0:3]
	v_mfma_f32_16x16x32_bf16 v[0:3], v[32:35], v[40:43], 0
	v_mfma_f32_16x16x32_bf16 v[40:43], v[36:39], v[44:47], v[0:3]
	v_mfma_f32_16x16x32_bf16 v[0:3], v[24:27], v[48:51], 0
	v_mfma_f32_16x16x32_bf16 v[44:47], v[28:31], v[52:55], v[0:3]
	v_mfma_f32_16x16x32_bf16 v[0:3], v[32:35], v[48:51], 0
	v_mfma_f32_16x16x32_bf16 v[48:51], v[36:39], v[52:55], v[0:3]
	v_mfma_f32_16x16x32_bf16 v[0:3], v[24:27], v[56:59], 0
	v_mfma_f32_16x16x32_bf16 v[52:55], v[28:31], v[60:63], v[0:3]
	v_mfma_f32_16x16x32_bf16 v[0:3], v[32:35], v[56:59], 0
	v_mfma_f32_16x16x32_bf16 v[96:99], v[28:31], v[4:7], v[96:99]
	v_mfma_f32_16x16x32_bf16 v[56:59], v[36:39], v[60:63], v[0:3]
	s_setprio 0
	s_barrier
	s_nop 3
	v_lshl_add_u64 v[0:1], s[38:39], 0, v[140:141]
	s_add_i32 s68, s59, s0
	v_lshl_add_u64 v[2:3], v[0:1], 0, s[22:23]
	s_mov_b32 m0, s68
	s_add_i32 s7, s68, 0x2000
	ds_read_b128 v[60:63], v157 offset:16384
	ds_read_b128 v[108:111], v157 offset:17408
	ds_read_b128 v[112:115], v157 offset:18432
	ds_read_b128 v[116:119], v157 offset:19456
	ds_read_b128 v[120:123], v157 offset:20480
	ds_read_b128 v[124:127], v157 offset:21504
	ds_read_b128 v[128:131], v157 offset:22528
	ds_read_b128 v[132:135], v157 offset:23552
	global_load_lds_dwordx4 v[2:3], off
	v_lshl_add_u64 v[2:3], s[38:39], 0, v[136:137]
	s_add_u32 s72, s38, 0x18100
	v_lshl_add_u64 v[4:5], v[2:3], 0, s[22:23]
	s_mov_b32 m0, s7
	s_addc_u32 s73, s39, 0
	s_add_i32 s66, s60, s0
	global_load_lds_dwordx4 v[4:5], off
	v_lshl_add_u64 v[4:5], s[72:73], 0, v[140:141]
	s_mov_b32 m0, s66
	s_add_i32 s67, s66, 0x2000
	global_load_lds_dwordx4 v[4:5], off
	v_lshl_add_u64 v[4:5], s[72:73], 0, v[136:137]
	s_mov_b32 m0, s67
	s_nop 0
	global_load_lds_dwordx4 v[4:5], off
	v_lshl_add_u64 v[4:5], s[36:37], 0, v[142:143]
	v_lshl_add_u64 v[6:7], v[4:5], 0, s[22:23]
	s_mov_b32 m0, s42
	s_nop 0
	global_load_lds_dwordx4 v[6:7], off
	v_lshl_add_u64 v[6:7], s[36:37], 0, v[138:139]
	v_lshl_add_u64 v[148:149], v[6:7], 0, s[22:23]
	s_mov_b32 m0, s51
	s_nop 0
	global_load_lds_dwordx4 v[148:149], off
	s_waitcnt vmcnt(8)
	s_waitcnt lgkmcnt(0)
	s_barrier
	s_setprio 1
	s_waitcnt lgkmcnt(0)
	v_mfma_f32_16x16x32_bf16 v[148:151], v[8:11], v[60:63], 0
	v_mfma_f32_16x16x32_bf16 v[160:163], v[8:11], v[112:115], 0
	v_mfma_f32_16x16x32_bf16 v[168:171], v[8:11], v[120:123], 0
	v_mfma_f32_16x16x32_bf16 v[8:11], v[8:11], v[128:131], 0
	v_mfma_f32_16x16x32_bf16 v[148:151], v[12:15], v[108:111], v[148:151]
	v_mfma_f32_16x16x32_bf16 v[152:155], v[16:19], v[60:63], 0
	v_mfma_f32_16x16x32_bf16 v[160:163], v[12:15], v[116:119], v[160:163]
	v_mfma_f32_16x16x32_bf16 v[164:167], v[16:19], v[112:115], 0
	v_mfma_f32_16x16x32_bf16 v[168:171], v[12:15], v[124:127], v[168:171]
	v_mfma_f32_16x16x32_bf16 v[172:175], v[16:19], v[120:123], 0
	v_mfma_f32_16x16x32_bf16 v[10:13], v[12:15], v[132:135], v[8:11]
	v_mfma_f32_16x16x32_bf16 v[14:17], v[16:19], v[128:131], 0
	v_mfma_f32_16x16x32_bf16 v[14:17], v[20:23], v[132:135], v[14:17]
	v_mfma_f32_16x16x32_bf16 v[152:155], v[20:23], v[108:111], v[152:155]
	v_mfma_f32_16x16x32_bf16 v[164:167], v[20:23], v[116:119], v[164:167]
	v_mfma_f32_16x16x32_bf16 v[172:175], v[20:23], v[124:127], v[172:175]
	v_mfma_f32_16x16x32_bf16 v[18:21], v[24:27], v[60:63], 0
	v_mfma_f32_16x16x32_bf16 v[60:63], v[32:35], v[60:63], 0
	v_mfma_f32_16x16x32_bf16 v[18:21], v[28:31], v[108:111], v[18:21]
	v_mfma_f32_16x16x32_bf16 v[60:63], v[36:39], v[108:111], v[60:63]
	v_mfma_f32_16x16x32_bf16 v[108:111], v[24:27], v[112:115], 0
	v_mfma_f32_16x16x32_bf16 v[112:115], v[32:35], v[112:115], 0
	v_mfma_f32_16x16x32_bf16 v[108:111], v[28:31], v[116:119], v[108:111]
	v_mfma_f32_16x16x32_bf16 v[112:115], v[36:39], v[116:119], v[112:115]
	v_mfma_f32_16x16x32_bf16 v[116:119], v[24:27], v[120:123], 0
	v_mfma_f32_16x16x32_bf16 v[22:25], v[24:27], v[128:131], 0
	v_mfma_f32_16x16x32_bf16 v[116:119], v[28:31], v[124:127], v[116:119]
	v_mfma_f32_16x16x32_bf16 v[22:25], v[28:31], v[132:135], v[22:25]
	v_mfma_f32_16x16x32_bf16 v[26:29], v[32:35], v[128:131], 0
	v_mfma_f32_16x16x32_bf16 v[120:123], v[32:35], v[120:123], 0
	v_mfma_f32_16x16x32_bf16 v[26:29], v[36:39], v[132:135], v[26:29]
	v_mfma_f32_16x16x32_bf16 v[120:123], v[36:39], v[124:127], v[120:123]
	s_setprio 0
	s_barrier
; #define PG8_STAGE(bufoff, gbase, voff) do { _Pragma("unroll") for (int _i = 0; _i < 2; ++_i) \
;         __builtin_amdgcn_global_load_lds((const unsigned*)((const char*)(gbase) + (voff)[_i]), (LAS unsigned*)(lds + (bufoff) + ldsw + _i * 8192), 16, 0, 0); } while (0)
; #define PG8_LDA(dst, b, h) do { _Pragma("unroll") for (int m = 0; m < 4; ++m) _Pragma("unroll") for (int k = 0; k < 2; ++k) dst[m][k] = *(const LAS bf16x8*)(lds + PG8_SA(b, h) + aoff + m * 2048 + k * 1024); } while (0)
; #define PG8_LDB(dst, b, h) do { _Pragma("unroll") for (int n = 0; n < 2; ++n) _Pragma("unroll") for (int k = 0; k < 2; ++k) dst[n][k] = *(const LAS bf16x8*)(lds + PG8_SB(b, h) + boff + n * 2048 + k * 1024); } while (0)
; #define PG8_MMA(ai, bj, At, Bt) do { __builtin_amdgcn_s_setprio(1); _Pragma("unroll") for (int m = 0; m < 4; ++m) _Pragma("unroll") for (int n = 0; n < 2; ++n) _Pragma("unroll") for (int k = 0; k < 2; ++k) \
;         acc[ai][bj][m][n] = __builtin_amdgcn_mfma_f32_16x16x32_bf16(Bt[n][k], At[m][k], acc[ai][bj][m][n], 0, 0, 0); __builtin_amdgcn_s_setprio(0); } while (0)
; #define PG8_WAIT_V(n) asm volatile("s_waitcnt vmcnt(" #n ")" ::: "memory")
; #define PG8_WAIT_L(n) asm volatile("s_waitcnt lgkmcnt(" #n ")" ::: "memory")
; #define PG8_BAR __builtin_amdgcn_s_barrier()
; #define PG8_SCHED __builtin_amdgcn_sched_barrier(0)
; template <class Epi, bool ALIGN_EPI, int K, int LDA, int LDB>
; __device__ __forceinline__ void gemm_phase(LAS unsigned char* lds, const int wid, const Gemm g, const StaticOrder& S, const Epi& E) {
;     ...
;             PG8_LDB(B0, 1, 0); PG8_LDB(B1, 1, 1); PG8_SCHED; PG8_LDA(At, 1, 0); PG8_STAGE(PG8_SA(0, 1), a2 + hA, voffA);
;             PG8_WAIT_V(8); PG8_WAIT_L(0); PG8_BAR; PG8_MMA(0, 0, At, B0); PG8_MMA(0, 1, At, B1); PG8_BAR; PG8_SCHED;
;             PG8_LDA(At, 1, 1); PG8_STAGE(PG8_SB(1, 0), b3, voffB); PG8_STAGE(PG8_SB(1, 1), b3 + hB, voffB); PG8_STAGE(PG8_SA(1, 0), a3, voffA);
;             PG8_WAIT_V(8); PG8_WAIT_L(0); PG8_BAR; PG8_MMA(1, 0, At, B0); PG8_MMA(1, 1, At, B1); PG8_BAR; PG8_SCHED;
	s_add_i32 s69, 0, 0x18000
	s_add_i32 s70, 0, 0x1c000
	v_add_u32_e32 v8, s69, v156
	v_add_u32_e32 v9, s70, v156
	ds_read_b128 v[30:33], v8
	ds_read_b128 v[34:37], v8 offset:1024
	ds_read_b128 v[124:127], v8 offset:2048
	ds_read_b128 v[128:131], v8 offset:3072
	ds_read_b128 v[132:135], v9
	ds_read_b128 v[176:179], v9 offset:1024
	ds_read_b128 v[180:183], v9 offset:2048
	ds_read_b128 v[184:187], v9 offset:3072
	s_add_u32 s72, s36, 0xa0100
	s_addc_u32 s73, s37, 0
	s_mov_b32 m0, s54
	v_lshl_add_u64 v[38:39], s[72:73], 0, v[142:143]
	ds_read_b128 v[188:191], v157 offset:32768
	ds_read_b128 v[192:195], v157 offset:33792
	ds_read_b128 v[196:199], v157 offset:34816
	ds_read_b128 v[200:203], v157 offset:35840
	ds_read_b128 v[204:207], v157 offset:36864
	ds_read_b128 v[208:211], v157 offset:37888
	ds_read_b128 v[212:215], v157 offset:38912
	ds_read_b128 v[216:219], v157 offset:39936
	global_load_lds_dwordx4 v[38:39], off
	v_lshl_add_u64 v[38:39], s[72:73], 0, v[138:139]
	s_mov_b32 m0, s55
	s_nop 0
	global_load_lds_dwordx4 v[38:39], off
	s_waitcnt vmcnt(8)
	s_waitcnt lgkmcnt(0)
	s_barrier
	s_setprio 1
	s_waitcnt lgkmcnt(0)
	v_mfma_f32_16x16x32_bf16 v[64:67], v[30:33], v[188:191], v[64:67]
	v_mfma_f32_16x16x32_bf16 v[68:71], v[124:127], v[188:191], v[68:71]
	v_mfma_f32_16x16x32_bf16 v[72:75], v[30:33], v[196:199], v[72:75]
	v_mfma_f32_16x16x32_bf16 v[76:79], v[124:127], v[196:199], v[76:79]
	v_mfma_f32_16x16x32_bf16 v[80:83], v[30:33], v[204:207], v[80:83]
	v_mfma_f32_16x16x32_bf16 v[84:87], v[124:127], v[204:207], v[84:87]
	v_mfma_f32_16x16x32_bf16 v[88:91], v[30:33], v[212:215], v[88:91]
	v_mfma_f32_16x16x32_bf16 v[92:95], v[124:127], v[212:215], v[92:95]
	v_mfma_f32_16x16x32_bf16 v[64:67], v[34:37], v[192:195], v[64:67]
	v_mfma_f32_16x16x32_bf16 v[68:71], v[128:131], v[192:195], v[68:71]
	v_mfma_f32_16x16x32_bf16 v[72:75], v[34:37], v[200:203], v[72:75]
	v_mfma_f32_16x16x32_bf16 v[76:79], v[128:131], v[200:203], v[76:79]
	v_mfma_f32_16x16x32_bf16 v[80:83], v[34:37], v[208:211], v[80:83]
	v_mfma_f32_16x16x32_bf16 v[84:87], v[128:131], v[208:211], v[84:87]
	v_mfma_f32_16x16x32_bf16 v[88:91], v[34:37], v[216:219], v[88:91]
	v_mfma_f32_16x16x32_bf16 v[92:95], v[128:131], v[216:219], v[92:95]
	v_mfma_f32_16x16x32_bf16 v[96:99], v[132:135], v[188:191], v[96:99]
	v_mfma_f32_16x16x32_bf16 v[100:103], v[180:183], v[188:191], v[100:103]
	v_mfma_f32_16x16x32_bf16 v[104:107], v[132:135], v[196:199], v[104:107]
	v_mfma_f32_16x16x32_bf16 v[38:41], v[180:183], v[196:199], v[40:43]
	v_mfma_f32_16x16x32_bf16 v[42:45], v[132:135], v[204:207], v[44:47]
	v_mfma_f32_16x16x32_bf16 v[46:49], v[180:183], v[204:207], v[48:51]
	v_mfma_f32_16x16x32_bf16 v[50:53], v[132:135], v[212:215], v[52:55]
	v_mfma_f32_16x16x32_bf16 v[54:57], v[180:183], v[212:215], v[56:59]
	v_mfma_f32_16x16x32_bf16 v[96:99], v[176:179], v[192:195], v[96:99]
	v_mfma_f32_16x16x32_bf16 v[100:103], v[184:187], v[192:195], v[100:103]
	v_mfma_f32_16x16x32_bf16 v[104:107], v[176:179], v[200:203], v[104:107]
	v_mfma_f32_16x16x32_bf16 v[38:41], v[184:187], v[200:203], v[38:41]
	v_mfma_f32_16x16x32_bf16 v[42:45], v[176:179], v[208:211], v[42:45]
	v_mfma_f32_16x16x32_bf16 v[46:49], v[184:187], v[208:211], v[46:49]
	v_mfma_f32_16x16x32_bf16 v[50:53], v[176:179], v[216:219], v[50:53]
	v_mfma_f32_16x16x32_bf16 v[54:57], v[184:187], v[216:219], v[54:57]
	s_setprio 0
	s_barrier
	s_add_i32 s73, s69, s0
	s_add_i32 s69, s73, 0x2000
	v_lshl_add_u64 v[58:59], v[0:1], 0, s[24:25]
	s_mov_b32 m0, s73
	s_add_u32 s74, s38, 0x18180
	ds_read_b128 v[188:191], v157 offset:49152
	ds_read_b128 v[192:195], v157 offset:50176
	ds_read_b128 v[196:199], v157 offset:51200
	ds_read_b128 v[200:203], v157 offset:52224
	ds_read_b128 v[204:207], v157 offset:53248
	ds_read_b128 v[208:211], v157 offset:54272
	ds_read_b128 v[212:215], v157 offset:55296
	ds_read_b128 v[216:219], v157 offset:56320
	global_load_lds_dwordx4 v[58:59], off
	v_lshl_add_u64 v[58:59], v[2:3], 0, s[24:25]
	s_mov_b32 m0, s69
	s_addc_u32 s75, s39, 0
	s_add_i32 s70, s70, s0
	global_load_lds_dwordx4 v[58:59], off
	v_lshl_add_u64 v[58:59], s[74:75], 0, v[140:141]
	s_mov_b32 m0, s70
	s_add_i32 s72, s70, 0x2000
	global_load_lds_dwordx4 v[58:59], off
	v_lshl_add_u64 v[58:59], s[74:75], 0, v[136:137]
	s_mov_b32 m0, s72
	s_nop 0
	global_load_lds_dwordx4 v[58:59], off
	v_lshl_add_u64 v[58:59], v[4:5], 0, s[24:25]
	s_mov_b32 m0, s56
	s_nop 0
	global_load_lds_dwordx4 v[58:59], off
	v_lshl_add_u64 v[58:59], v[6:7], 0, s[24:25]
	s_mov_b32 m0, s57
	s_nop 0
	global_load_lds_dwordx4 v[58:59], off
	s_waitcnt vmcnt(8)
	s_waitcnt lgkmcnt(0)
	s_barrier
; #define PG8_STAGE(bufoff, gbase, voff) do { _Pragma("unroll") for (int _i = 0; _i < 2; ++_i) \
;         __builtin_amdgcn_global_load_lds((const unsigned*)((const char*)(gbase) + (voff)[_i]), (LAS unsigned*)(lds + (bufoff) + ldsw + _i * 8192), 16, 0, 0); } while (0)
; #define PG8_LDA(dst, b, h) do { _Pragma("unroll") for (int m = 0; m < 4; ++m) _Pragma("unroll") for (int k = 0; k < 2; ++k) dst[m][k] = *(const LAS bf16x8*)(lds + PG8_SA(b, h) + aoff + m * 2048 + k * 1024); } while (0)
; #define PG8_LDB(dst, b, h) do { _Pragma("unroll") for (int n = 0; n < 2; ++n) _Pragma("unroll") for (int k = 0; k < 2; ++k) dst[n][k] = *(const LAS bf16x8*)(lds + PG8_SB(b, h) + boff + n * 2048 + k * 1024); } while (0)
; #define PG8_MMA(ai, bj, At, Bt) do { __builtin_amdgcn_s_setprio(1); _Pragma("unroll") for (int m = 0; m < 4; ++m) _Pragma("unroll") for (int n = 0; n < 2; ++n) _Pragma("unroll") for (int k = 0; k < 2; ++k) \
;         acc[ai][bj][m][n] = __builtin_amdgcn_mfma_f32_16x16x32_bf16(Bt[n][k], At[m][k], acc[ai][bj][m][n], 0, 0, 0); __builtin_amdgcn_s_setprio(0); } while (0)
; #define PG8_WAIT_V(n) asm volatile("s_waitcnt vmcnt(" #n ")" ::: "memory")
; #define PG8_WAIT_L(n) asm volatile("s_waitcnt lgkmcnt(" #n ")" ::: "memory")
; #define PG8_BAR __builtin_amdgcn_s_barrier()
; #define PG8_SCHED __builtin_amdgcn_sched_barrier(0)
; template <class Epi, bool ALIGN_EPI, int K, int LDA, int LDB>
; __device__ __forceinline__ void gemm_phase(LAS unsigned char* lds, const int wid, const Gemm g, const StaticOrder& S, const Epi& E) {
;     ...
;             PG8_LDB(B0, 0, 0); PG8_LDB(B1, 0, 1); PG8_SCHED; PG8_LDA(At, 0, 0); PG8_STAGE(PG8_SA(1, 1), a1 + hA, voffA);
;             PG8_WAIT_V(8); PG8_WAIT_L(0); PG8_BAR; PG8_MMA(0, 0, At, B0); PG8_MMA(0, 1, At, B1); PG8_BAR; PG8_SCHED;
;     ...
;             PG8_LDA(At, 1, 1); PG8_STAGE(PG8_SB(1, 0), b3, voffB); PG8_STAGE(PG8_SB(1, 1), b3 + hB, voffB); PG8_STAGE(PG8_SA(1, 0), a3, voffA);
;             PG8_WAIT_V(8); PG8_WAIT_L(0); PG8_BAR; PG8_MMA(1, 0, At, B0); PG8_MMA(1, 1, At, B1); PG8_BAR; PG8_SCHED;
	s_setprio 1
	s_waitcnt lgkmcnt(0)
	v_mfma_f32_16x16x32_bf16 v[10:13], v[30:33], v[212:215], v[10:13]
	v_mfma_f32_16x16x32_bf16 v[14:17], v[124:127], v[212:215], v[14:17]
	v_mfma_f32_16x16x32_bf16 v[148:151], v[30:33], v[188:191], v[148:151]
	v_mfma_f32_16x16x32_bf16 v[152:155], v[124:127], v[188:191], v[152:155]
	v_mfma_f32_16x16x32_bf16 v[160:163], v[30:33], v[196:199], v[160:163]
	v_mfma_f32_16x16x32_bf16 v[164:167], v[124:127], v[196:199], v[164:167]
	v_mfma_f32_16x16x32_bf16 v[168:171], v[30:33], v[204:207], v[168:171]
	v_mfma_f32_16x16x32_bf16 v[172:175], v[124:127], v[204:207], v[172:175]
	v_mfma_f32_16x16x32_bf16 v[10:13], v[34:37], v[216:219], v[10:13]
	v_mfma_f32_16x16x32_bf16 v[14:17], v[128:131], v[216:219], v[14:17]
	v_mfma_f32_16x16x32_bf16 v[148:151], v[34:37], v[192:195], v[148:151]
	v_mfma_f32_16x16x32_bf16 v[152:155], v[128:131], v[192:195], v[152:155]
	v_mfma_f32_16x16x32_bf16 v[160:163], v[34:37], v[200:203], v[160:163]
	v_mfma_f32_16x16x32_bf16 v[164:167], v[128:131], v[200:203], v[164:167]
	v_mfma_f32_16x16x32_bf16 v[168:171], v[34:37], v[208:211], v[168:171]
	v_mfma_f32_16x16x32_bf16 v[172:175], v[128:131], v[208:211], v[172:175]
	v_mfma_f32_16x16x32_bf16 v[18:21], v[132:135], v[188:191], v[18:21]
	v_mfma_f32_16x16x32_bf16 v[30:33], v[180:183], v[188:191], v[60:63]
	v_mfma_f32_16x16x32_bf16 v[34:37], v[132:135], v[196:199], v[108:111]
	v_mfma_f32_16x16x32_bf16 v[58:61], v[180:183], v[196:199], v[112:115]
	v_mfma_f32_16x16x32_bf16 v[108:111], v[132:135], v[204:207], v[116:119]
	v_mfma_f32_16x16x32_bf16 v[112:115], v[180:183], v[204:207], v[120:123]
	v_mfma_f32_16x16x32_bf16 v[22:25], v[132:135], v[212:215], v[22:25]
	v_mfma_f32_16x16x32_bf16 v[26:29], v[180:183], v[212:215], v[26:29]
	v_mfma_f32_16x16x32_bf16 v[18:21], v[176:179], v[192:195], v[18:21]
	v_mfma_f32_16x16x32_bf16 v[30:33], v[184:187], v[192:195], v[30:33]
	v_mfma_f32_16x16x32_bf16 v[34:37], v[176:179], v[200:203], v[34:37]
	v_mfma_f32_16x16x32_bf16 v[58:61], v[184:187], v[200:203], v[58:61]
	v_mfma_f32_16x16x32_bf16 v[108:111], v[176:179], v[208:211], v[108:111]
	v_mfma_f32_16x16x32_bf16 v[112:115], v[184:187], v[208:211], v[112:115]
	v_mfma_f32_16x16x32_bf16 v[22:25], v[176:179], v[216:219], v[22:25]
	v_mfma_f32_16x16x32_bf16 v[26:29], v[184:187], v[216:219], v[26:29]
	s_setprio 0
	s_barrier
	ds_read_b128 v[116:119], v158
	ds_read_b128 v[120:123], v158 offset:1024
	ds_read_b128 v[124:127], v158 offset:2048
	ds_read_b128 v[128:131], v158 offset:3072
	ds_read_b128 v[132:135], v159
	ds_read_b128 v[176:179], v159 offset:1024
	ds_read_b128 v[180:183], v159 offset:2048
	ds_read_b128 v[184:187], v159 offset:3072
	s_add_u32 s74, s36, 0xa0180
	s_addc_u32 s75, s37, 0
	s_mov_b32 m0, s71
	v_lshl_add_u64 v[62:63], s[74:75], 0, v[142:143]
	ds_read_b128 v[188:191], v157
	ds_read_b128 v[192:195], v157 offset:1024
	ds_read_b128 v[196:199], v157 offset:2048
	ds_read_b128 v[200:203], v157 offset:3072
	ds_read_b128 v[204:207], v157 offset:4096
	ds_read_b128 v[208:211], v157 offset:5120
	ds_read_b128 v[212:215], v157 offset:6144
	ds_read_b128 v[216:219], v157 offset:7168
	global_load_lds_dwordx4 v[62:63], off
	v_lshl_add_u64 v[62:63], s[74:75], 0, v[138:139]
	s_mov_b32 m0, s6
	s_nop 0
	global_load_lds_dwordx4 v[62:63], off
	s_waitcnt vmcnt(8)
	s_waitcnt lgkmcnt(0)
	s_barrier
	s_setprio 1
	s_waitcnt lgkmcnt(0)
	v_mfma_f32_16x16x32_bf16 v[62:65], v[116:119], v[188:191], v[64:67]
	v_mfma_f32_16x16x32_bf16 v[66:69], v[124:127], v[188:191], v[68:71]
	v_mfma_f32_16x16x32_bf16 v[70:73], v[116:119], v[196:199], v[72:75]
	v_mfma_f32_16x16x32_bf16 v[74:77], v[124:127], v[196:199], v[76:79]
	v_mfma_f32_16x16x32_bf16 v[78:81], v[116:119], v[204:207], v[80:83]
	v_mfma_f32_16x16x32_bf16 v[82:85], v[124:127], v[204:207], v[84:87]
	v_mfma_f32_16x16x32_bf16 v[86:89], v[116:119], v[212:215], v[88:91]
	v_mfma_f32_16x16x32_bf16 v[90:93], v[124:127], v[212:215], v[92:95]
	v_mfma_f32_16x16x32_bf16 v[62:65], v[120:123], v[192:195], v[62:65]
	v_mfma_f32_16x16x32_bf16 v[66:69], v[128:131], v[192:195], v[66:69]
	v_mfma_f32_16x16x32_bf16 v[70:73], v[120:123], v[200:203], v[70:73]
	v_mfma_f32_16x16x32_bf16 v[74:77], v[128:131], v[200:203], v[74:77]
	v_mfma_f32_16x16x32_bf16 v[78:81], v[120:123], v[208:211], v[78:81]
	v_mfma_f32_16x16x32_bf16 v[82:85], v[128:131], v[208:211], v[82:85]
	v_mfma_f32_16x16x32_bf16 v[86:89], v[120:123], v[216:219], v[86:89]
	v_mfma_f32_16x16x32_bf16 v[90:93], v[128:131], v[216:219], v[90:93]
	v_mfma_f32_16x16x32_bf16 v[94:97], v[132:135], v[188:191], v[96:99]
	v_mfma_f32_16x16x32_bf16 v[98:101], v[180:183], v[188:191], v[100:103]
	v_mfma_f32_16x16x32_bf16 v[102:105], v[132:135], v[196:199], v[104:107]
	v_mfma_f32_16x16x32_bf16 v[38:41], v[180:183], v[196:199], v[38:41]
	v_mfma_f32_16x16x32_bf16 v[42:45], v[132:135], v[204:207], v[42:45]
	v_mfma_f32_16x16x32_bf16 v[46:49], v[180:183], v[204:207], v[46:49]
	v_mfma_f32_16x16x32_bf16 v[50:53], v[132:135], v[212:215], v[50:53]
	v_mfma_f32_16x16x32_bf16 v[54:57], v[180:183], v[212:215], v[54:57]
	v_mfma_f32_16x16x32_bf16 v[94:97], v[176:179], v[192:195], v[94:97]
	v_mfma_f32_16x16x32_bf16 v[98:101], v[184:187], v[192:195], v[98:101]
	v_mfma_f32_16x16x32_bf16 v[102:105], v[176:179], v[200:203], v[102:105]
	v_mfma_f32_16x16x32_bf16 v[38:41], v[184:187], v[200:203], v[38:41]
	v_mfma_f32_16x16x32_bf16 v[42:45], v[176:179], v[208:211], v[42:45]
	v_mfma_f32_16x16x32_bf16 v[46:49], v[184:187], v[208:211], v[46:49]
	v_mfma_f32_16x16x32_bf16 v[50:53], v[176:179], v[216:219], v[50:53]
	v_mfma_f32_16x16x32_bf16 v[54:57], v[184:187], v[216:219], v[54:57]
	s_setprio 0
	s_barrier
; #define PG8_STAGE(bufoff, gbase, voff) do { _Pragma("unroll") for (int _i = 0; _i < 2; ++_i) \
;         __builtin_amdgcn_global_load_lds((const unsigned*)((const char*)(gbase) + (voff)[_i]), (LAS unsigned*)(lds + (bufoff) + ldsw + _i * 8192), 16, 0, 0); } while (0)
; #define PG8_LDA(dst, b, h) do { _Pragma("unroll") for (int m = 0; m < 4; ++m) _Pragma("unroll") for (int k = 0; k < 2; ++k) dst[m][k] = *(const LAS bf16x8*)(lds + PG8_SA(b, h) + aoff + m * 2048 + k * 1024); } while (0)
; #define PG8_LDB(dst, b, h) do { _Pragma("unroll") for (int n = 0; n < 2; ++n) _Pragma("unroll") for (int k = 0; k < 2; ++k) dst[n][k] = *(const LAS bf16x8*)(lds + PG8_SB(b, h) + boff + n * 2048 + k * 1024); } while (0)
; #define PG8_MMA(ai, bj, At, Bt) do { __builtin_amdgcn_s_setprio(1); _Pragma("unroll") for (int m = 0; m < 4; ++m) _Pragma("unroll") for (int n = 0; n < 2; ++n) _Pragma("unroll") for (int k = 0; k < 2; ++k) \
;         acc[ai][bj][m][n] = __builtin_amdgcn_mfma_f32_16x16x32_bf16(Bt[n][k], At[m][k], acc[ai][bj][m][n], 0, 0, 0); __builtin_amdgcn_s_setprio(0); } while (0)
; #define PG8_WAIT_V(n) asm volatile("s_waitcnt vmcnt(" #n ")" ::: "memory")
; #define PG8_WAIT_L(n) asm volatile("s_waitcnt lgkmcnt(" #n ")" ::: "memory")
; #define PG8_BAR __builtin_amdgcn_s_barrier()
; #define PG8_SCHED __builtin_amdgcn_sched_barrier(0)
; template <class Epi, bool ALIGN_EPI, int K, int LDA, int LDB>
; __device__ __forceinline__ void gemm_phase(LAS unsigned char* lds, const int wid, const Gemm g, const StaticOrder& S, const Epi& E) {
;     ...
;             PG8_LDA(At, 0, 1); PG8_STAGE(PG8_SB(0, 0), b2, voffB); PG8_STAGE(PG8_SB(0, 1), b2 + hB, voffB); PG8_STAGE(PG8_SA(0, 0), a2, voffA);
;             PG8_WAIT_V(8); PG8_WAIT_L(0); PG8_BAR; PG8_MMA(1, 0, At, B0); PG8_MMA(1, 1, At, B1); PG8_BAR; PG8_SCHED;
;             PG8_LDB(B0, 1, 0); PG8_LDB(B1, 1, 1); PG8_SCHED; PG8_LDA(At, 1, 0); PG8_STAGE(PG8_SA(0, 1), a2 + hA, voffA);
;             PG8_WAIT_V(8); PG8_WAIT_L(0); PG8_BAR; PG8_MMA(0, 0, At, B0); PG8_MMA(0, 1, At, B1); PG8_BAR; PG8_SCHED;
;             PG8_LDA(At, 1, 1); PG8_STAGE(PG8_SB(1, 0), b3, voffB); PG8_STAGE(PG8_SB(1, 1), b3 + hB, voffB); PG8_STAGE(PG8_SA(1, 0), a3, voffA);
;             PG8_WAIT_V(8); PG8_WAIT_L(0); PG8_BAR; PG8_MMA(1, 0, At, B0); PG8_MMA(1, 1, At, B1); PG8_BAR; PG8_SCHED;
	s_mov_b32 m0, s68
	v_lshl_add_u64 v[106:107], v[0:1], 0, s[26:27]
	s_add_u32 s74, s38, 0x18200
	ds_read_b128 v[188:191], v157 offset:16384
	ds_read_b128 v[192:195], v157 offset:17408
	ds_read_b128 v[196:199], v157 offset:18432
	ds_read_b128 v[200:203], v157 offset:19456
	ds_read_b128 v[204:207], v157 offset:20480
	ds_read_b128 v[208:211], v157 offset:21504
	ds_read_b128 v[212:215], v157 offset:22528
	ds_read_b128 v[216:219], v157 offset:23552
	global_load_lds_dwordx4 v[106:107], off
	v_lshl_add_u64 v[106:107], v[2:3], 0, s[26:27]
	s_mov_b32 m0, s7
	s_addc_u32 s75, s39, 0
	global_load_lds_dwordx4 v[106:107], off
	v_lshl_add_u64 v[106:107], s[74:75], 0, v[140:141]
	s_mov_b32 m0, s66
	s_nop 0
	global_load_lds_dwordx4 v[106:107], off
	v_lshl_add_u64 v[106:107], s[74:75], 0, v[136:137]
	s_mov_b32 m0, s67
	s_nop 0
	global_load_lds_dwordx4 v[106:107], off
	v_lshl_add_u64 v[106:107], v[4:5], 0, s[26:27]
	s_mov_b32 m0, s42
	s_nop 0
	global_load_lds_dwordx4 v[106:107], off
	v_lshl_add_u64 v[106:107], v[6:7], 0, s[26:27]
	s_mov_b32 m0, s51
	s_nop 0
	global_load_lds_dwordx4 v[106:107], off
	s_waitcnt vmcnt(8)
	s_waitcnt lgkmcnt(0)
	s_barrier
	s_setprio 1
	s_waitcnt lgkmcnt(0)
	v_mfma_f32_16x16x32_bf16 v[10:13], v[116:119], v[212:215], v[10:13]
	v_mfma_f32_16x16x32_bf16 v[14:17], v[124:127], v[212:215], v[14:17]
	v_mfma_f32_16x16x32_bf16 v[148:151], v[116:119], v[188:191], v[148:151]
	v_mfma_f32_16x16x32_bf16 v[152:155], v[124:127], v[188:191], v[152:155]
	v_mfma_f32_16x16x32_bf16 v[160:163], v[116:119], v[196:199], v[160:163]
	v_mfma_f32_16x16x32_bf16 v[164:167], v[124:127], v[196:199], v[164:167]
	v_mfma_f32_16x16x32_bf16 v[168:171], v[116:119], v[204:207], v[168:171]
	v_mfma_f32_16x16x32_bf16 v[172:175], v[124:127], v[204:207], v[172:175]
	v_mfma_f32_16x16x32_bf16 v[10:13], v[120:123], v[216:219], v[10:13]
	v_mfma_f32_16x16x32_bf16 v[14:17], v[128:131], v[216:219], v[14:17]
	v_mfma_f32_16x16x32_bf16 v[148:151], v[120:123], v[192:195], v[148:151]
	v_mfma_f32_16x16x32_bf16 v[152:155], v[128:131], v[192:195], v[152:155]
	v_mfma_f32_16x16x32_bf16 v[160:163], v[120:123], v[200:203], v[160:163]
	v_mfma_f32_16x16x32_bf16 v[164:167], v[128:131], v[200:203], v[164:167]
	v_mfma_f32_16x16x32_bf16 v[168:171], v[120:123], v[208:211], v[168:171]
	v_mfma_f32_16x16x32_bf16 v[172:175], v[128:131], v[208:211], v[172:175]
	v_mfma_f32_16x16x32_bf16 v[18:21], v[132:135], v[188:191], v[18:21]
	v_mfma_f32_16x16x32_bf16 v[30:33], v[180:183], v[188:191], v[30:33]
	v_mfma_f32_16x16x32_bf16 v[34:37], v[132:135], v[196:199], v[34:37]
	v_mfma_f32_16x16x32_bf16 v[58:61], v[180:183], v[196:199], v[58:61]
	v_mfma_f32_16x16x32_bf16 v[106:109], v[132:135], v[204:207], v[108:111]
	v_mfma_f32_16x16x32_bf16 v[110:113], v[180:183], v[204:207], v[112:115]
	v_mfma_f32_16x16x32_bf16 v[22:25], v[132:135], v[212:215], v[22:25]
	v_mfma_f32_16x16x32_bf16 v[26:29], v[180:183], v[212:215], v[26:29]
	v_mfma_f32_16x16x32_bf16 v[18:21], v[176:179], v[192:195], v[18:21]
	v_mfma_f32_16x16x32_bf16 v[30:33], v[184:187], v[192:195], v[30:33]
	v_mfma_f32_16x16x32_bf16 v[34:37], v[176:179], v[200:203], v[34:37]
	v_mfma_f32_16x16x32_bf16 v[58:61], v[184:187], v[200:203], v[58:61]
	v_mfma_f32_16x16x32_bf16 v[106:109], v[176:179], v[208:211], v[106:109]
	v_mfma_f32_16x16x32_bf16 v[110:113], v[184:187], v[208:211], v[110:113]
	v_mfma_f32_16x16x32_bf16 v[22:25], v[176:179], v[216:219], v[22:25]
	v_mfma_f32_16x16x32_bf16 v[26:29], v[184:187], v[216:219], v[26:29]
	s_setprio 0
	s_barrier
	ds_read_b128 v[114:117], v8
	ds_read_b128 v[118:121], v8 offset:1024
	ds_read_b128 v[122:125], v8 offset:2048
	ds_read_b128 v[126:129], v8 offset:3072
	ds_read_b128 v[130:133], v9
	ds_read_b128 v[176:179], v9 offset:1024
	ds_read_b128 v[180:183], v9 offset:2048
	ds_read_b128 v[184:187], v9 offset:3072
	s_add_u32 s74, s36, 0xa0200
	s_addc_u32 s75, s37, 0
	s_mov_b32 m0, s54
	v_lshl_add_u64 v[134:135], s[74:75], 0, v[142:143]
	ds_read_b128 v[188:191], v157 offset:32768
	ds_read_b128 v[192:195], v157 offset:33792
	ds_read_b128 v[196:199], v157 offset:34816
	ds_read_b128 v[200:203], v157 offset:35840
	ds_read_b128 v[204:207], v157 offset:36864
	ds_read_b128 v[208:211], v157 offset:37888
	ds_read_b128 v[212:215], v157 offset:38912
	ds_read_b128 v[216:219], v157 offset:39936
	global_load_lds_dwordx4 v[134:135], off
	v_lshl_add_u64 v[134:135], s[74:75], 0, v[138:139]
	s_mov_b32 m0, s55
	s_nop 0
	global_load_lds_dwordx4 v[134:135], off
	s_waitcnt vmcnt(8)
	s_waitcnt lgkmcnt(0)
	s_barrier
	s_setprio 1
	s_waitcnt lgkmcnt(0)
	v_mfma_f32_16x16x32_bf16 v[62:65], v[114:117], v[188:191], v[62:65]
	v_mfma_f32_16x16x32_bf16 v[66:69], v[122:125], v[188:191], v[66:69]
	v_mfma_f32_16x16x32_bf16 v[70:73], v[114:117], v[196:199], v[70:73]
	v_mfma_f32_16x16x32_bf16 v[74:77], v[122:125], v[196:199], v[74:77]
	v_mfma_f32_16x16x32_bf16 v[78:81], v[114:117], v[204:207], v[78:81]
	v_mfma_f32_16x16x32_bf16 v[82:85], v[122:125], v[204:207], v[82:85]
	v_mfma_f32_16x16x32_bf16 v[86:89], v[114:117], v[212:215], v[86:89]
	v_mfma_f32_16x16x32_bf16 v[90:93], v[122:125], v[212:215], v[90:93]
	v_mfma_f32_16x16x32_bf16 v[62:65], v[118:121], v[192:195], v[62:65]
	v_mfma_f32_16x16x32_bf16 v[66:69], v[126:129], v[192:195], v[66:69]
	v_mfma_f32_16x16x32_bf16 v[70:73], v[118:121], v[200:203], v[70:73]
	v_mfma_f32_16x16x32_bf16 v[74:77], v[126:129], v[200:203], v[74:77]
	v_mfma_f32_16x16x32_bf16 v[78:81], v[118:121], v[208:211], v[78:81]
	v_mfma_f32_16x16x32_bf16 v[82:85], v[126:129], v[208:211], v[82:85]
	v_mfma_f32_16x16x32_bf16 v[86:89], v[118:121], v[216:219], v[86:89]
	v_mfma_f32_16x16x32_bf16 v[90:93], v[126:129], v[216:219], v[90:93]
	v_mfma_f32_16x16x32_bf16 v[94:97], v[130:133], v[188:191], v[94:97]
	v_mfma_f32_16x16x32_bf16 v[98:101], v[180:183], v[188:191], v[98:101]
	v_mfma_f32_16x16x32_bf16 v[102:105], v[130:133], v[196:199], v[102:105]
	v_mfma_f32_16x16x32_bf16 v[38:41], v[180:183], v[196:199], v[38:41]
	v_mfma_f32_16x16x32_bf16 v[42:45], v[130:133], v[204:207], v[42:45]
	v_mfma_f32_16x16x32_bf16 v[46:49], v[180:183], v[204:207], v[46:49]
	v_mfma_f32_16x16x32_bf16 v[50:53], v[130:133], v[212:215], v[50:53]
	v_mfma_f32_16x16x32_bf16 v[54:57], v[180:183], v[212:215], v[54:57]
	v_mfma_f32_16x16x32_bf16 v[94:97], v[176:179], v[192:195], v[94:97]
	v_mfma_f32_16x16x32_bf16 v[98:101], v[184:187], v[192:195], v[98:101]
	v_mfma_f32_16x16x32_bf16 v[102:105], v[176:179], v[200:203], v[102:105]
	v_mfma_f32_16x16x32_bf16 v[38:41], v[184:187], v[200:203], v[38:41]
	v_mfma_f32_16x16x32_bf16 v[42:45], v[176:179], v[208:211], v[42:45]
	v_mfma_f32_16x16x32_bf16 v[46:49], v[184:187], v[208:211], v[46:49]
	v_mfma_f32_16x16x32_bf16 v[50:53], v[176:179], v[216:219], v[50:53]
	v_mfma_f32_16x16x32_bf16 v[54:57], v[184:187], v[216:219], v[54:57]
	s_setprio 0
	s_barrier
; #define PG8_STAGE(bufoff, gbase, voff) do { _Pragma("unroll") for (int _i = 0; _i < 2; ++_i) \
;         __builtin_amdgcn_global_load_lds((const unsigned*)((const char*)(gbase) + (voff)[_i]), (LAS unsigned*)(lds + (bufoff) + ldsw + _i * 8192), 16, 0, 0); } while (0)
; #define PG8_LDA(dst, b, h) do { _Pragma("unroll") for (int m = 0; m < 4; ++m) _Pragma("unroll") for (int k = 0; k < 2; ++k) dst[m][k] = *(const LAS bf16x8*)(lds + PG8_SA(b, h) + aoff + m * 2048 + k * 1024); } while (0)
; #define PG8_LDB(dst, b, h) do { _Pragma("unroll") for (int n = 0; n < 2; ++n) _Pragma("unroll") for (int k = 0; k < 2; ++k) dst[n][k] = *(const LAS bf16x8*)(lds + PG8_SB(b, h) + boff + n * 2048 + k * 1024); } while (0)
; #define PG8_MMA(ai, bj, At, Bt) do { __builtin_amdgcn_s_setprio(1); _Pragma("unroll") for (int m = 0; m < 4; ++m) _Pragma("unroll") for (int n = 0; n < 2; ++n) _Pragma("unroll") for (int k = 0; k < 2; ++k) \
;         acc[ai][bj][m][n] = __builtin_amdgcn_mfma_f32_16x16x32_bf16(Bt[n][k], At[m][k], acc[ai][bj][m][n], 0, 0, 0); __builtin_amdgcn_s_setprio(0); } while (0)
; #define PG8_WAIT_V(n) asm volatile("s_waitcnt vmcnt(" #n ")" ::: "memory")
; #define PG8_WAIT_L(n) asm volatile("s_waitcnt lgkmcnt(" #n ")" ::: "memory")
; #define PG8_BAR __builtin_amdgcn_s_barrier()
; #define PG8_SCHED __builtin_amdgcn_sched_barrier(0)
; template <class Epi, bool ALIGN_EPI, int K, int LDA, int LDB>
; __device__ __forceinline__ void gemm_phase(LAS unsigned char* lds, const int wid, const Gemm g, const StaticOrder& S, const Epi& E) {
;     ...
;             PG8_LDB(B0, 0, 0); PG8_LDB(B1, 0, 1); PG8_SCHED; PG8_LDA(At, 0, 0); PG8_STAGE(PG8_SA(1, 1), a1 + hA, voffA);
;             PG8_WAIT_V(8); PG8_WAIT_L(0); PG8_BAR; PG8_MMA(0, 0, At, B0); PG8_MMA(0, 1, At, B1); PG8_BAR; PG8_SCHED;
;     ...
;             PG8_LDA(At, 1, 1); PG8_STAGE(PG8_SB(1, 0), b3, voffB); PG8_STAGE(PG8_SB(1, 1), b3 + hB, voffB); PG8_STAGE(PG8_SA(1, 0), a3, voffA);
;             PG8_WAIT_V(8); PG8_WAIT_L(0); PG8_BAR; PG8_MMA(1, 0, At, B0); PG8_MMA(1, 1, At, B1); PG8_BAR; PG8_SCHED;
	s_mov_b32 m0, s73
	v_lshl_add_u64 v[0:1], v[0:1], 0, s[28:29]
	s_add_u32 s38, s38, 0x18280
	ds_read_b128 v[188:191], v157 offset:49152
	ds_read_b128 v[192:195], v157 offset:50176
	ds_read_b128 v[196:199], v157 offset:51200
	ds_read_b128 v[200:203], v157 offset:52224
	ds_read_b128 v[204:207], v157 offset:53248
	ds_read_b128 v[208:211], v157 offset:54272
	ds_read_b128 v[212:215], v157 offset:55296
	ds_read_b128 v[216:219], v157 offset:56320
	global_load_lds_dwordx4 v[0:1], off
	v_lshl_add_u64 v[0:1], v[2:3], 0, s[28:29]
	s_mov_b32 m0, s69
	s_addc_u32 s39, s39, 0
	global_load_lds_dwordx4 v[0:1], off
	v_lshl_add_u64 v[0:1], s[38:39], 0, v[140:141]
	s_mov_b32 m0, s70
	s_nop 0
	global_load_lds_dwordx4 v[0:1], off
	v_lshl_add_u64 v[0:1], s[38:39], 0, v[136:137]
	s_mov_b32 m0, s72
	s_nop 0
	global_load_lds_dwordx4 v[0:1], off
	v_lshl_add_u64 v[0:1], v[4:5], 0, s[28:29]
	s_mov_b32 m0, s56
	s_nop 0
	global_load_lds_dwordx4 v[0:1], off
	v_lshl_add_u64 v[0:1], v[6:7], 0, s[28:29]
	s_mov_b32 m0, s57
	s_nop 0
	global_load_lds_dwordx4 v[0:1], off
	s_waitcnt vmcnt(8)
	s_waitcnt lgkmcnt(0)
	s_barrier
	s_setprio 1
	s_waitcnt lgkmcnt(0)
	v_mfma_f32_16x16x32_bf16 v[0:3], v[114:117], v[188:191], v[148:151]
	v_mfma_f32_16x16x32_bf16 v[4:7], v[122:125], v[188:191], v[152:155]
	v_mfma_f32_16x16x32_bf16 v[10:13], v[114:117], v[212:215], v[10:13]
	v_mfma_f32_16x16x32_bf16 v[14:17], v[122:125], v[212:215], v[14:17]
	v_mfma_f32_16x16x32_bf16 v[0:3], v[118:121], v[192:195], v[0:3]
	v_mfma_f32_16x16x32_bf16 v[4:7], v[126:129], v[192:195], v[4:7]
	v_mfma_f32_16x16x32_bf16 v[148:151], v[114:117], v[196:199], v[160:163]
	v_mfma_f32_16x16x32_bf16 v[152:155], v[122:125], v[196:199], v[164:167]
	v_mfma_f32_16x16x32_bf16 v[160:163], v[114:117], v[204:207], v[168:171]
	v_mfma_f32_16x16x32_bf16 v[164:167], v[122:125], v[204:207], v[172:175]
	v_mfma_f32_16x16x32_bf16 v[10:13], v[118:121], v[216:219], v[10:13]
	v_mfma_f32_16x16x32_bf16 v[14:17], v[126:129], v[216:219], v[14:17]
	v_mfma_f32_16x16x32_bf16 v[148:151], v[118:121], v[200:203], v[148:151]
	v_mfma_f32_16x16x32_bf16 v[152:155], v[126:129], v[200:203], v[152:155]
	v_mfma_f32_16x16x32_bf16 v[160:163], v[118:121], v[208:211], v[160:163]
	v_mfma_f32_16x16x32_bf16 v[164:167], v[126:129], v[208:211], v[164:167]
	v_mfma_f32_16x16x32_bf16 v[18:21], v[130:133], v[188:191], v[18:21]
	v_mfma_f32_16x16x32_bf16 v[30:33], v[180:183], v[188:191], v[30:33]
	v_mfma_f32_16x16x32_bf16 v[34:37], v[130:133], v[196:199], v[34:37]
	v_mfma_f32_16x16x32_bf16 v[58:61], v[180:183], v[196:199], v[58:61]
	v_mfma_f32_16x16x32_bf16 v[106:109], v[130:133], v[204:207], v[106:109]
	v_mfma_f32_16x16x32_bf16 v[110:113], v[180:183], v[204:207], v[110:113]
	v_mfma_f32_16x16x32_bf16 v[22:25], v[130:133], v[212:215], v[22:25]
	v_mfma_f32_16x16x32_bf16 v[26:29], v[180:183], v[212:215], v[26:29]
	v_mfma_f32_16x16x32_bf16 v[18:21], v[176:179], v[192:195], v[18:21]
	v_mfma_f32_16x16x32_bf16 v[30:33], v[184:187], v[192:195], v[30:33]
	v_mfma_f32_16x16x32_bf16 v[34:37], v[176:179], v[200:203], v[34:37]
	v_mfma_f32_16x16x32_bf16 v[58:61], v[184:187], v[200:203], v[58:61]
	v_mfma_f32_16x16x32_bf16 v[106:109], v[176:179], v[208:211], v[106:109]
	v_mfma_f32_16x16x32_bf16 v[110:113], v[184:187], v[208:211], v[110:113]
	v_mfma_f32_16x16x32_bf16 v[22:25], v[176:179], v[216:219], v[22:25]
	v_mfma_f32_16x16x32_bf16 v[26:29], v[184:187], v[216:219], v[26:29]
	s_setprio 0
	s_barrier
	ds_read_b128 v[114:117], v158
	ds_read_b128 v[118:121], v158 offset:1024
	ds_read_b128 v[122:125], v158 offset:2048
	ds_read_b128 v[126:129], v158 offset:3072
	ds_read_b128 v[130:133], v159
	ds_read_b128 v[168:171], v159 offset:1024
	ds_read_b128 v[172:175], v159 offset:2048
	ds_read_b128 v[176:179], v159 offset:3072
	s_add_u32 s36, s36, 0xa0280
	s_addc_u32 s37, s37, 0
	s_mov_b32 m0, s71
	v_lshl_add_u64 v[134:135], s[36:37], 0, v[142:143]
	ds_read_b128 v[180:183], v157
	ds_read_b128 v[184:187], v157 offset:1024
	ds_read_b128 v[188:191], v157 offset:2048
	ds_read_b128 v[192:195], v157 offset:3072
	ds_read_b128 v[196:199], v157 offset:4096
	ds_read_b128 v[200:203], v157 offset:5120
	ds_read_b128 v[204:207], v157 offset:6144
	ds_read_b128 v[208:211], v157 offset:7168
	global_load_lds_dwordx4 v[134:135], off
	v_lshl_add_u64 v[134:135], s[36:37], 0, v[138:139]
	s_mov_b32 m0, s6
	s_nop 0
	global_load_lds_dwordx4 v[134:135], off
	s_waitcnt vmcnt(8)
	s_waitcnt lgkmcnt(0)
	s_barrier
	s_setprio 1
	s_waitcnt lgkmcnt(0)
	v_mfma_f32_16x16x32_bf16 v[62:65], v[114:117], v[180:183], v[62:65]
	v_mfma_f32_16x16x32_bf16 v[66:69], v[122:125], v[180:183], v[66:69]
	v_mfma_f32_16x16x32_bf16 v[70:73], v[114:117], v[188:191], v[70:73]
	v_mfma_f32_16x16x32_bf16 v[74:77], v[122:125], v[188:191], v[74:77]
	v_mfma_f32_16x16x32_bf16 v[78:81], v[114:117], v[196:199], v[78:81]
	v_mfma_f32_16x16x32_bf16 v[82:85], v[122:125], v[196:199], v[82:85]
	v_mfma_f32_16x16x32_bf16 v[86:89], v[114:117], v[204:207], v[86:89]
	v_mfma_f32_16x16x32_bf16 v[62:65], v[118:121], v[184:187], v[62:65]
	v_mfma_f32_16x16x32_bf16 v[66:69], v[126:129], v[184:187], v[66:69]
	v_mfma_f32_16x16x32_bf16 v[70:73], v[118:121], v[192:195], v[70:73]
	v_mfma_f32_16x16x32_bf16 v[74:77], v[126:129], v[192:195], v[74:77]
	v_mfma_f32_16x16x32_bf16 v[78:81], v[118:121], v[200:203], v[78:81]
	v_mfma_f32_16x16x32_bf16 v[82:85], v[126:129], v[200:203], v[82:85]
	v_mfma_f32_16x16x32_bf16 v[212:215], v[118:121], v[208:211], v[86:89]
	v_mfma_f32_16x16x32_bf16 v[86:89], v[122:125], v[204:207], v[90:93]
	v_mfma_f32_16x16x32_bf16 v[216:219], v[126:129], v[208:211], v[86:89]
	v_mfma_f32_16x16x32_bf16 v[86:89], v[130:133], v[180:183], v[94:97]
	v_mfma_f32_16x16x32_bf16 v[220:223], v[168:171], v[184:187], v[86:89]
	v_mfma_f32_16x16x32_bf16 v[86:89], v[172:175], v[180:183], v[98:101]
	v_mfma_f32_16x16x32_bf16 v[96:99], v[176:179], v[184:187], v[86:89]
	v_mfma_f32_16x16x32_bf16 v[86:89], v[130:133], v[188:191], v[102:105]
	v_mfma_f32_16x16x32_bf16 v[38:41], v[172:175], v[188:191], v[38:41]
	v_mfma_f32_16x16x32_bf16 v[42:45], v[130:133], v[196:199], v[42:45]
	v_mfma_f32_16x16x32_bf16 v[46:49], v[172:175], v[196:199], v[46:49]
	v_mfma_f32_16x16x32_bf16 v[50:53], v[130:133], v[204:207], v[50:53]
	v_mfma_f32_16x16x32_bf16 v[54:57], v[172:175], v[204:207], v[54:57]
	v_mfma_f32_16x16x32_bf16 v[100:103], v[168:171], v[192:195], v[86:89]
	v_mfma_f32_16x16x32_bf16 v[38:41], v[176:179], v[192:195], v[38:41]
	v_mfma_f32_16x16x32_bf16 v[42:45], v[168:171], v[200:203], v[42:45]
	v_mfma_f32_16x16x32_bf16 v[46:49], v[176:179], v[200:203], v[46:49]
	v_mfma_f32_16x16x32_bf16 v[50:53], v[168:171], v[208:211], v[50:53]
	v_mfma_f32_16x16x32_bf16 v[54:57], v[176:179], v[208:211], v[54:57]
	s_setprio 0
	s_barrier
; #define PG8_STAGE(bufoff, gbase, voff) do { _Pragma("unroll") for (int _i = 0; _i < 2; ++_i) \
;         __builtin_amdgcn_global_load_lds((const unsigned*)((const char*)(gbase) + (voff)[_i]), (LAS unsigned*)(lds + (bufoff) + ldsw + _i * 8192), 16, 0, 0); } while (0)
; #define PG8_LDA(dst, b, h) do { _Pragma("unroll") for (int m = 0; m < 4; ++m) _Pragma("unroll") for (int k = 0; k < 2; ++k) dst[m][k] = *(const LAS bf16x8*)(lds + PG8_SA(b, h) + aoff + m * 2048 + k * 1024); } while (0)
; #define PG8_LDB(dst, b, h) do { _Pragma("unroll") for (int n = 0; n < 2; ++n) _Pragma("unroll") for (int k = 0; k < 2; ++k) dst[n][k] = *(const LAS bf16x8*)(lds + PG8_SB(b, h) + boff + n * 2048 + k * 1024); } while (0)
; #define PG8_MMA(ai, bj, At, Bt) do { __builtin_amdgcn_s_setprio(1); _Pragma("unroll") for (int m = 0; m < 4; ++m) _Pragma("unroll") for (int n = 0; n < 2; ++n) _Pragma("unroll") for (int k = 0; k < 2; ++k) \
;         acc[ai][bj][m][n] = __builtin_amdgcn_mfma_f32_16x16x32_bf16(Bt[n][k], At[m][k], acc[ai][bj][m][n], 0, 0, 0); __builtin_amdgcn_s_setprio(0); } while (0)
; #define PG8_WAIT_V(n) asm volatile("s_waitcnt vmcnt(" #n ")" ::: "memory")
; #define PG8_WAIT_L(n) asm volatile("s_waitcnt lgkmcnt(" #n ")" ::: "memory")
; template <class Epi, bool ALIGN_EPI, int K, int LDA, int LDB>
; __device__ __forceinline__ void gemm_phase(LAS unsigned char* lds, const int wid, const Gemm g, const StaticOrder& S, const Epi& E) {
;     ...
;         const char* nA = has_next ? (const char*)g.A + (size_t)nxt.pm * tA : cA; const char* nB = has_next ? (const char*)g.Bt + (size_t)nxt.pn * tB : cB;
;         for (int t = 0; t < nt; t += 2) {
;             const bool last = (t == nt - 2);
;             const char* a1 = cA + (size_t)(t + 1) * kstep;
;             const char* a2 = last ? nA : cA + (size_t)(t + 2) * kstep; const char* b2 = last ? nB : cB + (size_t)(t + 2) * kstep;
;     ...
;             PG8_LDA(At, 0, 1); PG8_STAGE(PG8_SB(0, 0), b2, voffB); PG8_STAGE(PG8_SB(0, 1), b2 + hB, voffB); PG8_STAGE(PG8_SA(0, 0), a2, voffA);
;             PG8_WAIT_V(8); PG8_WAIT_L(0); PG8_BAR; PG8_MMA(1, 0, At, B0); PG8_MMA(1, 1, At, B1); PG8_BAR; PG8_SCHED;
;             PG8_LDB(B0, 1, 0); PG8_LDB(B1, 1, 1); PG8_SCHED; PG8_LDA(At, 1, 0); PG8_STAGE(PG8_SA(0, 1), a2 + hA, voffA);
;             PG8_WAIT_V(8); PG8_WAIT_L(0); PG8_BAR; PG8_MMA(0, 0, At, B0); PG8_MMA(0, 1, At, B1); PG8_BAR; PG8_SCHED;
	s_mov_b32 m0, s68
	v_lshl_add_u64 v[248:249], s[34:35], 0, v[140:141]
	s_add_u32 s6, s34, 0x18000
	ds_read_b128 v[86:89], v157 offset:16384
	ds_read_b128 v[90:93], v157 offset:17408
	ds_read_b128 v[180:183], v157 offset:18432
	ds_read_b128 v[184:187], v157 offset:19456
	ds_read_b128 v[188:191], v157 offset:20480
	ds_read_b128 v[192:195], v157 offset:21504
	ds_read_b128 v[196:199], v157 offset:22528
	ds_read_b128 v[200:203], v157 offset:23552
	global_load_lds_dwordx4 v[248:249], off
	v_lshl_add_u64 v[250:251], s[34:35], 0, v[136:137]
	s_mov_b32 m0, s7
	s_addc_u32 s7, s35, 0
	global_load_lds_dwordx4 v[250:251], off
	v_lshl_add_u64 v[94:95], s[6:7], 0, v[140:141]
	s_mov_b32 m0, s66
	v_lshl_add_u64 v[252:253], s[30:31], 0, v[142:143]
	global_load_lds_dwordx4 v[94:95], off
	v_lshl_add_u64 v[94:95], s[6:7], 0, v[136:137]
	s_mov_b32 m0, s67
	v_lshl_add_u64 v[144:145], s[30:31], 0, v[138:139]
	global_load_lds_dwordx4 v[94:95], off
	s_mov_b32 m0, s42
	s_nop 0
	global_load_lds_dwordx4 v[252:253], off
	s_mov_b32 m0, s51
	s_nop 0
	global_load_lds_dwordx4 v[144:145], off
	s_waitcnt vmcnt(8)
	s_waitcnt lgkmcnt(0)
	s_barrier
	s_setprio 1
	s_waitcnt lgkmcnt(0)
	v_mfma_f32_16x16x32_bf16 v[0:3], v[114:117], v[86:89], v[0:3]
	v_mfma_f32_16x16x32_bf16 v[4:7], v[122:125], v[86:89], v[4:7]
	v_mfma_f32_16x16x32_bf16 v[10:13], v[114:117], v[196:199], v[10:13]
	v_mfma_f32_16x16x32_bf16 v[0:3], v[118:121], v[90:93], v[0:3]
	v_mfma_f32_16x16x32_bf16 v[4:7], v[126:129], v[90:93], v[4:7]
	v_mfma_f32_16x16x32_bf16 v[148:151], v[114:117], v[180:183], v[148:151]
	v_mfma_f32_16x16x32_bf16 v[152:155], v[122:125], v[180:183], v[152:155]
	v_mfma_f32_16x16x32_bf16 v[160:163], v[114:117], v[188:191], v[160:163]
	v_mfma_f32_16x16x32_bf16 v[164:167], v[122:125], v[188:191], v[164:167]
	v_mfma_f32_16x16x32_bf16 v[10:13], v[118:121], v[200:203], v[10:13]
	v_mfma_f32_16x16x32_bf16 v[14:17], v[122:125], v[196:199], v[14:17]
	v_mfma_f32_16x16x32_bf16 v[148:151], v[118:121], v[184:187], v[148:151]
	v_mfma_f32_16x16x32_bf16 v[152:155], v[126:129], v[184:187], v[152:155]
	v_mfma_f32_16x16x32_bf16 v[160:163], v[118:121], v[192:195], v[160:163]
	v_mfma_f32_16x16x32_bf16 v[164:167], v[126:129], v[192:195], v[164:167]
	v_mfma_f32_16x16x32_bf16 v[120:123], v[126:129], v[200:203], v[14:17]
	v_mfma_f32_16x16x32_bf16 v[30:33], v[172:175], v[86:89], v[30:33]
	v_mfma_f32_16x16x32_bf16 v[58:61], v[172:175], v[180:183], v[58:61]
	v_mfma_f32_16x16x32_bf16 v[14:17], v[130:133], v[86:89], v[18:21]
	v_mfma_f32_16x16x32_bf16 v[124:127], v[176:179], v[90:93], v[30:33]
	v_mfma_f32_16x16x32_bf16 v[30:33], v[130:133], v[180:183], v[34:37]
	v_mfma_f32_16x16x32_bf16 v[180:183], v[176:179], v[184:187], v[58:61]
	v_mfma_f32_16x16x32_bf16 v[58:61], v[130:133], v[188:191], v[106:109]
	v_mfma_f32_16x16x32_bf16 v[20:23], v[130:133], v[196:199], v[22:25]
	v_mfma_f32_16x16x32_bf16 v[16:19], v[168:171], v[90:93], v[14:17]
	v_mfma_f32_16x16x32_bf16 v[32:35], v[168:171], v[184:187], v[30:33]
	v_mfma_f32_16x16x32_bf16 v[184:187], v[168:171], v[192:195], v[58:61]
	v_mfma_f32_16x16x32_bf16 v[58:61], v[172:175], v[188:191], v[110:113]
	v_mfma_f32_16x16x32_bf16 v[168:171], v[168:171], v[200:203], v[20:23]
	v_mfma_f32_16x16x32_bf16 v[20:23], v[172:175], v[196:199], v[26:29]
	v_mfma_f32_16x16x32_bf16 v[188:191], v[176:179], v[192:195], v[58:61]
	v_mfma_f32_16x16x32_bf16 v[172:175], v[176:179], v[200:203], v[20:23]
	s_setprio 0
	s_barrier
	s_nop 3
	ds_read_b128 v[20:23], v8
	ds_read_b128 v[176:179], v8 offset:1024
	ds_read_b128 v[192:195], v8 offset:2048
	ds_read_b128 v[196:199], v8 offset:3072
	ds_read_b128 v[200:203], v9
	ds_read_b128 v[204:207], v9 offset:1024
	ds_read_b128 v[208:211], v9 offset:2048
	ds_read_b128 v[224:227], v9 offset:3072
	s_add_u32 s6, s30, 0xa0000
	s_addc_u32 s7, s31, 0
	s_mov_b32 m0, s54
	v_lshl_add_u64 v[8:9], s[6:7], 0, v[142:143]
	ds_read_b128 v[24:27], v157 offset:32768
	ds_read_b128 v[28:31], v157 offset:33792
	ds_read_b128 v[58:61], v157 offset:34816
	ds_read_b128 v[228:231], v157 offset:35840
	ds_read_b128 v[232:235], v157 offset:36864
	ds_read_b128 v[236:239], v157 offset:37888
	ds_read_b128 v[240:243], v157 offset:38912
	ds_read_b128 v[244:247], v157 offset:39936
	global_load_lds_dwordx4 v[8:9], off
	v_lshl_add_u64 v[8:9], s[6:7], 0, v[138:139]
	s_mov_b32 m0, s55
	s_nop 0
	global_load_lds_dwordx4 v[8:9], off
	s_waitcnt vmcnt(8)
	s_waitcnt lgkmcnt(0)
	s_barrier
; #define PG8_STAGE(bufoff, gbase, voff) do { _Pragma("unroll") for (int _i = 0; _i < 2; ++_i) \
;         __builtin_amdgcn_global_load_lds((const unsigned*)((const char*)(gbase) + (voff)[_i]), (LAS unsigned*)(lds + (bufoff) + ldsw + _i * 8192), 16, 0, 0); } while (0)
; #define PG8_LDA(dst, b, h) do { _Pragma("unroll") for (int m = 0; m < 4; ++m) _Pragma("unroll") for (int k = 0; k < 2; ++k) dst[m][k] = *(const LAS bf16x8*)(lds + PG8_SA(b, h) + aoff + m * 2048 + k * 1024); } while (0)
; #define PG8_MMA(ai, bj, At, Bt) do { __builtin_amdgcn_s_setprio(1); _Pragma("unroll") for (int m = 0; m < 4; ++m) _Pragma("unroll") for (int n = 0; n < 2; ++n) _Pragma("unroll") for (int k = 0; k < 2; ++k) \
;         acc[ai][bj][m][n] = __builtin_amdgcn_mfma_f32_16x16x32_bf16(Bt[n][k], At[m][k], acc[ai][bj][m][n], 0, 0, 0); __builtin_amdgcn_s_setprio(0); } while (0)
; #define PG8_WAIT_V(n) asm volatile("s_waitcnt vmcnt(" #n ")" ::: "memory")
; #define PG8_WAIT_L(n) asm volatile("s_waitcnt lgkmcnt(" #n ")" ::: "memory")
; #define PG8_BAR __builtin_amdgcn_s_barrier()
; #define PG8_SCHED __builtin_amdgcn_sched_barrier(0)
; template <class Epi, bool ALIGN_EPI, int K, int LDA, int LDB>
; __device__ __forceinline__ void gemm_phase(LAS unsigned char* lds, const int wid, const Gemm g, const StaticOrder& S, const Epi& E) {
;     ...
;             PG8_WAIT_V(8); PG8_WAIT_L(0); PG8_BAR; PG8_MMA(0, 0, At, B0); PG8_MMA(0, 1, At, B1); PG8_BAR; PG8_SCHED;
;             PG8_LDA(At, 1, 1); PG8_STAGE(PG8_SB(1, 0), b3, voffB); PG8_STAGE(PG8_SB(1, 1), b3 + hB, voffB); PG8_STAGE(PG8_SA(1, 0), a3, voffA);
;             PG8_WAIT_V(8); PG8_WAIT_L(0); PG8_BAR; PG8_MMA(1, 0, At, B0); PG8_MMA(1, 1, At, B1); PG8_BAR; PG8_SCHED;
;         }
;         if constexpr (ALIGN_EPI) { if (wr == 0) PG8_BAR; }
	s_setprio 1
	s_waitcnt lgkmcnt(0)
	v_mfma_f32_16x16x32_bf16 v[62:65], v[20:23], v[24:27], v[62:65]
	v_mfma_f32_16x16x32_bf16 v[128:131], v[176:179], v[28:31], v[62:65]
	v_mfma_f32_16x16x32_bf16 v[62:65], v[192:195], v[24:27], v[66:69]
	v_mfma_f32_16x16x32_bf16 v[132:135], v[196:199], v[28:31], v[62:65]
	v_mfma_f32_16x16x32_bf16 v[62:65], v[20:23], v[58:61], v[70:73]
	v_mfma_f32_16x16x32_bf16 v[108:111], v[176:179], v[228:231], v[62:65]
	v_mfma_f32_16x16x32_bf16 v[62:65], v[192:195], v[58:61], v[74:77]
	v_mfma_f32_16x16x32_bf16 v[104:107], v[196:199], v[228:231], v[62:65]
	v_mfma_f32_16x16x32_bf16 v[62:65], v[20:23], v[232:235], v[78:81]
	v_mfma_f32_16x16x32_bf16 v[92:95], v[176:179], v[236:239], v[62:65]
	v_mfma_f32_16x16x32_bf16 v[62:65], v[192:195], v[232:235], v[82:85]
	v_mfma_f32_16x16x32_bf16 v[88:91], v[196:199], v[236:239], v[62:65]
	v_mfma_f32_16x16x32_bf16 v[62:65], v[20:23], v[240:243], v[212:215]
	v_mfma_f32_16x16x32_bf16 v[76:79], v[176:179], v[244:247], v[62:65]
	v_mfma_f32_16x16x32_bf16 v[62:65], v[192:195], v[240:243], v[216:219]
	v_mfma_f32_16x16x32_bf16 v[72:75], v[196:199], v[244:247], v[62:65]
	v_mfma_f32_16x16x32_bf16 v[62:65], v[200:203], v[24:27], v[220:223]
	v_mfma_f32_16x16x32_bf16 v[24:27], v[208:211], v[24:27], v[96:99]
	v_mfma_f32_16x16x32_bf16 v[112:115], v[224:227], v[28:31], v[24:27]
	v_mfma_f32_16x16x32_bf16 v[24:27], v[200:203], v[58:61], v[100:103]
	v_mfma_f32_16x16x32_bf16 v[100:103], v[204:207], v[228:231], v[24:27]
	v_mfma_f32_16x16x32_bf16 v[24:27], v[208:211], v[58:61], v[38:41]
	v_mfma_f32_16x16x32_bf16 v[96:99], v[224:227], v[228:231], v[24:27]
	v_mfma_f32_16x16x32_bf16 v[24:27], v[200:203], v[232:235], v[42:45]
	v_mfma_f32_16x16x32_bf16 v[84:87], v[204:207], v[236:239], v[24:27]
	v_mfma_f32_16x16x32_bf16 v[24:27], v[208:211], v[232:235], v[46:49]
	v_mfma_f32_16x16x32_bf16 v[80:83], v[224:227], v[236:239], v[24:27]
	v_mfma_f32_16x16x32_bf16 v[24:27], v[200:203], v[240:243], v[50:53]
	v_mfma_f32_16x16x32_bf16 v[68:71], v[204:207], v[244:247], v[24:27]
	v_mfma_f32_16x16x32_bf16 v[24:27], v[208:211], v[240:243], v[54:57]
	v_mfma_f32_16x16x32_bf16 v[116:119], v[204:207], v[28:31], v[62:65]
	v_mfma_f32_16x16x32_bf16 v[64:67], v[224:227], v[244:247], v[24:27]
	s_setprio 0
	s_barrier
	s_mov_b32 m0, s73
	v_lshl_add_u64 v[8:9], v[248:249], 0, s[16:17]
	s_add_u32 s6, s34, 0x18080
	ds_read_b128 v[36:39], v157 offset:49152
	ds_read_b128 v[48:51], v157 offset:50176
	ds_read_b128 v[212:215], v157 offset:51200
	ds_read_b128 v[216:219], v157 offset:52224
	ds_read_b128 v[220:223], v157 offset:53248
	ds_read_b128 v[228:231], v157 offset:54272
	ds_read_b128 v[232:235], v157 offset:55296
	ds_read_b128 v[236:239], v157 offset:56320
	global_load_lds_dwordx4 v[8:9], off
	v_lshl_add_u64 v[8:9], v[250:251], 0, s[16:17]
	s_mov_b32 m0, s69
	s_addc_u32 s7, s35, 0
	global_load_lds_dwordx4 v[8:9], off
	v_lshl_add_u64 v[8:9], s[6:7], 0, v[140:141]
	s_mov_b32 m0, s70
	s_nop 0
	global_load_lds_dwordx4 v[8:9], off
	v_lshl_add_u64 v[8:9], s[6:7], 0, v[136:137]
	s_mov_b32 m0, s72
	s_nop 0
	global_load_lds_dwordx4 v[8:9], off
	v_lshl_add_u64 v[8:9], v[252:253], 0, s[16:17]
	s_mov_b32 m0, s56
	s_nop 0
	global_load_lds_dwordx4 v[8:9], off
	v_lshl_add_u64 v[8:9], v[144:145], 0, s[16:17]
	s_mov_b32 m0, s57
	s_nop 0
	global_load_lds_dwordx4 v[8:9], off
	s_waitcnt vmcnt(8)
	s_waitcnt lgkmcnt(0)
	s_barrier
	s_setprio 1
	s_waitcnt lgkmcnt(0)
	v_mfma_f32_16x16x32_bf16 v[0:3], v[20:23], v[36:39], v[0:3]
	v_mfma_f32_16x16x32_bf16 v[60:63], v[176:179], v[48:51], v[0:3]
	v_mfma_f32_16x16x32_bf16 v[0:3], v[192:195], v[36:39], v[4:7]
	v_mfma_f32_16x16x32_bf16 v[56:59], v[196:199], v[48:51], v[0:3]
	v_mfma_f32_16x16x32_bf16 v[0:3], v[20:23], v[212:215], v[148:151]
	v_mfma_f32_16x16x32_bf16 v[44:47], v[176:179], v[216:219], v[0:3]
	v_mfma_f32_16x16x32_bf16 v[0:3], v[192:195], v[212:215], v[152:155]
	v_mfma_f32_16x16x32_bf16 v[40:43], v[196:199], v[216:219], v[0:3]
	v_mfma_f32_16x16x32_bf16 v[0:3], v[20:23], v[220:223], v[160:163]
	v_mfma_f32_16x16x32_bf16 v[28:31], v[176:179], v[228:231], v[0:3]
	v_mfma_f32_16x16x32_bf16 v[0:3], v[192:195], v[220:223], v[164:167]
	v_mfma_f32_16x16x32_bf16 v[24:27], v[196:199], v[228:231], v[0:3]
	v_mfma_f32_16x16x32_bf16 v[0:3], v[20:23], v[232:235], v[10:13]
	v_mfma_f32_16x16x32_bf16 v[12:15], v[176:179], v[236:239], v[0:3]
	v_mfma_f32_16x16x32_bf16 v[0:3], v[192:195], v[232:235], v[120:123]
	v_mfma_f32_16x16x32_bf16 v[8:11], v[196:199], v[236:239], v[0:3]
	v_mfma_f32_16x16x32_bf16 v[0:3], v[200:203], v[36:39], v[16:19]
	v_mfma_f32_16x16x32_bf16 v[52:55], v[204:207], v[48:51], v[0:3]
	v_mfma_f32_16x16x32_bf16 v[0:3], v[208:211], v[36:39], v[124:127]
	v_mfma_f32_16x16x32_bf16 v[48:51], v[224:227], v[48:51], v[0:3]
	v_mfma_f32_16x16x32_bf16 v[0:3], v[200:203], v[212:215], v[32:35]
	v_mfma_f32_16x16x32_bf16 v[36:39], v[204:207], v[216:219], v[0:3]
	v_mfma_f32_16x16x32_bf16 v[0:3], v[208:211], v[212:215], v[180:183]
	v_mfma_f32_16x16x32_bf16 v[32:35], v[224:227], v[216:219], v[0:3]
	v_mfma_f32_16x16x32_bf16 v[0:3], v[200:203], v[220:223], v[184:187]
	v_mfma_f32_16x16x32_bf16 v[20:23], v[204:207], v[228:231], v[0:3]
	v_mfma_f32_16x16x32_bf16 v[0:3], v[208:211], v[220:223], v[188:191]
	v_mfma_f32_16x16x32_bf16 v[16:19], v[224:227], v[228:231], v[0:3]
	v_mfma_f32_16x16x32_bf16 v[0:3], v[200:203], v[232:235], v[168:171]
	v_mfma_f32_16x16x32_bf16 v[4:7], v[204:207], v[236:239], v[0:3]
	v_mfma_f32_16x16x32_bf16 v[0:3], v[208:211], v[232:235], v[172:175]
	v_mfma_f32_16x16x32_bf16 v[0:3], v[224:227], v[236:239], v[0:3]
	s_setprio 0
	s_barrier
	s_andn2_b64 vcc, exec, s[18:19]
	s_cbranch_vccnz .LBB0_667
	s_barrier

; #define PG8_STAGE(bufoff, gbase, voff) do { _Pragma("unroll") for (int _i = 0; _i < 2; ++_i) \
;         __builtin_amdgcn_global_load_lds((const unsigned*)((const char*)(gbase) + (voff)[_i]), (LAS unsigned*)(lds + (bufoff) + ldsw + _i * 8192), 16, 0, 0); } while (0)
; #define PG8_LDA(dst, b, h) do { _Pragma("unroll") for (int m = 0; m < 4; ++m) _Pragma("unroll") for (int k = 0; k < 2; ++k) dst[m][k] = *(const LAS bf16x8*)(lds + PG8_SA(b, h) + aoff + m * 2048 + k * 1024); } while (0)
; #define PG8_LDB(dst, b, h) do { _Pragma("unroll") for (int n = 0; n < 2; ++n) _Pragma("unroll") for (int k = 0; k < 2; ++k) dst[n][k] = *(const LAS bf16x8*)(lds + PG8_SB(b, h) + boff + n * 2048 + k * 1024); } while (0)
; #define PG8_WAIT_V(n) asm volatile("s_waitcnt vmcnt(" #n ")" ::: "memory")
; #define PG8_WAIT_L(n) asm volatile("s_waitcnt lgkmcnt(" #n ")" ::: "memory")
; template <class Epi, bool ALIGN_EPI, int K, int LDA, int LDB>
; __device__ __forceinline__ void gemm_phase(LAS unsigned char* lds, const int wid, const Gemm g, const StaticOrder& S, const Epi& E) {
;     ...
;         const bool has_next = S.next(ui + 1, nxt);
;         const char* nA = has_next ? (const char*)g.A + (size_t)nxt.pm * tA : cA; const char* nB = has_next ? (const char*)g.Bt + (size_t)nxt.pn * tB : cB;
;         for (int t = 0; t < nt; t += 2) {
;             const bool last = (t == nt - 2);
;             const char* a1 = cA + (size_t)(t + 1) * kstep;
;             const char* a2 = last ? nA : cA + (size_t)(t + 2) * kstep; const char* b2 = last ? nB : cB + (size_t)(t + 2) * kstep;
;             const char* a3 = a2 + kstep; const char* b3 = b2 + kstep;
;             PG8_LDB(B0, 0, 0); PG8_LDB(B1, 0, 1); PG8_SCHED; PG8_LDA(At, 0, 0); PG8_STAGE(PG8_SA(1, 1), a1 + hA, voffA);
;             PG8_WAIT_V(8); PG8_WAIT_L(0); PG8_BAR; PG8_MMA(0, 0, At, B0); PG8_MMA(0, 1, At, B1); PG8_BAR; PG8_SCHED;
;             PG8_LDA(At, 0, 1); PG8_STAGE(PG8_SB(0, 0), b2, voffB); PG8_STAGE(PG8_SB(0, 1), b2 + hB, voffB); PG8_STAGE(PG8_SA(0, 0), a2, voffA);
;             PG8_WAIT_V(8); PG8_WAIT_L(0); PG8_BAR; PG8_MMA(1, 0, At, B0); PG8_MMA(1, 1, At, B1); PG8_BAR; PG8_SCHED;
;             PG8_LDB(B0, 1, 0); PG8_LDB(B1, 1, 1); PG8_SCHED; PG8_LDA(At, 1, 0); PG8_STAGE(PG8_SA(0, 1), a2 + hA, voffA);
;             PG8_WAIT_V(8); PG8_WAIT_L(0); PG8_BAR; PG8_MMA(0, 0, At, B0); PG8_MMA(0, 1, At, B1); PG8_BAR; PG8_SCHED;
.LBB0_689:
	ds_read_b128 v[0:3], v145
	ds_read_b128 v[4:7], v145 offset:1024
	ds_read_b128 v[8:11], v145 offset:2048
	ds_read_b128 v[12:15], v145 offset:3072
	ds_read_b128 v[16:19], v147
	ds_read_b128 v[20:23], v147 offset:1024
	ds_read_b128 v[24:27], v147 offset:2048
	ds_read_b128 v[28:31], v147 offset:3072
	s_ashr_i32 s31, s30, 31
	s_lshl_b64 s[36:37], s[30:31], 17
	s_add_u32 s36, s51, s36
	s_addc_u32 s37, s54, s37
	s_and_b64 s[8:9], s[8:9], exec
	s_cselect_b32 s9, s37, s41
	s_cselect_b32 s8, s36, s40
	s_add_u32 s66, s38, 0xa0080
	s_addc_u32 s67, s39, 0
	s_add_i32 s70, s55, 0xc000
	v_lshl_add_u64 v[64:65], s[66:67], 0, v[128:129]
	s_mov_b32 m0, s70
	s_add_i32 s31, s55, 0xe000
	ds_read_b128 v[32:35], v149
	ds_read_b128 v[36:39], v149 offset:1024
	ds_read_b128 v[40:43], v149 offset:2048
	ds_read_b128 v[44:47], v149 offset:3072
	ds_read_b128 v[48:51], v149 offset:4096
	ds_read_b128 v[52:55], v149 offset:5120
	ds_read_b128 v[56:59], v149 offset:6144
	ds_read_b128 v[60:63], v149 offset:7168
	global_load_lds_dwordx4 v[64:65], off
	v_lshl_add_u64 v[64:65], s[66:67], 0, v[132:133]
	s_mov_b32 m0, s31
	s_nop 0
	global_load_lds_dwordx4 v[64:65], off
	s_waitcnt vmcnt(8)
	s_waitcnt lgkmcnt(0)
	s_barrier
	s_setprio 1
	s_waitcnt lgkmcnt(0)
	v_mfma_f32_16x16x32_bf16 v[64:67], v[0:3], v[32:35], 0
	v_mfma_f32_16x16x32_bf16 v[68:71], v[8:11], v[32:35], 0
	v_mfma_f32_16x16x32_bf16 v[72:75], v[0:3], v[40:43], 0
	v_mfma_f32_16x16x32_bf16 v[76:79], v[8:11], v[40:43], 0
	v_mfma_f32_16x16x32_bf16 v[80:83], v[0:3], v[48:51], 0
	v_mfma_f32_16x16x32_bf16 v[84:87], v[8:11], v[48:51], 0
	s_waitcnt vmcnt(0)
	v_mfma_f32_16x16x32_bf16 v[88:91], v[0:3], v[56:59], 0
	v_mfma_f32_16x16x32_bf16 v[92:95], v[8:11], v[56:59], 0
	v_mfma_f32_16x16x32_bf16 v[64:67], v[4:7], v[36:39], v[64:67]
	v_mfma_f32_16x16x32_bf16 v[68:71], v[12:15], v[36:39], v[68:71]
	v_mfma_f32_16x16x32_bf16 v[72:75], v[4:7], v[44:47], v[72:75]
	v_mfma_f32_16x16x32_bf16 v[76:79], v[12:15], v[44:47], v[76:79]
	v_mfma_f32_16x16x32_bf16 v[80:83], v[4:7], v[52:55], v[80:83]
	v_mfma_f32_16x16x32_bf16 v[84:87], v[12:15], v[52:55], v[84:87]
	v_mfma_f32_16x16x32_bf16 v[88:91], v[4:7], v[60:63], v[88:91]
	v_mfma_f32_16x16x32_bf16 v[92:95], v[12:15], v[60:63], v[92:95]
	v_mfma_f32_16x16x32_bf16 v[96:99], v[16:19], v[32:35], 0
	v_mfma_f32_16x16x32_bf16 v[32:35], v[24:27], v[32:35], 0
	v_mfma_f32_16x16x32_bf16 v[96:99], v[20:23], v[36:39], v[96:99]
	v_mfma_f32_16x16x32_bf16 v[32:35], v[28:31], v[36:39], v[32:35]
	v_mfma_f32_16x16x32_bf16 v[36:39], v[16:19], v[40:43], 0
	v_mfma_f32_16x16x32_bf16 v[40:43], v[24:27], v[40:43], 0
	v_mfma_f32_16x16x32_bf16 v[36:39], v[20:23], v[44:47], v[36:39]
	v_mfma_f32_16x16x32_bf16 v[40:43], v[28:31], v[44:47], v[40:43]
	v_mfma_f32_16x16x32_bf16 v[44:47], v[16:19], v[48:51], 0
	v_mfma_f32_16x16x32_bf16 v[48:51], v[24:27], v[48:51], 0
	v_mfma_f32_16x16x32_bf16 v[44:47], v[20:23], v[52:55], v[44:47]
	v_mfma_f32_16x16x32_bf16 v[48:51], v[28:31], v[52:55], v[48:51]
	v_mfma_f32_16x16x32_bf16 v[52:55], v[16:19], v[56:59], 0
	v_mfma_f32_16x16x32_bf16 v[56:59], v[24:27], v[56:59], 0
	v_mfma_f32_16x16x32_bf16 v[52:55], v[20:23], v[60:63], v[52:55]
	v_mfma_f32_16x16x32_bf16 v[56:59], v[28:31], v[60:63], v[56:59]
	s_setprio 0
	s_barrier
	s_add_i32 s68, s43, s0
	v_lshl_add_u64 v[140:141], s[40:41], 0, v[130:131]
	s_add_i32 s65, s68, 0x2000
	v_lshl_add_u64 v[150:151], v[140:141], 0, s[24:25]
	s_mov_b32 m0, s68
	v_lshl_add_u64 v[214:215], s[40:41], 0, v[134:135]
	s_add_u32 s72, s40, 0x10100
	ds_read_b128 v[60:63], v149 offset:16384
	ds_read_b128 v[100:103], v149 offset:17408
	ds_read_b128 v[104:107], v149 offset:18432
	ds_read_b128 v[108:111], v149 offset:19456
	ds_read_b128 v[112:115], v149 offset:20480
	ds_read_b128 v[116:119], v149 offset:21504
	ds_read_b128 v[120:123], v149 offset:22528
	ds_read_b128 v[124:127], v149 offset:23552
	global_load_lds_dwordx4 v[150:151], off
	v_lshl_add_u64 v[150:151], v[214:215], 0, s[24:25]
	s_mov_b32 m0, s65
	s_addc_u32 s73, s41, 0
	s_add_i32 s66, s61, s0
	global_load_lds_dwordx4 v[150:151], off
	v_lshl_add_u64 v[150:151], s[72:73], 0, v[130:131]
	s_mov_b32 m0, s66
	s_add_i32 s67, s66, 0x2000
	global_load_lds_dwordx4 v[150:151], off
	v_lshl_add_u64 v[150:151], s[72:73], 0, v[134:135]
	s_mov_b32 m0, s67
	v_lshl_add_u64 v[216:217], s[38:39], 0, v[128:129]
	global_load_lds_dwordx4 v[150:151], off
	v_lshl_add_u64 v[150:151], v[216:217], 0, s[24:25]
	s_mov_b32 m0, s55
	v_lshl_add_u64 v[218:219], s[38:39], 0, v[132:133]
	global_load_lds_dwordx4 v[150:151], off
	v_lshl_add_u64 v[150:151], v[218:219], 0, s[24:25]
	s_mov_b32 m0, s56
	s_nop 0
	global_load_lds_dwordx4 v[150:151], off
	s_waitcnt vmcnt(8)
	s_waitcnt lgkmcnt(0)
	s_barrier
; #define PG8_STAGE(bufoff, gbase, voff) do { _Pragma("unroll") for (int _i = 0; _i < 2; ++_i) \
;         __builtin_amdgcn_global_load_lds((const unsigned*)((const char*)(gbase) + (voff)[_i]), (LAS unsigned*)(lds + (bufoff) + ldsw + _i * 8192), 16, 0, 0); } while (0)
; #define PG8_LDA(dst, b, h) do { _Pragma("unroll") for (int m = 0; m < 4; ++m) _Pragma("unroll") for (int k = 0; k < 2; ++k) dst[m][k] = *(const LAS bf16x8*)(lds + PG8_SA(b, h) + aoff + m * 2048 + k * 1024); } while (0)
; #define PG8_LDB(dst, b, h) do { _Pragma("unroll") for (int n = 0; n < 2; ++n) _Pragma("unroll") for (int k = 0; k < 2; ++k) dst[n][k] = *(const LAS bf16x8*)(lds + PG8_SB(b, h) + boff + n * 2048 + k * 1024); } while (0)
; #define PG8_MMA(ai, bj, At, Bt) do { __builtin_amdgcn_s_setprio(1); _Pragma("unroll") for (int m = 0; m < 4; ++m) _Pragma("unroll") for (int n = 0; n < 2; ++n) _Pragma("unroll") for (int k = 0; k < 2; ++k) \
;         acc[ai][bj][m][n] = __builtin_amdgcn_mfma_f32_16x16x32_bf16(Bt[n][k], At[m][k], acc[ai][bj][m][n], 0, 0, 0); __builtin_amdgcn_s_setprio(0); } while (0)
; #define PG8_WAIT_V(n) asm volatile("s_waitcnt vmcnt(" #n ")" ::: "memory")
; #define PG8_WAIT_L(n) asm volatile("s_waitcnt lgkmcnt(" #n ")" ::: "memory")
; #define PG8_BAR __builtin_amdgcn_s_barrier()
; #define PG8_SCHED __builtin_amdgcn_sched_barrier(0)
; template <class Epi, bool ALIGN_EPI, int K, int LDA, int LDB>
; __device__ __forceinline__ void gemm_phase(LAS unsigned char* lds, const int wid, const Gemm g, const StaticOrder& S, const Epi& E) {
;     ...
;             PG8_WAIT_V(8); PG8_WAIT_L(0); PG8_BAR; PG8_MMA(1, 0, At, B0); PG8_MMA(1, 1, At, B1); PG8_BAR; PG8_SCHED;
;             PG8_LDB(B0, 1, 0); PG8_LDB(B1, 1, 1); PG8_SCHED; PG8_LDA(At, 1, 0); PG8_STAGE(PG8_SA(0, 1), a2 + hA, voffA);
;             PG8_WAIT_V(8); PG8_WAIT_L(0); PG8_BAR; PG8_MMA(0, 0, At, B0); PG8_MMA(0, 1, At, B1); PG8_BAR; PG8_SCHED;
	s_setprio 1
	s_waitcnt lgkmcnt(0)
	v_mfma_f32_16x16x32_bf16 v[150:153], v[0:3], v[60:63], 0
	v_mfma_f32_16x16x32_bf16 v[158:161], v[0:3], v[104:107], 0
	v_mfma_f32_16x16x32_bf16 v[166:169], v[0:3], v[112:115], 0
	v_mfma_f32_16x16x32_bf16 v[0:3], v[0:3], v[120:123], 0
	v_mfma_f32_16x16x32_bf16 v[150:153], v[4:7], v[100:103], v[150:153]
	v_mfma_f32_16x16x32_bf16 v[158:161], v[4:7], v[108:111], v[158:161]
	v_mfma_f32_16x16x32_bf16 v[166:169], v[4:7], v[116:119], v[166:169]
	v_mfma_f32_16x16x32_bf16 v[0:3], v[4:7], v[124:127], v[0:3]
	v_mfma_f32_16x16x32_bf16 v[4:7], v[8:11], v[120:123], 0
	v_mfma_f32_16x16x32_bf16 v[154:157], v[8:11], v[60:63], 0
	v_mfma_f32_16x16x32_bf16 v[162:165], v[8:11], v[104:107], 0
	v_mfma_f32_16x16x32_bf16 v[170:173], v[8:11], v[112:115], 0
	v_mfma_f32_16x16x32_bf16 v[4:7], v[12:15], v[124:127], v[4:7]
	v_mfma_f32_16x16x32_bf16 v[154:157], v[12:15], v[100:103], v[154:157]
	v_mfma_f32_16x16x32_bf16 v[162:165], v[12:15], v[108:111], v[162:165]
	v_mfma_f32_16x16x32_bf16 v[170:173], v[12:15], v[116:119], v[170:173]
	v_mfma_f32_16x16x32_bf16 v[8:11], v[16:19], v[60:63], 0
	v_mfma_f32_16x16x32_bf16 v[12:15], v[24:27], v[60:63], 0
	v_mfma_f32_16x16x32_bf16 v[8:11], v[20:23], v[100:103], v[8:11]
	v_mfma_f32_16x16x32_bf16 v[12:15], v[28:31], v[100:103], v[12:15]
	v_mfma_f32_16x16x32_bf16 v[60:63], v[16:19], v[104:107], 0
	v_mfma_f32_16x16x32_bf16 v[100:103], v[24:27], v[104:107], 0
	v_mfma_f32_16x16x32_bf16 v[104:107], v[16:19], v[112:115], 0
	v_mfma_f32_16x16x32_bf16 v[16:19], v[16:19], v[120:123], 0
	v_mfma_f32_16x16x32_bf16 v[60:63], v[20:23], v[108:111], v[60:63]
	v_mfma_f32_16x16x32_bf16 v[100:103], v[28:31], v[108:111], v[100:103]
	v_mfma_f32_16x16x32_bf16 v[104:107], v[20:23], v[116:119], v[104:107]
	v_mfma_f32_16x16x32_bf16 v[108:111], v[24:27], v[112:115], 0
	v_mfma_f32_16x16x32_bf16 v[16:19], v[20:23], v[124:127], v[16:19]
	v_mfma_f32_16x16x32_bf16 v[20:23], v[24:27], v[120:123], 0
	v_mfma_f32_16x16x32_bf16 v[108:111], v[28:31], v[116:119], v[108:111]
	v_mfma_f32_16x16x32_bf16 v[20:23], v[28:31], v[124:127], v[20:23]
	s_setprio 0
	s_barrier
	s_add_i32 s71, 0, 0x18000
	s_add_i32 s74, 0, 0x1c000
	v_add_u32_e32 v142, s71, v143
	v_add_u32_e32 v144, s74, v143
	ds_read_b128 v[24:27], v142
	ds_read_b128 v[28:31], v142 offset:1024
	ds_read_b128 v[112:115], v142 offset:2048
	ds_read_b128 v[116:119], v142 offset:3072
	ds_read_b128 v[120:123], v144
	ds_read_b128 v[124:127], v144 offset:1024
	ds_read_b128 v[174:177], v144 offset:2048
	ds_read_b128 v[178:181], v144 offset:3072
	s_add_u32 s72, s38, 0xa0100
	s_addc_u32 s73, s39, 0
	s_mov_b32 m0, s57
	v_lshl_add_u64 v[220:221], s[72:73], 0, v[128:129]
	ds_read_b128 v[182:185], v149 offset:32768
	ds_read_b128 v[186:189], v149 offset:33792
	ds_read_b128 v[190:193], v149 offset:34816
	ds_read_b128 v[194:197], v149 offset:35840
	ds_read_b128 v[198:201], v149 offset:36864
	ds_read_b128 v[202:205], v149 offset:37888
	ds_read_b128 v[206:209], v149 offset:38912
	ds_read_b128 v[210:213], v149 offset:39936
	global_load_lds_dwordx4 v[220:221], off
	v_lshl_add_u64 v[220:221], s[72:73], 0, v[132:133]
	s_mov_b32 m0, s58
	s_nop 0
	global_load_lds_dwordx4 v[220:221], off
	s_waitcnt vmcnt(8)
	s_waitcnt lgkmcnt(0)
	s_barrier
	s_setprio 1
	s_waitcnt lgkmcnt(0)
	v_mfma_f32_16x16x32_bf16 v[64:67], v[24:27], v[182:185], v[64:67]
	v_mfma_f32_16x16x32_bf16 v[68:71], v[112:115], v[182:185], v[68:71]
	v_mfma_f32_16x16x32_bf16 v[72:75], v[24:27], v[190:193], v[72:75]
	v_mfma_f32_16x16x32_bf16 v[76:79], v[112:115], v[190:193], v[76:79]
	v_mfma_f32_16x16x32_bf16 v[80:83], v[24:27], v[198:201], v[80:83]
	v_mfma_f32_16x16x32_bf16 v[84:87], v[112:115], v[198:201], v[84:87]
	v_mfma_f32_16x16x32_bf16 v[88:91], v[24:27], v[206:209], v[88:91]
	v_mfma_f32_16x16x32_bf16 v[92:95], v[112:115], v[206:209], v[92:95]
	v_mfma_f32_16x16x32_bf16 v[64:67], v[28:31], v[186:189], v[64:67]
	v_mfma_f32_16x16x32_bf16 v[68:71], v[116:119], v[186:189], v[68:71]
	v_mfma_f32_16x16x32_bf16 v[72:75], v[28:31], v[194:197], v[72:75]
	v_mfma_f32_16x16x32_bf16 v[76:79], v[116:119], v[194:197], v[76:79]
	v_mfma_f32_16x16x32_bf16 v[80:83], v[28:31], v[202:205], v[80:83]
	v_mfma_f32_16x16x32_bf16 v[84:87], v[116:119], v[202:205], v[84:87]
	v_mfma_f32_16x16x32_bf16 v[88:91], v[28:31], v[210:213], v[88:91]
	v_mfma_f32_16x16x32_bf16 v[92:95], v[116:119], v[210:213], v[92:95]
	v_mfma_f32_16x16x32_bf16 v[96:99], v[120:123], v[182:185], v[96:99]
	v_mfma_f32_16x16x32_bf16 v[32:35], v[174:177], v[182:185], v[32:35]
	v_mfma_f32_16x16x32_bf16 v[36:39], v[120:123], v[190:193], v[36:39]
	v_mfma_f32_16x16x32_bf16 v[40:43], v[174:177], v[190:193], v[40:43]
	v_mfma_f32_16x16x32_bf16 v[44:47], v[120:123], v[198:201], v[44:47]
	v_mfma_f32_16x16x32_bf16 v[48:51], v[174:177], v[198:201], v[48:51]
	v_mfma_f32_16x16x32_bf16 v[52:55], v[120:123], v[206:209], v[52:55]
	v_mfma_f32_16x16x32_bf16 v[56:59], v[174:177], v[206:209], v[56:59]
	v_mfma_f32_16x16x32_bf16 v[96:99], v[124:127], v[186:189], v[96:99]
	v_mfma_f32_16x16x32_bf16 v[32:35], v[178:181], v[186:189], v[32:35]
	v_mfma_f32_16x16x32_bf16 v[36:39], v[124:127], v[194:197], v[36:39]
	v_mfma_f32_16x16x32_bf16 v[40:43], v[178:181], v[194:197], v[40:43]
	v_mfma_f32_16x16x32_bf16 v[44:47], v[124:127], v[202:205], v[44:47]
	v_mfma_f32_16x16x32_bf16 v[48:51], v[178:181], v[202:205], v[48:51]
	v_mfma_f32_16x16x32_bf16 v[52:55], v[124:127], v[210:213], v[52:55]
	v_mfma_f32_16x16x32_bf16 v[56:59], v[178:181], v[210:213], v[56:59]
	s_setprio 0
	s_barrier
; #define PG8_STAGE(bufoff, gbase, voff) do { _Pragma("unroll") for (int _i = 0; _i < 2; ++_i) \
;         __builtin_amdgcn_global_load_lds((const unsigned*)((const char*)(gbase) + (voff)[_i]), (LAS unsigned*)(lds + (bufoff) + ldsw + _i * 8192), 16, 0, 0); } while (0)
; #define PG8_LDA(dst, b, h) do { _Pragma("unroll") for (int m = 0; m < 4; ++m) _Pragma("unroll") for (int k = 0; k < 2; ++k) dst[m][k] = *(const LAS bf16x8*)(lds + PG8_SA(b, h) + aoff + m * 2048 + k * 1024); } while (0)
; #define PG8_LDB(dst, b, h) do { _Pragma("unroll") for (int n = 0; n < 2; ++n) _Pragma("unroll") for (int k = 0; k < 2; ++k) dst[n][k] = *(const LAS bf16x8*)(lds + PG8_SB(b, h) + boff + n * 2048 + k * 1024); } while (0)
; #define PG8_MMA(ai, bj, At, Bt) do { __builtin_amdgcn_s_setprio(1); _Pragma("unroll") for (int m = 0; m < 4; ++m) _Pragma("unroll") for (int n = 0; n < 2; ++n) _Pragma("unroll") for (int k = 0; k < 2; ++k) \
;         acc[ai][bj][m][n] = __builtin_amdgcn_mfma_f32_16x16x32_bf16(Bt[n][k], At[m][k], acc[ai][bj][m][n], 0, 0, 0); __builtin_amdgcn_s_setprio(0); } while (0)
; #define PG8_WAIT_V(n) asm volatile("s_waitcnt vmcnt(" #n ")" ::: "memory")
; #define PG8_WAIT_L(n) asm volatile("s_waitcnt lgkmcnt(" #n ")" ::: "memory")
; #define PG8_BAR __builtin_amdgcn_s_barrier()
; #define PG8_SCHED __builtin_amdgcn_sched_barrier(0)
; template <class Epi, bool ALIGN_EPI, int K, int LDA, int LDB>
; __device__ __forceinline__ void gemm_phase(LAS unsigned char* lds, const int wid, const Gemm g, const StaticOrder& S, const Epi& E) {
;     ...
;             PG8_LDB(B0, 0, 0); PG8_LDB(B1, 0, 1); PG8_SCHED; PG8_LDA(At, 0, 0); PG8_STAGE(PG8_SA(1, 1), a1 + hA, voffA);
;             PG8_WAIT_V(8); PG8_WAIT_L(0); PG8_BAR; PG8_MMA(0, 0, At, B0); PG8_MMA(0, 1, At, B1); PG8_BAR; PG8_SCHED;
;     ...
;             PG8_LDA(At, 1, 1); PG8_STAGE(PG8_SB(1, 0), b3, voffB); PG8_STAGE(PG8_SB(1, 1), b3 + hB, voffB); PG8_STAGE(PG8_SA(1, 0), a3, voffA);
;             PG8_WAIT_V(8); PG8_WAIT_L(0); PG8_BAR; PG8_MMA(1, 0, At, B0); PG8_MMA(1, 1, At, B1); PG8_BAR; PG8_SCHED;
	s_add_i32 s71, s71, s0
	s_add_i32 s69, s71, 0x2000
	v_lshl_add_u64 v[140:141], v[140:141], 0, s[26:27]
	s_mov_b32 m0, s71
	s_add_u32 s72, s40, 0x10180
	ds_read_b128 v[182:185], v149 offset:49152
	ds_read_b128 v[186:189], v149 offset:50176
	ds_read_b128 v[190:193], v149 offset:51200
	ds_read_b128 v[194:197], v149 offset:52224
	ds_read_b128 v[198:201], v149 offset:53248
	ds_read_b128 v[202:205], v149 offset:54272
	ds_read_b128 v[206:209], v149 offset:55296
	ds_read_b128 v[210:213], v149 offset:56320
	global_load_lds_dwordx4 v[140:141], off
	v_lshl_add_u64 v[140:141], v[214:215], 0, s[26:27]
	s_mov_b32 m0, s69
	s_addc_u32 s73, s41, 0
	s_add_i32 s40, s74, s0
	global_load_lds_dwordx4 v[140:141], off
	v_lshl_add_u64 v[140:141], s[72:73], 0, v[130:131]
	s_mov_b32 m0, s40
	s_add_i32 s41, s40, 0x2000
	global_load_lds_dwordx4 v[140:141], off
	v_lshl_add_u64 v[140:141], s[72:73], 0, v[134:135]
	s_mov_b32 m0, s41
	s_nop 0
	global_load_lds_dwordx4 v[140:141], off
	v_lshl_add_u64 v[140:141], v[216:217], 0, s[26:27]
	s_mov_b32 m0, s59
	s_nop 0
	global_load_lds_dwordx4 v[140:141], off
	v_lshl_add_u64 v[140:141], v[218:219], 0, s[26:27]
	s_mov_b32 m0, s60
	s_nop 0
	global_load_lds_dwordx4 v[140:141], off
	s_waitcnt vmcnt(8)
	s_waitcnt lgkmcnt(0)
	s_barrier
	s_setprio 1
	s_waitcnt lgkmcnt(0)
	v_mfma_f32_16x16x32_bf16 v[0:3], v[24:27], v[206:209], v[0:3]
	v_mfma_f32_16x16x32_bf16 v[4:7], v[112:115], v[206:209], v[4:7]
	v_mfma_f32_16x16x32_bf16 v[150:153], v[24:27], v[182:185], v[150:153]
	v_mfma_f32_16x16x32_bf16 v[154:157], v[112:115], v[182:185], v[154:157]
	v_mfma_f32_16x16x32_bf16 v[158:161], v[24:27], v[190:193], v[158:161]
	v_mfma_f32_16x16x32_bf16 v[162:165], v[112:115], v[190:193], v[162:165]
	v_mfma_f32_16x16x32_bf16 v[166:169], v[24:27], v[198:201], v[166:169]
	v_mfma_f32_16x16x32_bf16 v[170:173], v[112:115], v[198:201], v[170:173]
	v_mfma_f32_16x16x32_bf16 v[0:3], v[28:31], v[210:213], v[0:3]
	v_mfma_f32_16x16x32_bf16 v[4:7], v[116:119], v[210:213], v[4:7]
	v_mfma_f32_16x16x32_bf16 v[150:153], v[28:31], v[186:189], v[150:153]
	v_mfma_f32_16x16x32_bf16 v[154:157], v[116:119], v[186:189], v[154:157]
	v_mfma_f32_16x16x32_bf16 v[158:161], v[28:31], v[194:197], v[158:161]
	v_mfma_f32_16x16x32_bf16 v[162:165], v[116:119], v[194:197], v[162:165]
	v_mfma_f32_16x16x32_bf16 v[166:169], v[28:31], v[202:205], v[166:169]
	v_mfma_f32_16x16x32_bf16 v[170:173], v[116:119], v[202:205], v[170:173]
	v_mfma_f32_16x16x32_bf16 v[8:11], v[120:123], v[182:185], v[8:11]
	v_mfma_f32_16x16x32_bf16 v[12:15], v[174:177], v[182:185], v[12:15]
	v_mfma_f32_16x16x32_bf16 v[24:27], v[120:123], v[190:193], v[60:63]
	v_mfma_f32_16x16x32_bf16 v[28:31], v[174:177], v[190:193], v[100:103]
	v_mfma_f32_16x16x32_bf16 v[60:63], v[120:123], v[198:201], v[104:107]
	v_mfma_f32_16x16x32_bf16 v[100:103], v[174:177], v[198:201], v[108:111]
	v_mfma_f32_16x16x32_bf16 v[16:19], v[120:123], v[206:209], v[16:19]
	v_mfma_f32_16x16x32_bf16 v[20:23], v[174:177], v[206:209], v[20:23]
	v_mfma_f32_16x16x32_bf16 v[8:11], v[124:127], v[186:189], v[8:11]
	v_mfma_f32_16x16x32_bf16 v[12:15], v[178:181], v[186:189], v[12:15]
	v_mfma_f32_16x16x32_bf16 v[24:27], v[124:127], v[194:197], v[24:27]
	v_mfma_f32_16x16x32_bf16 v[28:31], v[178:181], v[194:197], v[28:31]
	v_mfma_f32_16x16x32_bf16 v[60:63], v[124:127], v[202:205], v[60:63]
	v_mfma_f32_16x16x32_bf16 v[100:103], v[178:181], v[202:205], v[100:103]
	v_mfma_f32_16x16x32_bf16 v[16:19], v[124:127], v[210:213], v[16:19]
	v_mfma_f32_16x16x32_bf16 v[20:23], v[178:181], v[210:213], v[20:23]
	s_setprio 0
	s_barrier
	ds_read_b128 v[104:107], v145
	ds_read_b128 v[108:111], v145 offset:1024
	ds_read_b128 v[112:115], v145 offset:2048
	ds_read_b128 v[116:119], v145 offset:3072
	ds_read_b128 v[120:123], v147
	ds_read_b128 v[124:127], v147 offset:1024
	ds_read_b128 v[174:177], v147 offset:2048
	ds_read_b128 v[178:181], v147 offset:3072
	s_add_u32 s38, s38, 0xa0180
	s_addc_u32 s39, s39, 0
	s_mov_b32 m0, s70
	v_lshl_add_u64 v[140:141], s[38:39], 0, v[128:129]
	ds_read_b128 v[182:185], v149
	ds_read_b128 v[186:189], v149 offset:1024
	ds_read_b128 v[190:193], v149 offset:2048
	ds_read_b128 v[194:197], v149 offset:3072
	ds_read_b128 v[198:201], v149 offset:4096
	ds_read_b128 v[202:205], v149 offset:5120
	ds_read_b128 v[206:209], v149 offset:6144
	ds_read_b128 v[210:213], v149 offset:7168
	global_load_lds_dwordx4 v[140:141], off
	v_lshl_add_u64 v[140:141], s[38:39], 0, v[132:133]
	s_mov_b32 m0, s31
	s_nop 0
	global_load_lds_dwordx4 v[140:141], off
	s_waitcnt vmcnt(8)
	s_waitcnt lgkmcnt(0)
	s_barrier
; #define PG8_STAGE(bufoff, gbase, voff) do { _Pragma("unroll") for (int _i = 0; _i < 2; ++_i) \
;         __builtin_amdgcn_global_load_lds((const unsigned*)((const char*)(gbase) + (voff)[_i]), (LAS unsigned*)(lds + (bufoff) + ldsw + _i * 8192), 16, 0, 0); } while (0)
; #define PG8_LDA(dst, b, h) do { _Pragma("unroll") for (int m = 0; m < 4; ++m) _Pragma("unroll") for (int k = 0; k < 2; ++k) dst[m][k] = *(const LAS bf16x8*)(lds + PG8_SA(b, h) + aoff + m * 2048 + k * 1024); } while (0)
; #define PG8_MMA(ai, bj, At, Bt) do { __builtin_amdgcn_s_setprio(1); _Pragma("unroll") for (int m = 0; m < 4; ++m) _Pragma("unroll") for (int n = 0; n < 2; ++n) _Pragma("unroll") for (int k = 0; k < 2; ++k) \
;         acc[ai][bj][m][n] = __builtin_amdgcn_mfma_f32_16x16x32_bf16(Bt[n][k], At[m][k], acc[ai][bj][m][n], 0, 0, 0); __builtin_amdgcn_s_setprio(0); } while (0)
; #define PG8_WAIT_V(n) asm volatile("s_waitcnt vmcnt(" #n ")" ::: "memory")
; #define PG8_WAIT_L(n) asm volatile("s_waitcnt lgkmcnt(" #n ")" ::: "memory")
; #define PG8_BAR __builtin_amdgcn_s_barrier()
; #define PG8_SCHED __builtin_amdgcn_sched_barrier(0)
; template <class Epi, bool ALIGN_EPI, int K, int LDA, int LDB>
; __device__ __forceinline__ void gemm_phase(LAS unsigned char* lds, const int wid, const Gemm g, const StaticOrder& S, const Epi& E) {
;     ...
;         const char* nA = has_next ? (const char*)g.A + (size_t)nxt.pm * tA : cA; const char* nB = has_next ? (const char*)g.Bt + (size_t)nxt.pn * tB : cB;
;         for (int t = 0; t < nt; t += 2) {
;             const bool last = (t == nt - 2);
;             const char* a1 = cA + (size_t)(t + 1) * kstep;
;             const char* a2 = last ? nA : cA + (size_t)(t + 2) * kstep; const char* b2 = last ? nB : cB + (size_t)(t + 2) * kstep;
;     ...
;             PG8_WAIT_V(8); PG8_WAIT_L(0); PG8_BAR; PG8_MMA(0, 0, At, B0); PG8_MMA(0, 1, At, B1); PG8_BAR; PG8_SCHED;
;             PG8_LDA(At, 0, 1); PG8_STAGE(PG8_SB(0, 0), b2, voffB); PG8_STAGE(PG8_SB(0, 1), b2 + hB, voffB); PG8_STAGE(PG8_SA(0, 0), a2, voffA);
;             PG8_WAIT_V(8); PG8_WAIT_L(0); PG8_BAR; PG8_MMA(1, 0, At, B0); PG8_MMA(1, 1, At, B1); PG8_BAR; PG8_SCHED;
	s_setprio 1
	s_waitcnt lgkmcnt(0)
	v_mfma_f32_16x16x32_bf16 v[64:67], v[104:107], v[182:185], v[64:67]
	v_mfma_f32_16x16x32_bf16 v[68:71], v[112:115], v[182:185], v[68:71]
	v_mfma_f32_16x16x32_bf16 v[72:75], v[104:107], v[190:193], v[72:75]
	v_mfma_f32_16x16x32_bf16 v[76:79], v[112:115], v[190:193], v[76:79]
	v_mfma_f32_16x16x32_bf16 v[80:83], v[104:107], v[198:201], v[80:83]
	v_mfma_f32_16x16x32_bf16 v[84:87], v[112:115], v[198:201], v[84:87]
	v_mfma_f32_16x16x32_bf16 v[88:91], v[104:107], v[206:209], v[88:91]
	v_mfma_f32_16x16x32_bf16 v[64:67], v[108:111], v[186:189], v[64:67]
	v_mfma_f32_16x16x32_bf16 v[68:71], v[116:119], v[186:189], v[68:71]
	v_mfma_f32_16x16x32_bf16 v[72:75], v[108:111], v[194:197], v[72:75]
	v_mfma_f32_16x16x32_bf16 v[76:79], v[116:119], v[194:197], v[76:79]
	v_mfma_f32_16x16x32_bf16 v[80:83], v[108:111], v[202:205], v[80:83]
	v_mfma_f32_16x16x32_bf16 v[84:87], v[116:119], v[202:205], v[84:87]
	v_mfma_f32_16x16x32_bf16 v[214:217], v[108:111], v[210:213], v[88:91]
	v_mfma_f32_16x16x32_bf16 v[88:91], v[112:115], v[206:209], v[92:95]
	v_mfma_f32_16x16x32_bf16 v[218:221], v[116:119], v[210:213], v[88:91]
	v_mfma_f32_16x16x32_bf16 v[88:91], v[120:123], v[182:185], v[96:99]
	v_mfma_f32_16x16x32_bf16 v[32:35], v[174:177], v[182:185], v[32:35]
	v_mfma_f32_16x16x32_bf16 v[36:39], v[120:123], v[190:193], v[36:39]
	v_mfma_f32_16x16x32_bf16 v[40:43], v[174:177], v[190:193], v[40:43]
	v_mfma_f32_16x16x32_bf16 v[44:47], v[120:123], v[198:201], v[44:47]
	v_mfma_f32_16x16x32_bf16 v[48:51], v[174:177], v[198:201], v[48:51]
	v_mfma_f32_16x16x32_bf16 v[52:55], v[120:123], v[206:209], v[52:55]
	v_mfma_f32_16x16x32_bf16 v[56:59], v[174:177], v[206:209], v[56:59]
	v_mfma_f32_16x16x32_bf16 v[96:99], v[124:127], v[186:189], v[88:91]
	v_mfma_f32_16x16x32_bf16 v[32:35], v[178:181], v[186:189], v[32:35]
	v_mfma_f32_16x16x32_bf16 v[36:39], v[124:127], v[194:197], v[36:39]
	v_mfma_f32_16x16x32_bf16 v[40:43], v[178:181], v[194:197], v[40:43]
	v_mfma_f32_16x16x32_bf16 v[44:47], v[124:127], v[202:205], v[44:47]
	v_mfma_f32_16x16x32_bf16 v[48:51], v[178:181], v[202:205], v[48:51]
	v_mfma_f32_16x16x32_bf16 v[52:55], v[124:127], v[210:213], v[52:55]
	v_mfma_f32_16x16x32_bf16 v[56:59], v[178:181], v[210:213], v[56:59]
	s_setprio 0
	s_barrier
	s_mov_b32 m0, s68
	v_lshl_add_u64 v[140:141], s[8:9], 0, v[130:131]
	s_add_u32 s38, s8, 0x10000
	ds_read_b128 v[88:91], v149 offset:16384
	ds_read_b128 v[92:95], v149 offset:17408
	ds_read_b128 v[182:185], v149 offset:18432
	ds_read_b128 v[186:189], v149 offset:19456
	ds_read_b128 v[190:193], v149 offset:20480
	ds_read_b128 v[194:197], v149 offset:21504
	ds_read_b128 v[198:201], v149 offset:22528
	ds_read_b128 v[202:205], v149 offset:23552
	global_load_lds_dwordx4 v[140:141], off
	v_lshl_add_u64 v[250:251], s[8:9], 0, v[134:135]
	s_mov_b32 m0, s65
	s_addc_u32 s39, s9, 0
	global_load_lds_dwordx4 v[250:251], off
	v_lshl_add_u64 v[206:207], s[38:39], 0, v[130:131]
	s_mov_b32 m0, s66
	v_lshl_add_u64 v[252:253], s[34:35], 0, v[128:129]
	global_load_lds_dwordx4 v[206:207], off
	v_lshl_add_u64 v[206:207], s[38:39], 0, v[134:135]
	s_mov_b32 m0, s67
	v_lshl_add_u64 v[136:137], s[34:35], 0, v[132:133]
	global_load_lds_dwordx4 v[206:207], off
	s_mov_b32 m0, s55
	s_nop 0
	global_load_lds_dwordx4 v[252:253], off
	s_mov_b32 m0, s56
	s_nop 0
	global_load_lds_dwordx4 v[136:137], off
	s_waitcnt vmcnt(8)
	s_waitcnt lgkmcnt(0)
	s_barrier
	s_setprio 1
	s_waitcnt lgkmcnt(0)
	v_mfma_f32_16x16x32_bf16 v[0:3], v[104:107], v[198:201], v[0:3]
	v_mfma_f32_16x16x32_bf16 v[4:7], v[112:115], v[198:201], v[4:7]
	v_mfma_f32_16x16x32_bf16 v[150:153], v[104:107], v[88:91], v[150:153]
	v_mfma_f32_16x16x32_bf16 v[154:157], v[112:115], v[88:91], v[154:157]
	v_mfma_f32_16x16x32_bf16 v[158:161], v[104:107], v[182:185], v[158:161]
	v_mfma_f32_16x16x32_bf16 v[162:165], v[112:115], v[182:185], v[162:165]
	v_mfma_f32_16x16x32_bf16 v[166:169], v[104:107], v[190:193], v[166:169]
	v_mfma_f32_16x16x32_bf16 v[170:173], v[112:115], v[190:193], v[170:173]
	v_mfma_f32_16x16x32_bf16 v[0:3], v[108:111], v[202:205], v[0:3]
	v_mfma_f32_16x16x32_bf16 v[4:7], v[116:119], v[202:205], v[4:7]
	v_mfma_f32_16x16x32_bf16 v[150:153], v[108:111], v[92:95], v[150:153]
	v_mfma_f32_16x16x32_bf16 v[154:157], v[116:119], v[92:95], v[154:157]
	v_mfma_f32_16x16x32_bf16 v[158:161], v[108:111], v[186:189], v[158:161]
	v_mfma_f32_16x16x32_bf16 v[162:165], v[116:119], v[186:189], v[162:165]
	v_mfma_f32_16x16x32_bf16 v[166:169], v[108:111], v[194:197], v[166:169]
	v_mfma_f32_16x16x32_bf16 v[170:173], v[116:119], v[194:197], v[170:173]
	v_mfma_f32_16x16x32_bf16 v[8:11], v[120:123], v[88:91], v[8:11]
	v_mfma_f32_16x16x32_bf16 v[206:209], v[124:127], v[92:95], v[8:11]
	v_mfma_f32_16x16x32_bf16 v[8:11], v[174:177], v[88:91], v[12:15]
	v_mfma_f32_16x16x32_bf16 v[210:213], v[178:181], v[92:95], v[8:11]
	v_mfma_f32_16x16x32_bf16 v[8:11], v[120:123], v[182:185], v[24:27]
	v_mfma_f32_16x16x32_bf16 v[222:225], v[124:127], v[186:189], v[8:11]
	v_mfma_f32_16x16x32_bf16 v[8:11], v[174:177], v[182:185], v[28:31]
	v_mfma_f32_16x16x32_bf16 v[182:185], v[178:181], v[186:189], v[8:11]
	v_mfma_f32_16x16x32_bf16 v[8:11], v[120:123], v[190:193], v[60:63]
	v_mfma_f32_16x16x32_bf16 v[186:189], v[124:127], v[194:197], v[8:11]
	v_mfma_f32_16x16x32_bf16 v[8:11], v[174:177], v[190:193], v[100:103]
	v_mfma_f32_16x16x32_bf16 v[190:193], v[178:181], v[194:197], v[8:11]
	v_mfma_f32_16x16x32_bf16 v[8:11], v[120:123], v[198:201], v[16:19]
	v_mfma_f32_16x16x32_bf16 v[194:197], v[124:127], v[202:205], v[8:11]
	v_mfma_f32_16x16x32_bf16 v[8:11], v[174:177], v[198:201], v[20:23]
	v_mfma_f32_16x16x32_bf16 v[174:177], v[178:181], v[202:205], v[8:11]
	s_setprio 0
	s_barrier
; #define PG8_STAGE(bufoff, gbase, voff) do { _Pragma("unroll") for (int _i = 0; _i < 2; ++_i) \
;         __builtin_amdgcn_global_load_lds((const unsigned*)((const char*)(gbase) + (voff)[_i]), (LAS unsigned*)(lds + (bufoff) + ldsw + _i * 8192), 16, 0, 0); } while (0)
; #define PG8_LDA(dst, b, h) do { _Pragma("unroll") for (int m = 0; m < 4; ++m) _Pragma("unroll") for (int k = 0; k < 2; ++k) dst[m][k] = *(const LAS bf16x8*)(lds + PG8_SA(b, h) + aoff + m * 2048 + k * 1024); } while (0)
; #define PG8_LDB(dst, b, h) do { _Pragma("unroll") for (int n = 0; n < 2; ++n) _Pragma("unroll") for (int k = 0; k < 2; ++k) dst[n][k] = *(const LAS bf16x8*)(lds + PG8_SB(b, h) + boff + n * 2048 + k * 1024); } while (0)
; #define PG8_MMA(ai, bj, At, Bt) do { __builtin_amdgcn_s_setprio(1); _Pragma("unroll") for (int m = 0; m < 4; ++m) _Pragma("unroll") for (int n = 0; n < 2; ++n) _Pragma("unroll") for (int k = 0; k < 2; ++k) \
;         acc[ai][bj][m][n] = __builtin_amdgcn_mfma_f32_16x16x32_bf16(Bt[n][k], At[m][k], acc[ai][bj][m][n], 0, 0, 0); __builtin_amdgcn_s_setprio(0); } while (0)
; #define PG8_WAIT_V(n) asm volatile("s_waitcnt vmcnt(" #n ")" ::: "memory")
; #define PG8_WAIT_L(n) asm volatile("s_waitcnt lgkmcnt(" #n ")" ::: "memory")
; #define PG8_BAR __builtin_amdgcn_s_barrier()
; #define PG8_SCHED __builtin_amdgcn_sched_barrier(0)
; template <class Epi, bool ALIGN_EPI, int K, int LDA, int LDB>
; __device__ __forceinline__ void gemm_phase(LAS unsigned char* lds, const int wid, const Gemm g, const StaticOrder& S, const Epi& E) {
;     ...
;             PG8_LDB(B0, 1, 0); PG8_LDB(B1, 1, 1); PG8_SCHED; PG8_LDA(At, 1, 0); PG8_STAGE(PG8_SA(0, 1), a2 + hA, voffA);
;             PG8_WAIT_V(8); PG8_WAIT_L(0); PG8_BAR; PG8_MMA(0, 0, At, B0); PG8_MMA(0, 1, At, B1); PG8_BAR; PG8_SCHED;
;             PG8_LDA(At, 1, 1); PG8_STAGE(PG8_SB(1, 0), b3, voffB); PG8_STAGE(PG8_SB(1, 1), b3 + hB, voffB); PG8_STAGE(PG8_SA(1, 0), a3, voffA);
;             PG8_WAIT_V(8); PG8_WAIT_L(0); PG8_BAR; PG8_MMA(1, 0, At, B0); PG8_MMA(1, 1, At, B1); PG8_BAR; PG8_SCHED;
;         }
;         if constexpr (ALIGN_EPI) { if (wr == 0) PG8_BAR; }
	s_nop 4
	ds_read_b128 v[8:11], v142
	ds_read_b128 v[12:15], v142 offset:1024
	ds_read_b128 v[16:19], v142 offset:2048
	ds_read_b128 v[20:23], v142 offset:3072
	ds_read_b128 v[178:181], v144
	ds_read_b128 v[198:201], v144 offset:1024
	ds_read_b128 v[202:205], v144 offset:2048
	ds_read_b128 v[226:229], v144 offset:3072
	s_add_u32 s38, s34, 0xa0000
	s_addc_u32 s39, s35, 0
	s_mov_b32 m0, s57
	v_lshl_add_u64 v[88:89], s[38:39], 0, v[128:129]
	ds_read_b128 v[24:27], v149 offset:32768
	ds_read_b128 v[28:31], v149 offset:33792
	ds_read_b128 v[60:63], v149 offset:34816
	ds_read_b128 v[230:233], v149 offset:35840
	ds_read_b128 v[234:237], v149 offset:36864
	ds_read_b128 v[238:241], v149 offset:37888
	ds_read_b128 v[242:245], v149 offset:38912
	ds_read_b128 v[246:249], v149 offset:39936
	global_load_lds_dwordx4 v[88:89], off
	v_lshl_add_u64 v[88:89], s[38:39], 0, v[132:133]
	s_mov_b32 m0, s58
	s_nop 0
	global_load_lds_dwordx4 v[88:89], off
	s_waitcnt vmcnt(8)
	s_waitcnt lgkmcnt(0)
	s_barrier
	s_setprio 1
	s_waitcnt lgkmcnt(0)
	v_mfma_f32_16x16x32_bf16 v[64:67], v[8:11], v[24:27], v[64:67]
	v_mfma_f32_16x16x32_bf16 v[112:115], v[12:15], v[28:31], v[64:67]
	v_mfma_f32_16x16x32_bf16 v[64:67], v[16:19], v[24:27], v[68:71]
	v_mfma_f32_16x16x32_bf16 v[116:119], v[20:23], v[28:31], v[64:67]
	v_mfma_f32_16x16x32_bf16 v[64:67], v[8:11], v[60:63], v[72:75]
	v_mfma_f32_16x16x32_bf16 v[108:111], v[12:15], v[230:233], v[64:67]
	v_mfma_f32_16x16x32_bf16 v[64:67], v[16:19], v[60:63], v[76:79]
	v_mfma_f32_16x16x32_bf16 v[104:107], v[20:23], v[230:233], v[64:67]
	v_mfma_f32_16x16x32_bf16 v[64:67], v[8:11], v[234:237], v[80:83]
	v_mfma_f32_16x16x32_bf16 v[92:95], v[12:15], v[238:241], v[64:67]
	v_mfma_f32_16x16x32_bf16 v[64:67], v[16:19], v[234:237], v[84:87]
	v_mfma_f32_16x16x32_bf16 v[88:91], v[20:23], v[238:241], v[64:67]
	v_mfma_f32_16x16x32_bf16 v[64:67], v[8:11], v[242:245], v[214:217]
	v_mfma_f32_16x16x32_bf16 v[76:79], v[12:15], v[246:249], v[64:67]
	v_mfma_f32_16x16x32_bf16 v[64:67], v[16:19], v[242:245], v[218:221]
	v_mfma_f32_16x16x32_bf16 v[72:75], v[20:23], v[246:249], v[64:67]
	v_mfma_f32_16x16x32_bf16 v[64:67], v[178:181], v[24:27], v[96:99]
	v_mfma_f32_16x16x32_bf16 v[24:27], v[202:205], v[24:27], v[32:35]
	v_mfma_f32_16x16x32_bf16 v[124:127], v[226:229], v[28:31], v[24:27]
	v_mfma_f32_16x16x32_bf16 v[24:27], v[178:181], v[60:63], v[36:39]
	v_mfma_f32_16x16x32_bf16 v[100:103], v[198:201], v[230:233], v[24:27]
	v_mfma_f32_16x16x32_bf16 v[24:27], v[202:205], v[60:63], v[40:43]
	v_mfma_f32_16x16x32_bf16 v[96:99], v[226:229], v[230:233], v[24:27]
	v_mfma_f32_16x16x32_bf16 v[24:27], v[178:181], v[234:237], v[44:47]
	v_mfma_f32_16x16x32_bf16 v[84:87], v[198:201], v[238:241], v[24:27]
	v_mfma_f32_16x16x32_bf16 v[24:27], v[202:205], v[234:237], v[48:51]
	v_mfma_f32_16x16x32_bf16 v[80:83], v[226:229], v[238:241], v[24:27]
	v_mfma_f32_16x16x32_bf16 v[24:27], v[178:181], v[242:245], v[52:55]
	v_mfma_f32_16x16x32_bf16 v[68:71], v[198:201], v[246:249], v[24:27]
	v_mfma_f32_16x16x32_bf16 v[24:27], v[202:205], v[242:245], v[56:59]
	v_mfma_f32_16x16x32_bf16 v[120:123], v[198:201], v[28:31], v[64:67]
	v_mfma_f32_16x16x32_bf16 v[60:63], v[226:229], v[246:249], v[24:27]
	s_setprio 0
	s_barrier
	s_mov_b32 m0, s71
	s_nop 2
	v_lshl_add_u64 v[24:25], v[140:141], 0, s[14:15]
	s_add_u32 s8, s8, 0x10080
	ds_read_b128 v[32:35], v149 offset:49152
	ds_read_b128 v[36:39], v149 offset:50176
	ds_read_b128 v[214:217], v149 offset:51200
	ds_read_b128 v[218:221], v149 offset:52224
	ds_read_b128 v[230:233], v149 offset:53248
	ds_read_b128 v[234:237], v149 offset:54272
	ds_read_b128 v[238:241], v149 offset:55296
	ds_read_b128 v[242:245], v149 offset:56320
	global_load_lds_dwordx4 v[24:25], off
	v_lshl_add_u64 v[24:25], v[250:251], 0, s[14:15]
	s_mov_b32 m0, s69
	s_addc_u32 s9, s9, 0
	global_load_lds_dwordx4 v[24:25], off
	v_lshl_add_u64 v[24:25], s[8:9], 0, v[130:131]
	s_mov_b32 m0, s40
	s_nop 0
	global_load_lds_dwordx4 v[24:25], off
	v_lshl_add_u64 v[24:25], s[8:9], 0, v[134:135]
	s_mov_b32 m0, s41
	s_nop 0
	global_load_lds_dwordx4 v[24:25], off
	v_lshl_add_u64 v[24:25], v[252:253], 0, s[14:15]
	s_mov_b32 m0, s59
	s_nop 0
	global_load_lds_dwordx4 v[24:25], off
	v_lshl_add_u64 v[24:25], v[136:137], 0, s[14:15]
	s_mov_b32 m0, s60
	s_nop 0
	global_load_lds_dwordx4 v[24:25], off
	s_waitcnt vmcnt(8)
	s_waitcnt lgkmcnt(0)
	s_barrier
	s_setprio 1
	s_waitcnt lgkmcnt(0)
	v_mfma_f32_16x16x32_bf16 v[24:27], v[8:11], v[32:35], v[150:153]
	v_mfma_f32_16x16x32_bf16 v[64:67], v[12:15], v[36:39], v[24:27]
	v_mfma_f32_16x16x32_bf16 v[24:27], v[16:19], v[32:35], v[154:157]
	v_mfma_f32_16x16x32_bf16 v[56:59], v[20:23], v[36:39], v[24:27]
	v_mfma_f32_16x16x32_bf16 v[24:27], v[8:11], v[214:217], v[158:161]
	v_mfma_f32_16x16x32_bf16 v[44:47], v[12:15], v[218:221], v[24:27]
	v_mfma_f32_16x16x32_bf16 v[24:27], v[16:19], v[214:217], v[162:165]
	v_mfma_f32_16x16x32_bf16 v[40:43], v[20:23], v[218:221], v[24:27]
	v_mfma_f32_16x16x32_bf16 v[24:27], v[8:11], v[230:233], v[166:169]
	v_mfma_f32_16x16x32_bf16 v[0:3], v[8:11], v[238:241], v[0:3]
	v_mfma_f32_16x16x32_bf16 v[28:31], v[12:15], v[234:237], v[24:27]
	v_mfma_f32_16x16x32_bf16 v[24:27], v[16:19], v[230:233], v[170:173]
	v_mfma_f32_16x16x32_bf16 v[12:15], v[12:15], v[242:245], v[0:3]
	v_mfma_f32_16x16x32_bf16 v[0:3], v[16:19], v[238:241], v[4:7]
	v_mfma_f32_16x16x32_bf16 v[24:27], v[20:23], v[234:237], v[24:27]
	v_mfma_f32_16x16x32_bf16 v[8:11], v[20:23], v[242:245], v[0:3]
	v_mfma_f32_16x16x32_bf16 v[0:3], v[178:181], v[32:35], v[206:209]
	v_mfma_f32_16x16x32_bf16 v[52:55], v[198:201], v[36:39], v[0:3]
	v_mfma_f32_16x16x32_bf16 v[0:3], v[202:205], v[32:35], v[210:213]
	v_mfma_f32_16x16x32_bf16 v[48:51], v[226:229], v[36:39], v[0:3]
	v_mfma_f32_16x16x32_bf16 v[0:3], v[178:181], v[214:217], v[222:225]
	v_mfma_f32_16x16x32_bf16 v[36:39], v[198:201], v[218:221], v[0:3]
	v_mfma_f32_16x16x32_bf16 v[0:3], v[202:205], v[214:217], v[182:185]
	v_mfma_f32_16x16x32_bf16 v[32:35], v[226:229], v[218:221], v[0:3]
	v_mfma_f32_16x16x32_bf16 v[0:3], v[178:181], v[230:233], v[186:189]
	v_mfma_f32_16x16x32_bf16 v[20:23], v[198:201], v[234:237], v[0:3]
	v_mfma_f32_16x16x32_bf16 v[0:3], v[202:205], v[230:233], v[190:193]
	v_mfma_f32_16x16x32_bf16 v[16:19], v[226:229], v[234:237], v[0:3]
	v_mfma_f32_16x16x32_bf16 v[0:3], v[178:181], v[238:241], v[194:197]
	v_mfma_f32_16x16x32_bf16 v[4:7], v[198:201], v[242:245], v[0:3]
	v_mfma_f32_16x16x32_bf16 v[0:3], v[202:205], v[238:241], v[174:177]
	v_mfma_f32_16x16x32_bf16 v[0:3], v[226:229], v[242:245], v[0:3]
	s_setprio 0
	s_barrier
	s_andn2_b64 vcc, exec, s[16:17]
	s_cbranch_vccnz .LBB0_691
	s_barrier

; #define PG8_STAGE(bufoff, gbase, voff) do { _Pragma("unroll") for (int _i = 0; _i < 2; ++_i) \
;         __builtin_amdgcn_global_load_lds((const unsigned*)((const char*)(gbase) + (voff)[_i]), (LAS unsigned*)(lds + (bufoff) + ldsw + _i * 8192), 16, 0, 0); } while (0)
; #define PG8_LDA(dst, b, h) do { _Pragma("unroll") for (int m = 0; m < 4; ++m) _Pragma("unroll") for (int k = 0; k < 2; ++k) dst[m][k] = *(const LAS bf16x8*)(lds + PG8_SA(b, h) + aoff + m * 2048 + k * 1024); } while (0)
; #define PG8_LDB(dst, b, h) do { _Pragma("unroll") for (int n = 0; n < 2; ++n) _Pragma("unroll") for (int k = 0; k < 2; ++k) dst[n][k] = *(const LAS bf16x8*)(lds + PG8_SB(b, h) + boff + n * 2048 + k * 1024); } while (0)
; #define PG8_WAIT_V(n) asm volatile("s_waitcnt vmcnt(" #n ")" ::: "memory")
; #define PG8_WAIT_L(n) asm volatile("s_waitcnt lgkmcnt(" #n ")" ::: "memory")
; template <class Epi, bool ALIGN_EPI, int K, int LDA, int LDB>
; __device__ __forceinline__ void gemm_phase(LAS unsigned char* lds, const int wid, const Gemm g, const StaticOrder& S, const Epi& E) {
;     ...
;         const bool has_next = S.next(ui + 1, nxt);
;         const char* nA = has_next ? (const char*)g.A + (size_t)nxt.pm * tA : cA; const char* nB = has_next ? (const char*)g.Bt + (size_t)nxt.pn * tB : cB;
;         for (int t = 0; t < nt; t += 2) {
;             const bool last = (t == nt - 2);
;             const char* a1 = cA + (size_t)(t + 1) * kstep;
;             const char* a2 = last ? nA : cA + (size_t)(t + 2) * kstep; const char* b2 = last ? nB : cB + (size_t)(t + 2) * kstep;
;             const char* a3 = a2 + kstep; const char* b3 = b2 + kstep;
;             PG8_LDB(B0, 0, 0); PG8_LDB(B1, 0, 1); PG8_SCHED; PG8_LDA(At, 0, 0); PG8_STAGE(PG8_SA(1, 1), a1 + hA, voffA);
;             PG8_WAIT_V(8); PG8_WAIT_L(0); PG8_BAR; PG8_MMA(0, 0, At, B0); PG8_MMA(0, 1, At, B1); PG8_BAR; PG8_SCHED;
;             PG8_LDA(At, 0, 1); PG8_STAGE(PG8_SB(0, 0), b2, voffB); PG8_STAGE(PG8_SB(0, 1), b2 + hB, voffB); PG8_STAGE(PG8_SA(0, 0), a2, voffA);
;             PG8_WAIT_V(8); PG8_WAIT_L(0); PG8_BAR; PG8_MMA(1, 0, At, B0); PG8_MMA(1, 1, At, B1); PG8_BAR; PG8_SCHED;
;             PG8_LDB(B0, 1, 0); PG8_LDB(B1, 1, 1); PG8_SCHED; PG8_LDA(At, 1, 0); PG8_STAGE(PG8_SA(0, 1), a2 + hA, voffA);
;             PG8_WAIT_V(8); PG8_WAIT_L(0); PG8_BAR; PG8_MMA(0, 0, At, B0); PG8_MMA(0, 1, At, B1); PG8_BAR; PG8_SCHED;
.LBB0_703:
	ds_read_b128 v[0:3], v140
	ds_read_b128 v[4:7], v140 offset:1024
	ds_read_b128 v[8:11], v140 offset:2048
	ds_read_b128 v[12:15], v140 offset:3072
	ds_read_b128 v[16:19], v141
	ds_read_b128 v[20:23], v141 offset:1024
	ds_read_b128 v[24:27], v141 offset:2048
	ds_read_b128 v[28:31], v141 offset:3072
	s_ashr_i32 s25, s24, 31
	s_lshl_b64 s[26:27], s[24:25], 17
	s_add_u32 s26, s40, s26
	s_addc_u32 s27, s41, s27
	s_and_b64 s[28:29], s[4:5], exec
	s_cselect_b32 s39, s27, s31
	s_cselect_b32 s38, s26, s30
	s_ashr_i32 s23, s22, 31
	s_lshl_b64 s[28:29], s[22:23], 17
	s_add_u32 s28, s42, s28
	s_addc_u32 s29, s43, s29
	s_and_b64 s[36:37], s[4:5], exec
	s_cselect_b32 s37, s29, s35
	s_cselect_b32 s36, s28, s34
	s_add_u32 s68, s30, 0x10080
	s_addc_u32 s69, s31, 0
	s_mov_b32 m0, s58
	v_lshl_add_u64 v[64:65], s[68:69], 0, v[134:135]
	ds_read_b128 v[32:35], v142
	ds_read_b128 v[36:39], v142 offset:1024
	ds_read_b128 v[40:43], v142 offset:2048
	ds_read_b128 v[44:47], v142 offset:3072
	ds_read_b128 v[48:51], v142 offset:4096
	ds_read_b128 v[52:55], v142 offset:5120
	ds_read_b128 v[56:59], v142 offset:6144
	ds_read_b128 v[60:63], v142 offset:7168
	global_load_lds_dwordx4 v[64:65], off
	v_lshl_add_u64 v[64:65], s[68:69], 0, v[130:131]
	s_mov_b32 m0, s59
	s_nop 0
	global_load_lds_dwordx4 v[64:65], off
	s_waitcnt vmcnt(8)
	s_waitcnt lgkmcnt(0)
	s_barrier
	s_setprio 1
	s_waitcnt lgkmcnt(0)
	v_mfma_f32_16x16x32_bf16 v[64:67], v[0:3], v[32:35], 0
	v_mfma_f32_16x16x32_bf16 v[68:71], v[8:11], v[32:35], 0
	v_mfma_f32_16x16x32_bf16 v[72:75], v[0:3], v[40:43], 0
	v_mfma_f32_16x16x32_bf16 v[76:79], v[8:11], v[40:43], 0
	v_mfma_f32_16x16x32_bf16 v[80:83], v[0:3], v[48:51], 0
	v_mfma_f32_16x16x32_bf16 v[84:87], v[8:11], v[48:51], 0
	v_mfma_f32_16x16x32_bf16 v[88:91], v[0:3], v[56:59], 0
	v_mfma_f32_16x16x32_bf16 v[92:95], v[8:11], v[56:59], 0
	v_mfma_f32_16x16x32_bf16 v[64:67], v[4:7], v[36:39], v[64:67]
	v_mfma_f32_16x16x32_bf16 v[68:71], v[12:15], v[36:39], v[68:71]
	v_mfma_f32_16x16x32_bf16 v[72:75], v[4:7], v[44:47], v[72:75]
	v_mfma_f32_16x16x32_bf16 v[76:79], v[12:15], v[44:47], v[76:79]
	v_mfma_f32_16x16x32_bf16 v[80:83], v[4:7], v[52:55], v[80:83]
	v_mfma_f32_16x16x32_bf16 v[84:87], v[12:15], v[52:55], v[84:87]
	v_mfma_f32_16x16x32_bf16 v[88:91], v[4:7], v[60:63], v[88:91]
	v_mfma_f32_16x16x32_bf16 v[92:95], v[12:15], v[60:63], v[92:95]
	v_mfma_f32_16x16x32_bf16 v[96:99], v[16:19], v[32:35], 0
	v_mfma_f32_16x16x32_bf16 v[32:35], v[24:27], v[32:35], 0
	v_mfma_f32_16x16x32_bf16 v[96:99], v[20:23], v[36:39], v[96:99]
	v_mfma_f32_16x16x32_bf16 v[32:35], v[28:31], v[36:39], v[32:35]
	v_mfma_f32_16x16x32_bf16 v[36:39], v[16:19], v[40:43], 0
	v_mfma_f32_16x16x32_bf16 v[40:43], v[24:27], v[40:43], 0
	v_mfma_f32_16x16x32_bf16 v[36:39], v[20:23], v[44:47], v[36:39]
	v_mfma_f32_16x16x32_bf16 v[40:43], v[28:31], v[44:47], v[40:43]
	v_mfma_f32_16x16x32_bf16 v[44:47], v[16:19], v[48:51], 0
	v_mfma_f32_16x16x32_bf16 v[48:51], v[24:27], v[48:51], 0
	v_mfma_f32_16x16x32_bf16 v[44:47], v[20:23], v[52:55], v[44:47]
	v_mfma_f32_16x16x32_bf16 v[48:51], v[28:31], v[52:55], v[48:51]
	v_mfma_f32_16x16x32_bf16 v[52:55], v[16:19], v[56:59], 0
	v_mfma_f32_16x16x32_bf16 v[56:59], v[24:27], v[56:59], 0
	v_mfma_f32_16x16x32_bf16 v[52:55], v[20:23], v[60:63], v[52:55]
	v_mfma_f32_16x16x32_bf16 v[56:59], v[28:31], v[60:63], v[56:59]
	s_setprio 0
	s_barrier
	v_lshl_add_u64 v[210:211], s[34:35], 0, v[132:133]
	s_mov_b32 m0, s60
	v_lshl_add_u64 v[146:147], v[210:211], 0, s[16:17]
	v_lshl_add_u64 v[212:213], s[34:35], 0, v[128:129]
	s_add_u32 s68, s34, 0x10100
	ds_read_b128 v[60:63], v142 offset:16384
	ds_read_b128 v[100:103], v142 offset:17408
	ds_read_b128 v[104:107], v142 offset:18432
	ds_read_b128 v[108:111], v142 offset:19456
	ds_read_b128 v[112:115], v142 offset:20480
	ds_read_b128 v[116:119], v142 offset:21504
	ds_read_b128 v[120:123], v142 offset:22528
	ds_read_b128 v[124:127], v142 offset:23552
	global_load_lds_dwordx4 v[146:147], off
	v_lshl_add_u64 v[146:147], v[212:213], 0, s[16:17]
	s_mov_b32 m0, s61
	s_addc_u32 s69, s35, 0
	global_load_lds_dwordx4 v[146:147], off
	v_lshl_add_u64 v[146:147], s[68:69], 0, v[132:133]
	s_mov_b32 m0, s62
	v_lshl_add_u64 v[214:215], s[30:31], 0, v[134:135]
	global_load_lds_dwordx4 v[146:147], off
	v_lshl_add_u64 v[146:147], s[68:69], 0, v[128:129]
	s_mov_b32 m0, s63
	v_lshl_add_u64 v[216:217], s[30:31], 0, v[130:131]
	global_load_lds_dwordx4 v[146:147], off
	v_lshl_add_u64 v[146:147], v[214:215], 0, s[16:17]
	s_mov_b32 m0, s21
	s_nop 0
	global_load_lds_dwordx4 v[146:147], off
	v_lshl_add_u64 v[146:147], v[216:217], 0, s[16:17]
	s_mov_b32 m0, s49
	s_nop 0
	global_load_lds_dwordx4 v[146:147], off
	s_waitcnt vmcnt(8)
	s_waitcnt lgkmcnt(0)
	s_barrier
; #define PG8_STAGE(bufoff, gbase, voff) do { _Pragma("unroll") for (int _i = 0; _i < 2; ++_i) \
;         __builtin_amdgcn_global_load_lds((const unsigned*)((const char*)(gbase) + (voff)[_i]), (LAS unsigned*)(lds + (bufoff) + ldsw + _i * 8192), 16, 0, 0); } while (0)
; #define PG8_LDA(dst, b, h) do { _Pragma("unroll") for (int m = 0; m < 4; ++m) _Pragma("unroll") for (int k = 0; k < 2; ++k) dst[m][k] = *(const LAS bf16x8*)(lds + PG8_SA(b, h) + aoff + m * 2048 + k * 1024); } while (0)
; #define PG8_LDB(dst, b, h) do { _Pragma("unroll") for (int n = 0; n < 2; ++n) _Pragma("unroll") for (int k = 0; k < 2; ++k) dst[n][k] = *(const LAS bf16x8*)(lds + PG8_SB(b, h) + boff + n * 2048 + k * 1024); } while (0)
; #define PG8_MMA(ai, bj, At, Bt) do { __builtin_amdgcn_s_setprio(1); _Pragma("unroll") for (int m = 0; m < 4; ++m) _Pragma("unroll") for (int n = 0; n < 2; ++n) _Pragma("unroll") for (int k = 0; k < 2; ++k) \
;         acc[ai][bj][m][n] = __builtin_amdgcn_mfma_f32_16x16x32_bf16(Bt[n][k], At[m][k], acc[ai][bj][m][n], 0, 0, 0); __builtin_amdgcn_s_setprio(0); } while (0)
; #define PG8_WAIT_V(n) asm volatile("s_waitcnt vmcnt(" #n ")" ::: "memory")
; #define PG8_WAIT_L(n) asm volatile("s_waitcnt lgkmcnt(" #n ")" ::: "memory")
; #define PG8_BAR __builtin_amdgcn_s_barrier()
; #define PG8_SCHED __builtin_amdgcn_sched_barrier(0)
; template <class Epi, bool ALIGN_EPI, int K, int LDA, int LDB>
; __device__ __forceinline__ void gemm_phase(LAS unsigned char* lds, const int wid, const Gemm g, const StaticOrder& S, const Epi& E) {
;     ...
;             PG8_WAIT_V(8); PG8_WAIT_L(0); PG8_BAR; PG8_MMA(1, 0, At, B0); PG8_MMA(1, 1, At, B1); PG8_BAR; PG8_SCHED;
;             PG8_LDB(B0, 1, 0); PG8_LDB(B1, 1, 1); PG8_SCHED; PG8_LDA(At, 1, 0); PG8_STAGE(PG8_SA(0, 1), a2 + hA, voffA);
;             PG8_WAIT_V(8); PG8_WAIT_L(0); PG8_BAR; PG8_MMA(0, 0, At, B0); PG8_MMA(0, 1, At, B1); PG8_BAR; PG8_SCHED;
	s_setprio 1
	s_waitcnt lgkmcnt(0)
	v_mfma_f32_16x16x32_bf16 v[146:149], v[0:3], v[60:63], 0
	v_mfma_f32_16x16x32_bf16 v[154:157], v[0:3], v[104:107], 0
	v_mfma_f32_16x16x32_bf16 v[162:165], v[0:3], v[112:115], 0
	v_mfma_f32_16x16x32_bf16 v[0:3], v[0:3], v[120:123], 0
	v_mfma_f32_16x16x32_bf16 v[146:149], v[4:7], v[100:103], v[146:149]
	v_mfma_f32_16x16x32_bf16 v[154:157], v[4:7], v[108:111], v[154:157]
	v_mfma_f32_16x16x32_bf16 v[162:165], v[4:7], v[116:119], v[162:165]
	v_mfma_f32_16x16x32_bf16 v[0:3], v[4:7], v[124:127], v[0:3]
	v_mfma_f32_16x16x32_bf16 v[4:7], v[8:11], v[120:123], 0
	v_mfma_f32_16x16x32_bf16 v[150:153], v[8:11], v[60:63], 0
	v_mfma_f32_16x16x32_bf16 v[158:161], v[8:11], v[104:107], 0
	v_mfma_f32_16x16x32_bf16 v[166:169], v[8:11], v[112:115], 0
	v_mfma_f32_16x16x32_bf16 v[4:7], v[12:15], v[124:127], v[4:7]
	v_mfma_f32_16x16x32_bf16 v[150:153], v[12:15], v[100:103], v[150:153]
	v_mfma_f32_16x16x32_bf16 v[158:161], v[12:15], v[108:111], v[158:161]
	v_mfma_f32_16x16x32_bf16 v[166:169], v[12:15], v[116:119], v[166:169]
	v_mfma_f32_16x16x32_bf16 v[8:11], v[16:19], v[60:63], 0
	v_mfma_f32_16x16x32_bf16 v[12:15], v[24:27], v[60:63], 0
	v_mfma_f32_16x16x32_bf16 v[8:11], v[20:23], v[100:103], v[8:11]
	v_mfma_f32_16x16x32_bf16 v[12:15], v[28:31], v[100:103], v[12:15]
	v_mfma_f32_16x16x32_bf16 v[60:63], v[16:19], v[104:107], 0
	v_mfma_f32_16x16x32_bf16 v[100:103], v[24:27], v[104:107], 0
	v_mfma_f32_16x16x32_bf16 v[104:107], v[16:19], v[112:115], 0
	v_mfma_f32_16x16x32_bf16 v[16:19], v[16:19], v[120:123], 0
	v_mfma_f32_16x16x32_bf16 v[60:63], v[20:23], v[108:111], v[60:63]
	v_mfma_f32_16x16x32_bf16 v[100:103], v[28:31], v[108:111], v[100:103]
	v_mfma_f32_16x16x32_bf16 v[104:107], v[20:23], v[116:119], v[104:107]
	v_mfma_f32_16x16x32_bf16 v[108:111], v[24:27], v[112:115], 0
	v_mfma_f32_16x16x32_bf16 v[16:19], v[20:23], v[124:127], v[16:19]
	v_mfma_f32_16x16x32_bf16 v[20:23], v[24:27], v[120:123], 0
	v_mfma_f32_16x16x32_bf16 v[108:111], v[28:31], v[116:119], v[108:111]
	v_mfma_f32_16x16x32_bf16 v[20:23], v[28:31], v[124:127], v[20:23]
	s_setprio 0
	s_barrier
	ds_read_b128 v[24:27], v143
	ds_read_b128 v[28:31], v143 offset:1024
	ds_read_b128 v[112:115], v143 offset:2048
	ds_read_b128 v[116:119], v143 offset:3072
	ds_read_b128 v[120:123], v144
	ds_read_b128 v[124:127], v144 offset:1024
	ds_read_b128 v[170:173], v144 offset:2048
	ds_read_b128 v[174:177], v144 offset:3072
	s_add_u32 s68, s30, 0x10100
	s_addc_u32 s69, s31, 0
	s_mov_b32 m0, s51
	v_lshl_add_u64 v[218:219], s[68:69], 0, v[134:135]
	ds_read_b128 v[178:181], v142 offset:32768
	ds_read_b128 v[182:185], v142 offset:33792
	ds_read_b128 v[186:189], v142 offset:34816
	ds_read_b128 v[190:193], v142 offset:35840
	ds_read_b128 v[194:197], v142 offset:36864
	ds_read_b128 v[198:201], v142 offset:37888
	ds_read_b128 v[202:205], v142 offset:38912
	ds_read_b128 v[206:209], v142 offset:39936
	global_load_lds_dwordx4 v[218:219], off
	v_lshl_add_u64 v[218:219], s[68:69], 0, v[130:131]
	s_mov_b32 m0, s54
	s_nop 0
	global_load_lds_dwordx4 v[218:219], off
	s_waitcnt vmcnt(8)
	s_waitcnt lgkmcnt(0)
	s_barrier
	s_setprio 1
	s_waitcnt lgkmcnt(0)
	v_mfma_f32_16x16x32_bf16 v[64:67], v[24:27], v[178:181], v[64:67]
	v_mfma_f32_16x16x32_bf16 v[68:71], v[112:115], v[178:181], v[68:71]
	v_mfma_f32_16x16x32_bf16 v[72:75], v[24:27], v[186:189], v[72:75]
	v_mfma_f32_16x16x32_bf16 v[76:79], v[112:115], v[186:189], v[76:79]
	v_mfma_f32_16x16x32_bf16 v[80:83], v[24:27], v[194:197], v[80:83]
	v_mfma_f32_16x16x32_bf16 v[84:87], v[112:115], v[194:197], v[84:87]
	v_mfma_f32_16x16x32_bf16 v[88:91], v[24:27], v[202:205], v[88:91]
	v_mfma_f32_16x16x32_bf16 v[92:95], v[112:115], v[202:205], v[92:95]
	v_mfma_f32_16x16x32_bf16 v[64:67], v[28:31], v[182:185], v[64:67]
	v_mfma_f32_16x16x32_bf16 v[68:71], v[116:119], v[182:185], v[68:71]
	v_mfma_f32_16x16x32_bf16 v[72:75], v[28:31], v[190:193], v[72:75]
	v_mfma_f32_16x16x32_bf16 v[76:79], v[116:119], v[190:193], v[76:79]
	v_mfma_f32_16x16x32_bf16 v[80:83], v[28:31], v[198:201], v[80:83]
	v_mfma_f32_16x16x32_bf16 v[84:87], v[116:119], v[198:201], v[84:87]
	v_mfma_f32_16x16x32_bf16 v[88:91], v[28:31], v[206:209], v[88:91]
	v_mfma_f32_16x16x32_bf16 v[92:95], v[116:119], v[206:209], v[92:95]
	v_mfma_f32_16x16x32_bf16 v[96:99], v[120:123], v[178:181], v[96:99]
	v_mfma_f32_16x16x32_bf16 v[32:35], v[170:173], v[178:181], v[32:35]
	v_mfma_f32_16x16x32_bf16 v[36:39], v[120:123], v[186:189], v[36:39]
	v_mfma_f32_16x16x32_bf16 v[40:43], v[170:173], v[186:189], v[40:43]
	v_mfma_f32_16x16x32_bf16 v[44:47], v[120:123], v[194:197], v[44:47]
	v_mfma_f32_16x16x32_bf16 v[48:51], v[170:173], v[194:197], v[48:51]
	v_mfma_f32_16x16x32_bf16 v[52:55], v[120:123], v[202:205], v[52:55]
	v_mfma_f32_16x16x32_bf16 v[56:59], v[170:173], v[202:205], v[56:59]
	v_mfma_f32_16x16x32_bf16 v[96:99], v[124:127], v[182:185], v[96:99]
	v_mfma_f32_16x16x32_bf16 v[32:35], v[174:177], v[182:185], v[32:35]
	v_mfma_f32_16x16x32_bf16 v[36:39], v[124:127], v[190:193], v[36:39]
	v_mfma_f32_16x16x32_bf16 v[40:43], v[174:177], v[190:193], v[40:43]
	v_mfma_f32_16x16x32_bf16 v[44:47], v[124:127], v[198:201], v[44:47]
	v_mfma_f32_16x16x32_bf16 v[48:51], v[174:177], v[198:201], v[48:51]
	v_mfma_f32_16x16x32_bf16 v[52:55], v[124:127], v[206:209], v[52:55]
	v_mfma_f32_16x16x32_bf16 v[56:59], v[174:177], v[206:209], v[56:59]
	s_setprio 0
	s_barrier
; #define PG8_STAGE(bufoff, gbase, voff) do { _Pragma("unroll") for (int _i = 0; _i < 2; ++_i) \
;         __builtin_amdgcn_global_load_lds((const unsigned*)((const char*)(gbase) + (voff)[_i]), (LAS unsigned*)(lds + (bufoff) + ldsw + _i * 8192), 16, 0, 0); } while (0)
; #define PG8_LDA(dst, b, h) do { _Pragma("unroll") for (int m = 0; m < 4; ++m) _Pragma("unroll") for (int k = 0; k < 2; ++k) dst[m][k] = *(const LAS bf16x8*)(lds + PG8_SA(b, h) + aoff + m * 2048 + k * 1024); } while (0)
; #define PG8_LDB(dst, b, h) do { _Pragma("unroll") for (int n = 0; n < 2; ++n) _Pragma("unroll") for (int k = 0; k < 2; ++k) dst[n][k] = *(const LAS bf16x8*)(lds + PG8_SB(b, h) + boff + n * 2048 + k * 1024); } while (0)
; #define PG8_MMA(ai, bj, At, Bt) do { __builtin_amdgcn_s_setprio(1); _Pragma("unroll") for (int m = 0; m < 4; ++m) _Pragma("unroll") for (int n = 0; n < 2; ++n) _Pragma("unroll") for (int k = 0; k < 2; ++k) \
;         acc[ai][bj][m][n] = __builtin_amdgcn_mfma_f32_16x16x32_bf16(Bt[n][k], At[m][k], acc[ai][bj][m][n], 0, 0, 0); __builtin_amdgcn_s_setprio(0); } while (0)
; #define PG8_WAIT_V(n) asm volatile("s_waitcnt vmcnt(" #n ")" ::: "memory")
; #define PG8_WAIT_L(n) asm volatile("s_waitcnt lgkmcnt(" #n ")" ::: "memory")
; #define PG8_BAR __builtin_amdgcn_s_barrier()
; #define PG8_SCHED __builtin_amdgcn_sched_barrier(0)
; template <class Epi, bool ALIGN_EPI, int K, int LDA, int LDB>
; __device__ __forceinline__ void gemm_phase(LAS unsigned char* lds, const int wid, const Gemm g, const StaticOrder& S, const Epi& E) {
;     ...
;             PG8_LDB(B0, 0, 0); PG8_LDB(B1, 0, 1); PG8_SCHED; PG8_LDA(At, 0, 0); PG8_STAGE(PG8_SA(1, 1), a1 + hA, voffA);
;             PG8_WAIT_V(8); PG8_WAIT_L(0); PG8_BAR; PG8_MMA(0, 0, At, B0); PG8_MMA(0, 1, At, B1); PG8_BAR; PG8_SCHED;
;     ...
;             PG8_LDA(At, 1, 1); PG8_STAGE(PG8_SB(1, 0), b3, voffB); PG8_STAGE(PG8_SB(1, 1), b3 + hB, voffB); PG8_STAGE(PG8_SA(1, 0), a3, voffA);
;             PG8_WAIT_V(8); PG8_WAIT_L(0); PG8_BAR; PG8_MMA(1, 0, At, B0); PG8_MMA(1, 1, At, B1); PG8_BAR; PG8_SCHED;
	s_add_i32 s23, s65, 0x2000
	s_mov_b32 m0, s65
	v_lshl_add_u64 v[210:211], v[210:211], 0, s[18:19]
	s_add_u32 s34, s34, 0x10180
	ds_read_b128 v[178:181], v142 offset:49152
	ds_read_b128 v[182:185], v142 offset:50176
	ds_read_b128 v[186:189], v142 offset:51200
	ds_read_b128 v[190:193], v142 offset:52224
	ds_read_b128 v[194:197], v142 offset:53248
	ds_read_b128 v[198:201], v142 offset:54272
	ds_read_b128 v[202:205], v142 offset:55296
	ds_read_b128 v[206:209], v142 offset:56320
	global_load_lds_dwordx4 v[210:211], off
	v_lshl_add_u64 v[210:211], v[212:213], 0, s[18:19]
	s_mov_b32 m0, s23
	s_addc_u32 s35, s35, 0
	s_add_i32 s25, s64, s0
	global_load_lds_dwordx4 v[210:211], off
	v_lshl_add_u64 v[210:211], s[34:35], 0, v[132:133]
	s_mov_b32 m0, s25
	s_nop 0
	global_load_lds_dwordx4 v[210:211], off
	v_lshl_add_u64 v[210:211], s[34:35], 0, v[128:129]
	s_add_i32 s34, s25, 0x2000
	s_mov_b32 m0, s34
	s_nop 0
	global_load_lds_dwordx4 v[210:211], off
	v_lshl_add_u64 v[210:211], v[214:215], 0, s[18:19]
	s_mov_b32 m0, s55
	s_nop 0
	global_load_lds_dwordx4 v[210:211], off
	v_lshl_add_u64 v[210:211], v[216:217], 0, s[18:19]
	s_mov_b32 m0, s56
	s_nop 0
	global_load_lds_dwordx4 v[210:211], off
	s_waitcnt vmcnt(8)
	s_waitcnt lgkmcnt(0)
	s_barrier
	s_setprio 1
	s_waitcnt lgkmcnt(0)
	v_mfma_f32_16x16x32_bf16 v[0:3], v[24:27], v[202:205], v[0:3]
	v_mfma_f32_16x16x32_bf16 v[4:7], v[112:115], v[202:205], v[4:7]
	v_mfma_f32_16x16x32_bf16 v[146:149], v[24:27], v[178:181], v[146:149]
	v_mfma_f32_16x16x32_bf16 v[150:153], v[112:115], v[178:181], v[150:153]
	v_mfma_f32_16x16x32_bf16 v[154:157], v[24:27], v[186:189], v[154:157]
	v_mfma_f32_16x16x32_bf16 v[158:161], v[112:115], v[186:189], v[158:161]
	v_mfma_f32_16x16x32_bf16 v[162:165], v[24:27], v[194:197], v[162:165]
	v_mfma_f32_16x16x32_bf16 v[166:169], v[112:115], v[194:197], v[166:169]
	v_mfma_f32_16x16x32_bf16 v[0:3], v[28:31], v[206:209], v[0:3]
	v_mfma_f32_16x16x32_bf16 v[4:7], v[116:119], v[206:209], v[4:7]
	v_mfma_f32_16x16x32_bf16 v[146:149], v[28:31], v[182:185], v[146:149]
	v_mfma_f32_16x16x32_bf16 v[150:153], v[116:119], v[182:185], v[150:153]
	v_mfma_f32_16x16x32_bf16 v[154:157], v[28:31], v[190:193], v[154:157]
	v_mfma_f32_16x16x32_bf16 v[158:161], v[116:119], v[190:193], v[158:161]
	v_mfma_f32_16x16x32_bf16 v[162:165], v[28:31], v[198:201], v[162:165]
	v_mfma_f32_16x16x32_bf16 v[166:169], v[116:119], v[198:201], v[166:169]
	v_mfma_f32_16x16x32_bf16 v[8:11], v[120:123], v[178:181], v[8:11]
	v_mfma_f32_16x16x32_bf16 v[12:15], v[170:173], v[178:181], v[12:15]
	v_mfma_f32_16x16x32_bf16 v[24:27], v[120:123], v[186:189], v[60:63]
	v_mfma_f32_16x16x32_bf16 v[28:31], v[170:173], v[186:189], v[100:103]
	v_mfma_f32_16x16x32_bf16 v[60:63], v[120:123], v[194:197], v[104:107]
	v_mfma_f32_16x16x32_bf16 v[100:103], v[170:173], v[194:197], v[108:111]
	v_mfma_f32_16x16x32_bf16 v[16:19], v[120:123], v[202:205], v[16:19]
	v_mfma_f32_16x16x32_bf16 v[20:23], v[170:173], v[202:205], v[20:23]
	v_mfma_f32_16x16x32_bf16 v[8:11], v[124:127], v[182:185], v[8:11]
	v_mfma_f32_16x16x32_bf16 v[12:15], v[174:177], v[182:185], v[12:15]
	v_mfma_f32_16x16x32_bf16 v[24:27], v[124:127], v[190:193], v[24:27]
	v_mfma_f32_16x16x32_bf16 v[28:31], v[174:177], v[190:193], v[28:31]
	v_mfma_f32_16x16x32_bf16 v[60:63], v[124:127], v[198:201], v[60:63]
	v_mfma_f32_16x16x32_bf16 v[100:103], v[174:177], v[198:201], v[100:103]
	v_mfma_f32_16x16x32_bf16 v[16:19], v[124:127], v[206:209], v[16:19]
	v_mfma_f32_16x16x32_bf16 v[20:23], v[174:177], v[206:209], v[20:23]
	s_setprio 0
	s_barrier
	ds_read_b128 v[104:107], v140
	ds_read_b128 v[108:111], v140 offset:1024
	ds_read_b128 v[112:115], v140 offset:2048
	ds_read_b128 v[116:119], v140 offset:3072
	ds_read_b128 v[120:123], v141
	ds_read_b128 v[124:127], v141 offset:1024
	ds_read_b128 v[170:173], v141 offset:2048
	ds_read_b128 v[174:177], v141 offset:3072
	s_add_u32 s30, s30, 0x10180
	s_addc_u32 s31, s31, 0
	s_mov_b32 m0, s58
	v_lshl_add_u64 v[210:211], s[30:31], 0, v[134:135]
	ds_read_b128 v[178:181], v142
	ds_read_b128 v[182:185], v142 offset:1024
	ds_read_b128 v[186:189], v142 offset:2048
	ds_read_b128 v[190:193], v142 offset:3072
	ds_read_b128 v[194:197], v142 offset:4096
	ds_read_b128 v[198:201], v142 offset:5120
	ds_read_b128 v[202:205], v142 offset:6144
	ds_read_b128 v[206:209], v142 offset:7168
	global_load_lds_dwordx4 v[210:211], off
	v_lshl_add_u64 v[210:211], s[30:31], 0, v[130:131]
	s_mov_b32 m0, s59
	s_nop 0
	global_load_lds_dwordx4 v[210:211], off
	s_waitcnt vmcnt(8)
	s_waitcnt lgkmcnt(0)
	s_barrier
; #define PG8_STAGE(bufoff, gbase, voff) do { _Pragma("unroll") for (int _i = 0; _i < 2; ++_i) \
;         __builtin_amdgcn_global_load_lds((const unsigned*)((const char*)(gbase) + (voff)[_i]), (LAS unsigned*)(lds + (bufoff) + ldsw + _i * 8192), 16, 0, 0); } while (0)
; #define PG8_LDA(dst, b, h) do { _Pragma("unroll") for (int m = 0; m < 4; ++m) _Pragma("unroll") for (int k = 0; k < 2; ++k) dst[m][k] = *(const LAS bf16x8*)(lds + PG8_SA(b, h) + aoff + m * 2048 + k * 1024); } while (0)
; #define PG8_MMA(ai, bj, At, Bt) do { __builtin_amdgcn_s_setprio(1); _Pragma("unroll") for (int m = 0; m < 4; ++m) _Pragma("unroll") for (int n = 0; n < 2; ++n) _Pragma("unroll") for (int k = 0; k < 2; ++k) \
;         acc[ai][bj][m][n] = __builtin_amdgcn_mfma_f32_16x16x32_bf16(Bt[n][k], At[m][k], acc[ai][bj][m][n], 0, 0, 0); __builtin_amdgcn_s_setprio(0); } while (0)
; #define PG8_WAIT_V(n) asm volatile("s_waitcnt vmcnt(" #n ")" ::: "memory")
; #define PG8_WAIT_L(n) asm volatile("s_waitcnt lgkmcnt(" #n ")" ::: "memory")
; #define PG8_BAR __builtin_amdgcn_s_barrier()
; #define PG8_SCHED __builtin_amdgcn_sched_barrier(0)
; template <class Epi, bool ALIGN_EPI, int K, int LDA, int LDB>
; __device__ __forceinline__ void gemm_phase(LAS unsigned char* lds, const int wid, const Gemm g, const StaticOrder& S, const Epi& E) {
;     ...
;         const char* nA = has_next ? (const char*)g.A + (size_t)nxt.pm * tA : cA; const char* nB = has_next ? (const char*)g.Bt + (size_t)nxt.pn * tB : cB;
;         for (int t = 0; t < nt; t += 2) {
;             const bool last = (t == nt - 2);
;             const char* a1 = cA + (size_t)(t + 1) * kstep;
;             const char* a2 = last ? nA : cA + (size_t)(t + 2) * kstep; const char* b2 = last ? nB : cB + (size_t)(t + 2) * kstep;
;     ...
;             PG8_WAIT_V(8); PG8_WAIT_L(0); PG8_BAR; PG8_MMA(0, 0, At, B0); PG8_MMA(0, 1, At, B1); PG8_BAR; PG8_SCHED;
;             PG8_LDA(At, 0, 1); PG8_STAGE(PG8_SB(0, 0), b2, voffB); PG8_STAGE(PG8_SB(0, 1), b2 + hB, voffB); PG8_STAGE(PG8_SA(0, 0), a2, voffA);
;             PG8_WAIT_V(8); PG8_WAIT_L(0); PG8_BAR; PG8_MMA(1, 0, At, B0); PG8_MMA(1, 1, At, B1); PG8_BAR; PG8_SCHED;
	s_setprio 1
	s_waitcnt lgkmcnt(0)
	v_mfma_f32_16x16x32_bf16 v[80:83], v[104:107], v[194:197], v[80:83]
	v_mfma_f32_16x16x32_bf16 v[210:213], v[108:111], v[198:201], v[80:83]
	v_mfma_f32_16x16x32_bf16 v[80:83], v[112:115], v[194:197], v[84:87]
	v_mfma_f32_16x16x32_bf16 v[214:217], v[116:119], v[198:201], v[80:83]
	v_mfma_f32_16x16x32_bf16 v[80:83], v[104:107], v[202:205], v[88:91]
	v_mfma_f32_16x16x32_bf16 v[64:67], v[104:107], v[178:181], v[64:67]
	v_mfma_f32_16x16x32_bf16 v[68:71], v[112:115], v[178:181], v[68:71]
	v_mfma_f32_16x16x32_bf16 v[72:75], v[104:107], v[186:189], v[72:75]
	v_mfma_f32_16x16x32_bf16 v[76:79], v[112:115], v[186:189], v[76:79]
	v_mfma_f32_16x16x32_bf16 v[88:91], v[108:111], v[206:209], v[80:83]
	v_mfma_f32_16x16x32_bf16 v[80:83], v[112:115], v[202:205], v[92:95]
	v_mfma_f32_16x16x32_bf16 v[64:67], v[108:111], v[182:185], v[64:67]
	v_mfma_f32_16x16x32_bf16 v[68:71], v[116:119], v[182:185], v[68:71]
	v_mfma_f32_16x16x32_bf16 v[72:75], v[108:111], v[190:193], v[72:75]
	v_mfma_f32_16x16x32_bf16 v[76:79], v[116:119], v[190:193], v[76:79]
	v_mfma_f32_16x16x32_bf16 v[92:95], v[116:119], v[206:209], v[80:83]
	v_mfma_f32_16x16x32_bf16 v[48:51], v[170:173], v[194:197], v[48:51]
	v_mfma_f32_16x16x32_bf16 v[80:83], v[120:123], v[178:181], v[96:99]
	v_mfma_f32_16x16x32_bf16 v[32:35], v[170:173], v[178:181], v[32:35]
	v_mfma_f32_16x16x32_bf16 v[178:181], v[174:177], v[198:201], v[48:51]
	v_mfma_f32_16x16x32_bf16 v[48:51], v[120:123], v[202:205], v[52:55]
	v_mfma_f32_16x16x32_bf16 v[96:99], v[124:127], v[182:185], v[80:83]
	v_mfma_f32_16x16x32_bf16 v[32:35], v[174:177], v[182:185], v[32:35]
	v_mfma_f32_16x16x32_bf16 v[36:39], v[120:123], v[186:189], v[36:39]
	v_mfma_f32_16x16x32_bf16 v[40:43], v[170:173], v[186:189], v[40:43]
	v_mfma_f32_16x16x32_bf16 v[44:47], v[120:123], v[194:197], v[44:47]
	v_mfma_f32_16x16x32_bf16 v[182:185], v[124:127], v[206:209], v[48:51]
	v_mfma_f32_16x16x32_bf16 v[48:51], v[170:173], v[202:205], v[56:59]
	v_mfma_f32_16x16x32_bf16 v[36:39], v[124:127], v[190:193], v[36:39]
	v_mfma_f32_16x16x32_bf16 v[40:43], v[174:177], v[190:193], v[40:43]
	v_mfma_f32_16x16x32_bf16 v[44:47], v[124:127], v[198:201], v[44:47]
	v_mfma_f32_16x16x32_bf16 v[56:59], v[174:177], v[206:209], v[48:51]
	s_setprio 0
	s_barrier
	s_mov_b32 m0, s60
	v_lshl_add_u64 v[250:251], s[36:37], 0, v[132:133]
	s_add_u32 s30, s36, 0x10000
	ds_read_b128 v[48:51], v142 offset:16384
	ds_read_b128 v[52:55], v142 offset:17408
	ds_read_b128 v[80:83], v142 offset:18432
	ds_read_b128 v[84:87], v142 offset:19456
	ds_read_b128 v[186:189], v142 offset:20480
	ds_read_b128 v[190:193], v142 offset:21504
	ds_read_b128 v[194:197], v142 offset:22528
	ds_read_b128 v[198:201], v142 offset:23552
	global_load_lds_dwordx4 v[250:251], off
	v_lshl_add_u64 v[252:253], s[36:37], 0, v[128:129]
	s_mov_b32 m0, s61
	s_addc_u32 s31, s37, 0
	global_load_lds_dwordx4 v[252:253], off
	v_lshl_add_u64 v[202:203], s[30:31], 0, v[132:133]
	s_mov_b32 m0, s62
	v_lshl_add_u64 v[136:137], s[38:39], 0, v[134:135]
	global_load_lds_dwordx4 v[202:203], off
	v_lshl_add_u64 v[202:203], s[30:31], 0, v[128:129]
	s_mov_b32 m0, s63
	v_lshl_add_u64 v[138:139], s[38:39], 0, v[130:131]
	global_load_lds_dwordx4 v[202:203], off
	s_mov_b32 m0, s21
	s_nop 0
	global_load_lds_dwordx4 v[136:137], off
	s_mov_b32 m0, s49
	s_nop 0
	global_load_lds_dwordx4 v[138:139], off
	s_waitcnt vmcnt(8)
	s_waitcnt lgkmcnt(0)
	s_barrier
	s_setprio 1
	s_waitcnt lgkmcnt(0)
	v_mfma_f32_16x16x32_bf16 v[0:3], v[104:107], v[194:197], v[0:3]
	v_mfma_f32_16x16x32_bf16 v[4:7], v[112:115], v[194:197], v[4:7]
	v_mfma_f32_16x16x32_bf16 v[146:149], v[104:107], v[48:51], v[146:149]
	v_mfma_f32_16x16x32_bf16 v[150:153], v[112:115], v[48:51], v[150:153]
	v_mfma_f32_16x16x32_bf16 v[154:157], v[104:107], v[80:83], v[154:157]
	v_mfma_f32_16x16x32_bf16 v[158:161], v[112:115], v[80:83], v[158:161]
	v_mfma_f32_16x16x32_bf16 v[162:165], v[104:107], v[186:189], v[162:165]
	v_mfma_f32_16x16x32_bf16 v[166:169], v[112:115], v[186:189], v[166:169]
	v_mfma_f32_16x16x32_bf16 v[0:3], v[108:111], v[198:201], v[0:3]
	v_mfma_f32_16x16x32_bf16 v[4:7], v[116:119], v[198:201], v[4:7]
	v_mfma_f32_16x16x32_bf16 v[146:149], v[108:111], v[52:55], v[146:149]
	v_mfma_f32_16x16x32_bf16 v[150:153], v[116:119], v[52:55], v[150:153]
	v_mfma_f32_16x16x32_bf16 v[154:157], v[108:111], v[84:87], v[154:157]
	v_mfma_f32_16x16x32_bf16 v[158:161], v[116:119], v[84:87], v[158:161]
	v_mfma_f32_16x16x32_bf16 v[162:165], v[108:111], v[190:193], v[162:165]
	v_mfma_f32_16x16x32_bf16 v[166:169], v[116:119], v[190:193], v[166:169]
	v_mfma_f32_16x16x32_bf16 v[24:27], v[120:123], v[80:83], v[24:27]
	v_mfma_f32_16x16x32_bf16 v[202:205], v[124:127], v[84:87], v[24:27]
	v_mfma_f32_16x16x32_bf16 v[24:27], v[170:173], v[80:83], v[28:31]
	v_mfma_f32_16x16x32_bf16 v[206:209], v[174:177], v[84:87], v[24:27]
	v_mfma_f32_16x16x32_bf16 v[24:27], v[120:123], v[186:189], v[60:63]
	v_mfma_f32_16x16x32_bf16 v[8:11], v[120:123], v[48:51], v[8:11]
	v_mfma_f32_16x16x32_bf16 v[12:15], v[170:173], v[48:51], v[12:15]
	v_mfma_f32_16x16x32_bf16 v[218:221], v[124:127], v[190:193], v[24:27]
	v_mfma_f32_16x16x32_bf16 v[24:27], v[170:173], v[186:189], v[100:103]
	v_mfma_f32_16x16x32_bf16 v[16:19], v[120:123], v[194:197], v[16:19]
	v_mfma_f32_16x16x32_bf16 v[8:11], v[124:127], v[52:55], v[8:11]
	v_mfma_f32_16x16x32_bf16 v[12:15], v[174:177], v[52:55], v[12:15]
	v_mfma_f32_16x16x32_bf16 v[186:189], v[174:177], v[190:193], v[24:27]
	v_mfma_f32_16x16x32_bf16 v[190:193], v[124:127], v[198:201], v[16:19]
	v_mfma_f32_16x16x32_bf16 v[16:19], v[170:173], v[194:197], v[20:23]
	v_mfma_f32_16x16x32_bf16 v[170:173], v[174:177], v[198:201], v[16:19]
	s_setprio 0
	s_barrier
; #define PG8_STAGE(bufoff, gbase, voff) do { _Pragma("unroll") for (int _i = 0; _i < 2; ++_i) \
;         __builtin_amdgcn_global_load_lds((const unsigned*)((const char*)(gbase) + (voff)[_i]), (LAS unsigned*)(lds + (bufoff) + ldsw + _i * 8192), 16, 0, 0); } while (0)
; #define PG8_LDA(dst, b, h) do { _Pragma("unroll") for (int m = 0; m < 4; ++m) _Pragma("unroll") for (int k = 0; k < 2; ++k) dst[m][k] = *(const LAS bf16x8*)(lds + PG8_SA(b, h) + aoff + m * 2048 + k * 1024); } while (0)
; #define PG8_LDB(dst, b, h) do { _Pragma("unroll") for (int n = 0; n < 2; ++n) _Pragma("unroll") for (int k = 0; k < 2; ++k) dst[n][k] = *(const LAS bf16x8*)(lds + PG8_SB(b, h) + boff + n * 2048 + k * 1024); } while (0)
; #define PG8_MMA(ai, bj, At, Bt) do { __builtin_amdgcn_s_setprio(1); _Pragma("unroll") for (int m = 0; m < 4; ++m) _Pragma("unroll") for (int n = 0; n < 2; ++n) _Pragma("unroll") for (int k = 0; k < 2; ++k) \
;         acc[ai][bj][m][n] = __builtin_amdgcn_mfma_f32_16x16x32_bf16(Bt[n][k], At[m][k], acc[ai][bj][m][n], 0, 0, 0); __builtin_amdgcn_s_setprio(0); } while (0)
; #define PG8_WAIT_V(n) asm volatile("s_waitcnt vmcnt(" #n ")" ::: "memory")
; #define PG8_WAIT_L(n) asm volatile("s_waitcnt lgkmcnt(" #n ")" ::: "memory")
; #define PG8_BAR __builtin_amdgcn_s_barrier()
; #define PG8_SCHED __builtin_amdgcn_sched_barrier(0)
; template <class Epi, bool ALIGN_EPI, int K, int LDA, int LDB>
; __device__ __forceinline__ void gemm_phase(LAS unsigned char* lds, const int wid, const Gemm g, const StaticOrder& S, const Epi& E) {
;     ...
;             PG8_LDB(B0, 1, 0); PG8_LDB(B1, 1, 1); PG8_SCHED; PG8_LDA(At, 1, 0); PG8_STAGE(PG8_SA(0, 1), a2 + hA, voffA);
;             PG8_WAIT_V(8); PG8_WAIT_L(0); PG8_BAR; PG8_MMA(0, 0, At, B0); PG8_MMA(0, 1, At, B1); PG8_BAR; PG8_SCHED;
;             PG8_LDA(At, 1, 1); PG8_STAGE(PG8_SB(1, 0), b3, voffB); PG8_STAGE(PG8_SB(1, 1), b3 + hB, voffB); PG8_STAGE(PG8_SA(1, 0), a3, voffA);
;             PG8_WAIT_V(8); PG8_WAIT_L(0); PG8_BAR; PG8_MMA(1, 0, At, B0); PG8_MMA(1, 1, At, B1); PG8_BAR; PG8_SCHED;
;         }
;         if constexpr (ALIGN_EPI) { if (wr == 0) PG8_BAR; }
	ds_read_b128 v[104:107], v143
	ds_read_b128 v[108:111], v143 offset:1024
	ds_read_b128 v[174:177], v143 offset:2048
	ds_read_b128 v[194:197], v143 offset:3072
	ds_read_b128 v[198:201], v144
	ds_read_b128 v[222:225], v144 offset:1024
	ds_read_b128 v[226:229], v144 offset:2048
	ds_read_b128 v[230:233], v144 offset:3072
	s_add_u32 s30, s38, 0x10000
	s_addc_u32 s31, s39, 0
	s_mov_b32 m0, s51
	v_lshl_add_u64 v[16:17], s[30:31], 0, v[134:135]
	ds_read_b128 v[24:27], v142 offset:32768
	ds_read_b128 v[28:31], v142 offset:33792
	ds_read_b128 v[60:63], v142 offset:34816
	ds_read_b128 v[100:103], v142 offset:35840
	ds_read_b128 v[234:237], v142 offset:36864
	ds_read_b128 v[238:241], v142 offset:37888
	ds_read_b128 v[242:245], v142 offset:38912
	ds_read_b128 v[246:249], v142 offset:39936
	global_load_lds_dwordx4 v[16:17], off
	v_lshl_add_u64 v[16:17], s[30:31], 0, v[130:131]
	s_mov_b32 m0, s54
	s_nop 0
	global_load_lds_dwordx4 v[16:17], off
	s_waitcnt vmcnt(8)
	s_waitcnt lgkmcnt(0)
	s_barrier
	s_setprio 1
	s_waitcnt lgkmcnt(0)
	v_mfma_f32_16x16x32_bf16 v[16:19], v[104:107], v[24:27], v[64:67]
	v_mfma_f32_16x16x32_bf16 v[112:115], v[108:111], v[28:31], v[16:19]
	v_mfma_f32_16x16x32_bf16 v[16:19], v[174:177], v[24:27], v[68:71]
	v_mfma_f32_16x16x32_bf16 v[116:119], v[194:197], v[28:31], v[16:19]
	v_mfma_f32_16x16x32_bf16 v[16:19], v[104:107], v[60:63], v[72:75]
	v_mfma_f32_16x16x32_bf16 v[80:83], v[108:111], v[100:103], v[16:19]
	v_mfma_f32_16x16x32_bf16 v[16:19], v[174:177], v[60:63], v[76:79]
	v_mfma_f32_16x16x32_bf16 v[84:87], v[194:197], v[100:103], v[16:19]
	v_mfma_f32_16x16x32_bf16 v[16:19], v[104:107], v[234:237], v[210:213]
	v_mfma_f32_16x16x32_bf16 v[48:51], v[108:111], v[238:241], v[16:19]
	v_mfma_f32_16x16x32_bf16 v[16:19], v[174:177], v[234:237], v[214:217]
	v_mfma_f32_16x16x32_bf16 v[52:55], v[194:197], v[238:241], v[16:19]
	v_mfma_f32_16x16x32_bf16 v[16:19], v[104:107], v[242:245], v[88:91]
	v_mfma_f32_16x16x32_bf16 v[20:23], v[174:177], v[242:245], v[92:95]
	v_mfma_f32_16x16x32_bf16 v[16:19], v[108:111], v[246:249], v[16:19]
	v_mfma_f32_16x16x32_bf16 v[20:23], v[194:197], v[246:249], v[20:23]
	v_mfma_f32_16x16x32_bf16 v[64:67], v[198:201], v[24:27], v[96:99]
	v_mfma_f32_16x16x32_bf16 v[24:27], v[226:229], v[24:27], v[32:35]
	v_mfma_f32_16x16x32_bf16 v[124:127], v[230:233], v[28:31], v[24:27]
	v_mfma_f32_16x16x32_bf16 v[24:27], v[198:201], v[60:63], v[36:39]
	v_mfma_f32_16x16x32_bf16 v[96:99], v[222:225], v[100:103], v[24:27]
	v_mfma_f32_16x16x32_bf16 v[24:27], v[226:229], v[60:63], v[40:43]
	v_mfma_f32_16x16x32_bf16 v[100:103], v[230:233], v[100:103], v[24:27]
	v_mfma_f32_16x16x32_bf16 v[24:27], v[198:201], v[234:237], v[44:47]
	v_mfma_f32_16x16x32_bf16 v[120:123], v[222:225], v[28:31], v[64:67]
	v_mfma_f32_16x16x32_bf16 v[64:67], v[222:225], v[238:241], v[24:27]
	v_mfma_f32_16x16x32_bf16 v[24:27], v[226:229], v[234:237], v[178:181]
	v_mfma_f32_16x16x32_bf16 v[68:71], v[230:233], v[238:241], v[24:27]
	v_mfma_f32_16x16x32_bf16 v[24:27], v[198:201], v[242:245], v[182:185]
	v_mfma_f32_16x16x32_bf16 v[32:35], v[222:225], v[246:249], v[24:27]
	v_mfma_f32_16x16x32_bf16 v[24:27], v[226:229], v[242:245], v[56:59]
	v_mfma_f32_16x16x32_bf16 v[36:39], v[230:233], v[246:249], v[24:27]
	s_setprio 0
	s_barrier
	s_mov_b32 m0, s65
	s_nop 3
	v_lshl_add_u64 v[24:25], v[250:251], 0, s[10:11]
	s_add_u32 s30, s36, 0x10080
	ds_read_b128 v[40:43], v142 offset:49152
	ds_read_b128 v[44:47], v142 offset:50176
	ds_read_b128 v[76:79], v142 offset:51200
	ds_read_b128 v[178:181], v142 offset:52224
	ds_read_b128 v[182:185], v142 offset:53248
	ds_read_b128 v[210:213], v142 offset:54272
	ds_read_b128 v[214:217], v142 offset:55296
	ds_read_b128 v[234:237], v142 offset:56320
	global_load_lds_dwordx4 v[24:25], off
	v_lshl_add_u64 v[24:25], v[252:253], 0, s[10:11]
	s_mov_b32 m0, s23
	s_addc_u32 s31, s37, 0
	global_load_lds_dwordx4 v[24:25], off
	v_lshl_add_u64 v[24:25], s[30:31], 0, v[132:133]
	s_mov_b32 m0, s25
	s_nop 0
	global_load_lds_dwordx4 v[24:25], off
	v_lshl_add_u64 v[24:25], s[30:31], 0, v[128:129]
	s_mov_b32 m0, s34
	s_nop 0
	global_load_lds_dwordx4 v[24:25], off
	v_lshl_add_u64 v[24:25], v[136:137], 0, s[10:11]
	s_mov_b32 m0, s55
	s_nop 0
	global_load_lds_dwordx4 v[24:25], off
	v_lshl_add_u64 v[24:25], v[138:139], 0, s[10:11]
	s_mov_b32 m0, s56
	s_nop 0
	global_load_lds_dwordx4 v[24:25], off
	s_waitcnt vmcnt(8)
	s_waitcnt lgkmcnt(0)
	s_barrier
	s_setprio 1
	s_waitcnt lgkmcnt(0)
	v_mfma_f32_16x16x32_bf16 v[24:27], v[104:107], v[40:43], v[146:149]
	v_mfma_f32_16x16x32_bf16 v[88:91], v[108:111], v[44:47], v[24:27]
	v_mfma_f32_16x16x32_bf16 v[24:27], v[174:177], v[40:43], v[150:153]
	v_mfma_f32_16x16x32_bf16 v[92:95], v[194:197], v[44:47], v[24:27]
	v_mfma_f32_16x16x32_bf16 v[24:27], v[104:107], v[76:79], v[154:157]
	v_mfma_f32_16x16x32_bf16 v[56:59], v[108:111], v[178:181], v[24:27]
	v_mfma_f32_16x16x32_bf16 v[24:27], v[174:177], v[76:79], v[158:161]
	v_mfma_f32_16x16x32_bf16 v[60:63], v[194:197], v[178:181], v[24:27]
	v_mfma_f32_16x16x32_bf16 v[24:27], v[104:107], v[182:185], v[162:165]
	v_mfma_f32_16x16x32_bf16 v[28:31], v[174:177], v[182:185], v[166:169]
	v_mfma_f32_16x16x32_bf16 v[0:3], v[104:107], v[214:217], v[0:3]
	v_mfma_f32_16x16x32_bf16 v[4:7], v[174:177], v[214:217], v[4:7]
	v_mfma_f32_16x16x32_bf16 v[24:27], v[108:111], v[210:213], v[24:27]
	v_mfma_f32_16x16x32_bf16 v[28:31], v[194:197], v[210:213], v[28:31]
	v_mfma_f32_16x16x32_bf16 v[0:3], v[108:111], v[234:237], v[0:3]
	v_mfma_f32_16x16x32_bf16 v[4:7], v[194:197], v[234:237], v[4:7]
	v_mfma_f32_16x16x32_bf16 v[8:11], v[198:201], v[40:43], v[8:11]
	v_mfma_f32_16x16x32_bf16 v[104:107], v[222:225], v[44:47], v[8:11]
	v_mfma_f32_16x16x32_bf16 v[8:11], v[226:229], v[40:43], v[12:15]
	v_mfma_f32_16x16x32_bf16 v[108:111], v[230:233], v[44:47], v[8:11]
	v_mfma_f32_16x16x32_bf16 v[8:11], v[198:201], v[76:79], v[202:205]
	v_mfma_f32_16x16x32_bf16 v[72:75], v[222:225], v[178:181], v[8:11]
	v_mfma_f32_16x16x32_bf16 v[8:11], v[226:229], v[76:79], v[206:209]
	v_mfma_f32_16x16x32_bf16 v[76:79], v[230:233], v[178:181], v[8:11]
	v_mfma_f32_16x16x32_bf16 v[8:11], v[198:201], v[182:185], v[218:221]
	v_mfma_f32_16x16x32_bf16 v[40:43], v[222:225], v[210:213], v[8:11]
	v_mfma_f32_16x16x32_bf16 v[8:11], v[226:229], v[182:185], v[186:189]
	v_mfma_f32_16x16x32_bf16 v[44:47], v[230:233], v[210:213], v[8:11]
	v_mfma_f32_16x16x32_bf16 v[8:11], v[198:201], v[214:217], v[190:193]
	v_mfma_f32_16x16x32_bf16 v[12:15], v[226:229], v[214:217], v[170:173]
	v_mfma_f32_16x16x32_bf16 v[8:11], v[222:225], v[234:237], v[8:11]
	v_mfma_f32_16x16x32_bf16 v[12:15], v[230:233], v[234:237], v[12:15]
	s_setprio 0
	s_barrier
	s_andn2_b64 vcc, exec, s[12:13]
	s_cbranch_vccnz .LBB0_705
	s_barrier

; #define LAS __attribute__((address_space(3)))
; __device__ __forceinline__ void attn_bh(const Ctx& F, int b, int h) {
;     ...
;         f32x16 o0, o1;
; #pragma unroll
;         for (int r = 0; r < 16; ++r) { o0[r] = 0.f; o1[r] = 0.f; }
;         float mrun = -INFINITY, lrun = 0.f;
;         u32x4 kr0, kr1, vr;
;         kr0 = *(const u32x4*)(Kh + (size_t)tid * 8); kr1 = (u32x4){0u, 0u, 0u, 0u}; if (tid < 256) kr1 = *(const u32x4*)(Krp + (size_t)tid * 8); vr = *(const u32x4*)(Vh + (size_t)tid * 8);
;         for (int t = 0; t < NT; ++t) {
;             __syncthreads();
;             *(LAS u32x4*)(Kl + (tid >> 3) * KP + (tid & 7) * 16) = kr0;
;             if (tid < 256) *(LAS u32x4*)(Kl + (tid >> 2) * KP + 128 + (tid & 3) * 16) = kr1;
;             { const int kv = tid >> 3, dc = tid & 7;
; #pragma unroll
;               for (int j = 0; j < 4; ++j) { const unsigned wv = vr[j];
;                   *(LAS bf16_t*)(Vl + (8 * dc + 2 * j) * VP + kv * 2) = (bf16_t)(wv & 0xffffu); *(LAS bf16_t*)(Vl + (8 * dc + 2 * j + 1) * VP + kv * 2) = (bf16_t)(wv >> 16); } }
;             __syncthreads();
;             if (t + 1 < NT) { const bf16_t* kn = Kh + (size_t)(t + 1) * 64 * 64; const bf16_t* krn = Krp + (size_t)(t + 1) * 64 * 32; const bf16_t* vn = Vh + (size_t)(t + 1) * 64 * 64;
;                 kr0 = *(const u32x4*)(kn + (size_t)tid * 8); if (tid < 256) kr1 = *(const u32x4*)(krn + (size_t)tid * 8); vr = *(const u32x4*)(vn + (size_t)tid * 8); }
.LBB0_773:
	s_or_b64 exec, exec, s[18:19]
	global_load_dwordx4 v[98:101], v[108:109], off
	v_mov_b32_e32 v14, v0
	v_mov_b32_e32 v15, v0
	v_mov_b32_e32 v1, v0
	v_mov_b32_e32 v2, v0
	v_mov_b32_e32 v3, v0
	v_mov_b32_e32 v4, v0
	v_mov_b32_e32 v5, v0
	v_mov_b32_e32 v6, v0
	v_mov_b32_e32 v7, v0
	v_mov_b32_e32 v8, v0
	v_mov_b32_e32 v9, v0
	v_mov_b32_e32 v10, v0
	v_mov_b32_e32 v11, v0
	v_mov_b32_e32 v12, v0
	v_mov_b32_e32 v13, v0
	v_mov_b64_e32 v[32:33], v[14:15]
	s_add_i32 s38, s38, 1
	v_mov_b64_e32 v[30:31], v[12:13]
	v_mov_b64_e32 v[28:29], v[10:11]
	v_mov_b64_e32 v[26:27], v[8:9]
	v_mov_b64_e32 v[24:25], v[6:7]
	v_mov_b64_e32 v[22:23], v[4:5]
	v_mov_b64_e32 v[20:21], v[2:3]
	v_mov_b64_e32 v[18:19], v[0:1]
	v_mov_b64_e32 v[16:17], v[14:15]
	v_ashrrev_i32_e32 v117, 31, v116
	s_mov_b32 s40, 1
	s_lshl_b32 s41, s38, 2
	s_or_b32 s42, s39, 31
	v_subrev_u32_e32 v129, 32, v128
	v_subrev_u32_e32 v130, 33, v128
	v_subrev_u32_e32 v131, 34, v128
	v_subrev_u32_e32 v132, 35, v128
	v_add_u32_e32 v133, -8, v128
	v_subrev_u32_e32 v134, 40, v128
	v_add_u32_e32 v135, -9, v128
	v_subrev_u32_e32 v136, 41, v128
	v_add_u32_e32 v137, -10, v128
	v_subrev_u32_e32 v138, 42, v128
	v_add_u32_e32 v139, -11, v128
	v_subrev_u32_e32 v140, 43, v128
	v_add_u32_e32 v141, -16, v128
	v_subrev_u32_e32 v142, 48, v128
	v_subrev_u32_e32 v143, 17, v128
	v_subrev_u32_e32 v144, 49, v128
	v_subrev_u32_e32 v145, 18, v128
	v_subrev_u32_e32 v146, 50, v128
	v_subrev_u32_e32 v147, 19, v128
	v_subrev_u32_e32 v148, 51, v128
	v_subrev_u32_e32 v149, 24, v128
	v_subrev_u32_e32 v150, 56, v128
	v_subrev_u32_e32 v151, 25, v128
	v_subrev_u32_e32 v152, 57, v128
	v_subrev_u32_e32 v153, 26, v128
	v_subrev_u32_e32 v154, 58, v128
	v_subrev_u32_e32 v155, 27, v128
	v_subrev_u32_e32 v157, 59, v128
	v_mov_b32_e32 v158, 0xff800000
	v_mov_b32_e32 v156, 0
	s_mov_b32 s43, 63
	s_mov_b64 s[18:19], s[16:17]
	s_mov_b64 s[20:21], s[8:9]
	v_mov_b64_e32 v[14:15], v[12:13]
	v_mov_b64_e32 v[12:13], v[10:11]
	v_mov_b64_e32 v[10:11], v[8:9]
	v_mov_b64_e32 v[8:9], v[6:7]
	v_mov_b64_e32 v[6:7], v[4:5]
	v_mov_b64_e32 v[4:5], v[2:3]
	v_mov_b64_e32 v[2:3], v[0:1]
	s_waitcnt vmcnt(0)
	ds_write_b128 v113, v[90:93]
	s_and_saveexec_b64 s[22:23], s[4:5]
	ds_write_b128 v124, v[94:97] offset:128
	s_or_b64 exec, exec, s[22:23]
	ds_write_b16 v125, v98 offset:13312
	ds_write_b16_d16_hi v125, v98 offset:13448
	ds_write_b16 v125, v99 offset:13584
	ds_write_b16_d16_hi v125, v99 offset:13720
	ds_write_b16 v125, v100 offset:13856
	ds_write_b16_d16_hi v125, v100 offset:13992
	ds_write_b16 v125, v101 offset:14128
	ds_write_b16_d16_hi v125, v101 offset:14264
	v_lshl_add_u64 v[34:35], s[20:21], 0, v[104:105]
	global_load_dwordx4 v[90:93], v[34:35], off
	s_and_saveexec_b64 s[22:23], s[4:5]
	v_lshl_add_u64 v[36:37], s[18:19], 0, v[104:105]
	global_load_dwordx4 v[94:97], v[36:37], off
	s_or_b64 exec, exec, s[22:23]
	v_add_co_u32_e32 v34, vcc, 0x6000000, v34
	s_nop 1
	v_addc_co_u32_e32 v35, vcc, 0, v35, vcc
	global_load_dwordx4 v[98:101], v[34:35], off
	s_add_u32 s20, s20, 0x2000
	s_addc_u32 s21, s21, 0
	s_add_u32 s18, s18, 0x1000
	s_addc_u32 s19, s19, 0
	s_mov_b32 s60, 0
	s_mov_b32 s61, 0x5800
	s_branch .LBB0_776
; #define LAS __attribute__((address_space(3)))
; __device__ __forceinline__ void attn_bh(const Ctx& F, int b, int h) {
;     ...
;         for (int t = 0; t < NT; ++t) {
;             __syncthreads();
;             *(LAS u32x4*)(Kl + (tid >> 3) * KP + (tid & 7) * 16) = kr0;
;             if (tid < 256) *(LAS u32x4*)(Kl + (tid >> 2) * KP + 128 + (tid & 3) * 16) = kr1;
;             { const int kv = tid >> 3, dc = tid & 7;
; #pragma unroll
;               for (int j = 0; j < 4; ++j) { const unsigned wv = vr[j];
;                   *(LAS bf16_t*)(Vl + (8 * dc + 2 * j) * VP + kv * 2) = (bf16_t)(wv & 0xffffu); *(LAS bf16_t*)(Vl + (8 * dc + 2 * j + 1) * VP + kv * 2) = (bf16_t)(wv >> 16); } }
;             __syncthreads();
;             if (t + 1 < NT) { const bf16_t* kn = Kh + (size_t)(t + 1) * 64 * 64; const bf16_t* krn = Krp + (size_t)(t + 1) * 64 * 32; const bf16_t* vn = Vh + (size_t)(t + 1) * 64 * 64;
;     ...
;                 float ls = 0.f;
; #pragma unroll
;                 for (int r = 0; r < 16; ++r) { p0[r] = __builtin_amdgcn_exp2f(p0[r] - mrun); p1[r] = __builtin_amdgcn_exp2f(p1[r] - mrun); ls += p0[r] + p1[r]; }
;                 lrun += ls;
;                 bf16x8 pk[4];
; #pragma unroll
;                 for (int c2 = 0; c2 < 2; ++c2) {
;                     u32x4 a, bq;
; #pragma unroll
;                     for (int j = 0; j < 4; ++j) { a[j] = pk2(p0[8 * c2 + 2 * j], p0[8 * c2 + 2 * j + 1]); bq[j] = pk2(p1[8 * c2 + 2 * j], p1[8 * c2 + 2 * j + 1]); }
;                     pk[c2] = __builtin_bit_cast(bf16x8, a); pk[2 + c2] = __builtin_bit_cast(bf16x8, bq);
;                 }
; #pragma unroll
;                 for (int hc = 0; hc < 4; ++hc) {
;                     const int kvb = 16 * hc + 4 * hi;
;                     const u32x2 l0 = *(const LAS u32x2*)(Vl + q31 * VP + kvb * 2), h0 = *(const LAS u32x2*)(Vl + q31 * VP + (kvb + 8) * 2);
;                     const u32x2 l1 = *(const LAS u32x2*)(Vl + (32 + q31) * VP + kvb * 2), h1 = *(const LAS u32x2*)(Vl + (32 + q31) * VP + (kvb + 8) * 2);
;                     const u32x4 va = {l0.x, l0.y, h0.x, h0.y}, vb = {l1.x, l1.y, h1.x, h1.y};
;                     o0 = __builtin_amdgcn_mfma_f32_32x32x16_bf16(__builtin_bit_cast(bf16x8, va), pk[hc], o0, 0, 0, 0);
;                     o1 = __builtin_amdgcn_mfma_f32_32x32x16_bf16(__builtin_bit_cast(bf16x8, vb), pk[hc], o1, 0, 0, 0);
;                 }
.LBB0_774:
	v_sub_f32_e32 v34, v34, v158
	v_exp_f32_e32 v159, v34
	v_sub_f32_e32 v34, v51, v158
	v_exp_f32_e32 v166, v34
	v_sub_f32_e32 v34, v35, v158
	v_sub_f32_e32 v1, v50, v158
	v_exp_f32_e32 v167, v34
	v_sub_f32_e32 v34, v52, v158
	v_exp_f32_e32 v1, v1
	v_exp_f32_e32 v168, v34
	v_sub_f32_e32 v34, v36, v158
	v_sub_f32_e32 v36, v53, v158
	v_exp_f32_e32 v170, v36
	v_sub_f32_e32 v36, v37, v158
	v_exp_f32_e32 v171, v36
	v_sub_f32_e32 v36, v54, v158
	v_exp_f32_e32 v51, v36
	v_sub_f32_e32 v36, v38, v158
	v_add_f32_e32 v50, v1, v159
	v_exp_f32_e32 v169, v34
	v_exp_f32_e32 v161, v36
	v_sub_f32_e32 v36, v55, v158
	v_add_f32_e32 v34, 0, v50
	v_exp_f32_e32 v50, v36
	v_sub_f32_e32 v36, v39, v158
	v_exp_f32_e32 v160, v36
	v_add_f32_e32 v35, v166, v167
	v_add_f32_e32 v34, v35, v34
	v_add_f32_e32 v35, v168, v169
	v_add_f32_e32 v34, v35, v34
	v_add_f32_e32 v35, v170, v171
	v_add_f32_e32 v36, v35, v34
	v_pk_add_f32 v[34:35], v[50:51], v[160:161]
	v_add_u32_e32 v173, 0x3000, v175
	v_add_f32_e32 v35, v35, v36
	v_add_f32_e32 v36, v34, v35
	v_sub_f32_e32 v34, v56, v158
	v_exp_f32_e32 v53, v34
	v_sub_f32_e32 v34, v40, v158
	v_exp_f32_e32 v55, v34
	v_sub_f32_e32 v34, v57, v158
	v_exp_f32_e32 v52, v34
	v_sub_f32_e32 v34, v41, v158
	v_exp_f32_e32 v54, v34
	v_sub_f32_e32 v34, v58, v158
	v_exp_f32_e32 v57, v34
	v_sub_f32_e32 v34, v42, v158
	v_exp_f32_e32 v163, v34
	v_sub_f32_e32 v34, v59, v158
	v_exp_f32_e32 v56, v34
	v_sub_f32_e32 v34, v43, v158
	v_exp_f32_e32 v162, v34
	v_pk_add_f32 v[34:35], v[52:53], v[54:55]
	v_cvt_pk_bf16_f32 v38, v1, v166
	v_add_f32_e32 v35, v35, v36
	v_add_f32_e32 v36, v34, v35
	v_pk_add_f32 v[34:35], v[56:57], v[162:163]
	v_pk_mov_b32 v[40:41], v[50:51], v[50:51] op_sel:[1,0]
	v_add_f32_e32 v35, v35, v36
	v_add_f32_e32 v172, v34, v35
	v_sub_f32_e32 v34, v60, v158
	v_exp_f32_e32 v59, v34
	v_sub_f32_e32 v34, v44, v158
	v_exp_f32_e32 v165, v34
	v_sub_f32_e32 v34, v61, v158
	v_exp_f32_e32 v58, v34
	v_sub_f32_e32 v34, v45, v158
	v_exp_f32_e32 v164, v34
	v_sub_f32_e32 v34, v62, v158
	v_exp_f32_e32 v61, v34
	v_sub_f32_e32 v34, v63, v158
	v_exp_f32_e32 v60, v34
	ds_read2_b64 v[34:37], v173 offset0:128 offset1:130
	v_pk_mov_b32 v[42:43], v[52:53], v[52:53] op_sel:[1,0]
	v_add_u32_e32 v1, 0x4000, v175
	v_cvt_pk_bf16_f32 v40, v40, v41
	v_cvt_pk_bf16_f32 v41, v42, v43
	ds_read2_b64 v[42:45], v1 offset0:160 offset1:162
	v_cvt_pk_bf16_f32 v39, v168, v170
	ds_read2_b64 v[50:53], v173 offset0:132 offset1:134
	s_waitcnt lgkmcnt(2)
	v_mfma_f32_32x32x16_bf16 v[18:33], v[34:37], v[38:41], v[18:33]
	v_sub_f32_e32 v34, v64, v158
	v_exp_f32_e32 v63, v34
	v_sub_f32_e32 v34, v65, v158
	v_exp_f32_e32 v62, v34
	v_pk_mov_b32 v[34:35], v[56:57], v[56:57] op_sel:[1,0]
	v_pk_mov_b32 v[36:37], v[58:59], v[58:59] op_sel:[1,0]
	v_cvt_pk_bf16_f32 v34, v34, v35
	s_waitcnt lgkmcnt(1)
	v_mfma_f32_32x32x16_bf16 v[2:17], v[42:45], v[38:41], v[2:17]
	v_cvt_pk_bf16_f32 v35, v36, v37
	v_pk_mov_b32 v[36:37], v[60:61], v[60:61] op_sel:[1,0]
	v_pk_mov_b32 v[38:39], v[62:63], v[62:63] op_sel:[1,0]
	v_cvt_pk_bf16_f32 v36, v36, v37
	v_cvt_pk_bf16_f32 v37, v38, v39
	ds_read2_b64 v[38:41], v1 offset0:164 offset1:166
	v_sub_f32_e32 v42, v46, v158
	s_waitcnt lgkmcnt(1)
	v_mfma_f32_32x32x16_bf16 v[18:33], v[50:53], v[34:37], v[18:33]
	v_exp_f32_e32 v53, v42
	v_sub_f32_e32 v42, v47, v158
	v_exp_f32_e32 v52, v42
	ds_read2_b64 v[42:45], v173 offset0:136 offset1:138
	v_pk_add_f32 v[50:51], v[58:59], v[164:165]
	s_nop 0
	v_add_f32_e32 v51, v51, v172
	s_waitcnt lgkmcnt(1)
	v_mfma_f32_32x32x16_bf16 v[2:17], v[38:41], v[34:37], v[2:17]
	v_pk_mov_b32 v[36:37], v[160:161], v[160:161] op_sel:[1,0]
	v_pk_mov_b32 v[38:39], v[54:55], v[54:55] op_sel:[1,0]
	v_cvt_pk_bf16_f32 v36, v36, v37
	v_cvt_pk_bf16_f32 v37, v38, v39
	ds_read2_b64 v[38:41], v1 offset0:168 offset1:170
	v_cvt_pk_bf16_f32 v34, v159, v167
	v_cvt_pk_bf16_f32 v35, v169, v171
	s_waitcnt lgkmcnt(1)
	s_nop 0
	v_mfma_f32_32x32x16_bf16 v[18:33], v[42:45], v[34:37], v[18:33]
	v_sub_f32_e32 v42, v48, v158
	v_exp_f32_e32 v55, v42
	v_sub_f32_e32 v42, v49, v158
	v_exp_f32_e32 v54, v42
	v_pk_mov_b32 v[42:43], v[162:163], v[162:163] op_sel:[1,0]
	ds_read2_b64 v[46:49], v173 offset0:140 offset1:142
	v_cvt_pk_bf16_f32 v42, v42, v43
	s_waitcnt lgkmcnt(1)
	v_mfma_f32_32x32x16_bf16 v[2:17], v[38:41], v[34:37], v[2:17]
	v_pk_mov_b32 v[34:35], v[164:165], v[164:165] op_sel:[1,0]
	v_pk_add_f32 v[38:39], v[60:61], v[52:53]
	v_cvt_pk_bf16_f32 v43, v34, v35
	v_pk_mov_b32 v[34:35], v[52:53], v[52:53] op_sel:[1,0]
	s_nop 0
	v_cvt_pk_bf16_f32 v44, v34, v35
	v_pk_mov_b32 v[34:35], v[54:55], v[54:55] op_sel:[1,0]
	s_nop 0
	v_cvt_pk_bf16_f32 v45, v34, v35
	ds_read2_b64 v[34:37], v1 offset0:172 offset1:174
	v_add_f32_e32 v1, v50, v51
	s_waitcnt lgkmcnt(1)
	v_mfma_f32_32x32x16_bf16 v[18:33], v[46:49], v[42:45], v[18:33]
	v_add_f32_e32 v1, v39, v1
	v_add_f32_e32 v1, v38, v1
	v_add_f32_e64 v38, v62, v54
	v_add_f32_e64 v39, v63, v55
	v_add_f32_e32 v1, v39, v1
	v_add_f32_e32 v1, v38, v1
	v_add_f32_e32 v156, v156, v1
	s_waitcnt lgkmcnt(0)
	v_mfma_f32_32x32x16_bf16 v[2:17], v[34:37], v[42:45], v[2:17]
.LBB0_775:
	s_cmp_lt_u32 s50, 4
	s_cbranch_scc1 .Lat_stage
.Lat_latch:
	s_xor_b32 s60, s60, 0x5800
	s_xor_b32 s61, s61, 0x5800
	s_add_i32 s43, s43, 64
	s_add_u32 s20, s20, 0x2000
	s_addc_u32 s21, s21, 0
	s_add_u32 s18, s18, 0x1000
	s_addc_u32 s19, s19, 0
	s_add_i32 s22, s37, s43
	s_add_i32 s40, s40, 1
	s_cmp_eq_u32 s22, 63
	s_cbranch_scc1 .LBB0_770
.LBB0_776:
	s_waitcnt lgkmcnt(0)
	s_barrier
	v_add_u32_e32 v174, s60, v126
	v_add_u32_e32 v175, s60, v127
	s_cmp_lt_u32 s50, 4
	s_cbranch_scc1 .LBB0_782
.Lat_stage:
	s_cmp_ge_u32 s40, s41
	s_cbranch_scc1 .Lat_stage_done
	s_waitcnt vmcnt(0)
	v_add_u32_e32 v176, s61, v113
	v_add_u32_e32 v177, s61, v124
	v_add_u32_e32 v178, s61, v125
	ds_write_b128 v176, v[90:93]
	s_and_saveexec_b64 s[22:23], s[4:5]
	ds_write_b128 v177, v[94:97] offset:128
	s_or_b64 exec, exec, s[22:23]
	ds_write_b16 v178, v98 offset:13312
	ds_write_b16_d16_hi v178, v98 offset:13448
	ds_write_b16 v178, v99 offset:13584
	ds_write_b16_d16_hi v178, v99 offset:13720
	ds_write_b16 v178, v100 offset:13856
	ds_write_b16_d16_hi v178, v100 offset:13992
	ds_write_b16 v178, v101 offset:14128
	ds_write_b16_d16_hi v178, v101 offset:14264
	s_add_i32 s62, s40, 1
	s_cmp_ge_u32 s62, s41
	s_cbranch_scc1 .Lat_stage_done
	v_lshl_add_u64 v[34:35], s[20:21], 0, v[104:105]
	global_load_dwordx4 v[90:93], v[34:35], off
	s_and_saveexec_b64 s[22:23], s[4:5]
	v_lshl_add_u64 v[36:37], s[18:19], 0, v[104:105]
	global_load_dwordx4 v[94:97], v[36:37], off
	s_or_b64 exec, exec, s[22:23]
	v_add_co_u32_e32 v34, vcc, 0x6000000, v34
	s_nop 1
	v_addc_co_u32_e32 v35, vcc, 0, v35, vcc
	global_load_dwordx4 v[98:101], v[34:35], off

; #define LAS __attribute__((address_space(3)))
; __device__ __forceinline__ int crow(int r, int hi) { return (r & 3) + 8 * (r >> 2) + 4 * hi; }
; __device__ __forceinline__ void attn_bh(const Ctx& F, int b, int h) {
;     ...
;                 for (int d0 = 0; d0 < 6; ++d0) {
;                     const bf16x8 a0 = *(const LAS bf16x8*)(Kl + q31 * KP + (16 * d0 + 8 * hi) * 2);
;                     const bf16x8 a1 = *(const LAS bf16x8*)(Kl + (32 + q31) * KP + (16 * d0 + 8 * hi) * 2);
;                     p0 = __builtin_amdgcn_mfma_f32_32x32x16_bf16(a0, qf[d0], p0, 0, 0, 0);
;                     p1 = __builtin_amdgcn_mfma_f32_32x32x16_bf16(a1, qf[d0], p1, 0, 0, 0);
;                 }
;                 if (kv0 + 63 > q0 + 32 * w) {
; #pragma unroll
;                     for (int r = 0; r < 16; ++r) { const int kv = kv0 + crow(r, hi); if (kv > qrow) p0[r] = -INFINITY; if (kv + 32 > qrow) p1[r] = -INFINITY; }
.LBB0_782:
	s_sub_i32 s22, s43, 63
	s_cmp_gt_u32 s22, s42
	s_cbranch_scc1 .LBB0_775
	ds_read_b128 v[34:37], v174
	ds_read_b128 v[160:163], v174 offset:32
	s_cmp_le_u32 s43, s39
	s_waitcnt lgkmcnt(1)
	v_mfma_f32_32x32x16_bf16 v[50:65], v[34:37], v[86:89], 0
	ds_read_b128 v[34:37], v174 offset:6656
	ds_read_b128 v[164:167], v174 offset:6688
	s_waitcnt lgkmcnt(1)
	v_mfma_f32_32x32x16_bf16 v[34:49], v[34:37], v[86:89], 0
	v_mfma_f32_32x32x16_bf16 v[50:65], v[160:163], v[66:69], v[50:65]
	s_waitcnt lgkmcnt(0)
	v_mfma_f32_32x32x16_bf16 v[34:49], v[164:167], v[66:69], v[34:49]
	ds_read_b128 v[160:163], v174 offset:64
	ds_read_b128 v[164:167], v174 offset:96
	s_waitcnt lgkmcnt(1)
	v_mfma_f32_32x32x16_bf16 v[50:65], v[160:163], v[70:73], v[50:65]
	ds_read_b128 v[160:163], v174 offset:6720
	ds_read_b128 v[168:171], v174 offset:6752
	s_waitcnt lgkmcnt(1)
	v_mfma_f32_32x32x16_bf16 v[34:49], v[160:163], v[70:73], v[34:49]
	v_mfma_f32_32x32x16_bf16 v[50:65], v[164:167], v[74:77], v[50:65]
	ds_read_b128 v[160:163], v174 offset:128
	ds_read_b128 v[164:167], v174 offset:160
	s_waitcnt lgkmcnt(2)
	v_mfma_f32_32x32x16_bf16 v[34:49], v[168:171], v[74:77], v[34:49]
	s_waitcnt lgkmcnt(1)
	v_mfma_f32_32x32x16_bf16 v[50:65], v[160:163], v[78:81], v[50:65]
	ds_read_b128 v[160:163], v174 offset:6784
	ds_read_b128 v[168:171], v174 offset:6816
	s_waitcnt lgkmcnt(1)
	v_mfma_f32_32x32x16_bf16 v[34:49], v[160:163], v[78:81], v[34:49]
	v_mfma_f32_32x32x16_bf16 v[50:65], v[164:167], v[82:85], v[50:65]
	s_waitcnt lgkmcnt(0)
	v_mfma_f32_32x32x16_bf16 v[34:49], v[168:171], v[82:85], v[34:49]
	s_cbranch_scc1 .LBB0_785
	v_add_u32_e32 v1, s43, v112
	v_subrev_u32_e32 v159, 63, v1
	v_cmp_le_i32_e32 vcc, v159, v129
	v_subrev_u32_e32 v160, 61, v1
	v_subrev_u32_e32 v1, 60, v1
	s_nop 5
	v_cndmask_b32_e32 v34, v121, v34, vcc
	v_cmp_lt_i32_e32 vcc, v159, v128
	s_nop 1
	v_cndmask_b32_e32 v51, v121, v51, vcc
	v_cmp_le_i32_e32 vcc, v159, v128
	s_nop 1
	v_cndmask_b32_e32 v50, v121, v50, vcc
	v_cmp_le_i32_e32 vcc, v159, v130
	s_nop 1
	v_cndmask_b32_e32 v35, v121, v35, vcc
	v_cmp_le_i32_e32 vcc, v160, v128
	s_nop 1
	v_cndmask_b32_e32 v52, v121, v52, vcc
	v_cmp_le_i32_e32 vcc, v159, v131
	s_nop 1
	v_cndmask_b32_e32 v36, v121, v36, vcc
	v_cmp_le_i32_e32 vcc, v1, v128
	s_nop 1
	v_cndmask_b32_e32 v53, v121, v53, vcc
	v_cmp_le_i32_e32 vcc, v159, v132
	s_nop 1
	v_cndmask_b32_e32 v37, v121, v37, vcc
	v_cmp_le_i32_e32 vcc, v159, v133
	s_nop 1
	v_cndmask_b32_e32 v54, v121, v54, vcc
	v_cmp_le_i32_e32 vcc, v159, v134
	s_nop 1
	v_cndmask_b32_e32 v38, v121, v38, vcc
	v_cmp_le_i32_e32 vcc, v159, v135
	s_nop 1
	v_cndmask_b32_e32 v55, v121, v55, vcc
	v_cmp_le_i32_e32 vcc, v159, v136
	s_nop 1
	v_cndmask_b32_e32 v39, v121, v39, vcc
	v_cmp_le_i32_e32 vcc, v159, v137
	s_nop 1
	v_cndmask_b32_e32 v56, v121, v56, vcc
	v_cmp_le_i32_e32 vcc, v159, v138
	s_nop 1
	v_cndmask_b32_e32 v40, v121, v40, vcc
	v_cmp_le_i32_e32 vcc, v159, v139
	s_nop 1
	v_cndmask_b32_e32 v57, v121, v57, vcc
	v_cmp_le_i32_e32 vcc, v159, v140
	s_nop 1
	v_cndmask_b32_e32 v41, v121, v41, vcc
	v_cmp_le_i32_e32 vcc, v159, v141
	s_nop 1
	v_cndmask_b32_e32 v58, v121, v58, vcc
	v_cmp_le_i32_e32 vcc, v159, v142
	s_nop 1
	v_cndmask_b32_e32 v42, v121, v42, vcc
	v_cmp_le_i32_e32 vcc, v159, v143
	s_nop 1
	v_cndmask_b32_e32 v59, v121, v59, vcc
	v_cmp_le_i32_e32 vcc, v159, v144
	s_nop 1
	v_cndmask_b32_e32 v43, v121, v43, vcc
	v_cmp_le_i32_e32 vcc, v159, v145
	s_nop 1
	v_cndmask_b32_e32 v60, v121, v60, vcc
	v_cmp_le_i32_e32 vcc, v159, v146
	s_nop 1
	v_cndmask_b32_e32 v44, v121, v44, vcc
	v_cmp_le_i32_e32 vcc, v159, v147
	s_nop 1
	v_cndmask_b32_e32 v61, v121, v61, vcc
	v_cmp_le_i32_e32 vcc, v159, v148
	s_nop 1
	v_cndmask_b32_e32 v45, v121, v45, vcc
	v_cmp_le_i32_e32 vcc, v159, v149
	s_nop 1
	v_cndmask_b32_e32 v62, v121, v62, vcc
	v_cmp_le_i32_e32 vcc, v159, v150
	s_nop 1
	v_cndmask_b32_e32 v46, v121, v46, vcc
	v_cmp_le_i32_e32 vcc, v159, v151
	s_nop 1
	v_cndmask_b32_e32 v63, v121, v63, vcc
	v_cmp_le_i32_e32 vcc, v159, v152
	s_nop 1
	v_cndmask_b32_e32 v47, v121, v47, vcc
	v_cmp_le_i32_e32 vcc, v159, v153
	s_nop 1
	v_cndmask_b32_e32 v64, v121, v64, vcc
	v_cmp_le_i32_e32 vcc, v159, v154
	s_nop 1
	v_cndmask_b32_e32 v48, v121, v48, vcc
	v_cmp_le_i32_e32 vcc, v159, v155
	s_nop 1
	v_cndmask_b32_e32 v65, v121, v65, vcc
	v_cmp_le_i32_e32 vcc, v159, v157
	s_nop 1
	v_cndmask_b32_e32 v49, v121, v49, vcc

; #define PG8_STAGE(bufoff, gbase, voff) do { _Pragma("unroll") for (int _i = 0; _i < 2; ++_i) \
;         __builtin_amdgcn_global_load_lds((const unsigned*)((const char*)(gbase) + (voff)[_i]), (LAS unsigned*)(lds + (bufoff) + ldsw + _i * 8192), 16, 0, 0); } while (0)
; #define PG8_LDA(dst, b, h) do { _Pragma("unroll") for (int m = 0; m < 4; ++m) _Pragma("unroll") for (int k = 0; k < 2; ++k) dst[m][k] = *(const LAS bf16x8*)(lds + PG8_SA(b, h) + aoff + m * 2048 + k * 1024); } while (0)
; #define PG8_LDB(dst, b, h) do { _Pragma("unroll") for (int n = 0; n < 2; ++n) _Pragma("unroll") for (int k = 0; k < 2; ++k) dst[n][k] = *(const LAS bf16x8*)(lds + PG8_SB(b, h) + boff + n * 2048 + k * 1024); } while (0)
; #define PG8_MMA(ai, bj, At, Bt) do { __builtin_amdgcn_s_setprio(1); _Pragma("unroll") for (int m = 0; m < 4; ++m) _Pragma("unroll") for (int n = 0; n < 2; ++n) _Pragma("unroll") for (int k = 0; k < 2; ++k) \
;         acc[ai][bj][m][n] = __builtin_amdgcn_mfma_f32_16x16x32_bf16(Bt[n][k], At[m][k], acc[ai][bj][m][n], 0, 0, 0); __builtin_amdgcn_s_setprio(0); } while (0)
; #define PG8_WAIT_V(n) asm volatile("s_waitcnt vmcnt(" #n ")" ::: "memory")
; #define PG8_WAIT_L(n) asm volatile("s_waitcnt lgkmcnt(" #n ")" ::: "memory")
; #define PG8_BAR __builtin_amdgcn_s_barrier()
; #define PG8_SCHED __builtin_amdgcn_sched_barrier(0)
; template <class Epi, bool ALIGN_EPI, int K, int LDA, int LDB>
; __device__ __forceinline__ void gemm_phase(LAS unsigned char* lds, const int wid, const Gemm g, const StaticOrder& S, const Epi& E) {
;     ...
;             const char* a1 = cA + (size_t)(t + 1) * kstep;
;             const char* a2 = last ? nA : cA + (size_t)(t + 2) * kstep; const char* b2 = last ? nB : cB + (size_t)(t + 2) * kstep;
;             const char* a3 = a2 + kstep; const char* b3 = b2 + kstep;
;             PG8_LDB(B0, 0, 0); PG8_LDB(B1, 0, 1); PG8_SCHED; PG8_LDA(At, 0, 0); PG8_STAGE(PG8_SA(1, 1), a1 + hA, voffA);
;             PG8_WAIT_V(8); PG8_WAIT_L(0); PG8_BAR; PG8_MMA(0, 0, At, B0); PG8_MMA(0, 1, At, B1); PG8_BAR; PG8_SCHED;
;             PG8_LDA(At, 0, 1); PG8_STAGE(PG8_SB(0, 0), b2, voffB); PG8_STAGE(PG8_SB(0, 1), b2 + hB, voffB); PG8_STAGE(PG8_SA(0, 0), a2, voffA);
;             PG8_WAIT_V(8); PG8_WAIT_L(0); PG8_BAR; PG8_MMA(1, 0, At, B0); PG8_MMA(1, 1, At, B1); PG8_BAR; PG8_SCHED;
.LBB0_917:
	ds_read_b128 v[128:131], v163
	ds_read_b128 v[132:135], v163 offset:1024
	ds_read_b128 v[136:139], v163 offset:2048
	ds_read_b128 v[140:143], v163 offset:3072
	ds_read_b128 v[166:169], v164
	ds_read_b128 v[170:173], v164 offset:1024
	ds_read_b128 v[174:177], v164 offset:2048
	ds_read_b128 v[178:181], v164 offset:3072
	s_add_u32 s38, s36, 0xfffc0080
	s_addc_u32 s39, s37, -1
	s_cmp_eq_u32 s67, 12
	s_cselect_b32 s41, s27, s39
	s_cselect_b32 s40, s63, s38
	s_cselect_b32 s39, s25, s66
	s_cselect_b32 s38, s64, s65
	s_add_i32 m0, s35, 0xc000
	ds_read_b128 v[182:185], v165
	ds_read_b128 v[186:189], v165 offset:1024
	ds_read_b128 v[190:193], v165 offset:2048
	ds_read_b128 v[194:197], v165 offset:3072
	ds_read_b128 v[198:201], v165 offset:4096
	ds_read_b128 v[202:205], v165 offset:5120
	ds_read_b128 v[206:209], v165 offset:6144
	ds_read_b128 v[210:213], v165 offset:7168
	global_load_lds_dwordx4 v152, s[36:37]
	s_add_i32 m0, s35, 0xe000
	s_nop 0
	global_load_lds_dwordx4 v154, s[36:37]
	s_waitcnt vmcnt(8)
	s_waitcnt lgkmcnt(0)
	s_barrier
	s_setprio 1
	s_waitcnt lgkmcnt(0)
	v_mfma_f32_16x16x32_bf16 v[124:127], v[128:131], v[182:185], v[124:127]
	v_mfma_f32_16x16x32_bf16 v[120:123], v[136:139], v[182:185], v[120:123]
	v_mfma_f32_16x16x32_bf16 v[108:111], v[128:131], v[190:193], v[108:111]
	v_mfma_f32_16x16x32_bf16 v[104:107], v[136:139], v[190:193], v[104:107]
	v_mfma_f32_16x16x32_bf16 v[92:95], v[128:131], v[198:201], v[92:95]
	v_mfma_f32_16x16x32_bf16 v[88:91], v[136:139], v[198:201], v[88:91]
	v_mfma_f32_16x16x32_bf16 v[76:79], v[128:131], v[206:209], v[76:79]
	v_mfma_f32_16x16x32_bf16 v[72:75], v[136:139], v[206:209], v[72:75]
	v_mfma_f32_16x16x32_bf16 v[124:127], v[132:135], v[186:189], v[124:127]
	v_mfma_f32_16x16x32_bf16 v[120:123], v[140:143], v[186:189], v[120:123]
	v_mfma_f32_16x16x32_bf16 v[108:111], v[132:135], v[194:197], v[108:111]
	v_mfma_f32_16x16x32_bf16 v[104:107], v[140:143], v[194:197], v[104:107]
	v_mfma_f32_16x16x32_bf16 v[92:95], v[132:135], v[202:205], v[92:95]
	v_mfma_f32_16x16x32_bf16 v[88:91], v[140:143], v[202:205], v[88:91]
	v_mfma_f32_16x16x32_bf16 v[76:79], v[132:135], v[210:213], v[76:79]
	v_mfma_f32_16x16x32_bf16 v[72:75], v[140:143], v[210:213], v[72:75]
	v_mfma_f32_16x16x32_bf16 v[116:119], v[166:169], v[182:185], v[116:119]
	v_mfma_f32_16x16x32_bf16 v[112:115], v[174:177], v[182:185], v[112:115]
	v_mfma_f32_16x16x32_bf16 v[100:103], v[166:169], v[190:193], v[100:103]
	v_mfma_f32_16x16x32_bf16 v[96:99], v[174:177], v[190:193], v[96:99]
	v_mfma_f32_16x16x32_bf16 v[84:87], v[166:169], v[198:201], v[84:87]
	v_mfma_f32_16x16x32_bf16 v[80:83], v[174:177], v[198:201], v[80:83]
	v_mfma_f32_16x16x32_bf16 v[68:71], v[166:169], v[206:209], v[68:71]
	v_mfma_f32_16x16x32_bf16 v[64:67], v[174:177], v[206:209], v[64:67]
	v_mfma_f32_16x16x32_bf16 v[116:119], v[170:173], v[186:189], v[116:119]
	v_mfma_f32_16x16x32_bf16 v[112:115], v[178:181], v[186:189], v[112:115]
	v_mfma_f32_16x16x32_bf16 v[100:103], v[170:173], v[194:197], v[100:103]
	v_mfma_f32_16x16x32_bf16 v[96:99], v[178:181], v[194:197], v[96:99]
	v_mfma_f32_16x16x32_bf16 v[84:87], v[170:173], v[202:205], v[84:87]
	v_mfma_f32_16x16x32_bf16 v[80:83], v[178:181], v[202:205], v[80:83]
	v_mfma_f32_16x16x32_bf16 v[68:71], v[170:173], v[210:213], v[68:71]
	v_mfma_f32_16x16x32_bf16 v[64:67], v[178:181], v[210:213], v[64:67]
	s_setprio 0
	s_barrier
	s_add_u32 s98, s38, s12
	s_addc_u32 s99, s39, s13
	s_add_u32 s100, s40, s12
	s_addc_u32 s101, s41, s13
	s_add_i32 s52, s58, s33
	s_mov_b32 m0, s52
	ds_read_b128 v[182:185], v165 offset:16384
	ds_read_b128 v[186:189], v165 offset:17408
	ds_read_b128 v[190:193], v165 offset:18432
	ds_read_b128 v[194:197], v165 offset:19456
	ds_read_b128 v[198:201], v165 offset:20480
	ds_read_b128 v[202:205], v165 offset:21504
	ds_read_b128 v[206:209], v165 offset:22528
	ds_read_b128 v[210:213], v165 offset:23552
	global_load_lds_dwordx4 v146, s[38:39]
	s_add_i32 m0, s52, 0x2000
	s_add_u32 s68, s38, 0x40000
	s_addc_u32 s69, s39, 0
	s_add_i32 s52, s59, s33
	global_load_lds_dwordx4 v150, s[38:39]
	s_mov_b32 m0, s52
	s_nop 0
	global_load_lds_dwordx4 v146, s[68:69]
	s_add_i32 m0, s52, 0x2000
	s_nop 0
	global_load_lds_dwordx4 v150, s[68:69]
	s_mov_b32 m0, s35
	s_nop 0
	global_load_lds_dwordx4 v144, s[40:41]
	s_mov_b32 m0, s42
	s_nop 0
	global_load_lds_dwordx4 v148, s[40:41]
	s_waitcnt vmcnt(8)
	s_waitcnt lgkmcnt(0)
	s_barrier
	s_setprio 1
	s_waitcnt lgkmcnt(0)
	v_mfma_f32_16x16x32_bf16 v[60:63], v[128:131], v[182:185], v[60:63]
	v_mfma_f32_16x16x32_bf16 v[56:59], v[136:139], v[182:185], v[56:59]
	v_mfma_f32_16x16x32_bf16 v[44:47], v[128:131], v[190:193], v[44:47]
	v_mfma_f32_16x16x32_bf16 v[40:43], v[136:139], v[190:193], v[40:43]
	v_mfma_f32_16x16x32_bf16 v[28:31], v[128:131], v[198:201], v[28:31]
	v_mfma_f32_16x16x32_bf16 v[24:27], v[136:139], v[198:201], v[24:27]
	v_mfma_f32_16x16x32_bf16 v[12:15], v[128:131], v[206:209], v[12:15]
	v_mfma_f32_16x16x32_bf16 v[8:11], v[136:139], v[206:209], v[8:11]
	v_mfma_f32_16x16x32_bf16 v[60:63], v[132:135], v[186:189], v[60:63]
	v_mfma_f32_16x16x32_bf16 v[56:59], v[140:143], v[186:189], v[56:59]
	v_mfma_f32_16x16x32_bf16 v[44:47], v[132:135], v[194:197], v[44:47]
	v_mfma_f32_16x16x32_bf16 v[40:43], v[140:143], v[194:197], v[40:43]
	v_mfma_f32_16x16x32_bf16 v[28:31], v[132:135], v[202:205], v[28:31]
	v_mfma_f32_16x16x32_bf16 v[24:27], v[140:143], v[202:205], v[24:27]
	v_mfma_f32_16x16x32_bf16 v[12:15], v[132:135], v[210:213], v[12:15]
	v_mfma_f32_16x16x32_bf16 v[8:11], v[140:143], v[210:213], v[8:11]
	v_mfma_f32_16x16x32_bf16 v[52:55], v[166:169], v[182:185], v[52:55]
	v_mfma_f32_16x16x32_bf16 v[48:51], v[174:177], v[182:185], v[48:51]
	v_mfma_f32_16x16x32_bf16 v[36:39], v[166:169], v[190:193], v[36:39]
	v_mfma_f32_16x16x32_bf16 v[32:35], v[174:177], v[190:193], v[32:35]
	v_mfma_f32_16x16x32_bf16 v[20:23], v[166:169], v[198:201], v[20:23]
	v_mfma_f32_16x16x32_bf16 v[16:19], v[174:177], v[198:201], v[16:19]
	v_mfma_f32_16x16x32_bf16 v[4:7], v[166:169], v[206:209], v[4:7]
	v_mfma_f32_16x16x32_bf16 v[0:3], v[174:177], v[206:209], v[0:3]
	v_mfma_f32_16x16x32_bf16 v[52:55], v[170:173], v[186:189], v[52:55]
	v_mfma_f32_16x16x32_bf16 v[48:51], v[178:181], v[186:189], v[48:51]
	v_mfma_f32_16x16x32_bf16 v[36:39], v[170:173], v[194:197], v[36:39]
	v_mfma_f32_16x16x32_bf16 v[32:35], v[178:181], v[194:197], v[32:35]
	v_mfma_f32_16x16x32_bf16 v[20:23], v[170:173], v[202:205], v[20:23]
	v_mfma_f32_16x16x32_bf16 v[16:19], v[178:181], v[202:205], v[16:19]
	v_mfma_f32_16x16x32_bf16 v[4:7], v[170:173], v[210:213], v[4:7]
	v_mfma_f32_16x16x32_bf16 v[0:3], v[178:181], v[210:213], v[0:3]
	s_setprio 0
	s_barrier
; #define PG8_STAGE(bufoff, gbase, voff) do { _Pragma("unroll") for (int _i = 0; _i < 2; ++_i) \
;         __builtin_amdgcn_global_load_lds((const unsigned*)((const char*)(gbase) + (voff)[_i]), (LAS unsigned*)(lds + (bufoff) + ldsw + _i * 8192), 16, 0, 0); } while (0)
; #define PG8_LDA(dst, b, h) do { _Pragma("unroll") for (int m = 0; m < 4; ++m) _Pragma("unroll") for (int k = 0; k < 2; ++k) dst[m][k] = *(const LAS bf16x8*)(lds + PG8_SA(b, h) + aoff + m * 2048 + k * 1024); } while (0)
; #define PG8_LDB(dst, b, h) do { _Pragma("unroll") for (int n = 0; n < 2; ++n) _Pragma("unroll") for (int k = 0; k < 2; ++k) dst[n][k] = *(const LAS bf16x8*)(lds + PG8_SB(b, h) + boff + n * 2048 + k * 1024); } while (0)
; #define PG8_MMA(ai, bj, At, Bt) do { __builtin_amdgcn_s_setprio(1); _Pragma("unroll") for (int m = 0; m < 4; ++m) _Pragma("unroll") for (int n = 0; n < 2; ++n) _Pragma("unroll") for (int k = 0; k < 2; ++k) \
;         acc[ai][bj][m][n] = __builtin_amdgcn_mfma_f32_16x16x32_bf16(Bt[n][k], At[m][k], acc[ai][bj][m][n], 0, 0, 0); __builtin_amdgcn_s_setprio(0); } while (0)
; #define PG8_WAIT_V(n) asm volatile("s_waitcnt vmcnt(" #n ")" ::: "memory")
; #define PG8_WAIT_L(n) asm volatile("s_waitcnt lgkmcnt(" #n ")" ::: "memory")
; #define PG8_BAR __builtin_amdgcn_s_barrier()
; #define PG8_SCHED __builtin_amdgcn_sched_barrier(0)
; template <class Epi, bool ALIGN_EPI, int K, int LDA, int LDB>
; __device__ __forceinline__ void gemm_phase(LAS unsigned char* lds, const int wid, const Gemm g, const StaticOrder& S, const Epi& E) {
;     ...
;             PG8_LDB(B0, 1, 0); PG8_LDB(B1, 1, 1); PG8_SCHED; PG8_LDA(At, 1, 0); PG8_STAGE(PG8_SA(0, 1), a2 + hA, voffA);
;             PG8_WAIT_V(8); PG8_WAIT_L(0); PG8_BAR; PG8_MMA(0, 0, At, B0); PG8_MMA(0, 1, At, B1); PG8_BAR; PG8_SCHED;
;             PG8_LDA(At, 1, 1); PG8_STAGE(PG8_SB(1, 0), b3, voffB); PG8_STAGE(PG8_SB(1, 1), b3 + hB, voffB); PG8_STAGE(PG8_SA(1, 0), a3, voffA);
;             PG8_WAIT_V(8); PG8_WAIT_L(0); PG8_BAR; PG8_MMA(1, 0, At, B0); PG8_MMA(1, 1, At, B1); PG8_BAR; PG8_SCHED;
;         }
;         if constexpr (ALIGN_EPI) { if (wr == 0) PG8_BAR; }
	s_add_i32 s52, 0, 0x18000
	s_add_i32 s53, 0, 0x1c000
	v_add_u32_e32 v140, s52, v162
	v_add_u32_e32 v178, s53, v162
	ds_read_b128 v[128:131], v140
	ds_read_b128 v[132:135], v140 offset:1024
	ds_read_b128 v[136:139], v140 offset:2048
	ds_read_b128 v[140:143], v140 offset:3072
	ds_read_b128 v[166:169], v178
	ds_read_b128 v[170:173], v178 offset:1024
	ds_read_b128 v[174:177], v178 offset:2048
	ds_read_b128 v[178:181], v178 offset:3072
	s_add_u32 s40, s40, 0x40000
	s_addc_u32 s41, s41, 0
	s_mov_b32 m0, s43
	ds_read_b128 v[182:185], v165 offset:32768
	ds_read_b128 v[186:189], v165 offset:33792
	ds_read_b128 v[190:193], v165 offset:34816
	ds_read_b128 v[194:197], v165 offset:35840
	ds_read_b128 v[198:201], v165 offset:36864
	ds_read_b128 v[202:205], v165 offset:37888
	ds_read_b128 v[206:209], v165 offset:38912
	ds_read_b128 v[210:213], v165 offset:39936
	global_load_lds_dwordx4 v144, s[40:41]
	s_mov_b32 m0, s48
	s_nop 0
	global_load_lds_dwordx4 v148, s[40:41]
	s_waitcnt vmcnt(8)
	s_waitcnt lgkmcnt(0)
	s_barrier
	s_setprio 1
	s_waitcnt lgkmcnt(0)
	v_mfma_f32_16x16x32_bf16 v[124:127], v[128:131], v[182:185], v[124:127]
	v_mfma_f32_16x16x32_bf16 v[120:123], v[136:139], v[182:185], v[120:123]
	v_mfma_f32_16x16x32_bf16 v[108:111], v[128:131], v[190:193], v[108:111]
	v_mfma_f32_16x16x32_bf16 v[104:107], v[136:139], v[190:193], v[104:107]
	v_mfma_f32_16x16x32_bf16 v[92:95], v[128:131], v[198:201], v[92:95]
	v_mfma_f32_16x16x32_bf16 v[88:91], v[136:139], v[198:201], v[88:91]
	v_mfma_f32_16x16x32_bf16 v[76:79], v[128:131], v[206:209], v[76:79]
	v_mfma_f32_16x16x32_bf16 v[72:75], v[136:139], v[206:209], v[72:75]
	v_mfma_f32_16x16x32_bf16 v[124:127], v[132:135], v[186:189], v[124:127]
	v_mfma_f32_16x16x32_bf16 v[120:123], v[140:143], v[186:189], v[120:123]
	v_mfma_f32_16x16x32_bf16 v[108:111], v[132:135], v[194:197], v[108:111]
	v_mfma_f32_16x16x32_bf16 v[104:107], v[140:143], v[194:197], v[104:107]
	v_mfma_f32_16x16x32_bf16 v[92:95], v[132:135], v[202:205], v[92:95]
	v_mfma_f32_16x16x32_bf16 v[88:91], v[140:143], v[202:205], v[88:91]
	v_mfma_f32_16x16x32_bf16 v[76:79], v[132:135], v[210:213], v[76:79]
	v_mfma_f32_16x16x32_bf16 v[72:75], v[140:143], v[210:213], v[72:75]
	v_mfma_f32_16x16x32_bf16 v[116:119], v[166:169], v[182:185], v[116:119]
	v_mfma_f32_16x16x32_bf16 v[112:115], v[174:177], v[182:185], v[112:115]
	v_mfma_f32_16x16x32_bf16 v[100:103], v[166:169], v[190:193], v[100:103]
	v_mfma_f32_16x16x32_bf16 v[96:99], v[174:177], v[190:193], v[96:99]
	v_mfma_f32_16x16x32_bf16 v[84:87], v[166:169], v[198:201], v[84:87]
	v_mfma_f32_16x16x32_bf16 v[80:83], v[174:177], v[198:201], v[80:83]
	v_mfma_f32_16x16x32_bf16 v[68:71], v[166:169], v[206:209], v[68:71]
	v_mfma_f32_16x16x32_bf16 v[64:67], v[174:177], v[206:209], v[64:67]
	v_mfma_f32_16x16x32_bf16 v[116:119], v[170:173], v[186:189], v[116:119]
	v_mfma_f32_16x16x32_bf16 v[112:115], v[178:181], v[186:189], v[112:115]
	v_mfma_f32_16x16x32_bf16 v[100:103], v[170:173], v[194:197], v[100:103]
	v_mfma_f32_16x16x32_bf16 v[96:99], v[178:181], v[194:197], v[96:99]
	v_mfma_f32_16x16x32_bf16 v[84:87], v[170:173], v[202:205], v[84:87]
	v_mfma_f32_16x16x32_bf16 v[80:83], v[178:181], v[202:205], v[80:83]
	v_mfma_f32_16x16x32_bf16 v[68:71], v[170:173], v[210:213], v[68:71]
	v_mfma_f32_16x16x32_bf16 v[64:67], v[178:181], v[210:213], v[64:67]
	s_setprio 0
	s_barrier
	s_add_i32 s40, s52, s33
	s_mov_b32 m0, s40
	ds_read_b128 v[182:185], v165 offset:49152
	ds_read_b128 v[186:189], v165 offset:50176
	ds_read_b128 v[190:193], v165 offset:51200
	ds_read_b128 v[194:197], v165 offset:52224
	ds_read_b128 v[198:201], v165 offset:53248
	ds_read_b128 v[202:205], v165 offset:54272
	ds_read_b128 v[206:209], v165 offset:55296
	ds_read_b128 v[210:213], v165 offset:56320
	global_load_lds_dwordx4 v146, s[98:99]
	s_add_i32 m0, s40, 0x2000
	s_add_u32 s38, s38, 0x40080
	s_addc_u32 s39, s39, 0
	s_add_i32 s40, s53, s33
	global_load_lds_dwordx4 v150, s[98:99]
	s_mov_b32 m0, s40
	s_nop 0
	global_load_lds_dwordx4 v146, s[38:39]
	s_add_i32 m0, s40, 0x2000
	s_nop 0
	global_load_lds_dwordx4 v150, s[38:39]
	s_mov_b32 m0, s55
	s_nop 0
	global_load_lds_dwordx4 v144, s[100:101]
	s_mov_b32 m0, s56
	s_nop 0
	global_load_lds_dwordx4 v148, s[100:101]
	s_waitcnt vmcnt(8)
	s_waitcnt lgkmcnt(0)
	s_barrier
	s_setprio 1
	s_waitcnt lgkmcnt(0)
	v_mfma_f32_16x16x32_bf16 v[60:63], v[128:131], v[182:185], v[60:63]
	v_mfma_f32_16x16x32_bf16 v[56:59], v[136:139], v[182:185], v[56:59]
	v_mfma_f32_16x16x32_bf16 v[44:47], v[128:131], v[190:193], v[44:47]
	v_mfma_f32_16x16x32_bf16 v[40:43], v[136:139], v[190:193], v[40:43]
	v_mfma_f32_16x16x32_bf16 v[28:31], v[128:131], v[198:201], v[28:31]
	v_mfma_f32_16x16x32_bf16 v[24:27], v[136:139], v[198:201], v[24:27]
	v_mfma_f32_16x16x32_bf16 v[12:15], v[128:131], v[206:209], v[12:15]
	v_mfma_f32_16x16x32_bf16 v[8:11], v[136:139], v[206:209], v[8:11]
	v_mfma_f32_16x16x32_bf16 v[60:63], v[132:135], v[186:189], v[60:63]
	v_mfma_f32_16x16x32_bf16 v[56:59], v[140:143], v[186:189], v[56:59]
	v_mfma_f32_16x16x32_bf16 v[44:47], v[132:135], v[194:197], v[44:47]
	v_mfma_f32_16x16x32_bf16 v[40:43], v[140:143], v[194:197], v[40:43]
	v_mfma_f32_16x16x32_bf16 v[28:31], v[132:135], v[202:205], v[28:31]
	v_mfma_f32_16x16x32_bf16 v[24:27], v[140:143], v[202:205], v[24:27]
	v_mfma_f32_16x16x32_bf16 v[12:15], v[132:135], v[210:213], v[12:15]
	v_mfma_f32_16x16x32_bf16 v[8:11], v[140:143], v[210:213], v[8:11]
	v_mfma_f32_16x16x32_bf16 v[52:55], v[166:169], v[182:185], v[52:55]
	v_mfma_f32_16x16x32_bf16 v[48:51], v[174:177], v[182:185], v[48:51]
	v_mfma_f32_16x16x32_bf16 v[36:39], v[166:169], v[190:193], v[36:39]
	v_mfma_f32_16x16x32_bf16 v[32:35], v[174:177], v[190:193], v[32:35]
	v_mfma_f32_16x16x32_bf16 v[20:23], v[166:169], v[198:201], v[20:23]
	v_mfma_f32_16x16x32_bf16 v[16:19], v[174:177], v[198:201], v[16:19]
	v_mfma_f32_16x16x32_bf16 v[4:7], v[166:169], v[206:209], v[4:7]
	v_mfma_f32_16x16x32_bf16 v[0:3], v[174:177], v[206:209], v[0:3]
	v_mfma_f32_16x16x32_bf16 v[52:55], v[170:173], v[186:189], v[52:55]
	v_mfma_f32_16x16x32_bf16 v[48:51], v[178:181], v[186:189], v[48:51]
	v_mfma_f32_16x16x32_bf16 v[36:39], v[170:173], v[194:197], v[36:39]
	v_mfma_f32_16x16x32_bf16 v[32:35], v[178:181], v[194:197], v[32:35]
	v_mfma_f32_16x16x32_bf16 v[20:23], v[170:173], v[202:205], v[20:23]
	v_mfma_f32_16x16x32_bf16 v[16:19], v[178:181], v[202:205], v[16:19]
	v_mfma_f32_16x16x32_bf16 v[4:7], v[170:173], v[210:213], v[4:7]
	v_mfma_f32_16x16x32_bf16 v[0:3], v[178:181], v[210:213], v[0:3]
	s_setprio 0
	s_barrier
	s_add_i32 s67, s67, 2
	s_add_u32 s36, s36, 0x100
	s_addc_u32 s37, s37, 0
	s_add_u32 s65, s65, 0x100
	s_addc_u32 s66, s66, 0
	s_cmp_gt_u32 s67, 13
	s_cbranch_scc0 .LBB0_917
	s_and_b64 vcc, exec, s[14:15]
	s_cbranch_vccz .LBB0_920
	s_barrier

; #define PG8_STAGE(bufoff, gbase, voff) do { _Pragma("unroll") for (int _i = 0; _i < 2; ++_i) \
;         __builtin_amdgcn_global_load_lds((const unsigned*)((const char*)(gbase) + (voff)[_i]), (LAS unsigned*)(lds + (bufoff) + ldsw + _i * 8192), 16, 0, 0); } while (0)
; #define PG8_LDA(dst, b, h) do { _Pragma("unroll") for (int m = 0; m < 4; ++m) _Pragma("unroll") for (int k = 0; k < 2; ++k) dst[m][k] = *(const LAS bf16x8*)(lds + PG8_SA(b, h) + aoff + m * 2048 + k * 1024); } while (0)
; #define PG8_LDB(dst, b, h) do { _Pragma("unroll") for (int n = 0; n < 2; ++n) _Pragma("unroll") for (int k = 0; k < 2; ++k) dst[n][k] = *(const LAS bf16x8*)(lds + PG8_SB(b, h) + boff + n * 2048 + k * 1024); } while (0)
; #define PG8_MMA(ai, bj, At, Bt) do { __builtin_amdgcn_s_setprio(1); _Pragma("unroll") for (int m = 0; m < 4; ++m) _Pragma("unroll") for (int n = 0; n < 2; ++n) _Pragma("unroll") for (int k = 0; k < 2; ++k) \
;         acc[ai][bj][m][n] = __builtin_amdgcn_mfma_f32_16x16x32_bf16(Bt[n][k], At[m][k], acc[ai][bj][m][n], 0, 0, 0); __builtin_amdgcn_s_setprio(0); } while (0)
; #define PG8_WAIT_V(n) asm volatile("s_waitcnt vmcnt(" #n ")" ::: "memory")
; #define PG8_WAIT_L(n) asm volatile("s_waitcnt lgkmcnt(" #n ")" ::: "memory")
; #define PG8_BAR __builtin_amdgcn_s_barrier()
; #define PG8_SCHED __builtin_amdgcn_sched_barrier(0)
; template <class Epi, bool ALIGN_EPI, int K, int LDA, int LDB>
; __device__ __forceinline__ void gemm_phase(LAS unsigned char* lds, const int wid, const Gemm g, const StaticOrder& S, const Epi& E) {
;     ...
;             const char* a1 = cA + (size_t)(t + 1) * kstep;
;             const char* a2 = last ? nA : cA + (size_t)(t + 2) * kstep; const char* b2 = last ? nB : cB + (size_t)(t + 2) * kstep;
;             const char* a3 = a2 + kstep; const char* b3 = b2 + kstep;
;             PG8_LDB(B0, 0, 0); PG8_LDB(B1, 0, 1); PG8_SCHED; PG8_LDA(At, 0, 0); PG8_STAGE(PG8_SA(1, 1), a1 + hA, voffA);
;             PG8_WAIT_V(8); PG8_WAIT_L(0); PG8_BAR; PG8_MMA(0, 0, At, B0); PG8_MMA(0, 1, At, B1); PG8_BAR; PG8_SCHED;
;             PG8_LDA(At, 0, 1); PG8_STAGE(PG8_SB(0, 0), b2, voffB); PG8_STAGE(PG8_SB(0, 1), b2 + hB, voffB); PG8_STAGE(PG8_SA(0, 0), a2, voffA);
;             PG8_WAIT_V(8); PG8_WAIT_L(0); PG8_BAR; PG8_MMA(1, 0, At, B0); PG8_MMA(1, 1, At, B1); PG8_BAR; PG8_SCHED;
.LBB0_1052:
	ds_read_b128 v[148:151], v145
	ds_read_b128 v[152:155], v145 offset:1024
	ds_read_b128 v[156:159], v145 offset:2048
	ds_read_b128 v[160:163], v145 offset:3072
	ds_read_b128 v[164:167], v146
	ds_read_b128 v[168:171], v146 offset:1024
	ds_read_b128 v[172:175], v146 offset:2048
	ds_read_b128 v[176:179], v146 offset:3072
	s_add_u32 s24, s22, 0xfffc0080
	s_addc_u32 s25, s23, -1
	s_cmp_eq_u32 s55, 12
	s_cselect_b32 s27, s15, s25
	s_cselect_b32 s26, s48, s24
	s_cselect_b32 s25, s13, s54
	s_cselect_b32 s24, s49, s51
	s_add_i32 m0, s21, 0xc000
	ds_read_b128 v[180:183], v147
	ds_read_b128 v[184:187], v147 offset:1024
	ds_read_b128 v[188:191], v147 offset:2048
	ds_read_b128 v[192:195], v147 offset:3072
	ds_read_b128 v[196:199], v147 offset:4096
	ds_read_b128 v[200:203], v147 offset:5120
	ds_read_b128 v[204:207], v147 offset:6144
	ds_read_b128 v[208:211], v147 offset:7168
	global_load_lds_dwordx4 v136, s[22:23]
	s_add_i32 m0, s21, 0xe000
	s_nop 0
	global_load_lds_dwordx4 v138, s[22:23]
	s_waitcnt vmcnt(8)
	s_waitcnt lgkmcnt(0)
	s_barrier
	s_setprio 1
	s_waitcnt lgkmcnt(0)
	v_mfma_f32_16x16x32_bf16 v[124:127], v[148:151], v[180:183], v[124:127]
	v_mfma_f32_16x16x32_bf16 v[120:123], v[156:159], v[180:183], v[120:123]
	v_mfma_f32_16x16x32_bf16 v[108:111], v[148:151], v[188:191], v[108:111]
	v_mfma_f32_16x16x32_bf16 v[104:107], v[156:159], v[188:191], v[104:107]
	v_mfma_f32_16x16x32_bf16 v[92:95], v[148:151], v[196:199], v[92:95]
	v_mfma_f32_16x16x32_bf16 v[88:91], v[156:159], v[196:199], v[88:91]
	v_mfma_f32_16x16x32_bf16 v[76:79], v[148:151], v[204:207], v[76:79]
	v_mfma_f32_16x16x32_bf16 v[72:75], v[156:159], v[204:207], v[72:75]
	v_mfma_f32_16x16x32_bf16 v[124:127], v[152:155], v[184:187], v[124:127]
	v_mfma_f32_16x16x32_bf16 v[120:123], v[160:163], v[184:187], v[120:123]
	v_mfma_f32_16x16x32_bf16 v[108:111], v[152:155], v[192:195], v[108:111]
	v_mfma_f32_16x16x32_bf16 v[104:107], v[160:163], v[192:195], v[104:107]
	v_mfma_f32_16x16x32_bf16 v[92:95], v[152:155], v[200:203], v[92:95]
	v_mfma_f32_16x16x32_bf16 v[88:91], v[160:163], v[200:203], v[88:91]
	v_mfma_f32_16x16x32_bf16 v[76:79], v[152:155], v[208:211], v[76:79]
	v_mfma_f32_16x16x32_bf16 v[72:75], v[160:163], v[208:211], v[72:75]
	v_mfma_f32_16x16x32_bf16 v[116:119], v[164:167], v[180:183], v[116:119]
	v_mfma_f32_16x16x32_bf16 v[112:115], v[172:175], v[180:183], v[112:115]
	v_mfma_f32_16x16x32_bf16 v[100:103], v[164:167], v[188:191], v[100:103]
	v_mfma_f32_16x16x32_bf16 v[96:99], v[172:175], v[188:191], v[96:99]
	v_mfma_f32_16x16x32_bf16 v[84:87], v[164:167], v[196:199], v[84:87]
	v_mfma_f32_16x16x32_bf16 v[80:83], v[172:175], v[196:199], v[80:83]
	v_mfma_f32_16x16x32_bf16 v[68:71], v[164:167], v[204:207], v[68:71]
	v_mfma_f32_16x16x32_bf16 v[64:67], v[172:175], v[204:207], v[64:67]
	v_mfma_f32_16x16x32_bf16 v[116:119], v[168:171], v[184:187], v[116:119]
	v_mfma_f32_16x16x32_bf16 v[112:115], v[176:179], v[184:187], v[112:115]
	v_mfma_f32_16x16x32_bf16 v[100:103], v[168:171], v[192:195], v[100:103]
	v_mfma_f32_16x16x32_bf16 v[96:99], v[176:179], v[192:195], v[96:99]
	v_mfma_f32_16x16x32_bf16 v[84:87], v[168:171], v[200:203], v[84:87]
	v_mfma_f32_16x16x32_bf16 v[80:83], v[176:179], v[200:203], v[80:83]
	v_mfma_f32_16x16x32_bf16 v[68:71], v[168:171], v[208:211], v[68:71]
	v_mfma_f32_16x16x32_bf16 v[64:67], v[176:179], v[208:211], v[64:67]
	s_setprio 0
	s_barrier
	s_add_u32 s98, s24, s10
	s_addc_u32 s99, s25, s11
	s_add_u32 s100, s26, s10
	s_addc_u32 s101, s27, s11
	s_add_i32 s52, s40, s3
	s_mov_b32 m0, s52
	ds_read_b128 v[180:183], v147 offset:16384
	ds_read_b128 v[184:187], v147 offset:17408
	ds_read_b128 v[188:191], v147 offset:18432
	ds_read_b128 v[192:195], v147 offset:19456
	ds_read_b128 v[196:199], v147 offset:20480
	ds_read_b128 v[200:203], v147 offset:21504
	ds_read_b128 v[204:207], v147 offset:22528
	ds_read_b128 v[208:211], v147 offset:23552
	global_load_lds_dwordx4 v132, s[24:25]
	s_add_i32 m0, s52, 0x2000
	s_add_u32 s56, s24, 0x40000
	s_addc_u32 s57, s25, 0
	s_add_i32 s52, s41, s3
	global_load_lds_dwordx4 v128, s[24:25]
	s_mov_b32 m0, s52
	s_nop 0
	global_load_lds_dwordx4 v132, s[56:57]
	s_add_i32 m0, s52, 0x2000
	s_nop 0
	global_load_lds_dwordx4 v128, s[56:57]
	s_mov_b32 m0, s21
	s_nop 0
	global_load_lds_dwordx4 v134, s[26:27]
	s_mov_b32 m0, s30
	s_nop 0
	global_load_lds_dwordx4 v130, s[26:27]
	s_waitcnt vmcnt(8)
	s_waitcnt lgkmcnt(0)
	s_barrier
	s_setprio 1
	s_waitcnt lgkmcnt(0)
	v_mfma_f32_16x16x32_bf16 v[60:63], v[148:151], v[180:183], v[60:63]
	v_mfma_f32_16x16x32_bf16 v[56:59], v[156:159], v[180:183], v[56:59]
	v_mfma_f32_16x16x32_bf16 v[44:47], v[148:151], v[188:191], v[44:47]
	v_mfma_f32_16x16x32_bf16 v[40:43], v[156:159], v[188:191], v[40:43]
	v_mfma_f32_16x16x32_bf16 v[28:31], v[148:151], v[196:199], v[28:31]
	v_mfma_f32_16x16x32_bf16 v[24:27], v[156:159], v[196:199], v[24:27]
	v_mfma_f32_16x16x32_bf16 v[12:15], v[148:151], v[204:207], v[12:15]
	v_mfma_f32_16x16x32_bf16 v[8:11], v[156:159], v[204:207], v[8:11]
	v_mfma_f32_16x16x32_bf16 v[60:63], v[152:155], v[184:187], v[60:63]
	v_mfma_f32_16x16x32_bf16 v[56:59], v[160:163], v[184:187], v[56:59]
	v_mfma_f32_16x16x32_bf16 v[44:47], v[152:155], v[192:195], v[44:47]
	v_mfma_f32_16x16x32_bf16 v[40:43], v[160:163], v[192:195], v[40:43]
	v_mfma_f32_16x16x32_bf16 v[28:31], v[152:155], v[200:203], v[28:31]
	v_mfma_f32_16x16x32_bf16 v[24:27], v[160:163], v[200:203], v[24:27]
	v_mfma_f32_16x16x32_bf16 v[12:15], v[152:155], v[208:211], v[12:15]
	v_mfma_f32_16x16x32_bf16 v[8:11], v[160:163], v[208:211], v[8:11]
	v_mfma_f32_16x16x32_bf16 v[52:55], v[164:167], v[180:183], v[52:55]
	v_mfma_f32_16x16x32_bf16 v[48:51], v[172:175], v[180:183], v[48:51]
	v_mfma_f32_16x16x32_bf16 v[36:39], v[164:167], v[188:191], v[36:39]
	v_mfma_f32_16x16x32_bf16 v[32:35], v[172:175], v[188:191], v[32:35]
	v_mfma_f32_16x16x32_bf16 v[20:23], v[164:167], v[196:199], v[20:23]
	v_mfma_f32_16x16x32_bf16 v[16:19], v[172:175], v[196:199], v[16:19]
	v_mfma_f32_16x16x32_bf16 v[4:7], v[164:167], v[204:207], v[4:7]
	v_mfma_f32_16x16x32_bf16 v[0:3], v[172:175], v[204:207], v[0:3]
	v_mfma_f32_16x16x32_bf16 v[52:55], v[168:171], v[184:187], v[52:55]
	v_mfma_f32_16x16x32_bf16 v[48:51], v[176:179], v[184:187], v[48:51]
	v_mfma_f32_16x16x32_bf16 v[36:39], v[168:171], v[192:195], v[36:39]
	v_mfma_f32_16x16x32_bf16 v[32:35], v[176:179], v[192:195], v[32:35]
	v_mfma_f32_16x16x32_bf16 v[20:23], v[168:171], v[200:203], v[20:23]
	v_mfma_f32_16x16x32_bf16 v[16:19], v[176:179], v[200:203], v[16:19]
	v_mfma_f32_16x16x32_bf16 v[4:7], v[168:171], v[208:211], v[4:7]
	v_mfma_f32_16x16x32_bf16 v[0:3], v[176:179], v[208:211], v[0:3]
	s_setprio 0
	s_barrier
; __device__ __forceinline__ int lane_id_() { int l; asm volatile("v_mbcnt_lo_u32_b32 %0, -1, 0\n\tv_mbcnt_hi_u32_b32 %0, -1, %0" : "=v"(l)); return l; }
; #define PG8_STAGE(bufoff, gbase, voff) do { _Pragma("unroll") for (int _i = 0; _i < 2; ++_i) \
;         __builtin_amdgcn_global_load_lds((const unsigned*)((const char*)(gbase) + (voff)[_i]), (LAS unsigned*)(lds + (bufoff) + ldsw + _i * 8192), 16, 0, 0); } while (0)
; #define PG8_LDA(dst, b, h) do { _Pragma("unroll") for (int m = 0; m < 4; ++m) _Pragma("unroll") for (int k = 0; k < 2; ++k) dst[m][k] = *(const LAS bf16x8*)(lds + PG8_SA(b, h) + aoff + m * 2048 + k * 1024); } while (0)
; #define PG8_LDB(dst, b, h) do { _Pragma("unroll") for (int n = 0; n < 2; ++n) _Pragma("unroll") for (int k = 0; k < 2; ++k) dst[n][k] = *(const LAS bf16x8*)(lds + PG8_SB(b, h) + boff + n * 2048 + k * 1024); } while (0)
; #define PG8_MMA(ai, bj, At, Bt) do { __builtin_amdgcn_s_setprio(1); _Pragma("unroll") for (int m = 0; m < 4; ++m) _Pragma("unroll") for (int n = 0; n < 2; ++n) _Pragma("unroll") for (int k = 0; k < 2; ++k) \
;         acc[ai][bj][m][n] = __builtin_amdgcn_mfma_f32_16x16x32_bf16(Bt[n][k], At[m][k], acc[ai][bj][m][n], 0, 0, 0); __builtin_amdgcn_s_setprio(0); } while (0)
; #define PG8_WAIT_V(n) asm volatile("s_waitcnt vmcnt(" #n ")" ::: "memory")
; #define PG8_WAIT_L(n) asm volatile("s_waitcnt lgkmcnt(" #n ")" ::: "memory")
; #define PG8_BAR __builtin_amdgcn_s_barrier()
; #define PG8_SCHED __builtin_amdgcn_sched_barrier(0)
; template <class Epi, bool ALIGN_EPI, int K, int LDA, int LDB>
; __device__ __forceinline__ void gemm_phase(LAS unsigned char* lds, const int wid, const Gemm g, const StaticOrder& S, const Epi& E) {
;     ...
;             PG8_LDB(B0, 1, 0); PG8_LDB(B1, 1, 1); PG8_SCHED; PG8_LDA(At, 1, 0); PG8_STAGE(PG8_SA(0, 1), a2 + hA, voffA);
;             PG8_WAIT_V(8); PG8_WAIT_L(0); PG8_BAR; PG8_MMA(0, 0, At, B0); PG8_MMA(0, 1, At, B1); PG8_BAR; PG8_SCHED;
;             PG8_LDA(At, 1, 1); PG8_STAGE(PG8_SB(1, 0), b3, voffB); PG8_STAGE(PG8_SB(1, 1), b3 + hB, voffB); PG8_STAGE(PG8_SA(1, 0), a3, voffA);
;             PG8_WAIT_V(8); PG8_WAIT_L(0); PG8_BAR; PG8_MMA(1, 0, At, B0); PG8_MMA(1, 1, At, B1); PG8_BAR; PG8_SCHED;
;         }
;         if constexpr (ALIGN_EPI) { if (wr == 0) PG8_BAR; }
;         { const int l2 = lane_id_(); E(acc, cur, wid >> 2, wid & 3, l2 & 15, l2 >> 4); }
;         if (!has_next) break;
	s_add_i32 s52, 0, 0x18000
	s_add_i32 s53, 0, 0x1c000
	v_add_u32_e32 v160, s52, v144
	v_add_u32_e32 v176, s53, v144
	ds_read_b128 v[148:151], v160
	ds_read_b128 v[152:155], v160 offset:1024
	ds_read_b128 v[156:159], v160 offset:2048
	ds_read_b128 v[160:163], v160 offset:3072
	ds_read_b128 v[164:167], v176
	ds_read_b128 v[168:171], v176 offset:1024
	ds_read_b128 v[172:175], v176 offset:2048
	ds_read_b128 v[176:179], v176 offset:3072
	s_add_u32 s26, s26, 0x40000
	s_addc_u32 s27, s27, 0
	s_mov_b32 m0, s31
	ds_read_b128 v[180:183], v147 offset:32768
	ds_read_b128 v[184:187], v147 offset:33792
	ds_read_b128 v[188:191], v147 offset:34816
	ds_read_b128 v[192:195], v147 offset:35840
	ds_read_b128 v[196:199], v147 offset:36864
	ds_read_b128 v[200:203], v147 offset:37888
	ds_read_b128 v[204:207], v147 offset:38912
	ds_read_b128 v[208:211], v147 offset:39936
	global_load_lds_dwordx4 v134, s[26:27]
	s_mov_b32 m0, s33
	s_nop 0
	global_load_lds_dwordx4 v130, s[26:27]
	s_waitcnt vmcnt(8)
	s_waitcnt lgkmcnt(0)
	s_barrier
	s_setprio 1
	s_waitcnt lgkmcnt(0)
	v_mfma_f32_16x16x32_bf16 v[124:127], v[148:151], v[180:183], v[124:127]
	v_mfma_f32_16x16x32_bf16 v[120:123], v[156:159], v[180:183], v[120:123]
	v_mfma_f32_16x16x32_bf16 v[108:111], v[148:151], v[188:191], v[108:111]
	v_mfma_f32_16x16x32_bf16 v[104:107], v[156:159], v[188:191], v[104:107]
	v_mfma_f32_16x16x32_bf16 v[92:95], v[148:151], v[196:199], v[92:95]
	v_mfma_f32_16x16x32_bf16 v[88:91], v[156:159], v[196:199], v[88:91]
	v_mfma_f32_16x16x32_bf16 v[76:79], v[148:151], v[204:207], v[76:79]
	v_mfma_f32_16x16x32_bf16 v[72:75], v[156:159], v[204:207], v[72:75]
	v_mfma_f32_16x16x32_bf16 v[124:127], v[152:155], v[184:187], v[124:127]
	v_mfma_f32_16x16x32_bf16 v[120:123], v[160:163], v[184:187], v[120:123]
	v_mfma_f32_16x16x32_bf16 v[108:111], v[152:155], v[192:195], v[108:111]
	v_mfma_f32_16x16x32_bf16 v[104:107], v[160:163], v[192:195], v[104:107]
	v_mfma_f32_16x16x32_bf16 v[92:95], v[152:155], v[200:203], v[92:95]
	v_mfma_f32_16x16x32_bf16 v[88:91], v[160:163], v[200:203], v[88:91]
	v_mfma_f32_16x16x32_bf16 v[76:79], v[152:155], v[208:211], v[76:79]
	v_mfma_f32_16x16x32_bf16 v[72:75], v[160:163], v[208:211], v[72:75]
	v_mfma_f32_16x16x32_bf16 v[116:119], v[164:167], v[180:183], v[116:119]
	v_mfma_f32_16x16x32_bf16 v[112:115], v[172:175], v[180:183], v[112:115]
	v_mfma_f32_16x16x32_bf16 v[100:103], v[164:167], v[188:191], v[100:103]
	v_mfma_f32_16x16x32_bf16 v[96:99], v[172:175], v[188:191], v[96:99]
	v_mfma_f32_16x16x32_bf16 v[84:87], v[164:167], v[196:199], v[84:87]
	v_mfma_f32_16x16x32_bf16 v[80:83], v[172:175], v[196:199], v[80:83]
	v_mfma_f32_16x16x32_bf16 v[68:71], v[164:167], v[204:207], v[68:71]
	v_mfma_f32_16x16x32_bf16 v[64:67], v[172:175], v[204:207], v[64:67]
	v_mfma_f32_16x16x32_bf16 v[116:119], v[168:171], v[184:187], v[116:119]
	v_mfma_f32_16x16x32_bf16 v[112:115], v[176:179], v[184:187], v[112:115]
	v_mfma_f32_16x16x32_bf16 v[100:103], v[168:171], v[192:195], v[100:103]
	v_mfma_f32_16x16x32_bf16 v[96:99], v[176:179], v[192:195], v[96:99]
	v_mfma_f32_16x16x32_bf16 v[84:87], v[168:171], v[200:203], v[84:87]
	v_mfma_f32_16x16x32_bf16 v[80:83], v[176:179], v[200:203], v[80:83]
	v_mfma_f32_16x16x32_bf16 v[68:71], v[168:171], v[208:211], v[68:71]
	v_mfma_f32_16x16x32_bf16 v[64:67], v[176:179], v[208:211], v[64:67]
	s_setprio 0
	s_barrier
	s_add_i32 s26, s52, s3
	s_mov_b32 m0, s26
	ds_read_b128 v[180:183], v147 offset:49152
	ds_read_b128 v[184:187], v147 offset:50176
	ds_read_b128 v[188:191], v147 offset:51200
	ds_read_b128 v[192:195], v147 offset:52224
	ds_read_b128 v[196:199], v147 offset:53248
	ds_read_b128 v[200:203], v147 offset:54272
	ds_read_b128 v[204:207], v147 offset:55296
	ds_read_b128 v[208:211], v147 offset:56320
	global_load_lds_dwordx4 v132, s[98:99]
	s_add_i32 m0, s26, 0x2000
	s_add_u32 s24, s24, 0x40080
	s_addc_u32 s25, s25, 0
	s_add_i32 s26, s53, s3
	global_load_lds_dwordx4 v128, s[98:99]
	s_mov_b32 m0, s26
	s_nop 0
	global_load_lds_dwordx4 v132, s[24:25]
	s_add_i32 m0, s26, 0x2000
	s_nop 0
	global_load_lds_dwordx4 v128, s[24:25]
	s_mov_b32 m0, s38
	s_nop 0
	global_load_lds_dwordx4 v134, s[100:101]
	s_mov_b32 m0, s39
	s_nop 0
	global_load_lds_dwordx4 v130, s[100:101]
	s_waitcnt vmcnt(8)
	s_waitcnt lgkmcnt(0)
	s_barrier
	s_setprio 1
	s_waitcnt lgkmcnt(0)
	v_mfma_f32_16x16x32_bf16 v[60:63], v[148:151], v[180:183], v[60:63]
	v_mfma_f32_16x16x32_bf16 v[56:59], v[156:159], v[180:183], v[56:59]
	v_mfma_f32_16x16x32_bf16 v[44:47], v[148:151], v[188:191], v[44:47]
	v_mfma_f32_16x16x32_bf16 v[40:43], v[156:159], v[188:191], v[40:43]
	v_mfma_f32_16x16x32_bf16 v[28:31], v[148:151], v[196:199], v[28:31]
	v_mfma_f32_16x16x32_bf16 v[24:27], v[156:159], v[196:199], v[24:27]
	v_mfma_f32_16x16x32_bf16 v[12:15], v[148:151], v[204:207], v[12:15]
	v_mfma_f32_16x16x32_bf16 v[8:11], v[156:159], v[204:207], v[8:11]
	v_mfma_f32_16x16x32_bf16 v[60:63], v[152:155], v[184:187], v[60:63]
	v_mfma_f32_16x16x32_bf16 v[56:59], v[160:163], v[184:187], v[56:59]
	v_mfma_f32_16x16x32_bf16 v[44:47], v[152:155], v[192:195], v[44:47]
	v_mfma_f32_16x16x32_bf16 v[40:43], v[160:163], v[192:195], v[40:43]
	v_mfma_f32_16x16x32_bf16 v[28:31], v[152:155], v[200:203], v[28:31]
	v_mfma_f32_16x16x32_bf16 v[24:27], v[160:163], v[200:203], v[24:27]
	v_mfma_f32_16x16x32_bf16 v[12:15], v[152:155], v[208:211], v[12:15]
	v_mfma_f32_16x16x32_bf16 v[8:11], v[160:163], v[208:211], v[8:11]
	v_mfma_f32_16x16x32_bf16 v[52:55], v[164:167], v[180:183], v[52:55]
	v_mfma_f32_16x16x32_bf16 v[48:51], v[172:175], v[180:183], v[48:51]
	v_mfma_f32_16x16x32_bf16 v[36:39], v[164:167], v[188:191], v[36:39]
	v_mfma_f32_16x16x32_bf16 v[32:35], v[172:175], v[188:191], v[32:35]
	v_mfma_f32_16x16x32_bf16 v[20:23], v[164:167], v[196:199], v[20:23]
	v_mfma_f32_16x16x32_bf16 v[16:19], v[172:175], v[196:199], v[16:19]
	v_mfma_f32_16x16x32_bf16 v[4:7], v[164:167], v[204:207], v[4:7]
	v_mfma_f32_16x16x32_bf16 v[0:3], v[172:175], v[204:207], v[0:3]
	v_mfma_f32_16x16x32_bf16 v[52:55], v[168:171], v[184:187], v[52:55]
	v_mfma_f32_16x16x32_bf16 v[48:51], v[176:179], v[184:187], v[48:51]
	v_mfma_f32_16x16x32_bf16 v[36:39], v[168:171], v[192:195], v[36:39]
	v_mfma_f32_16x16x32_bf16 v[32:35], v[176:179], v[192:195], v[32:35]
	v_mfma_f32_16x16x32_bf16 v[20:23], v[168:171], v[200:203], v[20:23]
	v_mfma_f32_16x16x32_bf16 v[16:19], v[176:179], v[200:203], v[16:19]
	v_mfma_f32_16x16x32_bf16 v[4:7], v[168:171], v[208:211], v[4:7]
	v_mfma_f32_16x16x32_bf16 v[0:3], v[176:179], v[208:211], v[0:3]
	s_setprio 0
	s_barrier
	s_add_i32 s55, s55, 2
	s_add_u32 s22, s22, 0x100
	s_addc_u32 s23, s23, 0
	s_add_u32 s51, s51, 0x100
	s_addc_u32 s54, s54, 0
	s_cmp_gt_u32 s55, 13
	s_cbranch_scc0 .LBB0_1052
	s_and_b64 vcc, exec, s[8:9]
	s_cbranch_vccz .LBB0_1055
	s_barrier

; #define PG8_STAGE(bufoff, gbase, voff) do { _Pragma("unroll") for (int _i = 0; _i < 2; ++_i) \
;         __builtin_amdgcn_global_load_lds((const unsigned*)((const char*)(gbase) + (voff)[_i]), (LAS unsigned*)(lds + (bufoff) + ldsw + _i * 8192), 16, 0, 0); } while (0)
; #define PG8_LDA(dst, b, h) do { _Pragma("unroll") for (int m = 0; m < 4; ++m) _Pragma("unroll") for (int k = 0; k < 2; ++k) dst[m][k] = *(const LAS bf16x8*)(lds + PG8_SA(b, h) + aoff + m * 2048 + k * 1024); } while (0)
; #define PG8_LDB(dst, b, h) do { _Pragma("unroll") for (int n = 0; n < 2; ++n) _Pragma("unroll") for (int k = 0; k < 2; ++k) dst[n][k] = *(const LAS bf16x8*)(lds + PG8_SB(b, h) + boff + n * 2048 + k * 1024); } while (0)
; #define PG8_MMA(ai, bj, At, Bt) do { __builtin_amdgcn_s_setprio(1); _Pragma("unroll") for (int m = 0; m < 4; ++m) _Pragma("unroll") for (int n = 0; n < 2; ++n) _Pragma("unroll") for (int k = 0; k < 2; ++k) \
;         acc[ai][bj][m][n] = __builtin_amdgcn_mfma_f32_16x16x32_bf16(Bt[n][k], At[m][k], acc[ai][bj][m][n], 0, 0, 0); __builtin_amdgcn_s_setprio(0); } while (0)
; #define PG8_WAIT_V(n) asm volatile("s_waitcnt vmcnt(" #n ")" ::: "memory")
; #define PG8_WAIT_L(n) asm volatile("s_waitcnt lgkmcnt(" #n ")" ::: "memory")
; #define PG8_BAR __builtin_amdgcn_s_barrier()
; template <class Epi, bool ALIGN_EPI, int K, int LDA, int LDB>
; __device__ __forceinline__ void gemm_phase(LAS unsigned char* lds, const int wid, const Gemm g, const StaticOrder& S, const Epi& E) {
;     ...
;         for (int t = 0; t < nt; t += 2) {
;             const bool last = (t == nt - 2);
;             const char* a1 = cA + (size_t)(t + 1) * kstep;
;             const char* a2 = last ? nA : cA + (size_t)(t + 2) * kstep; const char* b2 = last ? nB : cB + (size_t)(t + 2) * kstep;
;             const char* a3 = a2 + kstep; const char* b3 = b2 + kstep;
;             PG8_LDB(B0, 0, 0); PG8_LDB(B1, 0, 1); PG8_SCHED; PG8_LDA(At, 0, 0); PG8_STAGE(PG8_SA(1, 1), a1 + hA, voffA);
;             PG8_WAIT_V(8); PG8_WAIT_L(0); PG8_BAR; PG8_MMA(0, 0, At, B0); PG8_MMA(0, 1, At, B1); PG8_BAR; PG8_SCHED;
;             PG8_LDA(At, 0, 1); PG8_STAGE(PG8_SB(0, 0), b2, voffB); PG8_STAGE(PG8_SB(0, 1), b2 + hB, voffB); PG8_STAGE(PG8_SA(0, 0), a2, voffA);
;             PG8_WAIT_V(8); PG8_WAIT_L(0); PG8_BAR; PG8_MMA(1, 0, At, B0); PG8_MMA(1, 1, At, B1); PG8_BAR; PG8_SCHED;
.LBB0_1137:
	ds_read_b128 v[128:131], v175
	ds_read_b128 v[132:135], v175 offset:1024
	ds_read_b128 v[136:139], v175 offset:2048
	ds_read_b128 v[140:143], v175 offset:3072
	ds_read_b128 v[144:147], v176
	ds_read_b128 v[164:167], v176 offset:1024
	ds_read_b128 v[168:171], v176 offset:2048
	ds_read_b128 v[178:181], v176 offset:3072
	s_add_u32 s28, s26, 0x100
	s_addc_u32 s29, s27, 0
	s_cmp_eq_u32 s67, 40
	s_cselect_b32 s35, s7, s29
	s_cselect_b32 s34, s6, s28
	s_cselect_b32 s31, s25, s66
	s_cselect_b32 s30, s24, s65
	s_add_i32 m0, s36, 0xc000
	ds_read_b128 v[182:185], v177
	ds_read_b128 v[186:189], v177 offset:1024
	ds_read_b128 v[190:193], v177 offset:2048
	ds_read_b128 v[194:197], v177 offset:3072
	ds_read_b128 v[198:201], v177 offset:4096
	ds_read_b128 v[202:205], v177 offset:5120
	ds_read_b128 v[206:209], v177 offset:6144
	ds_read_b128 v[210:213], v177 offset:7168
	global_load_lds_dwordx4 v156, s[26:27]
	s_add_i32 m0, s36, 0xe000
	s_nop 0
	global_load_lds_dwordx4 v158, s[26:27]
	s_waitcnt vmcnt(8)
	s_waitcnt lgkmcnt(0)
	s_barrier
	s_setprio 1
	s_waitcnt lgkmcnt(0)
	v_mfma_f32_16x16x32_bf16 v[124:127], v[128:131], v[182:185], v[124:127]
	v_mfma_f32_16x16x32_bf16 v[116:119], v[136:139], v[182:185], v[116:119]
	v_mfma_f32_16x16x32_bf16 v[120:123], v[128:131], v[190:193], v[120:123]
	v_mfma_f32_16x16x32_bf16 v[112:115], v[136:139], v[190:193], v[112:115]
	v_mfma_f32_16x16x32_bf16 v[92:95], v[128:131], v[198:201], v[92:95]
	v_mfma_f32_16x16x32_bf16 v[88:91], v[136:139], v[198:201], v[88:91]
	v_mfma_f32_16x16x32_bf16 v[76:79], v[128:131], v[206:209], v[76:79]
	v_mfma_f32_16x16x32_bf16 v[72:75], v[136:139], v[206:209], v[72:75]
	v_mfma_f32_16x16x32_bf16 v[124:127], v[132:135], v[186:189], v[124:127]
	v_mfma_f32_16x16x32_bf16 v[116:119], v[140:143], v[186:189], v[116:119]
	v_mfma_f32_16x16x32_bf16 v[120:123], v[132:135], v[194:197], v[120:123]
	v_mfma_f32_16x16x32_bf16 v[112:115], v[140:143], v[194:197], v[112:115]
	v_mfma_f32_16x16x32_bf16 v[92:95], v[132:135], v[202:205], v[92:95]
	v_mfma_f32_16x16x32_bf16 v[88:91], v[140:143], v[202:205], v[88:91]
	v_mfma_f32_16x16x32_bf16 v[76:79], v[132:135], v[210:213], v[76:79]
	v_mfma_f32_16x16x32_bf16 v[72:75], v[140:143], v[210:213], v[72:75]
	v_mfma_f32_16x16x32_bf16 v[108:111], v[144:147], v[182:185], v[108:111]
	v_mfma_f32_16x16x32_bf16 v[104:107], v[168:171], v[182:185], v[104:107]
	v_mfma_f32_16x16x32_bf16 v[100:103], v[144:147], v[190:193], v[100:103]
	v_mfma_f32_16x16x32_bf16 v[96:99], v[168:171], v[190:193], v[96:99]
	v_mfma_f32_16x16x32_bf16 v[84:87], v[144:147], v[198:201], v[84:87]
	v_mfma_f32_16x16x32_bf16 v[80:83], v[168:171], v[198:201], v[80:83]
	v_mfma_f32_16x16x32_bf16 v[68:71], v[144:147], v[206:209], v[68:71]
	v_mfma_f32_16x16x32_bf16 v[64:67], v[168:171], v[206:209], v[64:67]
	v_mfma_f32_16x16x32_bf16 v[108:111], v[164:167], v[186:189], v[108:111]
	v_mfma_f32_16x16x32_bf16 v[104:107], v[178:181], v[186:189], v[104:107]
	v_mfma_f32_16x16x32_bf16 v[100:103], v[164:167], v[194:197], v[100:103]
	v_mfma_f32_16x16x32_bf16 v[96:99], v[178:181], v[194:197], v[96:99]
	v_mfma_f32_16x16x32_bf16 v[84:87], v[164:167], v[202:205], v[84:87]
	v_mfma_f32_16x16x32_bf16 v[80:83], v[178:181], v[202:205], v[80:83]
	v_mfma_f32_16x16x32_bf16 v[68:71], v[164:167], v[210:213], v[68:71]
	v_mfma_f32_16x16x32_bf16 v[64:67], v[178:181], v[210:213], v[64:67]
	s_setprio 0
	s_barrier
	s_add_u32 s98, s30, s12
	s_addc_u32 s99, s31, s13
	s_add_u32 s100, s34, s12
	s_addc_u32 s101, s35, s13
	s_add_i32 s26, s54, s33
	s_mov_b32 m0, s26
	ds_read_b128 v[182:185], v177 offset:16384
	ds_read_b128 v[186:189], v177 offset:17408
	ds_read_b128 v[190:193], v177 offset:18432
	ds_read_b128 v[194:197], v177 offset:19456
	ds_read_b128 v[198:201], v177 offset:20480
	ds_read_b128 v[202:205], v177 offset:21504
	ds_read_b128 v[206:209], v177 offset:22528
	ds_read_b128 v[210:213], v177 offset:23552
	global_load_lds_dwordx4 v150, s[30:31]
	s_add_i32 m0, s26, 0x2000
	s_add_u32 s26, s30, 0xb0000
	s_addc_u32 s27, s31, 0
	s_add_i32 s52, s55, s33
	global_load_lds_dwordx4 v154, s[30:31]
	s_mov_b32 m0, s52
	s_nop 0
	global_load_lds_dwordx4 v150, s[26:27]
	s_add_i32 m0, s52, 0x2000
	s_nop 0
	global_load_lds_dwordx4 v154, s[26:27]
	s_mov_b32 m0, s36
	s_nop 0
	global_load_lds_dwordx4 v148, s[34:35]
	s_mov_b32 m0, s37
	s_nop 0
	global_load_lds_dwordx4 v152, s[34:35]
	s_waitcnt vmcnt(8)
	s_waitcnt lgkmcnt(0)
	s_barrier
	s_setprio 1
	s_waitcnt lgkmcnt(0)
	v_mfma_f32_16x16x32_bf16 v[60:63], v[128:131], v[182:185], v[60:63]
	v_mfma_f32_16x16x32_bf16 v[56:59], v[136:139], v[182:185], v[56:59]
	v_mfma_f32_16x16x32_bf16 v[44:47], v[128:131], v[190:193], v[44:47]
	v_mfma_f32_16x16x32_bf16 v[40:43], v[136:139], v[190:193], v[40:43]
	v_mfma_f32_16x16x32_bf16 v[36:39], v[128:131], v[198:201], v[36:39]
	v_mfma_f32_16x16x32_bf16 v[32:35], v[136:139], v[198:201], v[32:35]
	v_mfma_f32_16x16x32_bf16 v[20:23], v[128:131], v[206:209], v[20:23]
	v_mfma_f32_16x16x32_bf16 v[16:19], v[136:139], v[206:209], v[16:19]
	v_mfma_f32_16x16x32_bf16 v[60:63], v[132:135], v[186:189], v[60:63]
	v_mfma_f32_16x16x32_bf16 v[56:59], v[140:143], v[186:189], v[56:59]
	v_mfma_f32_16x16x32_bf16 v[44:47], v[132:135], v[194:197], v[44:47]
	v_mfma_f32_16x16x32_bf16 v[40:43], v[140:143], v[194:197], v[40:43]
	v_mfma_f32_16x16x32_bf16 v[36:39], v[132:135], v[202:205], v[36:39]
	v_mfma_f32_16x16x32_bf16 v[32:35], v[140:143], v[202:205], v[32:35]
	v_mfma_f32_16x16x32_bf16 v[20:23], v[132:135], v[210:213], v[20:23]
	v_mfma_f32_16x16x32_bf16 v[16:19], v[140:143], v[210:213], v[16:19]
	v_mfma_f32_16x16x32_bf16 v[52:55], v[144:147], v[182:185], v[52:55]
	v_mfma_f32_16x16x32_bf16 v[48:51], v[168:171], v[182:185], v[48:51]
	v_mfma_f32_16x16x32_bf16 v[28:31], v[144:147], v[190:193], v[28:31]
	v_mfma_f32_16x16x32_bf16 v[24:27], v[168:171], v[190:193], v[24:27]
	v_mfma_f32_16x16x32_bf16 v[12:15], v[144:147], v[198:201], v[12:15]
	v_mfma_f32_16x16x32_bf16 v[8:11], v[168:171], v[198:201], v[8:11]
	v_mfma_f32_16x16x32_bf16 v[4:7], v[144:147], v[206:209], v[4:7]
	v_mfma_f32_16x16x32_bf16 v[0:3], v[168:171], v[206:209], v[0:3]
	v_mfma_f32_16x16x32_bf16 v[52:55], v[164:167], v[186:189], v[52:55]
	v_mfma_f32_16x16x32_bf16 v[48:51], v[178:181], v[186:189], v[48:51]
	v_mfma_f32_16x16x32_bf16 v[28:31], v[164:167], v[194:197], v[28:31]
	v_mfma_f32_16x16x32_bf16 v[24:27], v[178:181], v[194:197], v[24:27]
	v_mfma_f32_16x16x32_bf16 v[12:15], v[164:167], v[202:205], v[12:15]
	v_mfma_f32_16x16x32_bf16 v[8:11], v[178:181], v[202:205], v[8:11]
	v_mfma_f32_16x16x32_bf16 v[4:7], v[164:167], v[210:213], v[4:7]
	v_mfma_f32_16x16x32_bf16 v[0:3], v[178:181], v[210:213], v[0:3]
	s_setprio 0
	s_barrier
; __device__ __forceinline__ int lane_id_() { int l; asm volatile("v_mbcnt_lo_u32_b32 %0, -1, 0\n\tv_mbcnt_hi_u32_b32 %0, -1, %0" : "=v"(l)); return l; }
; #define PG8_STAGE(bufoff, gbase, voff) do { _Pragma("unroll") for (int _i = 0; _i < 2; ++_i) \
;         __builtin_amdgcn_global_load_lds((const unsigned*)((const char*)(gbase) + (voff)[_i]), (LAS unsigned*)(lds + (bufoff) + ldsw + _i * 8192), 16, 0, 0); } while (0)
; #define PG8_LDA(dst, b, h) do { _Pragma("unroll") for (int m = 0; m < 4; ++m) _Pragma("unroll") for (int k = 0; k < 2; ++k) dst[m][k] = *(const LAS bf16x8*)(lds + PG8_SA(b, h) + aoff + m * 2048 + k * 1024); } while (0)
; #define PG8_LDB(dst, b, h) do { _Pragma("unroll") for (int n = 0; n < 2; ++n) _Pragma("unroll") for (int k = 0; k < 2; ++k) dst[n][k] = *(const LAS bf16x8*)(lds + PG8_SB(b, h) + boff + n * 2048 + k * 1024); } while (0)
; #define PG8_MMA(ai, bj, At, Bt) do { __builtin_amdgcn_s_setprio(1); _Pragma("unroll") for (int m = 0; m < 4; ++m) _Pragma("unroll") for (int n = 0; n < 2; ++n) _Pragma("unroll") for (int k = 0; k < 2; ++k) \
;         acc[ai][bj][m][n] = __builtin_amdgcn_mfma_f32_16x16x32_bf16(Bt[n][k], At[m][k], acc[ai][bj][m][n], 0, 0, 0); __builtin_amdgcn_s_setprio(0); } while (0)
; #define PG8_WAIT_V(n) asm volatile("s_waitcnt vmcnt(" #n ")" ::: "memory")
; #define PG8_WAIT_L(n) asm volatile("s_waitcnt lgkmcnt(" #n ")" ::: "memory")
; #define PG8_BAR __builtin_amdgcn_s_barrier()
; #define PG8_SCHED __builtin_amdgcn_sched_barrier(0)
; template <class Epi, bool ALIGN_EPI, int K, int LDA, int LDB>
; __device__ __forceinline__ void gemm_phase(LAS unsigned char* lds, const int wid, const Gemm g, const StaticOrder& S, const Epi& E) {
;     ...
;             PG8_LDB(B0, 1, 0); PG8_LDB(B1, 1, 1); PG8_SCHED; PG8_LDA(At, 1, 0); PG8_STAGE(PG8_SA(0, 1), a2 + hA, voffA);
;             PG8_WAIT_V(8); PG8_WAIT_L(0); PG8_BAR; PG8_MMA(0, 0, At, B0); PG8_MMA(0, 1, At, B1); PG8_BAR; PG8_SCHED;
;             PG8_LDA(At, 1, 1); PG8_STAGE(PG8_SB(1, 0), b3, voffB); PG8_STAGE(PG8_SB(1, 1), b3 + hB, voffB); PG8_STAGE(PG8_SA(1, 0), a3, voffA);
;             PG8_WAIT_V(8); PG8_WAIT_L(0); PG8_BAR; PG8_MMA(1, 0, At, B0); PG8_MMA(1, 1, At, B1); PG8_BAR; PG8_SCHED;
;         }
;         if constexpr (ALIGN_EPI) { if (wr == 0) PG8_BAR; }
;         { const int l2 = lane_id_(); E(acc, cur, wid >> 2, wid & 3, l2 & 15, l2 >> 4); }
;         if (!has_next) break;
	s_add_i32 s52, 0, 0x18000
	s_add_i32 s53, 0, 0x1c000
	v_add_u32_e32 v140, s52, v174
	v_add_u32_e32 v178, s53, v174
	ds_read_b128 v[128:131], v140
	ds_read_b128 v[132:135], v140 offset:1024
	ds_read_b128 v[136:139], v140 offset:2048
	ds_read_b128 v[140:143], v140 offset:3072
	ds_read_b128 v[144:147], v178
	ds_read_b128 v[164:167], v178 offset:1024
	ds_read_b128 v[168:171], v178 offset:2048
	ds_read_b128 v[178:181], v178 offset:3072
	s_add_u32 s26, s34, 0xb0000
	s_addc_u32 s27, s35, 0
	s_mov_b32 m0, s38
	ds_read_b128 v[182:185], v177 offset:32768
	ds_read_b128 v[186:189], v177 offset:33792
	ds_read_b128 v[190:193], v177 offset:34816
	ds_read_b128 v[194:197], v177 offset:35840
	ds_read_b128 v[198:201], v177 offset:36864
	ds_read_b128 v[202:205], v177 offset:37888
	ds_read_b128 v[206:209], v177 offset:38912
	ds_read_b128 v[210:213], v177 offset:39936
	global_load_lds_dwordx4 v148, s[26:27]
	s_mov_b32 m0, s39
	s_nop 0
	global_load_lds_dwordx4 v152, s[26:27]
	s_waitcnt vmcnt(8)
	s_waitcnt lgkmcnt(0)
	s_barrier
	s_setprio 1
	s_waitcnt lgkmcnt(0)
	v_mfma_f32_16x16x32_bf16 v[124:127], v[128:131], v[182:185], v[124:127]
	v_mfma_f32_16x16x32_bf16 v[116:119], v[136:139], v[182:185], v[116:119]
	v_mfma_f32_16x16x32_bf16 v[120:123], v[128:131], v[190:193], v[120:123]
	v_mfma_f32_16x16x32_bf16 v[112:115], v[136:139], v[190:193], v[112:115]
	v_mfma_f32_16x16x32_bf16 v[92:95], v[128:131], v[198:201], v[92:95]
	v_mfma_f32_16x16x32_bf16 v[88:91], v[136:139], v[198:201], v[88:91]
	v_mfma_f32_16x16x32_bf16 v[76:79], v[128:131], v[206:209], v[76:79]
	v_mfma_f32_16x16x32_bf16 v[72:75], v[136:139], v[206:209], v[72:75]
	v_mfma_f32_16x16x32_bf16 v[124:127], v[132:135], v[186:189], v[124:127]
	v_mfma_f32_16x16x32_bf16 v[116:119], v[140:143], v[186:189], v[116:119]
	v_mfma_f32_16x16x32_bf16 v[120:123], v[132:135], v[194:197], v[120:123]
	v_mfma_f32_16x16x32_bf16 v[112:115], v[140:143], v[194:197], v[112:115]
	v_mfma_f32_16x16x32_bf16 v[92:95], v[132:135], v[202:205], v[92:95]
	v_mfma_f32_16x16x32_bf16 v[88:91], v[140:143], v[202:205], v[88:91]
	v_mfma_f32_16x16x32_bf16 v[76:79], v[132:135], v[210:213], v[76:79]
	v_mfma_f32_16x16x32_bf16 v[72:75], v[140:143], v[210:213], v[72:75]
	v_mfma_f32_16x16x32_bf16 v[108:111], v[144:147], v[182:185], v[108:111]
	v_mfma_f32_16x16x32_bf16 v[104:107], v[168:171], v[182:185], v[104:107]
	v_mfma_f32_16x16x32_bf16 v[100:103], v[144:147], v[190:193], v[100:103]
	v_mfma_f32_16x16x32_bf16 v[96:99], v[168:171], v[190:193], v[96:99]
	v_mfma_f32_16x16x32_bf16 v[84:87], v[144:147], v[198:201], v[84:87]
	v_mfma_f32_16x16x32_bf16 v[80:83], v[168:171], v[198:201], v[80:83]
	v_mfma_f32_16x16x32_bf16 v[68:71], v[144:147], v[206:209], v[68:71]
	v_mfma_f32_16x16x32_bf16 v[64:67], v[168:171], v[206:209], v[64:67]
	v_mfma_f32_16x16x32_bf16 v[108:111], v[164:167], v[186:189], v[108:111]
	v_mfma_f32_16x16x32_bf16 v[104:107], v[178:181], v[186:189], v[104:107]
	v_mfma_f32_16x16x32_bf16 v[100:103], v[164:167], v[194:197], v[100:103]
	v_mfma_f32_16x16x32_bf16 v[96:99], v[178:181], v[194:197], v[96:99]
	v_mfma_f32_16x16x32_bf16 v[84:87], v[164:167], v[202:205], v[84:87]
	v_mfma_f32_16x16x32_bf16 v[80:83], v[178:181], v[202:205], v[80:83]
	v_mfma_f32_16x16x32_bf16 v[68:71], v[164:167], v[210:213], v[68:71]
	v_mfma_f32_16x16x32_bf16 v[64:67], v[178:181], v[210:213], v[64:67]
	s_setprio 0
	s_barrier
	s_add_i32 s26, s52, s33
	s_mov_b32 m0, s26
	ds_read_b128 v[182:185], v177 offset:49152
	ds_read_b128 v[186:189], v177 offset:50176
	ds_read_b128 v[190:193], v177 offset:51200
	ds_read_b128 v[194:197], v177 offset:52224
	ds_read_b128 v[198:201], v177 offset:53248
	ds_read_b128 v[202:205], v177 offset:54272
	ds_read_b128 v[206:209], v177 offset:55296
	ds_read_b128 v[210:213], v177 offset:56320
	global_load_lds_dwordx4 v150, s[98:99]
	s_add_i32 m0, s26, 0x2000
	s_add_u32 s26, s30, 0xb0080
	s_addc_u32 s27, s31, 0
	s_add_i32 s30, s53, s33
	global_load_lds_dwordx4 v154, s[98:99]
	s_mov_b32 m0, s30
	s_nop 0
	global_load_lds_dwordx4 v150, s[26:27]
	s_add_i32 m0, s30, 0x2000
	s_nop 0
	global_load_lds_dwordx4 v154, s[26:27]
	s_mov_b32 m0, s48
	s_nop 0
	global_load_lds_dwordx4 v148, s[100:101]
	s_mov_b32 m0, s49
	s_nop 0
	global_load_lds_dwordx4 v152, s[100:101]
	s_waitcnt vmcnt(8)
	s_waitcnt lgkmcnt(0)
	s_barrier
	s_setprio 1
	s_waitcnt lgkmcnt(0)
	v_mfma_f32_16x16x32_bf16 v[60:63], v[128:131], v[182:185], v[60:63]
	v_mfma_f32_16x16x32_bf16 v[56:59], v[136:139], v[182:185], v[56:59]
	v_mfma_f32_16x16x32_bf16 v[44:47], v[128:131], v[190:193], v[44:47]
	v_mfma_f32_16x16x32_bf16 v[40:43], v[136:139], v[190:193], v[40:43]
	v_mfma_f32_16x16x32_bf16 v[36:39], v[128:131], v[198:201], v[36:39]
	v_mfma_f32_16x16x32_bf16 v[32:35], v[136:139], v[198:201], v[32:35]
	v_mfma_f32_16x16x32_bf16 v[20:23], v[128:131], v[206:209], v[20:23]
	v_mfma_f32_16x16x32_bf16 v[16:19], v[136:139], v[206:209], v[16:19]
	v_mfma_f32_16x16x32_bf16 v[60:63], v[132:135], v[186:189], v[60:63]
	v_mfma_f32_16x16x32_bf16 v[56:59], v[140:143], v[186:189], v[56:59]
	v_mfma_f32_16x16x32_bf16 v[44:47], v[132:135], v[194:197], v[44:47]
	v_mfma_f32_16x16x32_bf16 v[40:43], v[140:143], v[194:197], v[40:43]
	v_mfma_f32_16x16x32_bf16 v[36:39], v[132:135], v[202:205], v[36:39]
	v_mfma_f32_16x16x32_bf16 v[32:35], v[140:143], v[202:205], v[32:35]
	v_mfma_f32_16x16x32_bf16 v[20:23], v[132:135], v[210:213], v[20:23]
	v_mfma_f32_16x16x32_bf16 v[16:19], v[140:143], v[210:213], v[16:19]
	v_mfma_f32_16x16x32_bf16 v[52:55], v[144:147], v[182:185], v[52:55]
	v_mfma_f32_16x16x32_bf16 v[48:51], v[168:171], v[182:185], v[48:51]
	v_mfma_f32_16x16x32_bf16 v[28:31], v[144:147], v[190:193], v[28:31]
	v_mfma_f32_16x16x32_bf16 v[24:27], v[168:171], v[190:193], v[24:27]
	v_mfma_f32_16x16x32_bf16 v[12:15], v[144:147], v[198:201], v[12:15]
	v_mfma_f32_16x16x32_bf16 v[8:11], v[168:171], v[198:201], v[8:11]
	v_mfma_f32_16x16x32_bf16 v[4:7], v[144:147], v[206:209], v[4:7]
	v_mfma_f32_16x16x32_bf16 v[0:3], v[168:171], v[206:209], v[0:3]
	v_mfma_f32_16x16x32_bf16 v[52:55], v[164:167], v[186:189], v[52:55]
	v_mfma_f32_16x16x32_bf16 v[48:51], v[178:181], v[186:189], v[48:51]
	v_mfma_f32_16x16x32_bf16 v[28:31], v[164:167], v[194:197], v[28:31]
	v_mfma_f32_16x16x32_bf16 v[24:27], v[178:181], v[194:197], v[24:27]
	v_mfma_f32_16x16x32_bf16 v[12:15], v[164:167], v[202:205], v[12:15]
	v_mfma_f32_16x16x32_bf16 v[8:11], v[178:181], v[202:205], v[8:11]
	v_mfma_f32_16x16x32_bf16 v[4:7], v[164:167], v[210:213], v[4:7]
	v_mfma_f32_16x16x32_bf16 v[0:3], v[178:181], v[210:213], v[0:3]
	s_setprio 0
	s_barrier
	s_add_i32 s67, s67, 2
	s_add_u32 s65, s65, 0x100
	s_addc_u32 s66, s66, 0
	s_cmp_gt_u32 s67, 41
	s_mov_b64 s[26:27], s[28:29]
	s_cbranch_scc0 .LBB0_1137
	s_and_b64 vcc, exec, s[14:15]
	s_cbranch_vccz .LBB0_1140
	s_barrier

; #define PG8_STAGE(bufoff, gbase, voff) do { _Pragma("unroll") for (int _i = 0; _i < 2; ++_i) \
;         __builtin_amdgcn_global_load_lds((const unsigned*)((const char*)(gbase) + (voff)[_i]), (LAS unsigned*)(lds + (bufoff) + ldsw + _i * 8192), 16, 0, 0); } while (0)
; #define PG8_LDA(dst, b, h) do { _Pragma("unroll") for (int m = 0; m < 4; ++m) _Pragma("unroll") for (int k = 0; k < 2; ++k) dst[m][k] = *(const LAS bf16x8*)(lds + PG8_SA(b, h) + aoff + m * 2048 + k * 1024); } while (0)
; #define PG8_LDB(dst, b, h) do { _Pragma("unroll") for (int n = 0; n < 2; ++n) _Pragma("unroll") for (int k = 0; k < 2; ++k) dst[n][k] = *(const LAS bf16x8*)(lds + PG8_SB(b, h) + boff + n * 2048 + k * 1024); } while (0)
; #define PG8_MMA(ai, bj, At, Bt) do { __builtin_amdgcn_s_setprio(1); _Pragma("unroll") for (int m = 0; m < 4; ++m) _Pragma("unroll") for (int n = 0; n < 2; ++n) _Pragma("unroll") for (int k = 0; k < 2; ++k) \
;         acc[ai][bj][m][n] = __builtin_amdgcn_mfma_f32_16x16x32_bf16(Bt[n][k], At[m][k], acc[ai][bj][m][n], 0, 0, 0); __builtin_amdgcn_s_setprio(0); } while (0)
; #define PG8_WAIT_V(n) asm volatile("s_waitcnt vmcnt(" #n ")" ::: "memory")
; #define PG8_WAIT_L(n) asm volatile("s_waitcnt lgkmcnt(" #n ")" ::: "memory")
; #define PG8_BAR __builtin_amdgcn_s_barrier()
; template <class Epi, bool ALIGN_EPI, int K, int LDA, int LDB>
; __device__ __forceinline__ void gemm_phase(LAS unsigned char* lds, const int wid, const Gemm g, const StaticOrder& S, const Epi& E) {
;     ...
;         for (int t = 0; t < nt; t += 2) {
;             const bool last = (t == nt - 2);
;             const char* a1 = cA + (size_t)(t + 1) * kstep;
;             const char* a2 = last ? nA : cA + (size_t)(t + 2) * kstep; const char* b2 = last ? nB : cB + (size_t)(t + 2) * kstep;
;             const char* a3 = a2 + kstep; const char* b3 = b2 + kstep;
;             PG8_LDB(B0, 0, 0); PG8_LDB(B1, 0, 1); PG8_SCHED; PG8_LDA(At, 0, 0); PG8_STAGE(PG8_SA(1, 1), a1 + hA, voffA);
;             PG8_WAIT_V(8); PG8_WAIT_L(0); PG8_BAR; PG8_MMA(0, 0, At, B0); PG8_MMA(0, 1, At, B1); PG8_BAR; PG8_SCHED;
;             PG8_LDA(At, 0, 1); PG8_STAGE(PG8_SB(0, 0), b2, voffB); PG8_STAGE(PG8_SB(0, 1), b2 + hB, voffB); PG8_STAGE(PG8_SA(0, 0), a2, voffA);
;             PG8_WAIT_V(8); PG8_WAIT_L(0); PG8_BAR; PG8_MMA(1, 0, At, B0); PG8_MMA(1, 1, At, B1); PG8_BAR; PG8_SCHED;
.LBB0_1279:
	ds_read_b128 v[144:147], v151
	ds_read_b128 v[154:157], v151 offset:1024
	ds_read_b128 v[158:161], v151 offset:2048
	ds_read_b128 v[162:165], v151 offset:3072
	ds_read_b128 v[166:169], v152
	ds_read_b128 v[170:173], v152 offset:1024
	ds_read_b128 v[174:177], v152 offset:2048
	ds_read_b128 v[178:181], v152 offset:3072
	s_add_u32 s36, s34, 0xfffc0080
	s_addc_u32 s37, s35, -1
	s_cmp_eq_u32 s61, 12
	s_cselect_b32 s39, s7, s37
	s_cselect_b32 s38, s25, s36
	s_cselect_b32 s37, s23, s60
	s_cselect_b32 s36, s42, s59
	s_add_i32 m0, s31, 0xc000
	ds_read_b128 v[182:185], v153
	ds_read_b128 v[186:189], v153 offset:1024
	ds_read_b128 v[190:193], v153 offset:2048
	ds_read_b128 v[194:197], v153 offset:3072
	ds_read_b128 v[198:201], v153 offset:4096
	ds_read_b128 v[202:205], v153 offset:5120
	ds_read_b128 v[206:209], v153 offset:6144
	ds_read_b128 v[210:213], v153 offset:7168
	global_load_lds_dwordx4 v136, s[34:35]
	s_add_i32 m0, s31, 0xe000
	s_nop 0
	global_load_lds_dwordx4 v138, s[34:35]
	s_waitcnt vmcnt(8)
	s_waitcnt lgkmcnt(0)
	s_barrier
	s_setprio 1
	s_waitcnt lgkmcnt(0)
	v_mfma_f32_16x16x32_bf16 v[124:127], v[144:147], v[182:185], v[124:127]
	v_mfma_f32_16x16x32_bf16 v[120:123], v[158:161], v[182:185], v[120:123]
	v_mfma_f32_16x16x32_bf16 v[108:111], v[144:147], v[190:193], v[108:111]
	v_mfma_f32_16x16x32_bf16 v[104:107], v[158:161], v[190:193], v[104:107]
	v_mfma_f32_16x16x32_bf16 v[92:95], v[144:147], v[198:201], v[92:95]
	v_mfma_f32_16x16x32_bf16 v[88:91], v[158:161], v[198:201], v[88:91]
	v_mfma_f32_16x16x32_bf16 v[76:79], v[144:147], v[206:209], v[76:79]
	v_mfma_f32_16x16x32_bf16 v[72:75], v[158:161], v[206:209], v[72:75]
	v_mfma_f32_16x16x32_bf16 v[124:127], v[154:157], v[186:189], v[124:127]
	v_mfma_f32_16x16x32_bf16 v[120:123], v[162:165], v[186:189], v[120:123]
	v_mfma_f32_16x16x32_bf16 v[108:111], v[154:157], v[194:197], v[108:111]
	v_mfma_f32_16x16x32_bf16 v[104:107], v[162:165], v[194:197], v[104:107]
	v_mfma_f32_16x16x32_bf16 v[92:95], v[154:157], v[202:205], v[92:95]
	v_mfma_f32_16x16x32_bf16 v[88:91], v[162:165], v[202:205], v[88:91]
	v_mfma_f32_16x16x32_bf16 v[76:79], v[154:157], v[210:213], v[76:79]
	v_mfma_f32_16x16x32_bf16 v[72:75], v[162:165], v[210:213], v[72:75]
	v_mfma_f32_16x16x32_bf16 v[116:119], v[166:169], v[182:185], v[116:119]
	v_mfma_f32_16x16x32_bf16 v[112:115], v[174:177], v[182:185], v[112:115]
	v_mfma_f32_16x16x32_bf16 v[100:103], v[166:169], v[190:193], v[100:103]
	v_mfma_f32_16x16x32_bf16 v[96:99], v[174:177], v[190:193], v[96:99]
	v_mfma_f32_16x16x32_bf16 v[84:87], v[166:169], v[198:201], v[84:87]
	v_mfma_f32_16x16x32_bf16 v[80:83], v[174:177], v[198:201], v[80:83]
	v_mfma_f32_16x16x32_bf16 v[68:71], v[166:169], v[206:209], v[68:71]
	v_mfma_f32_16x16x32_bf16 v[64:67], v[174:177], v[206:209], v[64:67]
	v_mfma_f32_16x16x32_bf16 v[116:119], v[170:173], v[186:189], v[116:119]
	v_mfma_f32_16x16x32_bf16 v[112:115], v[178:181], v[186:189], v[112:115]
	v_mfma_f32_16x16x32_bf16 v[100:103], v[170:173], v[194:197], v[100:103]
	v_mfma_f32_16x16x32_bf16 v[96:99], v[178:181], v[194:197], v[96:99]
	v_mfma_f32_16x16x32_bf16 v[84:87], v[170:173], v[202:205], v[84:87]
	v_mfma_f32_16x16x32_bf16 v[80:83], v[178:181], v[202:205], v[80:83]
	v_mfma_f32_16x16x32_bf16 v[68:71], v[170:173], v[210:213], v[68:71]
	v_mfma_f32_16x16x32_bf16 v[64:67], v[178:181], v[210:213], v[64:67]
	s_setprio 0
	s_barrier
	s_add_u32 s98, s36, s12
	s_addc_u32 s99, s37, s13
	s_add_u32 s100, s38, s12
	s_addc_u32 s101, s39, s13
	s_add_i32 s52, s57, s3
	s_mov_b32 m0, s52
	ds_read_b128 v[182:185], v153 offset:16384
	ds_read_b128 v[186:189], v153 offset:17408
	ds_read_b128 v[190:193], v153 offset:18432
	ds_read_b128 v[194:197], v153 offset:19456
	ds_read_b128 v[198:201], v153 offset:20480
	ds_read_b128 v[202:205], v153 offset:21504
	ds_read_b128 v[206:209], v153 offset:22528
	ds_read_b128 v[210:213], v153 offset:23552
	global_load_lds_dwordx4 v130, s[36:37]
	s_add_i32 m0, s52, 0x2000
	s_add_u32 s62, s36, 0x40000
	s_addc_u32 s63, s37, 0
	s_add_i32 s52, s58, s3
	global_load_lds_dwordx4 v134, s[36:37]
	s_mov_b32 m0, s52
	s_nop 0
	global_load_lds_dwordx4 v130, s[62:63]
	s_add_i32 m0, s52, 0x2000
	s_nop 0
	global_load_lds_dwordx4 v134, s[62:63]
	s_mov_b32 m0, s31
	s_nop 0
	global_load_lds_dwordx4 v128, s[38:39]
	s_mov_b32 m0, s33
	s_nop 0
	global_load_lds_dwordx4 v132, s[38:39]
	s_waitcnt vmcnt(8)
	s_waitcnt lgkmcnt(0)
	s_barrier
	s_setprio 1
	s_waitcnt lgkmcnt(0)
	v_mfma_f32_16x16x32_bf16 v[60:63], v[144:147], v[182:185], v[60:63]
	v_mfma_f32_16x16x32_bf16 v[56:59], v[158:161], v[182:185], v[56:59]
	v_mfma_f32_16x16x32_bf16 v[44:47], v[144:147], v[190:193], v[44:47]
	v_mfma_f32_16x16x32_bf16 v[40:43], v[158:161], v[190:193], v[40:43]
	v_mfma_f32_16x16x32_bf16 v[28:31], v[144:147], v[198:201], v[28:31]
	v_mfma_f32_16x16x32_bf16 v[24:27], v[158:161], v[198:201], v[24:27]
	v_mfma_f32_16x16x32_bf16 v[12:15], v[144:147], v[206:209], v[12:15]
	v_mfma_f32_16x16x32_bf16 v[8:11], v[158:161], v[206:209], v[8:11]
	v_mfma_f32_16x16x32_bf16 v[60:63], v[154:157], v[186:189], v[60:63]
	v_mfma_f32_16x16x32_bf16 v[56:59], v[162:165], v[186:189], v[56:59]
	v_mfma_f32_16x16x32_bf16 v[44:47], v[154:157], v[194:197], v[44:47]
	v_mfma_f32_16x16x32_bf16 v[40:43], v[162:165], v[194:197], v[40:43]
	v_mfma_f32_16x16x32_bf16 v[28:31], v[154:157], v[202:205], v[28:31]
	v_mfma_f32_16x16x32_bf16 v[24:27], v[162:165], v[202:205], v[24:27]
	v_mfma_f32_16x16x32_bf16 v[12:15], v[154:157], v[210:213], v[12:15]
	v_mfma_f32_16x16x32_bf16 v[8:11], v[162:165], v[210:213], v[8:11]
	v_mfma_f32_16x16x32_bf16 v[52:55], v[166:169], v[182:185], v[52:55]
	v_mfma_f32_16x16x32_bf16 v[48:51], v[174:177], v[182:185], v[48:51]
	v_mfma_f32_16x16x32_bf16 v[36:39], v[166:169], v[190:193], v[36:39]
	v_mfma_f32_16x16x32_bf16 v[32:35], v[174:177], v[190:193], v[32:35]
	v_mfma_f32_16x16x32_bf16 v[20:23], v[166:169], v[198:201], v[20:23]
	v_mfma_f32_16x16x32_bf16 v[16:19], v[174:177], v[198:201], v[16:19]
	v_mfma_f32_16x16x32_bf16 v[4:7], v[166:169], v[206:209], v[4:7]
	v_mfma_f32_16x16x32_bf16 v[0:3], v[174:177], v[206:209], v[0:3]
	v_mfma_f32_16x16x32_bf16 v[52:55], v[170:173], v[186:189], v[52:55]
	v_mfma_f32_16x16x32_bf16 v[48:51], v[178:181], v[186:189], v[48:51]
	v_mfma_f32_16x16x32_bf16 v[36:39], v[170:173], v[194:197], v[36:39]
	v_mfma_f32_16x16x32_bf16 v[32:35], v[178:181], v[194:197], v[32:35]
	v_mfma_f32_16x16x32_bf16 v[20:23], v[170:173], v[202:205], v[20:23]
	v_mfma_f32_16x16x32_bf16 v[16:19], v[178:181], v[202:205], v[16:19]
	v_mfma_f32_16x16x32_bf16 v[4:7], v[170:173], v[210:213], v[4:7]
	v_mfma_f32_16x16x32_bf16 v[0:3], v[178:181], v[210:213], v[0:3]
	s_setprio 0
	s_barrier
; __device__ __forceinline__ int lane_id_() { int l; asm volatile("v_mbcnt_lo_u32_b32 %0, -1, 0\n\tv_mbcnt_hi_u32_b32 %0, -1, %0" : "=v"(l)); return l; }
; #define PG8_STAGE(bufoff, gbase, voff) do { _Pragma("unroll") for (int _i = 0; _i < 2; ++_i) \
;         __builtin_amdgcn_global_load_lds((const unsigned*)((const char*)(gbase) + (voff)[_i]), (LAS unsigned*)(lds + (bufoff) + ldsw + _i * 8192), 16, 0, 0); } while (0)
; #define PG8_LDA(dst, b, h) do { _Pragma("unroll") for (int m = 0; m < 4; ++m) _Pragma("unroll") for (int k = 0; k < 2; ++k) dst[m][k] = *(const LAS bf16x8*)(lds + PG8_SA(b, h) + aoff + m * 2048 + k * 1024); } while (0)
; #define PG8_LDB(dst, b, h) do { _Pragma("unroll") for (int n = 0; n < 2; ++n) _Pragma("unroll") for (int k = 0; k < 2; ++k) dst[n][k] = *(const LAS bf16x8*)(lds + PG8_SB(b, h) + boff + n * 2048 + k * 1024); } while (0)
; #define PG8_MMA(ai, bj, At, Bt) do { __builtin_amdgcn_s_setprio(1); _Pragma("unroll") for (int m = 0; m < 4; ++m) _Pragma("unroll") for (int n = 0; n < 2; ++n) _Pragma("unroll") for (int k = 0; k < 2; ++k) \
;         acc[ai][bj][m][n] = __builtin_amdgcn_mfma_f32_16x16x32_bf16(Bt[n][k], At[m][k], acc[ai][bj][m][n], 0, 0, 0); __builtin_amdgcn_s_setprio(0); } while (0)
; #define PG8_WAIT_V(n) asm volatile("s_waitcnt vmcnt(" #n ")" ::: "memory")
; #define PG8_WAIT_L(n) asm volatile("s_waitcnt lgkmcnt(" #n ")" ::: "memory")
; #define PG8_BAR __builtin_amdgcn_s_barrier()
; #define PG8_SCHED __builtin_amdgcn_sched_barrier(0)
; template <class Epi, bool ALIGN_EPI, int K, int LDA, int LDB>
; __device__ __forceinline__ void gemm_phase(LAS unsigned char* lds, const int wid, const Gemm g, const StaticOrder& S, const Epi& E) {
;     ...
;             PG8_LDB(B0, 1, 0); PG8_LDB(B1, 1, 1); PG8_SCHED; PG8_LDA(At, 1, 0); PG8_STAGE(PG8_SA(0, 1), a2 + hA, voffA);
;             PG8_WAIT_V(8); PG8_WAIT_L(0); PG8_BAR; PG8_MMA(0, 0, At, B0); PG8_MMA(0, 1, At, B1); PG8_BAR; PG8_SCHED;
;             PG8_LDA(At, 1, 1); PG8_STAGE(PG8_SB(1, 0), b3, voffB); PG8_STAGE(PG8_SB(1, 1), b3 + hB, voffB); PG8_STAGE(PG8_SA(1, 0), a3, voffA);
;             PG8_WAIT_V(8); PG8_WAIT_L(0); PG8_BAR; PG8_MMA(1, 0, At, B0); PG8_MMA(1, 1, At, B1); PG8_BAR; PG8_SCHED;
;         }
;         if constexpr (ALIGN_EPI) { if (wr == 0) PG8_BAR; }
;         { const int l2 = lane_id_(); E(acc, cur, wid >> 2, wid & 3, l2 & 15, l2 >> 4); }
;         if (!has_next) break;
	s_add_i32 s52, 0, 0x18000
	s_add_i32 s53, 0, 0x1c000
	v_add_u32_e32 v162, s52, v150
	v_add_u32_e32 v178, s53, v150
	ds_read_b128 v[144:147], v162
	ds_read_b128 v[154:157], v162 offset:1024
	ds_read_b128 v[158:161], v162 offset:2048
	ds_read_b128 v[162:165], v162 offset:3072
	ds_read_b128 v[166:169], v178
	ds_read_b128 v[170:173], v178 offset:1024
	ds_read_b128 v[174:177], v178 offset:2048
	ds_read_b128 v[178:181], v178 offset:3072
	s_add_u32 s38, s38, 0x40000
	s_addc_u32 s39, s39, 0
	s_mov_b32 m0, s40
	ds_read_b128 v[182:185], v153 offset:32768
	ds_read_b128 v[186:189], v153 offset:33792
	ds_read_b128 v[190:193], v153 offset:34816
	ds_read_b128 v[194:197], v153 offset:35840
	ds_read_b128 v[198:201], v153 offset:36864
	ds_read_b128 v[202:205], v153 offset:37888
	ds_read_b128 v[206:209], v153 offset:38912
	ds_read_b128 v[210:213], v153 offset:39936
	global_load_lds_dwordx4 v128, s[38:39]
	s_mov_b32 m0, s41
	s_nop 0
	global_load_lds_dwordx4 v132, s[38:39]
	s_waitcnt vmcnt(8)
	s_waitcnt lgkmcnt(0)
	s_barrier
	s_setprio 1
	s_waitcnt lgkmcnt(0)
	v_mfma_f32_16x16x32_bf16 v[124:127], v[144:147], v[182:185], v[124:127]
	v_mfma_f32_16x16x32_bf16 v[120:123], v[158:161], v[182:185], v[120:123]
	v_mfma_f32_16x16x32_bf16 v[108:111], v[144:147], v[190:193], v[108:111]
	v_mfma_f32_16x16x32_bf16 v[104:107], v[158:161], v[190:193], v[104:107]
	v_mfma_f32_16x16x32_bf16 v[92:95], v[144:147], v[198:201], v[92:95]
	v_mfma_f32_16x16x32_bf16 v[88:91], v[158:161], v[198:201], v[88:91]
	v_mfma_f32_16x16x32_bf16 v[76:79], v[144:147], v[206:209], v[76:79]
	v_mfma_f32_16x16x32_bf16 v[72:75], v[158:161], v[206:209], v[72:75]
	v_mfma_f32_16x16x32_bf16 v[124:127], v[154:157], v[186:189], v[124:127]
	v_mfma_f32_16x16x32_bf16 v[120:123], v[162:165], v[186:189], v[120:123]
	v_mfma_f32_16x16x32_bf16 v[108:111], v[154:157], v[194:197], v[108:111]
	v_mfma_f32_16x16x32_bf16 v[104:107], v[162:165], v[194:197], v[104:107]
	v_mfma_f32_16x16x32_bf16 v[92:95], v[154:157], v[202:205], v[92:95]
	v_mfma_f32_16x16x32_bf16 v[88:91], v[162:165], v[202:205], v[88:91]
	v_mfma_f32_16x16x32_bf16 v[76:79], v[154:157], v[210:213], v[76:79]
	v_mfma_f32_16x16x32_bf16 v[72:75], v[162:165], v[210:213], v[72:75]
	v_mfma_f32_16x16x32_bf16 v[116:119], v[166:169], v[182:185], v[116:119]
	v_mfma_f32_16x16x32_bf16 v[112:115], v[174:177], v[182:185], v[112:115]
	v_mfma_f32_16x16x32_bf16 v[100:103], v[166:169], v[190:193], v[100:103]
	v_mfma_f32_16x16x32_bf16 v[96:99], v[174:177], v[190:193], v[96:99]
	v_mfma_f32_16x16x32_bf16 v[84:87], v[166:169], v[198:201], v[84:87]
	v_mfma_f32_16x16x32_bf16 v[80:83], v[174:177], v[198:201], v[80:83]
	v_mfma_f32_16x16x32_bf16 v[68:71], v[166:169], v[206:209], v[68:71]
	v_mfma_f32_16x16x32_bf16 v[64:67], v[174:177], v[206:209], v[64:67]
	v_mfma_f32_16x16x32_bf16 v[116:119], v[170:173], v[186:189], v[116:119]
	v_mfma_f32_16x16x32_bf16 v[112:115], v[178:181], v[186:189], v[112:115]
	v_mfma_f32_16x16x32_bf16 v[100:103], v[170:173], v[194:197], v[100:103]
	v_mfma_f32_16x16x32_bf16 v[96:99], v[178:181], v[194:197], v[96:99]
	v_mfma_f32_16x16x32_bf16 v[84:87], v[170:173], v[202:205], v[84:87]
	v_mfma_f32_16x16x32_bf16 v[80:83], v[178:181], v[202:205], v[80:83]
	v_mfma_f32_16x16x32_bf16 v[68:71], v[170:173], v[210:213], v[68:71]
	v_mfma_f32_16x16x32_bf16 v[64:67], v[178:181], v[210:213], v[64:67]
	s_setprio 0
	s_barrier
	s_add_i32 s38, s52, s3
	s_mov_b32 m0, s38
	ds_read_b128 v[182:185], v153 offset:49152
	ds_read_b128 v[186:189], v153 offset:50176
	ds_read_b128 v[190:193], v153 offset:51200
	ds_read_b128 v[194:197], v153 offset:52224
	ds_read_b128 v[198:201], v153 offset:53248
	ds_read_b128 v[202:205], v153 offset:54272
	ds_read_b128 v[206:209], v153 offset:55296
	ds_read_b128 v[210:213], v153 offset:56320
	global_load_lds_dwordx4 v130, s[98:99]
	s_add_i32 m0, s38, 0x2000
	s_add_u32 s36, s36, 0x40080
	s_addc_u32 s37, s37, 0
	s_add_i32 s38, s53, s3
	global_load_lds_dwordx4 v134, s[98:99]
	s_mov_b32 m0, s38
	s_nop 0
	global_load_lds_dwordx4 v130, s[36:37]
	s_add_i32 m0, s38, 0x2000
	s_nop 0
	global_load_lds_dwordx4 v134, s[36:37]
	s_mov_b32 m0, s55
	s_nop 0
	global_load_lds_dwordx4 v128, s[100:101]
	s_mov_b32 m0, s56
	s_nop 0
	global_load_lds_dwordx4 v132, s[100:101]
	s_waitcnt vmcnt(8)
	s_waitcnt lgkmcnt(0)
	s_barrier
	s_setprio 1
	s_waitcnt lgkmcnt(0)
	v_mfma_f32_16x16x32_bf16 v[60:63], v[144:147], v[182:185], v[60:63]
	v_mfma_f32_16x16x32_bf16 v[56:59], v[158:161], v[182:185], v[56:59]
	v_mfma_f32_16x16x32_bf16 v[44:47], v[144:147], v[190:193], v[44:47]
	v_mfma_f32_16x16x32_bf16 v[40:43], v[158:161], v[190:193], v[40:43]
	v_mfma_f32_16x16x32_bf16 v[28:31], v[144:147], v[198:201], v[28:31]
	v_mfma_f32_16x16x32_bf16 v[24:27], v[158:161], v[198:201], v[24:27]
	v_mfma_f32_16x16x32_bf16 v[12:15], v[144:147], v[206:209], v[12:15]
	v_mfma_f32_16x16x32_bf16 v[8:11], v[158:161], v[206:209], v[8:11]
	v_mfma_f32_16x16x32_bf16 v[60:63], v[154:157], v[186:189], v[60:63]
	v_mfma_f32_16x16x32_bf16 v[56:59], v[162:165], v[186:189], v[56:59]
	v_mfma_f32_16x16x32_bf16 v[44:47], v[154:157], v[194:197], v[44:47]
	v_mfma_f32_16x16x32_bf16 v[40:43], v[162:165], v[194:197], v[40:43]
	v_mfma_f32_16x16x32_bf16 v[28:31], v[154:157], v[202:205], v[28:31]
	v_mfma_f32_16x16x32_bf16 v[24:27], v[162:165], v[202:205], v[24:27]
	v_mfma_f32_16x16x32_bf16 v[12:15], v[154:157], v[210:213], v[12:15]
	v_mfma_f32_16x16x32_bf16 v[8:11], v[162:165], v[210:213], v[8:11]
	v_mfma_f32_16x16x32_bf16 v[52:55], v[166:169], v[182:185], v[52:55]
	v_mfma_f32_16x16x32_bf16 v[48:51], v[174:177], v[182:185], v[48:51]
	v_mfma_f32_16x16x32_bf16 v[36:39], v[166:169], v[190:193], v[36:39]
	v_mfma_f32_16x16x32_bf16 v[32:35], v[174:177], v[190:193], v[32:35]
	v_mfma_f32_16x16x32_bf16 v[20:23], v[166:169], v[198:201], v[20:23]
	v_mfma_f32_16x16x32_bf16 v[16:19], v[174:177], v[198:201], v[16:19]
	v_mfma_f32_16x16x32_bf16 v[4:7], v[166:169], v[206:209], v[4:7]
	v_mfma_f32_16x16x32_bf16 v[0:3], v[174:177], v[206:209], v[0:3]
	v_mfma_f32_16x16x32_bf16 v[52:55], v[170:173], v[186:189], v[52:55]
	v_mfma_f32_16x16x32_bf16 v[48:51], v[178:181], v[186:189], v[48:51]
	v_mfma_f32_16x16x32_bf16 v[36:39], v[170:173], v[194:197], v[36:39]
	v_mfma_f32_16x16x32_bf16 v[32:35], v[178:181], v[194:197], v[32:35]
	v_mfma_f32_16x16x32_bf16 v[20:23], v[170:173], v[202:205], v[20:23]
	v_mfma_f32_16x16x32_bf16 v[16:19], v[178:181], v[202:205], v[16:19]
	v_mfma_f32_16x16x32_bf16 v[4:7], v[170:173], v[210:213], v[4:7]
	v_mfma_f32_16x16x32_bf16 v[0:3], v[178:181], v[210:213], v[0:3]
	s_setprio 0
	s_barrier
	s_add_i32 s61, s61, 2
	s_add_u32 s34, s34, 0x100
	s_addc_u32 s35, s35, 0
	s_add_u32 s59, s59, 0x100
	s_addc_u32 s60, s60, 0
	s_cmp_gt_u32 s61, 13
	s_cbranch_scc0 .LBB0_1279
	s_and_b64 vcc, exec, s[10:11]
	s_cbranch_vccz .LBB0_1282
	s_barrier

; #define PG8_STAGE(bufoff, gbase, voff) do { _Pragma("unroll") for (int _i = 0; _i < 2; ++_i) \
;         __builtin_amdgcn_global_load_lds((const unsigned*)((const char*)(gbase) + (voff)[_i]), (LAS unsigned*)(lds + (bufoff) + ldsw + _i * 8192), 16, 0, 0); } while (0)
; #define PG8_LDA(dst, b, h) do { _Pragma("unroll") for (int m = 0; m < 4; ++m) _Pragma("unroll") for (int k = 0; k < 2; ++k) dst[m][k] = *(const LAS bf16x8*)(lds + PG8_SA(b, h) + aoff + m * 2048 + k * 1024); } while (0)
; #define PG8_LDB(dst, b, h) do { _Pragma("unroll") for (int n = 0; n < 2; ++n) _Pragma("unroll") for (int k = 0; k < 2; ++k) dst[n][k] = *(const LAS bf16x8*)(lds + PG8_SB(b, h) + boff + n * 2048 + k * 1024); } while (0)
; #define PG8_MMA(ai, bj, At, Bt) do { __builtin_amdgcn_s_setprio(1); _Pragma("unroll") for (int m = 0; m < 4; ++m) _Pragma("unroll") for (int n = 0; n < 2; ++n) _Pragma("unroll") for (int k = 0; k < 2; ++k) \
;         acc[ai][bj][m][n] = __builtin_amdgcn_mfma_f32_16x16x32_bf16(Bt[n][k], At[m][k], acc[ai][bj][m][n], 0, 0, 0); __builtin_amdgcn_s_setprio(0); } while (0)
; #define PG8_WAIT_V(n) asm volatile("s_waitcnt vmcnt(" #n ")" ::: "memory")
; #define PG8_WAIT_L(n) asm volatile("s_waitcnt lgkmcnt(" #n ")" ::: "memory")
; #define PG8_BAR __builtin_amdgcn_s_barrier()
; template <class Epi, bool ALIGN_EPI, int K, int LDA, int LDB>
; __device__ __forceinline__ void gemm_phase(LAS unsigned char* lds, const int wid, const Gemm g, const StaticOrder& S, const Epi& E) {
;     ...
;         for (int t = 0; t < nt; t += 2) {
;             const bool last = (t == nt - 2);
;             const char* a1 = cA + (size_t)(t + 1) * kstep;
;             const char* a2 = last ? nA : cA + (size_t)(t + 2) * kstep; const char* b2 = last ? nB : cB + (size_t)(t + 2) * kstep;
;             const char* a3 = a2 + kstep; const char* b3 = b2 + kstep;
;             PG8_LDB(B0, 0, 0); PG8_LDB(B1, 0, 1); PG8_SCHED; PG8_LDA(At, 0, 0); PG8_STAGE(PG8_SA(1, 1), a1 + hA, voffA);
;             PG8_WAIT_V(8); PG8_WAIT_L(0); PG8_BAR; PG8_MMA(0, 0, At, B0); PG8_MMA(0, 1, At, B1); PG8_BAR; PG8_SCHED;
;             PG8_LDA(At, 0, 1); PG8_STAGE(PG8_SB(0, 0), b2, voffB); PG8_STAGE(PG8_SB(0, 1), b2 + hB, voffB); PG8_STAGE(PG8_SA(0, 0), a2, voffA);
;             PG8_WAIT_V(8); PG8_WAIT_L(0); PG8_BAR; PG8_MMA(1, 0, At, B0); PG8_MMA(1, 1, At, B1); PG8_BAR; PG8_SCHED;
.LBB0_1477:
	ds_read_b128 v[128:131], v175
	ds_read_b128 v[132:135], v175 offset:1024
	ds_read_b128 v[136:139], v175 offset:2048
	ds_read_b128 v[140:143], v175 offset:3072
	ds_read_b128 v[144:147], v176
	ds_read_b128 v[164:167], v176 offset:1024
	ds_read_b128 v[168:171], v176 offset:2048
	ds_read_b128 v[178:181], v176 offset:3072
	s_add_u32 s36, s34, 0xfffc0080
	s_addc_u32 s37, s35, -1
	s_cmp_eq_u32 s69, 12
	s_cselect_b32 s39, s25, s37
	s_cselect_b32 s38, s42, s36
	s_cselect_b32 s37, s23, s68
	s_cselect_b32 s36, s66, s67
	s_add_i32 m0, s40, 0xc000
	ds_read_b128 v[182:185], v177
	ds_read_b128 v[186:189], v177 offset:1024
	ds_read_b128 v[190:193], v177 offset:2048
	ds_read_b128 v[194:197], v177 offset:3072
	ds_read_b128 v[198:201], v177 offset:4096
	ds_read_b128 v[202:205], v177 offset:5120
	ds_read_b128 v[206:209], v177 offset:6144
	ds_read_b128 v[210:213], v177 offset:7168
	global_load_lds_dwordx4 v156, s[34:35]
	s_add_i32 m0, s40, 0xe000
	s_nop 0
	global_load_lds_dwordx4 v158, s[34:35]
	s_waitcnt vmcnt(8)
	s_waitcnt lgkmcnt(0)
	s_barrier
	s_setprio 1
	s_waitcnt lgkmcnt(0)
	v_mfma_f32_16x16x32_bf16 v[124:127], v[128:131], v[182:185], v[124:127]
	v_mfma_f32_16x16x32_bf16 v[116:119], v[136:139], v[182:185], v[116:119]
	v_mfma_f32_16x16x32_bf16 v[120:123], v[128:131], v[190:193], v[120:123]
	v_mfma_f32_16x16x32_bf16 v[112:115], v[136:139], v[190:193], v[112:115]
	v_mfma_f32_16x16x32_bf16 v[92:95], v[128:131], v[198:201], v[92:95]
	v_mfma_f32_16x16x32_bf16 v[88:91], v[136:139], v[198:201], v[88:91]
	v_mfma_f32_16x16x32_bf16 v[76:79], v[128:131], v[206:209], v[76:79]
	v_mfma_f32_16x16x32_bf16 v[72:75], v[136:139], v[206:209], v[72:75]
	v_mfma_f32_16x16x32_bf16 v[124:127], v[132:135], v[186:189], v[124:127]
	v_mfma_f32_16x16x32_bf16 v[116:119], v[140:143], v[186:189], v[116:119]
	v_mfma_f32_16x16x32_bf16 v[120:123], v[132:135], v[194:197], v[120:123]
	v_mfma_f32_16x16x32_bf16 v[112:115], v[140:143], v[194:197], v[112:115]
	v_mfma_f32_16x16x32_bf16 v[92:95], v[132:135], v[202:205], v[92:95]
	v_mfma_f32_16x16x32_bf16 v[88:91], v[140:143], v[202:205], v[88:91]
	v_mfma_f32_16x16x32_bf16 v[76:79], v[132:135], v[210:213], v[76:79]
	v_mfma_f32_16x16x32_bf16 v[72:75], v[140:143], v[210:213], v[72:75]
	v_mfma_f32_16x16x32_bf16 v[108:111], v[144:147], v[182:185], v[108:111]
	v_mfma_f32_16x16x32_bf16 v[104:107], v[168:171], v[182:185], v[104:107]
	v_mfma_f32_16x16x32_bf16 v[100:103], v[144:147], v[190:193], v[100:103]
	v_mfma_f32_16x16x32_bf16 v[96:99], v[168:171], v[190:193], v[96:99]
	v_mfma_f32_16x16x32_bf16 v[84:87], v[144:147], v[198:201], v[84:87]
	v_mfma_f32_16x16x32_bf16 v[80:83], v[168:171], v[198:201], v[80:83]
	v_mfma_f32_16x16x32_bf16 v[68:71], v[144:147], v[206:209], v[68:71]
	v_mfma_f32_16x16x32_bf16 v[64:67], v[168:171], v[206:209], v[64:67]
	v_mfma_f32_16x16x32_bf16 v[108:111], v[164:167], v[186:189], v[108:111]
	v_mfma_f32_16x16x32_bf16 v[104:107], v[178:181], v[186:189], v[104:107]
	v_mfma_f32_16x16x32_bf16 v[100:103], v[164:167], v[194:197], v[100:103]
	v_mfma_f32_16x16x32_bf16 v[96:99], v[178:181], v[194:197], v[96:99]
	v_mfma_f32_16x16x32_bf16 v[84:87], v[164:167], v[202:205], v[84:87]
	v_mfma_f32_16x16x32_bf16 v[80:83], v[178:181], v[202:205], v[80:83]
	v_mfma_f32_16x16x32_bf16 v[68:71], v[164:167], v[210:213], v[68:71]
	v_mfma_f32_16x16x32_bf16 v[64:67], v[178:181], v[210:213], v[64:67]
	s_setprio 0
	s_barrier
	s_add_u32 s98, s36, s12
	s_addc_u32 s99, s37, s13
	s_add_u32 s100, s38, s12
	s_addc_u32 s101, s39, s13
	s_add_i32 s52, s58, s33
	s_mov_b32 m0, s52
	ds_read_b128 v[182:185], v177 offset:16384
	ds_read_b128 v[186:189], v177 offset:17408
	ds_read_b128 v[190:193], v177 offset:18432
	ds_read_b128 v[194:197], v177 offset:19456
	ds_read_b128 v[198:201], v177 offset:20480
	ds_read_b128 v[202:205], v177 offset:21504
	ds_read_b128 v[206:209], v177 offset:22528
	ds_read_b128 v[210:213], v177 offset:23552
	global_load_lds_dwordx4 v150, s[36:37]
	s_add_i32 m0, s52, 0x2000
	s_add_u32 s70, s36, 0x40000
	s_addc_u32 s71, s37, 0
	s_add_i32 s52, s59, s33
	global_load_lds_dwordx4 v154, s[36:37]
	s_mov_b32 m0, s52
	s_nop 0
	global_load_lds_dwordx4 v150, s[70:71]
	s_add_i32 m0, s52, 0x2000
	s_nop 0
	global_load_lds_dwordx4 v154, s[70:71]
	s_mov_b32 m0, s40
	s_nop 0
	global_load_lds_dwordx4 v148, s[38:39]
	s_mov_b32 m0, s41
	s_nop 0
	global_load_lds_dwordx4 v152, s[38:39]
	s_waitcnt vmcnt(8)
	s_waitcnt lgkmcnt(0)
	s_barrier
	s_setprio 1
	s_waitcnt lgkmcnt(0)
	v_mfma_f32_16x16x32_bf16 v[60:63], v[128:131], v[182:185], v[60:63]
	v_mfma_f32_16x16x32_bf16 v[56:59], v[136:139], v[182:185], v[56:59]
	v_mfma_f32_16x16x32_bf16 v[44:47], v[128:131], v[190:193], v[44:47]
	v_mfma_f32_16x16x32_bf16 v[40:43], v[136:139], v[190:193], v[40:43]
	v_mfma_f32_16x16x32_bf16 v[36:39], v[128:131], v[198:201], v[36:39]
	v_mfma_f32_16x16x32_bf16 v[32:35], v[136:139], v[198:201], v[32:35]
	v_mfma_f32_16x16x32_bf16 v[20:23], v[128:131], v[206:209], v[20:23]
	v_mfma_f32_16x16x32_bf16 v[16:19], v[136:139], v[206:209], v[16:19]
	v_mfma_f32_16x16x32_bf16 v[60:63], v[132:135], v[186:189], v[60:63]
	v_mfma_f32_16x16x32_bf16 v[56:59], v[140:143], v[186:189], v[56:59]
	v_mfma_f32_16x16x32_bf16 v[44:47], v[132:135], v[194:197], v[44:47]
	v_mfma_f32_16x16x32_bf16 v[40:43], v[140:143], v[194:197], v[40:43]
	v_mfma_f32_16x16x32_bf16 v[36:39], v[132:135], v[202:205], v[36:39]
	v_mfma_f32_16x16x32_bf16 v[32:35], v[140:143], v[202:205], v[32:35]
	v_mfma_f32_16x16x32_bf16 v[20:23], v[132:135], v[210:213], v[20:23]
	v_mfma_f32_16x16x32_bf16 v[16:19], v[140:143], v[210:213], v[16:19]
	v_mfma_f32_16x16x32_bf16 v[52:55], v[144:147], v[182:185], v[52:55]
	v_mfma_f32_16x16x32_bf16 v[48:51], v[168:171], v[182:185], v[48:51]
	v_mfma_f32_16x16x32_bf16 v[28:31], v[144:147], v[190:193], v[28:31]
	v_mfma_f32_16x16x32_bf16 v[24:27], v[168:171], v[190:193], v[24:27]
	v_mfma_f32_16x16x32_bf16 v[12:15], v[144:147], v[198:201], v[12:15]
	v_mfma_f32_16x16x32_bf16 v[8:11], v[168:171], v[198:201], v[8:11]
	v_mfma_f32_16x16x32_bf16 v[4:7], v[144:147], v[206:209], v[4:7]
	v_mfma_f32_16x16x32_bf16 v[0:3], v[168:171], v[206:209], v[0:3]
	v_mfma_f32_16x16x32_bf16 v[52:55], v[164:167], v[186:189], v[52:55]
	v_mfma_f32_16x16x32_bf16 v[48:51], v[178:181], v[186:189], v[48:51]
	v_mfma_f32_16x16x32_bf16 v[28:31], v[164:167], v[194:197], v[28:31]
	v_mfma_f32_16x16x32_bf16 v[24:27], v[178:181], v[194:197], v[24:27]
	v_mfma_f32_16x16x32_bf16 v[12:15], v[164:167], v[202:205], v[12:15]
	v_mfma_f32_16x16x32_bf16 v[8:11], v[178:181], v[202:205], v[8:11]
	v_mfma_f32_16x16x32_bf16 v[4:7], v[164:167], v[210:213], v[4:7]
	v_mfma_f32_16x16x32_bf16 v[0:3], v[178:181], v[210:213], v[0:3]
	s_setprio 0
	s_barrier
; __device__ __forceinline__ int lane_id_() { int l; asm volatile("v_mbcnt_lo_u32_b32 %0, -1, 0\n\tv_mbcnt_hi_u32_b32 %0, -1, %0" : "=v"(l)); return l; }
; #define PG8_STAGE(bufoff, gbase, voff) do { _Pragma("unroll") for (int _i = 0; _i < 2; ++_i) \
;         __builtin_amdgcn_global_load_lds((const unsigned*)((const char*)(gbase) + (voff)[_i]), (LAS unsigned*)(lds + (bufoff) + ldsw + _i * 8192), 16, 0, 0); } while (0)
; #define PG8_LDA(dst, b, h) do { _Pragma("unroll") for (int m = 0; m < 4; ++m) _Pragma("unroll") for (int k = 0; k < 2; ++k) dst[m][k] = *(const LAS bf16x8*)(lds + PG8_SA(b, h) + aoff + m * 2048 + k * 1024); } while (0)
; #define PG8_LDB(dst, b, h) do { _Pragma("unroll") for (int n = 0; n < 2; ++n) _Pragma("unroll") for (int k = 0; k < 2; ++k) dst[n][k] = *(const LAS bf16x8*)(lds + PG8_SB(b, h) + boff + n * 2048 + k * 1024); } while (0)
; #define PG8_MMA(ai, bj, At, Bt) do { __builtin_amdgcn_s_setprio(1); _Pragma("unroll") for (int m = 0; m < 4; ++m) _Pragma("unroll") for (int n = 0; n < 2; ++n) _Pragma("unroll") for (int k = 0; k < 2; ++k) \
;         acc[ai][bj][m][n] = __builtin_amdgcn_mfma_f32_16x16x32_bf16(Bt[n][k], At[m][k], acc[ai][bj][m][n], 0, 0, 0); __builtin_amdgcn_s_setprio(0); } while (0)
; #define PG8_WAIT_V(n) asm volatile("s_waitcnt vmcnt(" #n ")" ::: "memory")
; #define PG8_WAIT_L(n) asm volatile("s_waitcnt lgkmcnt(" #n ")" ::: "memory")
; #define PG8_BAR __builtin_amdgcn_s_barrier()
; #define PG8_SCHED __builtin_amdgcn_sched_barrier(0)
; template <class Epi, bool ALIGN_EPI, int K, int LDA, int LDB>
; __device__ __forceinline__ void gemm_phase(LAS unsigned char* lds, const int wid, const Gemm g, const StaticOrder& S, const Epi& E) {
;     ...
;             PG8_LDB(B0, 1, 0); PG8_LDB(B1, 1, 1); PG8_SCHED; PG8_LDA(At, 1, 0); PG8_STAGE(PG8_SA(0, 1), a2 + hA, voffA);
;             PG8_WAIT_V(8); PG8_WAIT_L(0); PG8_BAR; PG8_MMA(0, 0, At, B0); PG8_MMA(0, 1, At, B1); PG8_BAR; PG8_SCHED;
;             PG8_LDA(At, 1, 1); PG8_STAGE(PG8_SB(1, 0), b3, voffB); PG8_STAGE(PG8_SB(1, 1), b3 + hB, voffB); PG8_STAGE(PG8_SA(1, 0), a3, voffA);
;             PG8_WAIT_V(8); PG8_WAIT_L(0); PG8_BAR; PG8_MMA(1, 0, At, B0); PG8_MMA(1, 1, At, B1); PG8_BAR; PG8_SCHED;
;         }
;         if constexpr (ALIGN_EPI) { if (wr == 0) PG8_BAR; }
;         { const int l2 = lane_id_(); E(acc, cur, wid >> 2, wid & 3, l2 & 15, l2 >> 4); }
;         if (!has_next) break;
	s_add_i32 s52, 0, 0x18000
	s_add_i32 s53, 0, 0x1c000
	v_add_u32_e32 v140, s52, v174
	v_add_u32_e32 v178, s53, v174
	ds_read_b128 v[128:131], v140
	ds_read_b128 v[132:135], v140 offset:1024
	ds_read_b128 v[136:139], v140 offset:2048
	ds_read_b128 v[140:143], v140 offset:3072
	ds_read_b128 v[144:147], v178
	ds_read_b128 v[164:167], v178 offset:1024
	ds_read_b128 v[168:171], v178 offset:2048
	ds_read_b128 v[178:181], v178 offset:3072
	s_add_u32 s38, s38, 0x40000
	s_addc_u32 s39, s39, 0
	s_mov_b32 m0, s43
	ds_read_b128 v[182:185], v177 offset:32768
	ds_read_b128 v[186:189], v177 offset:33792
	ds_read_b128 v[190:193], v177 offset:34816
	ds_read_b128 v[194:197], v177 offset:35840
	ds_read_b128 v[198:201], v177 offset:36864
	ds_read_b128 v[202:205], v177 offset:37888
	ds_read_b128 v[206:209], v177 offset:38912
	ds_read_b128 v[210:213], v177 offset:39936
	global_load_lds_dwordx4 v148, s[38:39]
	s_mov_b32 m0, s48
	s_nop 0
	global_load_lds_dwordx4 v152, s[38:39]
	s_waitcnt vmcnt(8)
	s_waitcnt lgkmcnt(0)
	s_barrier
	s_setprio 1
	s_waitcnt lgkmcnt(0)
	v_mfma_f32_16x16x32_bf16 v[124:127], v[128:131], v[182:185], v[124:127]
	v_mfma_f32_16x16x32_bf16 v[116:119], v[136:139], v[182:185], v[116:119]
	v_mfma_f32_16x16x32_bf16 v[120:123], v[128:131], v[190:193], v[120:123]
	v_mfma_f32_16x16x32_bf16 v[112:115], v[136:139], v[190:193], v[112:115]
	v_mfma_f32_16x16x32_bf16 v[92:95], v[128:131], v[198:201], v[92:95]
	v_mfma_f32_16x16x32_bf16 v[88:91], v[136:139], v[198:201], v[88:91]
	v_mfma_f32_16x16x32_bf16 v[76:79], v[128:131], v[206:209], v[76:79]
	v_mfma_f32_16x16x32_bf16 v[72:75], v[136:139], v[206:209], v[72:75]
	v_mfma_f32_16x16x32_bf16 v[124:127], v[132:135], v[186:189], v[124:127]
	v_mfma_f32_16x16x32_bf16 v[116:119], v[140:143], v[186:189], v[116:119]
	v_mfma_f32_16x16x32_bf16 v[120:123], v[132:135], v[194:197], v[120:123]
	v_mfma_f32_16x16x32_bf16 v[112:115], v[140:143], v[194:197], v[112:115]
	v_mfma_f32_16x16x32_bf16 v[92:95], v[132:135], v[202:205], v[92:95]
	v_mfma_f32_16x16x32_bf16 v[88:91], v[140:143], v[202:205], v[88:91]
	v_mfma_f32_16x16x32_bf16 v[76:79], v[132:135], v[210:213], v[76:79]
	v_mfma_f32_16x16x32_bf16 v[72:75], v[140:143], v[210:213], v[72:75]
	v_mfma_f32_16x16x32_bf16 v[108:111], v[144:147], v[182:185], v[108:111]
	v_mfma_f32_16x16x32_bf16 v[104:107], v[168:171], v[182:185], v[104:107]
	v_mfma_f32_16x16x32_bf16 v[100:103], v[144:147], v[190:193], v[100:103]
	v_mfma_f32_16x16x32_bf16 v[96:99], v[168:171], v[190:193], v[96:99]
	v_mfma_f32_16x16x32_bf16 v[84:87], v[144:147], v[198:201], v[84:87]
	v_mfma_f32_16x16x32_bf16 v[80:83], v[168:171], v[198:201], v[80:83]
	v_mfma_f32_16x16x32_bf16 v[68:71], v[144:147], v[206:209], v[68:71]
	v_mfma_f32_16x16x32_bf16 v[64:67], v[168:171], v[206:209], v[64:67]
	v_mfma_f32_16x16x32_bf16 v[108:111], v[164:167], v[186:189], v[108:111]
	v_mfma_f32_16x16x32_bf16 v[104:107], v[178:181], v[186:189], v[104:107]
	v_mfma_f32_16x16x32_bf16 v[100:103], v[164:167], v[194:197], v[100:103]
	v_mfma_f32_16x16x32_bf16 v[96:99], v[178:181], v[194:197], v[96:99]
	v_mfma_f32_16x16x32_bf16 v[84:87], v[164:167], v[202:205], v[84:87]
	v_mfma_f32_16x16x32_bf16 v[80:83], v[178:181], v[202:205], v[80:83]
	v_mfma_f32_16x16x32_bf16 v[68:71], v[164:167], v[210:213], v[68:71]
	v_mfma_f32_16x16x32_bf16 v[64:67], v[178:181], v[210:213], v[64:67]
	s_setprio 0
	s_barrier
	s_add_i32 s38, s52, s33
	s_mov_b32 m0, s38
	ds_read_b128 v[182:185], v177 offset:49152
	ds_read_b128 v[186:189], v177 offset:50176
	ds_read_b128 v[190:193], v177 offset:51200
	ds_read_b128 v[194:197], v177 offset:52224
	ds_read_b128 v[198:201], v177 offset:53248
	ds_read_b128 v[202:205], v177 offset:54272
	ds_read_b128 v[206:209], v177 offset:55296
	ds_read_b128 v[210:213], v177 offset:56320
	global_load_lds_dwordx4 v150, s[98:99]
	s_add_i32 m0, s38, 0x2000
	s_add_u32 s36, s36, 0x40080
	s_addc_u32 s37, s37, 0
	s_add_i32 s38, s53, s33
	global_load_lds_dwordx4 v154, s[98:99]
	s_mov_b32 m0, s38
	s_nop 0
	global_load_lds_dwordx4 v150, s[36:37]
	s_add_i32 m0, s38, 0x2000
	s_nop 0
	global_load_lds_dwordx4 v154, s[36:37]
	s_mov_b32 m0, s55
	s_nop 0
	global_load_lds_dwordx4 v148, s[100:101]
	s_mov_b32 m0, s56
	s_nop 0
	global_load_lds_dwordx4 v152, s[100:101]
	s_waitcnt vmcnt(8)
	s_waitcnt lgkmcnt(0)
	s_barrier
	s_setprio 1
	s_waitcnt lgkmcnt(0)
	v_mfma_f32_16x16x32_bf16 v[60:63], v[128:131], v[182:185], v[60:63]
	v_mfma_f32_16x16x32_bf16 v[56:59], v[136:139], v[182:185], v[56:59]
	v_mfma_f32_16x16x32_bf16 v[44:47], v[128:131], v[190:193], v[44:47]
	v_mfma_f32_16x16x32_bf16 v[40:43], v[136:139], v[190:193], v[40:43]
	v_mfma_f32_16x16x32_bf16 v[36:39], v[128:131], v[198:201], v[36:39]
	v_mfma_f32_16x16x32_bf16 v[32:35], v[136:139], v[198:201], v[32:35]
	v_mfma_f32_16x16x32_bf16 v[20:23], v[128:131], v[206:209], v[20:23]
	v_mfma_f32_16x16x32_bf16 v[16:19], v[136:139], v[206:209], v[16:19]
	v_mfma_f32_16x16x32_bf16 v[60:63], v[132:135], v[186:189], v[60:63]
	v_mfma_f32_16x16x32_bf16 v[56:59], v[140:143], v[186:189], v[56:59]
	v_mfma_f32_16x16x32_bf16 v[44:47], v[132:135], v[194:197], v[44:47]
	v_mfma_f32_16x16x32_bf16 v[40:43], v[140:143], v[194:197], v[40:43]
	v_mfma_f32_16x16x32_bf16 v[36:39], v[132:135], v[202:205], v[36:39]
	v_mfma_f32_16x16x32_bf16 v[32:35], v[140:143], v[202:205], v[32:35]
	v_mfma_f32_16x16x32_bf16 v[20:23], v[132:135], v[210:213], v[20:23]
	v_mfma_f32_16x16x32_bf16 v[16:19], v[140:143], v[210:213], v[16:19]
	v_mfma_f32_16x16x32_bf16 v[52:55], v[144:147], v[182:185], v[52:55]
	v_mfma_f32_16x16x32_bf16 v[48:51], v[168:171], v[182:185], v[48:51]
	v_mfma_f32_16x16x32_bf16 v[28:31], v[144:147], v[190:193], v[28:31]
	v_mfma_f32_16x16x32_bf16 v[24:27], v[168:171], v[190:193], v[24:27]
	v_mfma_f32_16x16x32_bf16 v[12:15], v[144:147], v[198:201], v[12:15]
	v_mfma_f32_16x16x32_bf16 v[8:11], v[168:171], v[198:201], v[8:11]
	v_mfma_f32_16x16x32_bf16 v[4:7], v[144:147], v[206:209], v[4:7]
	v_mfma_f32_16x16x32_bf16 v[0:3], v[168:171], v[206:209], v[0:3]
	v_mfma_f32_16x16x32_bf16 v[52:55], v[164:167], v[186:189], v[52:55]
	v_mfma_f32_16x16x32_bf16 v[48:51], v[178:181], v[186:189], v[48:51]
	v_mfma_f32_16x16x32_bf16 v[28:31], v[164:167], v[194:197], v[28:31]
	v_mfma_f32_16x16x32_bf16 v[24:27], v[178:181], v[194:197], v[24:27]
	v_mfma_f32_16x16x32_bf16 v[12:15], v[164:167], v[202:205], v[12:15]
	v_mfma_f32_16x16x32_bf16 v[8:11], v[178:181], v[202:205], v[8:11]
	v_mfma_f32_16x16x32_bf16 v[4:7], v[164:167], v[210:213], v[4:7]
	v_mfma_f32_16x16x32_bf16 v[0:3], v[178:181], v[210:213], v[0:3]
	s_setprio 0
	s_barrier
	s_add_i32 s69, s69, 2
	s_add_u32 s34, s34, 0x100
	s_addc_u32 s35, s35, 0
	s_add_u32 s67, s67, 0x100
	s_addc_u32 s68, s68, 0
	s_cmp_gt_u32 s69, 13
	s_cbranch_scc0 .LBB0_1477
	s_and_b64 vcc, exec, s[14:15]
	s_cbranch_vccz .LBB0_1480
	s_barrier

; #define PG8_STAGE(bufoff, gbase, voff) do { _Pragma("unroll") for (int _i = 0; _i < 2; ++_i) \
;         __builtin_amdgcn_global_load_lds((const unsigned*)((const char*)(gbase) + (voff)[_i]), (LAS unsigned*)(lds + (bufoff) + ldsw + _i * 8192), 16, 0, 0); } while (0)
; #define PG8_LDA(dst, b, h) do { _Pragma("unroll") for (int m = 0; m < 4; ++m) _Pragma("unroll") for (int k = 0; k < 2; ++k) dst[m][k] = *(const LAS bf16x8*)(lds + PG8_SA(b, h) + aoff + m * 2048 + k * 1024); } while (0)
; #define PG8_LDB(dst, b, h) do { _Pragma("unroll") for (int n = 0; n < 2; ++n) _Pragma("unroll") for (int k = 0; k < 2; ++k) dst[n][k] = *(const LAS bf16x8*)(lds + PG8_SB(b, h) + boff + n * 2048 + k * 1024); } while (0)
; #define PG8_MMA(ai, bj, At, Bt) do { __builtin_amdgcn_s_setprio(1); _Pragma("unroll") for (int m = 0; m < 4; ++m) _Pragma("unroll") for (int n = 0; n < 2; ++n) _Pragma("unroll") for (int k = 0; k < 2; ++k) \
;         acc[ai][bj][m][n] = __builtin_amdgcn_mfma_f32_16x16x32_bf16(Bt[n][k], At[m][k], acc[ai][bj][m][n], 0, 0, 0); __builtin_amdgcn_s_setprio(0); } while (0)
; #define PG8_WAIT_V(n) asm volatile("s_waitcnt vmcnt(" #n ")" ::: "memory")
; #define PG8_WAIT_L(n) asm volatile("s_waitcnt lgkmcnt(" #n ")" ::: "memory")
; #define PG8_BAR __builtin_amdgcn_s_barrier()
; template <class Epi, bool ALIGN_EPI, int K, int LDA, int LDB>
; __device__ __forceinline__ void gemm_phase(LAS unsigned char* lds, const int wid, const Gemm g, const StaticOrder& S, const Epi& E) {
;     ...
;         for (int t = 0; t < nt; t += 2) {
;             const bool last = (t == nt - 2);
;             const char* a1 = cA + (size_t)(t + 1) * kstep;
;             const char* a2 = last ? nA : cA + (size_t)(t + 2) * kstep; const char* b2 = last ? nB : cB + (size_t)(t + 2) * kstep;
;             const char* a3 = a2 + kstep; const char* b3 = b2 + kstep;
;             PG8_LDB(B0, 0, 0); PG8_LDB(B1, 0, 1); PG8_SCHED; PG8_LDA(At, 0, 0); PG8_STAGE(PG8_SA(1, 1), a1 + hA, voffA);
;             PG8_WAIT_V(8); PG8_WAIT_L(0); PG8_BAR; PG8_MMA(0, 0, At, B0); PG8_MMA(0, 1, At, B1); PG8_BAR; PG8_SCHED;
;             PG8_LDA(At, 0, 1); PG8_STAGE(PG8_SB(0, 0), b2, voffB); PG8_STAGE(PG8_SB(0, 1), b2 + hB, voffB); PG8_STAGE(PG8_SA(0, 0), a2, voffA);
;             PG8_WAIT_V(8); PG8_WAIT_L(0); PG8_BAR; PG8_MMA(1, 0, At, B0); PG8_MMA(1, 1, At, B1); PG8_BAR; PG8_SCHED;
.LBB0_1697:
	ds_read_b128 v[120:123], v167
	ds_read_b128 v[124:127], v167 offset:1024
	ds_read_b128 v[128:131], v167 offset:2048
	ds_read_b128 v[132:135], v167 offset:3072
	ds_read_b128 v[160:163], v168
	ds_read_b128 v[170:173], v168 offset:1024
	ds_read_b128 v[174:177], v168 offset:2048
	ds_read_b128 v[178:181], v168 offset:3072
	s_add_u32 s28, s26, 0x100
	s_addc_u32 s29, s27, 0
	s_cmp_eq_u32 s63, 40
	s_cselect_b32 s35, s7, s29
	s_cselect_b32 s34, s6, s28
	s_cselect_b32 s31, s25, s62
	s_cselect_b32 s30, s24, s61
	s_add_i32 m0, s36, 0xc000
	ds_read_b128 v[182:185], v169
	ds_read_b128 v[186:189], v169 offset:1024
	ds_read_b128 v[190:193], v169 offset:2048
	ds_read_b128 v[194:197], v169 offset:3072
	ds_read_b128 v[198:201], v169 offset:4096
	ds_read_b128 v[202:205], v169 offset:5120
	ds_read_b128 v[206:209], v169 offset:6144
	ds_read_b128 v[210:213], v169 offset:7168
	global_load_lds_dwordx4 v152, s[26:27]
	s_add_i32 m0, s36, 0xe000
	s_nop 0
	global_load_lds_dwordx4 v154, s[26:27]
	s_waitcnt vmcnt(8)
	s_waitcnt lgkmcnt(0)
	s_barrier
	s_setprio 1
	s_waitcnt lgkmcnt(0)
	v_mfma_f32_16x16x32_bf16 v[140:143], v[120:123], v[182:185], v[140:143]
	v_mfma_f32_16x16x32_bf16 v[136:139], v[128:131], v[182:185], v[136:139]
	v_mfma_f32_16x16x32_bf16 v[108:111], v[120:123], v[190:193], v[108:111]
	v_mfma_f32_16x16x32_bf16 v[104:107], v[128:131], v[190:193], v[104:107]
	v_mfma_f32_16x16x32_bf16 v[92:95], v[120:123], v[198:201], v[92:95]
	v_mfma_f32_16x16x32_bf16 v[88:91], v[128:131], v[198:201], v[88:91]
	v_mfma_f32_16x16x32_bf16 v[76:79], v[120:123], v[206:209], v[76:79]
	v_mfma_f32_16x16x32_bf16 v[72:75], v[128:131], v[206:209], v[72:75]
	v_mfma_f32_16x16x32_bf16 v[140:143], v[124:127], v[186:189], v[140:143]
	v_mfma_f32_16x16x32_bf16 v[136:139], v[132:135], v[186:189], v[136:139]
	v_mfma_f32_16x16x32_bf16 v[108:111], v[124:127], v[194:197], v[108:111]
	v_mfma_f32_16x16x32_bf16 v[104:107], v[132:135], v[194:197], v[104:107]
	v_mfma_f32_16x16x32_bf16 v[92:95], v[124:127], v[202:205], v[92:95]
	v_mfma_f32_16x16x32_bf16 v[88:91], v[132:135], v[202:205], v[88:91]
	v_mfma_f32_16x16x32_bf16 v[76:79], v[124:127], v[210:213], v[76:79]
	v_mfma_f32_16x16x32_bf16 v[72:75], v[132:135], v[210:213], v[72:75]
	v_mfma_f32_16x16x32_bf16 v[116:119], v[160:163], v[182:185], v[116:119]
	v_mfma_f32_16x16x32_bf16 v[112:115], v[174:177], v[182:185], v[112:115]
	v_mfma_f32_16x16x32_bf16 v[100:103], v[160:163], v[190:193], v[100:103]
	v_mfma_f32_16x16x32_bf16 v[96:99], v[174:177], v[190:193], v[96:99]
	v_mfma_f32_16x16x32_bf16 v[84:87], v[160:163], v[198:201], v[84:87]
	v_mfma_f32_16x16x32_bf16 v[80:83], v[174:177], v[198:201], v[80:83]
	v_mfma_f32_16x16x32_bf16 v[68:71], v[160:163], v[206:209], v[68:71]
	v_mfma_f32_16x16x32_bf16 v[64:67], v[174:177], v[206:209], v[64:67]
	v_mfma_f32_16x16x32_bf16 v[116:119], v[170:173], v[186:189], v[116:119]
	v_mfma_f32_16x16x32_bf16 v[112:115], v[178:181], v[186:189], v[112:115]
	v_mfma_f32_16x16x32_bf16 v[100:103], v[170:173], v[194:197], v[100:103]
	v_mfma_f32_16x16x32_bf16 v[96:99], v[178:181], v[194:197], v[96:99]
	v_mfma_f32_16x16x32_bf16 v[84:87], v[170:173], v[202:205], v[84:87]
	v_mfma_f32_16x16x32_bf16 v[80:83], v[178:181], v[202:205], v[80:83]
	v_mfma_f32_16x16x32_bf16 v[68:71], v[170:173], v[210:213], v[68:71]
	v_mfma_f32_16x16x32_bf16 v[64:67], v[178:181], v[210:213], v[64:67]
	s_setprio 0
	s_barrier
	s_add_u32 s98, s30, s12
	s_addc_u32 s99, s31, s13
	s_add_u32 s100, s34, s12
	s_addc_u32 s101, s35, s13
	s_add_i32 s26, s54, s33
	s_mov_b32 m0, s26
	ds_read_b128 v[182:185], v169 offset:16384
	ds_read_b128 v[186:189], v169 offset:17408
	ds_read_b128 v[190:193], v169 offset:18432
	ds_read_b128 v[194:197], v169 offset:19456
	ds_read_b128 v[198:201], v169 offset:20480
	ds_read_b128 v[202:205], v169 offset:21504
	ds_read_b128 v[206:209], v169 offset:22528
	ds_read_b128 v[210:213], v169 offset:23552
	global_load_lds_dwordx4 v146, s[30:31]
	s_add_i32 m0, s26, 0x2000
	s_add_u32 s26, s30, 0xb0000
	s_addc_u32 s27, s31, 0
	s_add_i32 s52, s55, s33
	global_load_lds_dwordx4 v150, s[30:31]
	s_mov_b32 m0, s52
	s_nop 0
	global_load_lds_dwordx4 v146, s[26:27]
	s_add_i32 m0, s52, 0x2000
	s_nop 0
	global_load_lds_dwordx4 v150, s[26:27]
	s_mov_b32 m0, s36
	s_nop 0
	global_load_lds_dwordx4 v144, s[34:35]
	s_mov_b32 m0, s37
	s_nop 0
	global_load_lds_dwordx4 v148, s[34:35]
	s_waitcnt vmcnt(8)
	s_waitcnt lgkmcnt(0)
	s_barrier
	s_setprio 1
	s_waitcnt lgkmcnt(0)
	v_mfma_f32_16x16x32_bf16 v[60:63], v[120:123], v[182:185], v[60:63]
	v_mfma_f32_16x16x32_bf16 v[56:59], v[128:131], v[182:185], v[56:59]
	v_mfma_f32_16x16x32_bf16 v[44:47], v[120:123], v[190:193], v[44:47]
	v_mfma_f32_16x16x32_bf16 v[40:43], v[128:131], v[190:193], v[40:43]
	v_mfma_f32_16x16x32_bf16 v[28:31], v[120:123], v[198:201], v[28:31]
	v_mfma_f32_16x16x32_bf16 v[24:27], v[128:131], v[198:201], v[24:27]
	v_mfma_f32_16x16x32_bf16 v[12:15], v[120:123], v[206:209], v[12:15]
	v_mfma_f32_16x16x32_bf16 v[8:11], v[128:131], v[206:209], v[8:11]
	v_mfma_f32_16x16x32_bf16 v[60:63], v[124:127], v[186:189], v[60:63]
	v_mfma_f32_16x16x32_bf16 v[56:59], v[132:135], v[186:189], v[56:59]
	v_mfma_f32_16x16x32_bf16 v[44:47], v[124:127], v[194:197], v[44:47]
	v_mfma_f32_16x16x32_bf16 v[40:43], v[132:135], v[194:197], v[40:43]
	v_mfma_f32_16x16x32_bf16 v[28:31], v[124:127], v[202:205], v[28:31]
	v_mfma_f32_16x16x32_bf16 v[24:27], v[132:135], v[202:205], v[24:27]
	v_mfma_f32_16x16x32_bf16 v[12:15], v[124:127], v[210:213], v[12:15]
	v_mfma_f32_16x16x32_bf16 v[8:11], v[132:135], v[210:213], v[8:11]
	v_mfma_f32_16x16x32_bf16 v[52:55], v[160:163], v[182:185], v[52:55]
	v_mfma_f32_16x16x32_bf16 v[48:51], v[174:177], v[182:185], v[48:51]
	v_mfma_f32_16x16x32_bf16 v[36:39], v[160:163], v[190:193], v[36:39]
	v_mfma_f32_16x16x32_bf16 v[32:35], v[174:177], v[190:193], v[32:35]
	v_mfma_f32_16x16x32_bf16 v[20:23], v[160:163], v[198:201], v[20:23]
	v_mfma_f32_16x16x32_bf16 v[16:19], v[174:177], v[198:201], v[16:19]
	v_mfma_f32_16x16x32_bf16 v[4:7], v[160:163], v[206:209], v[4:7]
	v_mfma_f32_16x16x32_bf16 v[0:3], v[174:177], v[206:209], v[0:3]
	v_mfma_f32_16x16x32_bf16 v[52:55], v[170:173], v[186:189], v[52:55]
	v_mfma_f32_16x16x32_bf16 v[48:51], v[178:181], v[186:189], v[48:51]
	v_mfma_f32_16x16x32_bf16 v[36:39], v[170:173], v[194:197], v[36:39]
	v_mfma_f32_16x16x32_bf16 v[32:35], v[178:181], v[194:197], v[32:35]
	v_mfma_f32_16x16x32_bf16 v[20:23], v[170:173], v[202:205], v[20:23]
	v_mfma_f32_16x16x32_bf16 v[16:19], v[178:181], v[202:205], v[16:19]
	v_mfma_f32_16x16x32_bf16 v[4:7], v[170:173], v[210:213], v[4:7]
	v_mfma_f32_16x16x32_bf16 v[0:3], v[178:181], v[210:213], v[0:3]
	s_setprio 0
	s_barrier
; __device__ __forceinline__ int lane_id_() { int l; asm volatile("v_mbcnt_lo_u32_b32 %0, -1, 0\n\tv_mbcnt_hi_u32_b32 %0, -1, %0" : "=v"(l)); return l; }
; #define PG8_STAGE(bufoff, gbase, voff) do { _Pragma("unroll") for (int _i = 0; _i < 2; ++_i) \
;         __builtin_amdgcn_global_load_lds((const unsigned*)((const char*)(gbase) + (voff)[_i]), (LAS unsigned*)(lds + (bufoff) + ldsw + _i * 8192), 16, 0, 0); } while (0)
; #define PG8_LDA(dst, b, h) do { _Pragma("unroll") for (int m = 0; m < 4; ++m) _Pragma("unroll") for (int k = 0; k < 2; ++k) dst[m][k] = *(const LAS bf16x8*)(lds + PG8_SA(b, h) + aoff + m * 2048 + k * 1024); } while (0)
; #define PG8_LDB(dst, b, h) do { _Pragma("unroll") for (int n = 0; n < 2; ++n) _Pragma("unroll") for (int k = 0; k < 2; ++k) dst[n][k] = *(const LAS bf16x8*)(lds + PG8_SB(b, h) + boff + n * 2048 + k * 1024); } while (0)
; #define PG8_MMA(ai, bj, At, Bt) do { __builtin_amdgcn_s_setprio(1); _Pragma("unroll") for (int m = 0; m < 4; ++m) _Pragma("unroll") for (int n = 0; n < 2; ++n) _Pragma("unroll") for (int k = 0; k < 2; ++k) \
;         acc[ai][bj][m][n] = __builtin_amdgcn_mfma_f32_16x16x32_bf16(Bt[n][k], At[m][k], acc[ai][bj][m][n], 0, 0, 0); __builtin_amdgcn_s_setprio(0); } while (0)
; #define PG8_WAIT_V(n) asm volatile("s_waitcnt vmcnt(" #n ")" ::: "memory")
; #define PG8_WAIT_L(n) asm volatile("s_waitcnt lgkmcnt(" #n ")" ::: "memory")
; #define PG8_BAR __builtin_amdgcn_s_barrier()
; #define PG8_SCHED __builtin_amdgcn_sched_barrier(0)
; template <class Epi, bool ALIGN_EPI, int K, int LDA, int LDB>
; __device__ __forceinline__ void gemm_phase(LAS unsigned char* lds, const int wid, const Gemm g, const StaticOrder& S, const Epi& E) {
;     ...
;             PG8_LDB(B0, 1, 0); PG8_LDB(B1, 1, 1); PG8_SCHED; PG8_LDA(At, 1, 0); PG8_STAGE(PG8_SA(0, 1), a2 + hA, voffA);
;             PG8_WAIT_V(8); PG8_WAIT_L(0); PG8_BAR; PG8_MMA(0, 0, At, B0); PG8_MMA(0, 1, At, B1); PG8_BAR; PG8_SCHED;
;             PG8_LDA(At, 1, 1); PG8_STAGE(PG8_SB(1, 0), b3, voffB); PG8_STAGE(PG8_SB(1, 1), b3 + hB, voffB); PG8_STAGE(PG8_SA(1, 0), a3, voffA);
;             PG8_WAIT_V(8); PG8_WAIT_L(0); PG8_BAR; PG8_MMA(1, 0, At, B0); PG8_MMA(1, 1, At, B1); PG8_BAR; PG8_SCHED;
;         }
;         if constexpr (ALIGN_EPI) { if (wr == 0) PG8_BAR; }
;         { const int l2 = lane_id_(); E(acc, cur, wid >> 2, wid & 3, l2 & 15, l2 >> 4); }
;         if (!has_next) break;
	s_add_i32 s52, 0, 0x18000
	s_add_i32 s53, 0, 0x1c000
	v_add_u32_e32 v132, s52, v166
	v_add_u32_e32 v178, s53, v166
	ds_read_b128 v[120:123], v132
	ds_read_b128 v[124:127], v132 offset:1024
	ds_read_b128 v[128:131], v132 offset:2048
	ds_read_b128 v[132:135], v132 offset:3072
	ds_read_b128 v[160:163], v178
	ds_read_b128 v[170:173], v178 offset:1024
	ds_read_b128 v[174:177], v178 offset:2048
	ds_read_b128 v[178:181], v178 offset:3072
	s_add_u32 s26, s34, 0xb0000
	s_addc_u32 s27, s35, 0
	s_mov_b32 m0, s38
	ds_read_b128 v[182:185], v169 offset:32768
	ds_read_b128 v[186:189], v169 offset:33792
	ds_read_b128 v[190:193], v169 offset:34816
	ds_read_b128 v[194:197], v169 offset:35840
	ds_read_b128 v[198:201], v169 offset:36864
	ds_read_b128 v[202:205], v169 offset:37888
	ds_read_b128 v[206:209], v169 offset:38912
	ds_read_b128 v[210:213], v169 offset:39936
	global_load_lds_dwordx4 v144, s[26:27]
	s_mov_b32 m0, s39
	s_nop 0
	global_load_lds_dwordx4 v148, s[26:27]
	s_waitcnt vmcnt(8)
	s_waitcnt lgkmcnt(0)
	s_barrier
	s_setprio 1
	s_waitcnt lgkmcnt(0)
	v_mfma_f32_16x16x32_bf16 v[140:143], v[120:123], v[182:185], v[140:143]
	v_mfma_f32_16x16x32_bf16 v[136:139], v[128:131], v[182:185], v[136:139]
	v_mfma_f32_16x16x32_bf16 v[108:111], v[120:123], v[190:193], v[108:111]
	v_mfma_f32_16x16x32_bf16 v[104:107], v[128:131], v[190:193], v[104:107]
	v_mfma_f32_16x16x32_bf16 v[92:95], v[120:123], v[198:201], v[92:95]
	v_mfma_f32_16x16x32_bf16 v[88:91], v[128:131], v[198:201], v[88:91]
	v_mfma_f32_16x16x32_bf16 v[76:79], v[120:123], v[206:209], v[76:79]
	v_mfma_f32_16x16x32_bf16 v[72:75], v[128:131], v[206:209], v[72:75]
	v_mfma_f32_16x16x32_bf16 v[140:143], v[124:127], v[186:189], v[140:143]
	v_mfma_f32_16x16x32_bf16 v[136:139], v[132:135], v[186:189], v[136:139]
	v_mfma_f32_16x16x32_bf16 v[108:111], v[124:127], v[194:197], v[108:111]
	v_mfma_f32_16x16x32_bf16 v[104:107], v[132:135], v[194:197], v[104:107]
	v_mfma_f32_16x16x32_bf16 v[92:95], v[124:127], v[202:205], v[92:95]
	v_mfma_f32_16x16x32_bf16 v[88:91], v[132:135], v[202:205], v[88:91]
	v_mfma_f32_16x16x32_bf16 v[76:79], v[124:127], v[210:213], v[76:79]
	v_mfma_f32_16x16x32_bf16 v[72:75], v[132:135], v[210:213], v[72:75]
	v_mfma_f32_16x16x32_bf16 v[116:119], v[160:163], v[182:185], v[116:119]
	v_mfma_f32_16x16x32_bf16 v[112:115], v[174:177], v[182:185], v[112:115]
	v_mfma_f32_16x16x32_bf16 v[100:103], v[160:163], v[190:193], v[100:103]
	v_mfma_f32_16x16x32_bf16 v[96:99], v[174:177], v[190:193], v[96:99]
	v_mfma_f32_16x16x32_bf16 v[84:87], v[160:163], v[198:201], v[84:87]
	v_mfma_f32_16x16x32_bf16 v[80:83], v[174:177], v[198:201], v[80:83]
	v_mfma_f32_16x16x32_bf16 v[68:71], v[160:163], v[206:209], v[68:71]
	v_mfma_f32_16x16x32_bf16 v[64:67], v[174:177], v[206:209], v[64:67]
	v_mfma_f32_16x16x32_bf16 v[116:119], v[170:173], v[186:189], v[116:119]
	v_mfma_f32_16x16x32_bf16 v[112:115], v[178:181], v[186:189], v[112:115]
	v_mfma_f32_16x16x32_bf16 v[100:103], v[170:173], v[194:197], v[100:103]
	v_mfma_f32_16x16x32_bf16 v[96:99], v[178:181], v[194:197], v[96:99]
	v_mfma_f32_16x16x32_bf16 v[84:87], v[170:173], v[202:205], v[84:87]
	v_mfma_f32_16x16x32_bf16 v[80:83], v[178:181], v[202:205], v[80:83]
	v_mfma_f32_16x16x32_bf16 v[68:71], v[170:173], v[210:213], v[68:71]
	v_mfma_f32_16x16x32_bf16 v[64:67], v[178:181], v[210:213], v[64:67]
	s_setprio 0
	s_barrier
	s_add_i32 s26, s52, s33
	s_mov_b32 m0, s26
	ds_read_b128 v[182:185], v169 offset:49152
	ds_read_b128 v[186:189], v169 offset:50176
	ds_read_b128 v[190:193], v169 offset:51200
	ds_read_b128 v[194:197], v169 offset:52224
	ds_read_b128 v[198:201], v169 offset:53248
	ds_read_b128 v[202:205], v169 offset:54272
	ds_read_b128 v[206:209], v169 offset:55296
	ds_read_b128 v[210:213], v169 offset:56320
	global_load_lds_dwordx4 v146, s[98:99]
	s_add_i32 m0, s26, 0x2000
	s_add_u32 s26, s30, 0xb0080
	s_addc_u32 s27, s31, 0
	s_add_i32 s30, s53, s33
	global_load_lds_dwordx4 v150, s[98:99]
	s_mov_b32 m0, s30
	s_nop 0
	global_load_lds_dwordx4 v146, s[26:27]
	s_add_i32 m0, s30, 0x2000
	s_nop 0
	global_load_lds_dwordx4 v150, s[26:27]
	s_mov_b32 m0, s48
	s_nop 0
	global_load_lds_dwordx4 v144, s[100:101]
	s_mov_b32 m0, s49
	s_nop 0
	global_load_lds_dwordx4 v148, s[100:101]
	s_waitcnt vmcnt(8)
	s_waitcnt lgkmcnt(0)
	s_barrier
	s_setprio 1
	s_waitcnt lgkmcnt(0)
	v_mfma_f32_16x16x32_bf16 v[60:63], v[120:123], v[182:185], v[60:63]
	v_mfma_f32_16x16x32_bf16 v[56:59], v[128:131], v[182:185], v[56:59]
	v_mfma_f32_16x16x32_bf16 v[44:47], v[120:123], v[190:193], v[44:47]
	v_mfma_f32_16x16x32_bf16 v[40:43], v[128:131], v[190:193], v[40:43]
	v_mfma_f32_16x16x32_bf16 v[28:31], v[120:123], v[198:201], v[28:31]
	v_mfma_f32_16x16x32_bf16 v[24:27], v[128:131], v[198:201], v[24:27]
	v_mfma_f32_16x16x32_bf16 v[12:15], v[120:123], v[206:209], v[12:15]
	v_mfma_f32_16x16x32_bf16 v[8:11], v[128:131], v[206:209], v[8:11]
	v_mfma_f32_16x16x32_bf16 v[60:63], v[124:127], v[186:189], v[60:63]
	v_mfma_f32_16x16x32_bf16 v[56:59], v[132:135], v[186:189], v[56:59]
	v_mfma_f32_16x16x32_bf16 v[44:47], v[124:127], v[194:197], v[44:47]
	v_mfma_f32_16x16x32_bf16 v[40:43], v[132:135], v[194:197], v[40:43]
	v_mfma_f32_16x16x32_bf16 v[28:31], v[124:127], v[202:205], v[28:31]
	v_mfma_f32_16x16x32_bf16 v[24:27], v[132:135], v[202:205], v[24:27]
	v_mfma_f32_16x16x32_bf16 v[12:15], v[124:127], v[210:213], v[12:15]
	v_mfma_f32_16x16x32_bf16 v[8:11], v[132:135], v[210:213], v[8:11]
	v_mfma_f32_16x16x32_bf16 v[52:55], v[160:163], v[182:185], v[52:55]
	v_mfma_f32_16x16x32_bf16 v[48:51], v[174:177], v[182:185], v[48:51]
	v_mfma_f32_16x16x32_bf16 v[36:39], v[160:163], v[190:193], v[36:39]
	v_mfma_f32_16x16x32_bf16 v[32:35], v[174:177], v[190:193], v[32:35]
	v_mfma_f32_16x16x32_bf16 v[20:23], v[160:163], v[198:201], v[20:23]
	v_mfma_f32_16x16x32_bf16 v[16:19], v[174:177], v[198:201], v[16:19]
	v_mfma_f32_16x16x32_bf16 v[4:7], v[160:163], v[206:209], v[4:7]
	v_mfma_f32_16x16x32_bf16 v[0:3], v[174:177], v[206:209], v[0:3]
	v_mfma_f32_16x16x32_bf16 v[52:55], v[170:173], v[186:189], v[52:55]
	v_mfma_f32_16x16x32_bf16 v[48:51], v[178:181], v[186:189], v[48:51]
	v_mfma_f32_16x16x32_bf16 v[36:39], v[170:173], v[194:197], v[36:39]
	v_mfma_f32_16x16x32_bf16 v[32:35], v[178:181], v[194:197], v[32:35]
	v_mfma_f32_16x16x32_bf16 v[20:23], v[170:173], v[202:205], v[20:23]
	v_mfma_f32_16x16x32_bf16 v[16:19], v[178:181], v[202:205], v[16:19]
	v_mfma_f32_16x16x32_bf16 v[4:7], v[170:173], v[210:213], v[4:7]
	v_mfma_f32_16x16x32_bf16 v[0:3], v[178:181], v[210:213], v[0:3]
	s_setprio 0
	s_barrier
	s_add_i32 s63, s63, 2
	s_add_u32 s61, s61, 0x100
	s_addc_u32 s62, s62, 0
	s_cmp_gt_u32 s63, 41
	s_mov_b64 s[26:27], s[28:29]
	s_cbranch_scc0 .LBB0_1697
	s_and_b64 vcc, exec, s[14:15]
	s_cbranch_vccz .LBB0_1700
	s_barrier
